# v22 + GEMM MFMA issue order changed so consecutive MFMAs share one source operand (A fixed for 4)
# baseline (speedup 1.0000x reference)
; #define PG8_STAGE(bufoff, gbase, voff) do { _Pragma("unroll") for (int _i = 0; _i < 2; ++_i) \
;         __builtin_amdgcn_global_load_lds((const unsigned*)((const char*)(gbase) + (voff)[_i]), (PG8_LAS unsigned*)(lds + (bufoff) + ldsw + _i * 8192), 16, 0, 0); } while (0)
; #define PG8_LDA(dst, b, h) do { _Pragma("unroll") for (int m = 0; m < 4; ++m) _Pragma("unroll") for (int k = 0; k < 2; ++k) dst[m][k] = *(const PG8_LAS bf16x8*)(lds + PG8_SA(b, h) + aoff + m * 2048 + k * 1024); } while (0)
; #define PG8_LDB(dst, b, h) do { _Pragma("unroll") for (int n = 0; n < 2; ++n) _Pragma("unroll") for (int k = 0; k < 2; ++k) dst[n][k] = *(const PG8_LAS bf16x8*)(lds + PG8_SB(b, h) + boff + n * 2048 + k * 1024); } while (0)
; #define PG8_MMA(ai, bj, At, Bt) do { __builtin_amdgcn_s_setprio(1); _Pragma("unroll") for (int m = 0; m < 4; ++m) _Pragma("unroll") for (int n = 0; n < 2; ++n) _Pragma("unroll") for (int k = 0; k < 2; ++k) \
;         acc[ai][bj][m][n] = __builtin_amdgcn_mfma_f32_16x16x32_bf16(Bt[n][k], At[m][k], acc[ai][bj][m][n], 0, 0, 0); __builtin_amdgcn_s_setprio(0); } while (0)
; #define PG8_WAIT_V(n) asm volatile("s_waitcnt vmcnt(" #n ")" ::: "memory")
; #define PG8_BAR __builtin_amdgcn_s_barrier()
; template <class Epi, class Sched, bool ALIGN_EPI = false, bool SP2 = false>
; __device__ __forceinline__ void gemm_phase(PG8_LAS unsigned char* lds, const Gemm g, const Sched& S, const Epi& E) {
;     ...
;         for (int t = 0; t < nt; t += 2) {
;             const bool last = (t == nt - 2);
;             const char* a1 = cA + (size_t)(t + 1) * kstep;
;             const char* a2 = last ? nA : cA + (size_t)(t + 2) * kstep; const char* b2 = last ? nB : cB + (size_t)(t + 2) * kstep;
;             const char* a3 = a2 + kstep; const char* b3 = b2 + kstep;
;             if (last && has_next) S.a_ready(nxt);
;             if constexpr (SP2) {
;             PG8_LDB(B0, 0, 0); PG8_LDB(B1, 0, 1); PG8_SCHED; PG8_LDA(At, 0, 0); PG8_STAGE(PG8_SA(1, 1), a1 + hstep, voffA);
;             PG8_WAIT_V(8); PG8_WAIT_L(0); PG8_BAR; PG8_MMA(0, 0, At, B0); PG8_MMA(0, 1, At, B1); PG8_BAR; PG8_SCHED;
;             PG8_LDA(At, 0, 1); PG8_STAGE(PG8_SB(0, 0), b2, voffB); PG8_STAGE(PG8_SB(0, 1), b2 + hstep, voffB); PG8_STAGE(PG8_SA(0, 0), a2, voffA);
;             PG8_WAIT_V(8); PG8_WAIT_L(0); PG8_BAR; PG8_MMA(1, 0, At, B0); PG8_MMA(1, 1, At, B1); PG8_BAR; PG8_SCHED;
.LBB0_347:
	s_and_b64 vcc, exec, s[6:7]
	s_cbranch_vccnz .Lcoldz_0
	s_add_u32 s38, s38, 0x80
	s_addc_u32 s39, s39, 0
	s_add_u32 s24, s40, 0x100
	s_addc_u32 s25, s41, 0
	s_mov_b32 s40, 0
	ds_read_b128 v[152:155], v148
	ds_read_b128 v[156:159], v148 offset:1024
	ds_read_b128 v[160:163], v148 offset:2048
	ds_read_b128 v[164:167], v148 offset:3072
	ds_read_b128 v[168:171], v149
	ds_read_b128 v[172:175], v149 offset:1024
	ds_read_b128 v[176:179], v149 offset:2048
	ds_read_b128 v[180:183], v149 offset:3072
	s_add_i32 s54, s40, 2
	s_add_u32 s55, s38, 0x80
	s_addc_u32 s41, s39, 0
	s_cmp_eq_u32 s43, s40
	s_cselect_b32 s40, s10, s55
	s_cselect_b32 s41, s11, s41
	s_cselect_b32 s57, s37, s25
	s_cselect_b32 s56, s36, s24
	s_mov_b32 m0, s47
	v_lshl_add_u64 v[216:217], s[38:39], 0, v[136:137]
	ds_read_b128 v[184:187], v150
	ds_read_b128 v[188:191], v150 offset:1024
	ds_read_b128 v[192:195], v150 offset:2048
	ds_read_b128 v[196:199], v150 offset:3072
	ds_read_b128 v[200:203], v150 offset:4096
	ds_read_b128 v[204:207], v150 offset:5120
	ds_read_b128 v[208:211], v150 offset:6144
	ds_read_b128 v[212:215], v150 offset:7168
	global_load_lds_dwordx4 v[216:217], off
	v_lshl_add_u64 v[216:217], s[38:39], 0, v[138:139]
	s_mov_b32 m0, s48
	s_nop 0
	global_load_lds_dwordx4 v[216:217], off
	s_waitcnt vmcnt(8)
	s_waitcnt lgkmcnt(0)
	s_barrier
	s_setprio 1
	s_waitcnt lgkmcnt(0)
	v_mfma_f32_16x16x32_bf16 v[120:123], v[152:155], v[184:187], 0
	v_mfma_f32_16x16x32_bf16 v[116:119], v[160:163], v[184:187], 0
	v_mfma_f32_16x16x32_bf16 v[108:111], v[152:155], v[192:195], 0
	v_mfma_f32_16x16x32_bf16 v[100:103], v[160:163], v[192:195], 0
	v_mfma_f32_16x16x32_bf16 v[92:95], v[152:155], v[200:203], 0
	v_mfma_f32_16x16x32_bf16 v[84:87], v[160:163], v[200:203], 0
	v_mfma_f32_16x16x32_bf16 v[76:79], v[152:155], v[208:211], 0
	v_mfma_f32_16x16x32_bf16 v[68:71], v[160:163], v[208:211], 0
	v_mfma_f32_16x16x32_bf16 v[120:123], v[156:159], v[188:191], v[120:123]
	v_mfma_f32_16x16x32_bf16 v[108:111], v[156:159], v[196:199], v[108:111]
	v_mfma_f32_16x16x32_bf16 v[92:95], v[156:159], v[204:207], v[92:95]
	v_mfma_f32_16x16x32_bf16 v[76:79], v[156:159], v[212:215], v[76:79]
	v_mfma_f32_16x16x32_bf16 v[68:71], v[164:167], v[212:215], v[68:71]
	v_mfma_f32_16x16x32_bf16 v[84:87], v[164:167], v[204:207], v[84:87]
	v_mfma_f32_16x16x32_bf16 v[100:103], v[164:167], v[196:199], v[100:103]
	v_mfma_f32_16x16x32_bf16 v[116:119], v[164:167], v[188:191], v[116:119]
	s_setprio 0
	s_setprio 1
	v_mfma_f32_16x16x32_bf16 v[124:127], v[168:171], v[184:187], 0
	v_mfma_f32_16x16x32_bf16 v[112:115], v[176:179], v[184:187], 0
	v_mfma_f32_16x16x32_bf16 v[104:107], v[168:171], v[192:195], 0
	v_mfma_f32_16x16x32_bf16 v[96:99], v[176:179], v[192:195], 0
	v_mfma_f32_16x16x32_bf16 v[88:91], v[168:171], v[200:203], 0
	v_mfma_f32_16x16x32_bf16 v[80:83], v[176:179], v[200:203], 0
	v_mfma_f32_16x16x32_bf16 v[72:75], v[168:171], v[208:211], 0
	v_mfma_f32_16x16x32_bf16 v[64:67], v[176:179], v[208:211], 0
	v_mfma_f32_16x16x32_bf16 v[124:127], v[172:175], v[188:191], v[124:127]
	v_mfma_f32_16x16x32_bf16 v[104:107], v[172:175], v[196:199], v[104:107]
	v_mfma_f32_16x16x32_bf16 v[88:91], v[172:175], v[204:207], v[88:91]
	v_mfma_f32_16x16x32_bf16 v[72:75], v[172:175], v[212:215], v[72:75]
	v_mfma_f32_16x16x32_bf16 v[64:67], v[180:183], v[212:215], v[64:67]
	v_mfma_f32_16x16x32_bf16 v[80:83], v[180:183], v[204:207], v[80:83]
	v_mfma_f32_16x16x32_bf16 v[96:99], v[180:183], v[196:199], v[96:99]
	v_mfma_f32_16x16x32_bf16 v[112:115], v[180:183], v[188:191], v[112:115]
	s_setprio 0
	s_barrier
	s_add_i32 s55, s44, s3
	v_lshl_add_u64 v[216:217], s[56:57], 0, v[132:133]
	s_mov_b32 m0, s55
	ds_read_b128 v[184:187], v150 offset:16384
	ds_read_b128 v[188:191], v150 offset:17408
	ds_read_b128 v[192:195], v150 offset:18432
	ds_read_b128 v[196:199], v150 offset:19456
	ds_read_b128 v[200:203], v150 offset:20480
	ds_read_b128 v[204:207], v150 offset:21504
	ds_read_b128 v[208:211], v150 offset:22528
	ds_read_b128 v[212:215], v150 offset:23552
	global_load_lds_dwordx4 v[216:217], off
	s_add_i32 m0, s55, 0x2000
	v_lshl_add_u64 v[218:219], s[56:57], 0, v[128:129]
	s_add_u32 s56, s56, s12
	s_addc_u32 s57, s57, s13
	s_add_i32 s55, s45, s3
	global_load_lds_dwordx4 v[218:219], off
	v_lshl_add_u64 v[220:221], s[56:57], 0, v[132:133]
	s_mov_b32 m0, s55
	v_lshl_add_u64 v[222:223], s[56:57], 0, v[128:129]
	global_load_lds_dwordx4 v[220:221], off
	s_add_i32 m0, s55, 0x2000
	v_lshl_add_u64 v[224:225], s[40:41], 0, v[134:135]
	global_load_lds_dwordx4 v[222:223], off
	s_mov_b32 m0, s17
	v_lshl_add_u64 v[226:227], s[40:41], 0, v[130:131]
	global_load_lds_dwordx4 v[224:225], off
	s_mov_b32 m0, s18
	s_nop 0
	global_load_lds_dwordx4 v[226:227], off
	s_waitcnt vmcnt(8)
	s_waitcnt lgkmcnt(0)
	s_barrier
; #define PG8_STAGE(bufoff, gbase, voff) do { _Pragma("unroll") for (int _i = 0; _i < 2; ++_i) \
;         __builtin_amdgcn_global_load_lds((const unsigned*)((const char*)(gbase) + (voff)[_i]), (PG8_LAS unsigned*)(lds + (bufoff) + ldsw + _i * 8192), 16, 0, 0); } while (0)
; #define PG8_LDA(dst, b, h) do { _Pragma("unroll") for (int m = 0; m < 4; ++m) _Pragma("unroll") for (int k = 0; k < 2; ++k) dst[m][k] = *(const PG8_LAS bf16x8*)(lds + PG8_SA(b, h) + aoff + m * 2048 + k * 1024); } while (0)
; #define PG8_LDB(dst, b, h) do { _Pragma("unroll") for (int n = 0; n < 2; ++n) _Pragma("unroll") for (int k = 0; k < 2; ++k) dst[n][k] = *(const PG8_LAS bf16x8*)(lds + PG8_SB(b, h) + boff + n * 2048 + k * 1024); } while (0)
; #define PG8_MMA(ai, bj, At, Bt) do { __builtin_amdgcn_s_setprio(1); _Pragma("unroll") for (int m = 0; m < 4; ++m) _Pragma("unroll") for (int n = 0; n < 2; ++n) _Pragma("unroll") for (int k = 0; k < 2; ++k) \
;         acc[ai][bj][m][n] = __builtin_amdgcn_mfma_f32_16x16x32_bf16(Bt[n][k], At[m][k], acc[ai][bj][m][n], 0, 0, 0); __builtin_amdgcn_s_setprio(0); } while (0)
; #define PG8_WAIT_V(n) asm volatile("s_waitcnt vmcnt(" #n ")" ::: "memory")
; #define PG8_WAIT_L(n) asm volatile("s_waitcnt lgkmcnt(" #n ")" ::: "memory")
; #define PG8_BAR __builtin_amdgcn_s_barrier()
; #define PG8_SCHED __builtin_amdgcn_sched_barrier(0)
; template <class Epi, class Sched, bool ALIGN_EPI = false, bool SP2 = false>
; __device__ __forceinline__ void gemm_phase(PG8_LAS unsigned char* lds, const Gemm g, const Sched& S, const Epi& E) {
;     ...
;             PG8_WAIT_V(8); PG8_WAIT_L(0); PG8_BAR; PG8_MMA(1, 0, At, B0); PG8_MMA(1, 1, At, B1); PG8_BAR; PG8_SCHED;
;             PG8_LDB(B0, 1, 0); PG8_LDB(B1, 1, 1); PG8_SCHED; PG8_LDA(At, 1, 0); PG8_STAGE(PG8_SA(0, 1), a2 + hstep, voffA);
;             PG8_WAIT_V(8); PG8_WAIT_L(0); PG8_BAR; PG8_MMA(0, 0, At, B0); PG8_MMA(0, 1, At, B1); PG8_BAR; PG8_SCHED;
	s_setprio 1
	s_waitcnt lgkmcnt(0)
	v_mfma_f32_16x16x32_bf16 v[60:63], v[152:155], v[184:187], 0
	v_mfma_f32_16x16x32_bf16 v[52:55], v[160:163], v[184:187], 0
	v_mfma_f32_16x16x32_bf16 v[44:47], v[152:155], v[192:195], 0
	v_mfma_f32_16x16x32_bf16 v[36:39], v[160:163], v[192:195], 0
	v_mfma_f32_16x16x32_bf16 v[28:31], v[152:155], v[200:203], 0
	v_mfma_f32_16x16x32_bf16 v[20:23], v[160:163], v[200:203], 0
	v_mfma_f32_16x16x32_bf16 v[12:15], v[152:155], v[208:211], 0
	v_mfma_f32_16x16x32_bf16 v[4:7], v[160:163], v[208:211], 0
	v_mfma_f32_16x16x32_bf16 v[60:63], v[156:159], v[188:191], v[60:63]
	v_mfma_f32_16x16x32_bf16 v[44:47], v[156:159], v[196:199], v[44:47]
	v_mfma_f32_16x16x32_bf16 v[28:31], v[156:159], v[204:207], v[28:31]
	v_mfma_f32_16x16x32_bf16 v[12:15], v[156:159], v[212:215], v[12:15]
	v_mfma_f32_16x16x32_bf16 v[4:7], v[164:167], v[212:215], v[4:7]
	v_mfma_f32_16x16x32_bf16 v[20:23], v[164:167], v[204:207], v[20:23]
	v_mfma_f32_16x16x32_bf16 v[36:39], v[164:167], v[196:199], v[36:39]
	v_mfma_f32_16x16x32_bf16 v[52:55], v[164:167], v[188:191], v[52:55]
	s_setprio 0
	s_setprio 1
	v_mfma_f32_16x16x32_bf16 v[56:59], v[168:171], v[184:187], 0
	v_mfma_f32_16x16x32_bf16 v[48:51], v[176:179], v[184:187], 0
	v_mfma_f32_16x16x32_bf16 v[40:43], v[168:171], v[192:195], 0
	v_mfma_f32_16x16x32_bf16 v[32:35], v[176:179], v[192:195], 0
	v_mfma_f32_16x16x32_bf16 v[24:27], v[168:171], v[200:203], 0
	v_mfma_f32_16x16x32_bf16 v[16:19], v[176:179], v[200:203], 0
	v_mfma_f32_16x16x32_bf16 v[8:11], v[168:171], v[208:211], 0
	v_mfma_f32_16x16x32_bf16 v[0:3], v[176:179], v[208:211], 0
	v_mfma_f32_16x16x32_bf16 v[56:59], v[172:175], v[188:191], v[56:59]
	v_mfma_f32_16x16x32_bf16 v[40:43], v[172:175], v[196:199], v[40:43]
	v_mfma_f32_16x16x32_bf16 v[24:27], v[172:175], v[204:207], v[24:27]
	v_mfma_f32_16x16x32_bf16 v[8:11], v[172:175], v[212:215], v[8:11]
	v_mfma_f32_16x16x32_bf16 v[0:3], v[180:183], v[212:215], v[0:3]
	v_mfma_f32_16x16x32_bf16 v[16:19], v[180:183], v[204:207], v[16:19]
	v_mfma_f32_16x16x32_bf16 v[32:35], v[180:183], v[196:199], v[32:35]
	v_mfma_f32_16x16x32_bf16 v[48:51], v[180:183], v[188:191], v[48:51]
	s_setprio 0
	s_barrier
	s_add_i32 s55, 0, 0x18000
	v_add_u32_e32 v151, s55, v145
	s_add_i32 s56, 0, 0x1c000
	ds_read_b128 v[152:155], v151
	ds_read_b128 v[156:159], v151 offset:1024
	ds_read_b128 v[160:163], v151 offset:2048
	ds_read_b128 v[164:167], v151 offset:3072
	v_add_u32_e32 v151, s56, v145
	ds_read_b128 v[168:171], v151
	ds_read_b128 v[172:175], v151 offset:1024
	ds_read_b128 v[176:179], v151 offset:2048
	ds_read_b128 v[180:183], v151 offset:3072
	s_add_u32 s40, s40, s12
	s_addc_u32 s41, s41, s13
	s_mov_b32 m0, s19
	v_lshl_add_u64 v[228:229], s[40:41], 0, v[134:135]
	ds_read_b128 v[184:187], v150 offset:32768
	ds_read_b128 v[188:191], v150 offset:33792
	ds_read_b128 v[192:195], v150 offset:34816
	ds_read_b128 v[196:199], v150 offset:35840
	ds_read_b128 v[200:203], v150 offset:36864
	ds_read_b128 v[204:207], v150 offset:37888
	ds_read_b128 v[208:211], v150 offset:38912
	ds_read_b128 v[212:215], v150 offset:39936
	global_load_lds_dwordx4 v[228:229], off
	v_lshl_add_u64 v[228:229], s[40:41], 0, v[130:131]
	s_mov_b32 m0, s26
	s_nop 0
	global_load_lds_dwordx4 v[228:229], off
	s_waitcnt vmcnt(8)
	s_waitcnt lgkmcnt(0)
	s_barrier
	s_setprio 1
	s_waitcnt lgkmcnt(0)
	v_mfma_f32_16x16x32_bf16 v[120:123], v[152:155], v[184:187], v[120:123]
	v_mfma_f32_16x16x32_bf16 v[108:111], v[152:155], v[192:195], v[108:111]
	v_mfma_f32_16x16x32_bf16 v[92:95], v[152:155], v[200:203], v[92:95]
	v_mfma_f32_16x16x32_bf16 v[76:79], v[152:155], v[208:211], v[76:79]
	v_mfma_f32_16x16x32_bf16 v[68:71], v[160:163], v[208:211], v[68:71]
	v_mfma_f32_16x16x32_bf16 v[84:87], v[160:163], v[200:203], v[84:87]
	v_mfma_f32_16x16x32_bf16 v[100:103], v[160:163], v[192:195], v[100:103]
	v_mfma_f32_16x16x32_bf16 v[116:119], v[160:163], v[184:187], v[116:119]
	v_mfma_f32_16x16x32_bf16 v[120:123], v[156:159], v[188:191], v[120:123]
	v_mfma_f32_16x16x32_bf16 v[108:111], v[156:159], v[196:199], v[108:111]
	v_mfma_f32_16x16x32_bf16 v[92:95], v[156:159], v[204:207], v[92:95]
	v_mfma_f32_16x16x32_bf16 v[76:79], v[156:159], v[212:215], v[76:79]
	v_mfma_f32_16x16x32_bf16 v[68:71], v[164:167], v[212:215], v[68:71]
	v_mfma_f32_16x16x32_bf16 v[84:87], v[164:167], v[204:207], v[84:87]
	v_mfma_f32_16x16x32_bf16 v[100:103], v[164:167], v[196:199], v[100:103]
	v_mfma_f32_16x16x32_bf16 v[116:119], v[164:167], v[188:191], v[116:119]
	s_setprio 0
	s_setprio 1
	v_mfma_f32_16x16x32_bf16 v[124:127], v[168:171], v[184:187], v[124:127]
	v_mfma_f32_16x16x32_bf16 v[104:107], v[168:171], v[192:195], v[104:107]
	v_mfma_f32_16x16x32_bf16 v[88:91], v[168:171], v[200:203], v[88:91]
	v_mfma_f32_16x16x32_bf16 v[72:75], v[168:171], v[208:211], v[72:75]
	v_mfma_f32_16x16x32_bf16 v[64:67], v[176:179], v[208:211], v[64:67]
	v_mfma_f32_16x16x32_bf16 v[80:83], v[176:179], v[200:203], v[80:83]
	v_mfma_f32_16x16x32_bf16 v[96:99], v[176:179], v[192:195], v[96:99]
	v_mfma_f32_16x16x32_bf16 v[112:115], v[176:179], v[184:187], v[112:115]
	v_mfma_f32_16x16x32_bf16 v[124:127], v[172:175], v[188:191], v[124:127]
	v_mfma_f32_16x16x32_bf16 v[104:107], v[172:175], v[196:199], v[104:107]
	v_mfma_f32_16x16x32_bf16 v[88:91], v[172:175], v[204:207], v[88:91]
	v_mfma_f32_16x16x32_bf16 v[72:75], v[172:175], v[212:215], v[72:75]
	v_mfma_f32_16x16x32_bf16 v[64:67], v[180:183], v[212:215], v[64:67]
	v_mfma_f32_16x16x32_bf16 v[80:83], v[180:183], v[204:207], v[80:83]
	v_mfma_f32_16x16x32_bf16 v[96:99], v[180:183], v[196:199], v[96:99]
	v_mfma_f32_16x16x32_bf16 v[112:115], v[180:183], v[188:191], v[112:115]
	s_setprio 0
	s_barrier
; #define PG8_STAGE(bufoff, gbase, voff) do { _Pragma("unroll") for (int _i = 0; _i < 2; ++_i) \
;         __builtin_amdgcn_global_load_lds((const unsigned*)((const char*)(gbase) + (voff)[_i]), (PG8_LAS unsigned*)(lds + (bufoff) + ldsw + _i * 8192), 16, 0, 0); } while (0)
; #define PG8_LDA(dst, b, h) do { _Pragma("unroll") for (int m = 0; m < 4; ++m) _Pragma("unroll") for (int k = 0; k < 2; ++k) dst[m][k] = *(const PG8_LAS bf16x8*)(lds + PG8_SA(b, h) + aoff + m * 2048 + k * 1024); } while (0)
; #define PG8_LDB(dst, b, h) do { _Pragma("unroll") for (int n = 0; n < 2; ++n) _Pragma("unroll") for (int k = 0; k < 2; ++k) dst[n][k] = *(const PG8_LAS bf16x8*)(lds + PG8_SB(b, h) + boff + n * 2048 + k * 1024); } while (0)
; #define PG8_MMA(ai, bj, At, Bt) do { __builtin_amdgcn_s_setprio(1); _Pragma("unroll") for (int m = 0; m < 4; ++m) _Pragma("unroll") for (int n = 0; n < 2; ++n) _Pragma("unroll") for (int k = 0; k < 2; ++k) \
;         acc[ai][bj][m][n] = __builtin_amdgcn_mfma_f32_16x16x32_bf16(Bt[n][k], At[m][k], acc[ai][bj][m][n], 0, 0, 0); __builtin_amdgcn_s_setprio(0); } while (0)
; #define PG8_WAIT_V(n) asm volatile("s_waitcnt vmcnt(" #n ")" ::: "memory")
; #define PG8_WAIT_L(n) asm volatile("s_waitcnt lgkmcnt(" #n ")" ::: "memory")
; #define PG8_BAR __builtin_amdgcn_s_barrier()
; #define PG8_SCHED __builtin_amdgcn_sched_barrier(0)
; template <class Epi, class Sched, bool ALIGN_EPI = false, bool SP2 = false>
; __device__ __forceinline__ void gemm_phase(PG8_LAS unsigned char* lds, const Gemm g, const Sched& S, const Epi& E) {
;     ...
;         for (int t = 0; t < nt; t += 2) {
;             const bool last = (t == nt - 2);
;             const char* a1 = cA + (size_t)(t + 1) * kstep;
;             const char* a2 = last ? nA : cA + (size_t)(t + 2) * kstep; const char* b2 = last ? nB : cB + (size_t)(t + 2) * kstep;
;             const char* a3 = a2 + kstep; const char* b3 = b2 + kstep;
;             if (last && has_next) S.a_ready(nxt);
;             if constexpr (SP2) {
;             PG8_LDB(B0, 0, 0); PG8_LDB(B1, 0, 1); PG8_SCHED; PG8_LDA(At, 0, 0); PG8_STAGE(PG8_SA(1, 1), a1 + hstep, voffA);
;     ...
;             PG8_LDA(At, 1, 1); PG8_STAGE(PG8_SB(1, 0), b3, voffB); PG8_STAGE(PG8_SB(1, 1), b3 + hstep, voffB); PG8_STAGE(PG8_SA(1, 0), a3, voffA);
;             PG8_WAIT_V(8); PG8_WAIT_L(0); PG8_BAR; PG8_MMA(1, 0, At, B0); PG8_MMA(1, 1, At, B1); PG8_BAR; PG8_SCHED;
	s_add_i32 s40, s55, s3
	v_lshl_add_u64 v[216:217], v[216:217], 0, s[30:31]
	s_mov_b32 m0, s40
	ds_read_b128 v[184:187], v150 offset:49152
	ds_read_b128 v[188:191], v150 offset:50176
	ds_read_b128 v[192:195], v150 offset:51200
	ds_read_b128 v[196:199], v150 offset:52224
	ds_read_b128 v[200:203], v150 offset:53248
	ds_read_b128 v[204:207], v150 offset:54272
	ds_read_b128 v[208:211], v150 offset:55296
	ds_read_b128 v[212:215], v150 offset:56320
	global_load_lds_dwordx4 v[216:217], off
	v_lshl_add_u64 v[216:217], v[218:219], 0, s[30:31]
	s_add_i32 m0, s40, 0x2000
	s_add_i32 s40, s56, s3
	global_load_lds_dwordx4 v[216:217], off
	v_lshl_add_u64 v[216:217], v[220:221], 0, s[30:31]
	s_mov_b32 m0, s40
	s_nop 0
	global_load_lds_dwordx4 v[216:217], off
	v_lshl_add_u64 v[216:217], v[222:223], 0, s[30:31]
	s_add_i32 m0, s40, 0x2000
	s_nop 0
	global_load_lds_dwordx4 v[216:217], off
	v_lshl_add_u64 v[216:217], v[224:225], 0, s[30:31]
	s_mov_b32 m0, s27
	s_nop 0
	global_load_lds_dwordx4 v[216:217], off
	v_lshl_add_u64 v[216:217], v[226:227], 0, s[30:31]
	s_mov_b32 m0, s33
	s_nop 0
	global_load_lds_dwordx4 v[216:217], off
	s_waitcnt vmcnt(8)
	s_waitcnt lgkmcnt(0)
	s_barrier
	s_setprio 1
	s_waitcnt lgkmcnt(0)
	v_mfma_f32_16x16x32_bf16 v[60:63], v[152:155], v[184:187], v[60:63]
	v_mfma_f32_16x16x32_bf16 v[44:47], v[152:155], v[192:195], v[44:47]
	v_mfma_f32_16x16x32_bf16 v[28:31], v[152:155], v[200:203], v[28:31]
	v_mfma_f32_16x16x32_bf16 v[12:15], v[152:155], v[208:211], v[12:15]
	v_mfma_f32_16x16x32_bf16 v[4:7], v[160:163], v[208:211], v[4:7]
	v_mfma_f32_16x16x32_bf16 v[20:23], v[160:163], v[200:203], v[20:23]
	v_mfma_f32_16x16x32_bf16 v[36:39], v[160:163], v[192:195], v[36:39]
	v_mfma_f32_16x16x32_bf16 v[52:55], v[160:163], v[184:187], v[52:55]
	v_mfma_f32_16x16x32_bf16 v[60:63], v[156:159], v[188:191], v[60:63]
	v_mfma_f32_16x16x32_bf16 v[44:47], v[156:159], v[196:199], v[44:47]
	v_mfma_f32_16x16x32_bf16 v[28:31], v[156:159], v[204:207], v[28:31]
	v_mfma_f32_16x16x32_bf16 v[12:15], v[156:159], v[212:215], v[12:15]
	v_mfma_f32_16x16x32_bf16 v[4:7], v[164:167], v[212:215], v[4:7]
	v_mfma_f32_16x16x32_bf16 v[20:23], v[164:167], v[204:207], v[20:23]
	v_mfma_f32_16x16x32_bf16 v[36:39], v[164:167], v[196:199], v[36:39]
	v_mfma_f32_16x16x32_bf16 v[52:55], v[164:167], v[188:191], v[52:55]
	s_setprio 0
	s_setprio 1
	v_mfma_f32_16x16x32_bf16 v[56:59], v[168:171], v[184:187], v[56:59]
	v_mfma_f32_16x16x32_bf16 v[40:43], v[168:171], v[192:195], v[40:43]
	v_mfma_f32_16x16x32_bf16 v[24:27], v[168:171], v[200:203], v[24:27]
	v_mfma_f32_16x16x32_bf16 v[8:11], v[168:171], v[208:211], v[8:11]
	v_mfma_f32_16x16x32_bf16 v[0:3], v[176:179], v[208:211], v[0:3]
	v_mfma_f32_16x16x32_bf16 v[16:19], v[176:179], v[200:203], v[16:19]
	v_mfma_f32_16x16x32_bf16 v[32:35], v[176:179], v[192:195], v[32:35]
	v_mfma_f32_16x16x32_bf16 v[48:51], v[176:179], v[184:187], v[48:51]
	v_mfma_f32_16x16x32_bf16 v[56:59], v[172:175], v[188:191], v[56:59]
	v_mfma_f32_16x16x32_bf16 v[40:43], v[172:175], v[196:199], v[40:43]
	v_mfma_f32_16x16x32_bf16 v[24:27], v[172:175], v[204:207], v[24:27]
	v_mfma_f32_16x16x32_bf16 v[8:11], v[172:175], v[212:215], v[8:11]
	v_mfma_f32_16x16x32_bf16 v[0:3], v[180:183], v[212:215], v[0:3]
	v_mfma_f32_16x16x32_bf16 v[16:19], v[180:183], v[204:207], v[16:19]
	v_mfma_f32_16x16x32_bf16 v[32:35], v[180:183], v[196:199], v[32:35]
	v_mfma_f32_16x16x32_bf16 v[48:51], v[180:183], v[188:191], v[48:51]
	s_setprio 0
	s_barrier
	s_add_u32 s38, s38, 0x100
	s_addc_u32 s39, s39, 0
	s_add_u32 s24, s24, 0x100
	s_addc_u32 s25, s25, 0
	s_cmp_ge_i32 s54, s42
	s_mov_b32 s40, s54
	s_cbranch_scc1 .Lpeelx_0
.LBB0_349:
	ds_read_b128 v[152:155], v148
	ds_read_b128 v[156:159], v148 offset:1024
	ds_read_b128 v[160:163], v148 offset:2048
	ds_read_b128 v[164:167], v148 offset:3072
	ds_read_b128 v[168:171], v149
	ds_read_b128 v[172:175], v149 offset:1024
	ds_read_b128 v[176:179], v149 offset:2048
	ds_read_b128 v[180:183], v149 offset:3072
	s_add_i32 s54, s40, 2
	s_add_u32 s55, s38, 0x80
	s_addc_u32 s41, s39, 0
	s_cmp_eq_u32 s43, s40
	s_cselect_b32 s40, s10, s55
	s_cselect_b32 s41, s11, s41
	s_cselect_b32 s57, s37, s25
	s_cselect_b32 s56, s36, s24
	s_mov_b32 m0, s47
	v_lshl_add_u64 v[216:217], s[38:39], 0, v[136:137]
	ds_read_b128 v[184:187], v150
	ds_read_b128 v[188:191], v150 offset:1024
	ds_read_b128 v[192:195], v150 offset:2048
	ds_read_b128 v[196:199], v150 offset:3072
	ds_read_b128 v[200:203], v150 offset:4096
	ds_read_b128 v[204:207], v150 offset:5120
	ds_read_b128 v[208:211], v150 offset:6144
	ds_read_b128 v[212:215], v150 offset:7168
	global_load_lds_dwordx4 v[216:217], off
	v_lshl_add_u64 v[216:217], s[38:39], 0, v[138:139]
	s_mov_b32 m0, s48
	s_nop 0
	global_load_lds_dwordx4 v[216:217], off
	s_waitcnt vmcnt(8)
	s_waitcnt lgkmcnt(0)
	s_barrier
; #define PG8_STAGE(bufoff, gbase, voff) do { _Pragma("unroll") for (int _i = 0; _i < 2; ++_i) \
;         __builtin_amdgcn_global_load_lds((const unsigned*)((const char*)(gbase) + (voff)[_i]), (PG8_LAS unsigned*)(lds + (bufoff) + ldsw + _i * 8192), 16, 0, 0); } while (0)
; #define PG8_LDA(dst, b, h) do { _Pragma("unroll") for (int m = 0; m < 4; ++m) _Pragma("unroll") for (int k = 0; k < 2; ++k) dst[m][k] = *(const PG8_LAS bf16x8*)(lds + PG8_SA(b, h) + aoff + m * 2048 + k * 1024); } while (0)
; #define PG8_LDB(dst, b, h) do { _Pragma("unroll") for (int n = 0; n < 2; ++n) _Pragma("unroll") for (int k = 0; k < 2; ++k) dst[n][k] = *(const PG8_LAS bf16x8*)(lds + PG8_SB(b, h) + boff + n * 2048 + k * 1024); } while (0)
; #define PG8_MMA(ai, bj, At, Bt) do { __builtin_amdgcn_s_setprio(1); _Pragma("unroll") for (int m = 0; m < 4; ++m) _Pragma("unroll") for (int n = 0; n < 2; ++n) _Pragma("unroll") for (int k = 0; k < 2; ++k) \
;         acc[ai][bj][m][n] = __builtin_amdgcn_mfma_f32_16x16x32_bf16(Bt[n][k], At[m][k], acc[ai][bj][m][n], 0, 0, 0); __builtin_amdgcn_s_setprio(0); } while (0)
; #define PG8_WAIT_V(n) asm volatile("s_waitcnt vmcnt(" #n ")" ::: "memory")
; #define PG8_WAIT_L(n) asm volatile("s_waitcnt lgkmcnt(" #n ")" ::: "memory")
; #define PG8_BAR __builtin_amdgcn_s_barrier()
; #define PG8_SCHED __builtin_amdgcn_sched_barrier(0)
; template <class Epi, class Sched, bool ALIGN_EPI = false, bool SP2 = false>
; __device__ __forceinline__ void gemm_phase(PG8_LAS unsigned char* lds, const Gemm g, const Sched& S, const Epi& E) {
;     ...
;             PG8_LDB(B0, 0, 0); PG8_LDB(B1, 0, 1); PG8_SCHED; PG8_LDA(At, 0, 0); PG8_STAGE(PG8_SA(1, 1), a1 + hstep, voffA);
;             PG8_WAIT_V(8); PG8_WAIT_L(0); PG8_BAR; PG8_MMA(0, 0, At, B0); PG8_MMA(0, 1, At, B1); PG8_BAR; PG8_SCHED;
;             PG8_LDA(At, 0, 1); PG8_STAGE(PG8_SB(0, 0), b2, voffB); PG8_STAGE(PG8_SB(0, 1), b2 + hstep, voffB); PG8_STAGE(PG8_SA(0, 0), a2, voffA);
;             PG8_WAIT_V(8); PG8_WAIT_L(0); PG8_BAR; PG8_MMA(1, 0, At, B0); PG8_MMA(1, 1, At, B1); PG8_BAR; PG8_SCHED;
	s_setprio 1
	s_waitcnt lgkmcnt(0)
	v_mfma_f32_16x16x32_bf16 v[120:123], v[152:155], v[184:187], v[120:123]
	v_mfma_f32_16x16x32_bf16 v[108:111], v[152:155], v[192:195], v[108:111]
	v_mfma_f32_16x16x32_bf16 v[92:95], v[152:155], v[200:203], v[92:95]
	v_mfma_f32_16x16x32_bf16 v[76:79], v[152:155], v[208:211], v[76:79]
	v_mfma_f32_16x16x32_bf16 v[68:71], v[160:163], v[208:211], v[68:71]
	v_mfma_f32_16x16x32_bf16 v[84:87], v[160:163], v[200:203], v[84:87]
	v_mfma_f32_16x16x32_bf16 v[100:103], v[160:163], v[192:195], v[100:103]
	v_mfma_f32_16x16x32_bf16 v[116:119], v[160:163], v[184:187], v[116:119]
	v_mfma_f32_16x16x32_bf16 v[120:123], v[156:159], v[188:191], v[120:123]
	v_mfma_f32_16x16x32_bf16 v[108:111], v[156:159], v[196:199], v[108:111]
	v_mfma_f32_16x16x32_bf16 v[92:95], v[156:159], v[204:207], v[92:95]
	v_mfma_f32_16x16x32_bf16 v[76:79], v[156:159], v[212:215], v[76:79]
	v_mfma_f32_16x16x32_bf16 v[68:71], v[164:167], v[212:215], v[68:71]
	v_mfma_f32_16x16x32_bf16 v[84:87], v[164:167], v[204:207], v[84:87]
	v_mfma_f32_16x16x32_bf16 v[100:103], v[164:167], v[196:199], v[100:103]
	v_mfma_f32_16x16x32_bf16 v[116:119], v[164:167], v[188:191], v[116:119]
	s_setprio 0
	s_setprio 1
	v_mfma_f32_16x16x32_bf16 v[124:127], v[168:171], v[184:187], v[124:127]
	v_mfma_f32_16x16x32_bf16 v[104:107], v[168:171], v[192:195], v[104:107]
	v_mfma_f32_16x16x32_bf16 v[88:91], v[168:171], v[200:203], v[88:91]
	v_mfma_f32_16x16x32_bf16 v[72:75], v[168:171], v[208:211], v[72:75]
	v_mfma_f32_16x16x32_bf16 v[64:67], v[176:179], v[208:211], v[64:67]
	v_mfma_f32_16x16x32_bf16 v[80:83], v[176:179], v[200:203], v[80:83]
	v_mfma_f32_16x16x32_bf16 v[96:99], v[176:179], v[192:195], v[96:99]
	v_mfma_f32_16x16x32_bf16 v[112:115], v[176:179], v[184:187], v[112:115]
	v_mfma_f32_16x16x32_bf16 v[124:127], v[172:175], v[188:191], v[124:127]
	v_mfma_f32_16x16x32_bf16 v[104:107], v[172:175], v[196:199], v[104:107]
	v_mfma_f32_16x16x32_bf16 v[88:91], v[172:175], v[204:207], v[88:91]
	v_mfma_f32_16x16x32_bf16 v[72:75], v[172:175], v[212:215], v[72:75]
	v_mfma_f32_16x16x32_bf16 v[64:67], v[180:183], v[212:215], v[64:67]
	v_mfma_f32_16x16x32_bf16 v[80:83], v[180:183], v[204:207], v[80:83]
	v_mfma_f32_16x16x32_bf16 v[96:99], v[180:183], v[196:199], v[96:99]
	v_mfma_f32_16x16x32_bf16 v[112:115], v[180:183], v[188:191], v[112:115]
	s_setprio 0
	s_barrier
	s_add_i32 s55, s44, s3
	v_lshl_add_u64 v[216:217], s[56:57], 0, v[132:133]
	s_mov_b32 m0, s55
	ds_read_b128 v[184:187], v150 offset:16384
	ds_read_b128 v[188:191], v150 offset:17408
	ds_read_b128 v[192:195], v150 offset:18432
	ds_read_b128 v[196:199], v150 offset:19456
	ds_read_b128 v[200:203], v150 offset:20480
	ds_read_b128 v[204:207], v150 offset:21504
	ds_read_b128 v[208:211], v150 offset:22528
	ds_read_b128 v[212:215], v150 offset:23552
	global_load_lds_dwordx4 v[216:217], off
	s_add_i32 m0, s55, 0x2000
	v_lshl_add_u64 v[218:219], s[56:57], 0, v[128:129]
	s_add_u32 s56, s56, s12
	s_addc_u32 s57, s57, s13
	s_add_i32 s55, s45, s3
	global_load_lds_dwordx4 v[218:219], off
	v_lshl_add_u64 v[220:221], s[56:57], 0, v[132:133]
	s_mov_b32 m0, s55
	v_lshl_add_u64 v[222:223], s[56:57], 0, v[128:129]
	global_load_lds_dwordx4 v[220:221], off
	s_add_i32 m0, s55, 0x2000
	v_lshl_add_u64 v[224:225], s[40:41], 0, v[134:135]
	global_load_lds_dwordx4 v[222:223], off
	s_mov_b32 m0, s17
	v_lshl_add_u64 v[226:227], s[40:41], 0, v[130:131]
	global_load_lds_dwordx4 v[224:225], off
	s_mov_b32 m0, s18
	s_nop 0
	global_load_lds_dwordx4 v[226:227], off
	s_waitcnt vmcnt(8)
	s_waitcnt lgkmcnt(0)
	s_barrier
	s_setprio 1
	s_waitcnt lgkmcnt(0)
	v_mfma_f32_16x16x32_bf16 v[60:63], v[152:155], v[184:187], v[60:63]
	v_mfma_f32_16x16x32_bf16 v[44:47], v[152:155], v[192:195], v[44:47]
	v_mfma_f32_16x16x32_bf16 v[28:31], v[152:155], v[200:203], v[28:31]
	v_mfma_f32_16x16x32_bf16 v[12:15], v[152:155], v[208:211], v[12:15]
	v_mfma_f32_16x16x32_bf16 v[4:7], v[160:163], v[208:211], v[4:7]
	v_mfma_f32_16x16x32_bf16 v[20:23], v[160:163], v[200:203], v[20:23]
	v_mfma_f32_16x16x32_bf16 v[36:39], v[160:163], v[192:195], v[36:39]
	v_mfma_f32_16x16x32_bf16 v[52:55], v[160:163], v[184:187], v[52:55]
	v_mfma_f32_16x16x32_bf16 v[60:63], v[156:159], v[188:191], v[60:63]
	v_mfma_f32_16x16x32_bf16 v[44:47], v[156:159], v[196:199], v[44:47]
	v_mfma_f32_16x16x32_bf16 v[28:31], v[156:159], v[204:207], v[28:31]
	v_mfma_f32_16x16x32_bf16 v[12:15], v[156:159], v[212:215], v[12:15]
	v_mfma_f32_16x16x32_bf16 v[4:7], v[164:167], v[212:215], v[4:7]
	v_mfma_f32_16x16x32_bf16 v[20:23], v[164:167], v[204:207], v[20:23]
	v_mfma_f32_16x16x32_bf16 v[36:39], v[164:167], v[196:199], v[36:39]
	v_mfma_f32_16x16x32_bf16 v[52:55], v[164:167], v[188:191], v[52:55]
	s_setprio 0
	s_setprio 1
	v_mfma_f32_16x16x32_bf16 v[56:59], v[168:171], v[184:187], v[56:59]
	v_mfma_f32_16x16x32_bf16 v[40:43], v[168:171], v[192:195], v[40:43]
	v_mfma_f32_16x16x32_bf16 v[24:27], v[168:171], v[200:203], v[24:27]
	v_mfma_f32_16x16x32_bf16 v[8:11], v[168:171], v[208:211], v[8:11]
	v_mfma_f32_16x16x32_bf16 v[0:3], v[176:179], v[208:211], v[0:3]
	v_mfma_f32_16x16x32_bf16 v[16:19], v[176:179], v[200:203], v[16:19]
	v_mfma_f32_16x16x32_bf16 v[32:35], v[176:179], v[192:195], v[32:35]
	v_mfma_f32_16x16x32_bf16 v[48:51], v[176:179], v[184:187], v[48:51]
	v_mfma_f32_16x16x32_bf16 v[56:59], v[172:175], v[188:191], v[56:59]
	v_mfma_f32_16x16x32_bf16 v[40:43], v[172:175], v[196:199], v[40:43]
	v_mfma_f32_16x16x32_bf16 v[24:27], v[172:175], v[204:207], v[24:27]
	v_mfma_f32_16x16x32_bf16 v[8:11], v[172:175], v[212:215], v[8:11]
	v_mfma_f32_16x16x32_bf16 v[0:3], v[180:183], v[212:215], v[0:3]
	v_mfma_f32_16x16x32_bf16 v[16:19], v[180:183], v[204:207], v[16:19]
	v_mfma_f32_16x16x32_bf16 v[32:35], v[180:183], v[196:199], v[32:35]
	v_mfma_f32_16x16x32_bf16 v[48:51], v[180:183], v[188:191], v[48:51]
	s_setprio 0
	s_barrier
; #define PG8_STAGE(bufoff, gbase, voff) do { _Pragma("unroll") for (int _i = 0; _i < 2; ++_i) \
;         __builtin_amdgcn_global_load_lds((const unsigned*)((const char*)(gbase) + (voff)[_i]), (PG8_LAS unsigned*)(lds + (bufoff) + ldsw + _i * 8192), 16, 0, 0); } while (0)
; #define PG8_LDA(dst, b, h) do { _Pragma("unroll") for (int m = 0; m < 4; ++m) _Pragma("unroll") for (int k = 0; k < 2; ++k) dst[m][k] = *(const PG8_LAS bf16x8*)(lds + PG8_SA(b, h) + aoff + m * 2048 + k * 1024); } while (0)
; #define PG8_LDB(dst, b, h) do { _Pragma("unroll") for (int n = 0; n < 2; ++n) _Pragma("unroll") for (int k = 0; k < 2; ++k) dst[n][k] = *(const PG8_LAS bf16x8*)(lds + PG8_SB(b, h) + boff + n * 2048 + k * 1024); } while (0)
; #define PG8_MMA(ai, bj, At, Bt) do { __builtin_amdgcn_s_setprio(1); _Pragma("unroll") for (int m = 0; m < 4; ++m) _Pragma("unroll") for (int n = 0; n < 2; ++n) _Pragma("unroll") for (int k = 0; k < 2; ++k) \
;         acc[ai][bj][m][n] = __builtin_amdgcn_mfma_f32_16x16x32_bf16(Bt[n][k], At[m][k], acc[ai][bj][m][n], 0, 0, 0); __builtin_amdgcn_s_setprio(0); } while (0)
; #define PG8_WAIT_V(n) asm volatile("s_waitcnt vmcnt(" #n ")" ::: "memory")
; #define PG8_WAIT_L(n) asm volatile("s_waitcnt lgkmcnt(" #n ")" ::: "memory")
; #define PG8_BAR __builtin_amdgcn_s_barrier()
; #define PG8_SCHED __builtin_amdgcn_sched_barrier(0)
; template <class Epi, class Sched, bool ALIGN_EPI = false, bool SP2 = false>
; __device__ __forceinline__ void gemm_phase(PG8_LAS unsigned char* lds, const Gemm g, const Sched& S, const Epi& E) {
;     ...
;             PG8_LDB(B0, 1, 0); PG8_LDB(B1, 1, 1); PG8_SCHED; PG8_LDA(At, 1, 0); PG8_STAGE(PG8_SA(0, 1), a2 + hstep, voffA);
;             PG8_WAIT_V(8); PG8_WAIT_L(0); PG8_BAR; PG8_MMA(0, 0, At, B0); PG8_MMA(0, 1, At, B1); PG8_BAR; PG8_SCHED;
	s_add_i32 s55, 0, 0x18000
	v_add_u32_e32 v151, s55, v145
	s_add_i32 s56, 0, 0x1c000
	ds_read_b128 v[152:155], v151
	ds_read_b128 v[156:159], v151 offset:1024
	ds_read_b128 v[160:163], v151 offset:2048
	ds_read_b128 v[164:167], v151 offset:3072
	v_add_u32_e32 v151, s56, v145
	ds_read_b128 v[168:171], v151
	ds_read_b128 v[172:175], v151 offset:1024
	ds_read_b128 v[176:179], v151 offset:2048
	ds_read_b128 v[180:183], v151 offset:3072
	s_add_u32 s40, s40, s12
	s_addc_u32 s41, s41, s13
	s_mov_b32 m0, s19
	v_lshl_add_u64 v[228:229], s[40:41], 0, v[134:135]
	ds_read_b128 v[184:187], v150 offset:32768
	ds_read_b128 v[188:191], v150 offset:33792
	ds_read_b128 v[192:195], v150 offset:34816
	ds_read_b128 v[196:199], v150 offset:35840
	ds_read_b128 v[200:203], v150 offset:36864
	ds_read_b128 v[204:207], v150 offset:37888
	ds_read_b128 v[208:211], v150 offset:38912
	ds_read_b128 v[212:215], v150 offset:39936
	global_load_lds_dwordx4 v[228:229], off
	v_lshl_add_u64 v[228:229], s[40:41], 0, v[130:131]
	s_mov_b32 m0, s26
	s_nop 0
	global_load_lds_dwordx4 v[228:229], off
	s_waitcnt vmcnt(8)
	s_waitcnt lgkmcnt(0)
	s_barrier
	s_setprio 1
	s_waitcnt lgkmcnt(0)
	v_mfma_f32_16x16x32_bf16 v[120:123], v[152:155], v[184:187], v[120:123]
	v_mfma_f32_16x16x32_bf16 v[108:111], v[152:155], v[192:195], v[108:111]
	v_mfma_f32_16x16x32_bf16 v[92:95], v[152:155], v[200:203], v[92:95]
	v_mfma_f32_16x16x32_bf16 v[76:79], v[152:155], v[208:211], v[76:79]
	v_mfma_f32_16x16x32_bf16 v[68:71], v[160:163], v[208:211], v[68:71]
	v_mfma_f32_16x16x32_bf16 v[84:87], v[160:163], v[200:203], v[84:87]
	v_mfma_f32_16x16x32_bf16 v[100:103], v[160:163], v[192:195], v[100:103]
	v_mfma_f32_16x16x32_bf16 v[116:119], v[160:163], v[184:187], v[116:119]
	v_mfma_f32_16x16x32_bf16 v[120:123], v[156:159], v[188:191], v[120:123]
	v_mfma_f32_16x16x32_bf16 v[108:111], v[156:159], v[196:199], v[108:111]
	v_mfma_f32_16x16x32_bf16 v[92:95], v[156:159], v[204:207], v[92:95]
	v_mfma_f32_16x16x32_bf16 v[76:79], v[156:159], v[212:215], v[76:79]
	v_mfma_f32_16x16x32_bf16 v[68:71], v[164:167], v[212:215], v[68:71]
	v_mfma_f32_16x16x32_bf16 v[84:87], v[164:167], v[204:207], v[84:87]
	v_mfma_f32_16x16x32_bf16 v[100:103], v[164:167], v[196:199], v[100:103]
	v_mfma_f32_16x16x32_bf16 v[116:119], v[164:167], v[188:191], v[116:119]
	s_setprio 0
	s_setprio 1
	v_mfma_f32_16x16x32_bf16 v[124:127], v[168:171], v[184:187], v[124:127]
	v_mfma_f32_16x16x32_bf16 v[104:107], v[168:171], v[192:195], v[104:107]
	v_mfma_f32_16x16x32_bf16 v[88:91], v[168:171], v[200:203], v[88:91]
	v_mfma_f32_16x16x32_bf16 v[72:75], v[168:171], v[208:211], v[72:75]
	v_mfma_f32_16x16x32_bf16 v[64:67], v[176:179], v[208:211], v[64:67]
	v_mfma_f32_16x16x32_bf16 v[80:83], v[176:179], v[200:203], v[80:83]
	v_mfma_f32_16x16x32_bf16 v[96:99], v[176:179], v[192:195], v[96:99]
	v_mfma_f32_16x16x32_bf16 v[112:115], v[176:179], v[184:187], v[112:115]
	v_mfma_f32_16x16x32_bf16 v[124:127], v[172:175], v[188:191], v[124:127]
	v_mfma_f32_16x16x32_bf16 v[104:107], v[172:175], v[196:199], v[104:107]
	v_mfma_f32_16x16x32_bf16 v[88:91], v[172:175], v[204:207], v[88:91]
	v_mfma_f32_16x16x32_bf16 v[72:75], v[172:175], v[212:215], v[72:75]
	v_mfma_f32_16x16x32_bf16 v[64:67], v[180:183], v[212:215], v[64:67]
	v_mfma_f32_16x16x32_bf16 v[80:83], v[180:183], v[204:207], v[80:83]
	v_mfma_f32_16x16x32_bf16 v[96:99], v[180:183], v[196:199], v[96:99]
	v_mfma_f32_16x16x32_bf16 v[112:115], v[180:183], v[188:191], v[112:115]
	s_setprio 0
	s_barrier
; #define PG8_STAGE(bufoff, gbase, voff) do { _Pragma("unroll") for (int _i = 0; _i < 2; ++_i) \
;         __builtin_amdgcn_global_load_lds((const unsigned*)((const char*)(gbase) + (voff)[_i]), (PG8_LAS unsigned*)(lds + (bufoff) + ldsw + _i * 8192), 16, 0, 0); } while (0)
; #define PG8_LDA(dst, b, h) do { _Pragma("unroll") for (int m = 0; m < 4; ++m) _Pragma("unroll") for (int k = 0; k < 2; ++k) dst[m][k] = *(const PG8_LAS bf16x8*)(lds + PG8_SA(b, h) + aoff + m * 2048 + k * 1024); } while (0)
; #define PG8_MMA(ai, bj, At, Bt) do { __builtin_amdgcn_s_setprio(1); _Pragma("unroll") for (int m = 0; m < 4; ++m) _Pragma("unroll") for (int n = 0; n < 2; ++n) _Pragma("unroll") for (int k = 0; k < 2; ++k) \
;         acc[ai][bj][m][n] = __builtin_amdgcn_mfma_f32_16x16x32_bf16(Bt[n][k], At[m][k], acc[ai][bj][m][n], 0, 0, 0); __builtin_amdgcn_s_setprio(0); } while (0)
; #define PG8_WAIT_V(n) asm volatile("s_waitcnt vmcnt(" #n ")" ::: "memory")
; #define PG8_WAIT_L(n) asm volatile("s_waitcnt lgkmcnt(" #n ")" ::: "memory")
; #define PG8_BAR __builtin_amdgcn_s_barrier()
; #define PG8_SCHED __builtin_amdgcn_sched_barrier(0)
; template <class Epi, class Sched, bool ALIGN_EPI = false, bool SP2 = false>
; __device__ __forceinline__ void gemm_phase(PG8_LAS unsigned char* lds, const Gemm g, const Sched& S, const Epi& E) {
;     ...
;             PG8_LDA(At, 1, 1); PG8_STAGE(PG8_SB(1, 0), b3, voffB); PG8_STAGE(PG8_SB(1, 1), b3 + hstep, voffB); PG8_STAGE(PG8_SA(1, 0), a3, voffA);
;             PG8_WAIT_V(8); PG8_WAIT_L(0); PG8_BAR; PG8_MMA(1, 0, At, B0); PG8_MMA(1, 1, At, B1); PG8_BAR; PG8_SCHED;
	s_add_i32 s40, s55, s3
	v_lshl_add_u64 v[216:217], v[216:217], 0, s[30:31]
	s_mov_b32 m0, s40
	ds_read_b128 v[184:187], v150 offset:49152
	ds_read_b128 v[188:191], v150 offset:50176
	ds_read_b128 v[192:195], v150 offset:51200
	ds_read_b128 v[196:199], v150 offset:52224
	ds_read_b128 v[200:203], v150 offset:53248
	ds_read_b128 v[204:207], v150 offset:54272
	ds_read_b128 v[208:211], v150 offset:55296
	ds_read_b128 v[212:215], v150 offset:56320
	global_load_lds_dwordx4 v[216:217], off
	v_lshl_add_u64 v[216:217], v[218:219], 0, s[30:31]
	s_add_i32 m0, s40, 0x2000
	s_add_i32 s40, s56, s3
	global_load_lds_dwordx4 v[216:217], off
	v_lshl_add_u64 v[216:217], v[220:221], 0, s[30:31]
	s_mov_b32 m0, s40
	s_nop 0
	global_load_lds_dwordx4 v[216:217], off
	v_lshl_add_u64 v[216:217], v[222:223], 0, s[30:31]
	s_add_i32 m0, s40, 0x2000
	s_nop 0
	global_load_lds_dwordx4 v[216:217], off
	v_lshl_add_u64 v[216:217], v[224:225], 0, s[30:31]
	s_mov_b32 m0, s27
	s_nop 0
	global_load_lds_dwordx4 v[216:217], off
	v_lshl_add_u64 v[216:217], v[226:227], 0, s[30:31]
	s_mov_b32 m0, s33
	s_nop 0
	global_load_lds_dwordx4 v[216:217], off
	s_waitcnt vmcnt(8)
	s_waitcnt lgkmcnt(0)
	s_barrier
	s_setprio 1
	s_waitcnt lgkmcnt(0)
	v_mfma_f32_16x16x32_bf16 v[60:63], v[152:155], v[184:187], v[60:63]
	v_mfma_f32_16x16x32_bf16 v[44:47], v[152:155], v[192:195], v[44:47]
	v_mfma_f32_16x16x32_bf16 v[28:31], v[152:155], v[200:203], v[28:31]
	v_mfma_f32_16x16x32_bf16 v[12:15], v[152:155], v[208:211], v[12:15]
	v_mfma_f32_16x16x32_bf16 v[4:7], v[160:163], v[208:211], v[4:7]
	v_mfma_f32_16x16x32_bf16 v[20:23], v[160:163], v[200:203], v[20:23]
	v_mfma_f32_16x16x32_bf16 v[36:39], v[160:163], v[192:195], v[36:39]
	v_mfma_f32_16x16x32_bf16 v[52:55], v[160:163], v[184:187], v[52:55]
	v_mfma_f32_16x16x32_bf16 v[60:63], v[156:159], v[188:191], v[60:63]
	v_mfma_f32_16x16x32_bf16 v[44:47], v[156:159], v[196:199], v[44:47]
	v_mfma_f32_16x16x32_bf16 v[28:31], v[156:159], v[204:207], v[28:31]
	v_mfma_f32_16x16x32_bf16 v[12:15], v[156:159], v[212:215], v[12:15]
	v_mfma_f32_16x16x32_bf16 v[4:7], v[164:167], v[212:215], v[4:7]
	v_mfma_f32_16x16x32_bf16 v[20:23], v[164:167], v[204:207], v[20:23]
	v_mfma_f32_16x16x32_bf16 v[36:39], v[164:167], v[196:199], v[36:39]
	v_mfma_f32_16x16x32_bf16 v[52:55], v[164:167], v[188:191], v[52:55]
	s_setprio 0
	s_setprio 1
	v_mfma_f32_16x16x32_bf16 v[56:59], v[168:171], v[184:187], v[56:59]
	v_mfma_f32_16x16x32_bf16 v[40:43], v[168:171], v[192:195], v[40:43]
	v_mfma_f32_16x16x32_bf16 v[24:27], v[168:171], v[200:203], v[24:27]
	v_mfma_f32_16x16x32_bf16 v[8:11], v[168:171], v[208:211], v[8:11]
	v_mfma_f32_16x16x32_bf16 v[0:3], v[176:179], v[208:211], v[0:3]
	v_mfma_f32_16x16x32_bf16 v[16:19], v[176:179], v[200:203], v[16:19]
	v_mfma_f32_16x16x32_bf16 v[32:35], v[176:179], v[192:195], v[32:35]
	v_mfma_f32_16x16x32_bf16 v[48:51], v[176:179], v[184:187], v[48:51]
	v_mfma_f32_16x16x32_bf16 v[56:59], v[172:175], v[188:191], v[56:59]
	v_mfma_f32_16x16x32_bf16 v[40:43], v[172:175], v[196:199], v[40:43]
	v_mfma_f32_16x16x32_bf16 v[24:27], v[172:175], v[204:207], v[24:27]
	v_mfma_f32_16x16x32_bf16 v[8:11], v[172:175], v[212:215], v[8:11]
	v_mfma_f32_16x16x32_bf16 v[0:3], v[180:183], v[212:215], v[0:3]
	v_mfma_f32_16x16x32_bf16 v[16:19], v[180:183], v[204:207], v[16:19]
	v_mfma_f32_16x16x32_bf16 v[32:35], v[180:183], v[196:199], v[32:35]
	v_mfma_f32_16x16x32_bf16 v[48:51], v[180:183], v[188:191], v[48:51]
	s_setprio 0
	s_barrier
	s_add_u32 s38, s38, 0x100
	s_addc_u32 s39, s39, 0
	s_add_u32 s24, s24, 0x100
	s_addc_u32 s25, s25, 0
	s_cmp_ge_i32 s54, s42
	s_mov_b32 s40, s54
	s_cbranch_scc0 .LBB0_349

; #define PG8_STAGE(bufoff, gbase, voff) do { _Pragma("unroll") for (int _i = 0; _i < 2; ++_i) \
;         __builtin_amdgcn_global_load_lds((const unsigned*)((const char*)(gbase) + (voff)[_i]), (PG8_LAS unsigned*)(lds + (bufoff) + ldsw + _i * 8192), 16, 0, 0); } while (0)
; #define PG8_LDA(dst, b, h) do { _Pragma("unroll") for (int m = 0; m < 4; ++m) _Pragma("unroll") for (int k = 0; k < 2; ++k) dst[m][k] = *(const PG8_LAS bf16x8*)(lds + PG8_SA(b, h) + aoff + m * 2048 + k * 1024); } while (0)
; #define PG8_LDB(dst, b, h) do { _Pragma("unroll") for (int n = 0; n < 2; ++n) _Pragma("unroll") for (int k = 0; k < 2; ++k) dst[n][k] = *(const PG8_LAS bf16x8*)(lds + PG8_SB(b, h) + boff + n * 2048 + k * 1024); } while (0)
; #define PG8_MMA(ai, bj, At, Bt) do { __builtin_amdgcn_s_setprio(1); _Pragma("unroll") for (int m = 0; m < 4; ++m) _Pragma("unroll") for (int n = 0; n < 2; ++n) _Pragma("unroll") for (int k = 0; k < 2; ++k) \
;         acc[ai][bj][m][n] = __builtin_amdgcn_mfma_f32_16x16x32_bf16(Bt[n][k], At[m][k], acc[ai][bj][m][n], 0, 0, 0); __builtin_amdgcn_s_setprio(0); } while (0)
; #define PG8_WAIT_V(n) asm volatile("s_waitcnt vmcnt(" #n ")" ::: "memory")
; #define PG8_BAR __builtin_amdgcn_s_barrier()
; template <class Epi, class Sched, bool ALIGN_EPI = false, bool SP2 = false>
; __device__ __forceinline__ void gemm_phase(PG8_LAS unsigned char* lds, const Gemm g, const Sched& S, const Epi& E) {
;     ...
;         for (int t = 0; t < nt; t += 2) {
;             const bool last = (t == nt - 2);
;             const char* a1 = cA + (size_t)(t + 1) * kstep;
;             const char* a2 = last ? nA : cA + (size_t)(t + 2) * kstep; const char* b2 = last ? nB : cB + (size_t)(t + 2) * kstep;
;             const char* a3 = a2 + kstep; const char* b3 = b2 + kstep;
;             if (last && has_next) S.a_ready(nxt);
;             if constexpr (SP2) {
;             PG8_LDB(B0, 0, 0); PG8_LDB(B1, 0, 1); PG8_SCHED; PG8_LDA(At, 0, 0); PG8_STAGE(PG8_SA(1, 1), a1 + hstep, voffA);
;             PG8_WAIT_V(8); PG8_WAIT_L(0); PG8_BAR; PG8_MMA(0, 0, At, B0); PG8_MMA(0, 1, At, B1); PG8_BAR; PG8_SCHED;
;             PG8_LDA(At, 0, 1); PG8_STAGE(PG8_SB(0, 0), b2, voffB); PG8_STAGE(PG8_SB(0, 1), b2 + hstep, voffB); PG8_STAGE(PG8_SA(0, 0), a2, voffA);
;             PG8_WAIT_V(8); PG8_WAIT_L(0); PG8_BAR; PG8_MMA(1, 0, At, B0); PG8_MMA(1, 1, At, B1); PG8_BAR; PG8_SCHED;
.LBB0_430:
	s_and_b64 vcc, exec, s[10:11]
	s_cbranch_vccnz .Lcoldz_1
	s_add_u32 s46, s46, 0x80
	s_addc_u32 s47, s47, 0
	s_add_u32 s2, s48, 0x100
	s_addc_u32 s24, s49, 0
	s_mov_b32 s25, 0
	ds_read_b128 v[142:145], v246
	ds_read_b128 v[146:149], v246 offset:1024
	ds_read_b128 v[150:153], v246 offset:2048
	ds_read_b128 v[154:157], v246 offset:3072
	ds_read_b128 v[158:161], v247
	ds_read_b128 v[162:165], v247 offset:1024
	ds_read_b128 v[166:169], v247 offset:2048
	ds_read_b128 v[170:173], v247 offset:3072
	s_add_i32 s56, s25, 2
	s_add_u32 s48, s46, 0x80
	s_addc_u32 s49, s47, 0
	s_cmp_eq_u32 s50, s25
	s_cselect_b32 s49, s15, s49
	s_cselect_b32 s48, s14, s48
	s_cselect_b32 s61, s45, s24
	s_cselect_b32 s60, s44, s2
	v_lshl_add_u64 v[206:207], s[46:47], 0, v[136:137]
	s_add_i32 m0, s7, 0xc000
	ds_read_b128 v[174:177], v248
	ds_read_b128 v[178:181], v248 offset:1024
	ds_read_b128 v[182:185], v248 offset:2048
	ds_read_b128 v[186:189], v248 offset:3072
	ds_read_b128 v[190:193], v248 offset:4096
	ds_read_b128 v[194:197], v248 offset:5120
	ds_read_b128 v[198:201], v248 offset:6144
	ds_read_b128 v[202:205], v248 offset:7168
	global_load_lds_dwordx4 v[206:207], off
	v_lshl_add_u64 v[206:207], s[46:47], 0, v[138:139]
	s_add_i32 m0, s7, 0xe000
	s_nop 0
	global_load_lds_dwordx4 v[206:207], off
	s_waitcnt vmcnt(8)
	s_waitcnt lgkmcnt(0)
	s_barrier
	s_setprio 1
	s_waitcnt lgkmcnt(0)
	v_mfma_f32_16x16x32_bf16 v[124:127], v[142:145], v[174:177], 0
	v_mfma_f32_16x16x32_bf16 v[120:123], v[150:153], v[174:177], 0
	v_mfma_f32_16x16x32_bf16 v[116:119], v[142:145], v[182:185], 0
	v_mfma_f32_16x16x32_bf16 v[112:115], v[150:153], v[182:185], 0
	v_mfma_f32_16x16x32_bf16 v[104:107], v[142:145], v[190:193], 0
	v_mfma_f32_16x16x32_bf16 v[96:99], v[150:153], v[190:193], 0
	v_mfma_f32_16x16x32_bf16 v[88:91], v[142:145], v[198:201], 0
	v_mfma_f32_16x16x32_bf16 v[80:83], v[150:153], v[198:201], 0
	v_mfma_f32_16x16x32_bf16 v[124:127], v[146:149], v[178:181], v[124:127]
	v_mfma_f32_16x16x32_bf16 v[116:119], v[146:149], v[186:189], v[116:119]
	v_mfma_f32_16x16x32_bf16 v[104:107], v[146:149], v[194:197], v[104:107]
	v_mfma_f32_16x16x32_bf16 v[88:91], v[146:149], v[202:205], v[88:91]
	v_mfma_f32_16x16x32_bf16 v[80:83], v[154:157], v[202:205], v[80:83]
	v_mfma_f32_16x16x32_bf16 v[96:99], v[154:157], v[194:197], v[96:99]
	v_mfma_f32_16x16x32_bf16 v[112:115], v[154:157], v[186:189], v[112:115]
	v_mfma_f32_16x16x32_bf16 v[120:123], v[154:157], v[178:181], v[120:123]
	s_setprio 0
	s_setprio 1
	v_mfma_f32_16x16x32_bf16 v[108:111], v[158:161], v[174:177], 0
	v_mfma_f32_16x16x32_bf16 v[100:103], v[166:169], v[174:177], 0
	v_mfma_f32_16x16x32_bf16 v[92:95], v[158:161], v[182:185], 0
	v_mfma_f32_16x16x32_bf16 v[84:87], v[166:169], v[182:185], 0
	v_mfma_f32_16x16x32_bf16 v[76:79], v[158:161], v[190:193], 0
	v_mfma_f32_16x16x32_bf16 v[72:75], v[166:169], v[190:193], 0
	v_mfma_f32_16x16x32_bf16 v[68:71], v[158:161], v[198:201], 0
	v_mfma_f32_16x16x32_bf16 v[64:67], v[166:169], v[198:201], 0
	v_mfma_f32_16x16x32_bf16 v[108:111], v[162:165], v[178:181], v[108:111]
	v_mfma_f32_16x16x32_bf16 v[92:95], v[162:165], v[186:189], v[92:95]
	v_mfma_f32_16x16x32_bf16 v[76:79], v[162:165], v[194:197], v[76:79]
	v_mfma_f32_16x16x32_bf16 v[68:71], v[162:165], v[202:205], v[68:71]
	v_mfma_f32_16x16x32_bf16 v[64:67], v[170:173], v[202:205], v[64:67]
	v_mfma_f32_16x16x32_bf16 v[72:75], v[170:173], v[194:197], v[72:75]
	v_mfma_f32_16x16x32_bf16 v[84:87], v[170:173], v[186:189], v[84:87]
	v_mfma_f32_16x16x32_bf16 v[100:103], v[170:173], v[178:181], v[100:103]
	s_setprio 0
	s_barrier
	s_add_i32 s25, s51, s6
	v_lshl_add_u64 v[206:207], s[60:61], 0, v[130:131]
	s_mov_b32 m0, s25
	ds_read_b128 v[174:177], v248 offset:16384
	ds_read_b128 v[178:181], v248 offset:17408
	ds_read_b128 v[182:185], v248 offset:18432
	ds_read_b128 v[186:189], v248 offset:19456
	ds_read_b128 v[190:193], v248 offset:20480
	ds_read_b128 v[194:197], v248 offset:21504
	ds_read_b128 v[198:201], v248 offset:22528
	ds_read_b128 v[202:205], v248 offset:23552
	global_load_lds_dwordx4 v[206:207], off
	s_add_i32 m0, s25, 0x2000
	v_lshl_add_u64 v[208:209], s[60:61], 0, v[134:135]
	s_add_u32 s60, s60, s30
	s_addc_u32 s61, s61, s31
	s_add_i32 s25, s52, s6
	global_load_lds_dwordx4 v[208:209], off
	v_lshl_add_u64 v[210:211], s[60:61], 0, v[130:131]
	s_mov_b32 m0, s25
	v_lshl_add_u64 v[212:213], s[60:61], 0, v[134:135]
	global_load_lds_dwordx4 v[210:211], off
	s_add_i32 m0, s25, 0x2000
	v_lshl_add_u64 v[214:215], s[48:49], 0, v[128:129]
	global_load_lds_dwordx4 v[212:213], off
	s_mov_b32 m0, s7
	v_lshl_add_u64 v[216:217], s[48:49], 0, v[132:133]
	global_load_lds_dwordx4 v[214:215], off
	s_mov_b32 m0, s16
	s_nop 0
	global_load_lds_dwordx4 v[216:217], off
	s_waitcnt vmcnt(8)
	s_waitcnt lgkmcnt(0)
	s_barrier
; #define PG8_STAGE(bufoff, gbase, voff) do { _Pragma("unroll") for (int _i = 0; _i < 2; ++_i) \
;         __builtin_amdgcn_global_load_lds((const unsigned*)((const char*)(gbase) + (voff)[_i]), (PG8_LAS unsigned*)(lds + (bufoff) + ldsw + _i * 8192), 16, 0, 0); } while (0)
; #define PG8_LDA(dst, b, h) do { _Pragma("unroll") for (int m = 0; m < 4; ++m) _Pragma("unroll") for (int k = 0; k < 2; ++k) dst[m][k] = *(const PG8_LAS bf16x8*)(lds + PG8_SA(b, h) + aoff + m * 2048 + k * 1024); } while (0)
; #define PG8_LDB(dst, b, h) do { _Pragma("unroll") for (int n = 0; n < 2; ++n) _Pragma("unroll") for (int k = 0; k < 2; ++k) dst[n][k] = *(const PG8_LAS bf16x8*)(lds + PG8_SB(b, h) + boff + n * 2048 + k * 1024); } while (0)
; #define PG8_MMA(ai, bj, At, Bt) do { __builtin_amdgcn_s_setprio(1); _Pragma("unroll") for (int m = 0; m < 4; ++m) _Pragma("unroll") for (int n = 0; n < 2; ++n) _Pragma("unroll") for (int k = 0; k < 2; ++k) \
;         acc[ai][bj][m][n] = __builtin_amdgcn_mfma_f32_16x16x32_bf16(Bt[n][k], At[m][k], acc[ai][bj][m][n], 0, 0, 0); __builtin_amdgcn_s_setprio(0); } while (0)
; #define PG8_WAIT_V(n) asm volatile("s_waitcnt vmcnt(" #n ")" ::: "memory")
; #define PG8_WAIT_L(n) asm volatile("s_waitcnt lgkmcnt(" #n ")" ::: "memory")
; #define PG8_BAR __builtin_amdgcn_s_barrier()
; #define PG8_SCHED __builtin_amdgcn_sched_barrier(0)
; template <class Epi, class Sched, bool ALIGN_EPI = false, bool SP2 = false>
; __device__ __forceinline__ void gemm_phase(PG8_LAS unsigned char* lds, const Gemm g, const Sched& S, const Epi& E) {
;     ...
;             PG8_WAIT_V(8); PG8_WAIT_L(0); PG8_BAR; PG8_MMA(1, 0, At, B0); PG8_MMA(1, 1, At, B1); PG8_BAR; PG8_SCHED;
;             PG8_LDB(B0, 1, 0); PG8_LDB(B1, 1, 1); PG8_SCHED; PG8_LDA(At, 1, 0); PG8_STAGE(PG8_SA(0, 1), a2 + hstep, voffA);
;             PG8_WAIT_V(8); PG8_WAIT_L(0); PG8_BAR; PG8_MMA(0, 0, At, B0); PG8_MMA(0, 1, At, B1); PG8_BAR; PG8_SCHED;
	s_setprio 1
	s_waitcnt lgkmcnt(0)
	v_mfma_f32_16x16x32_bf16 v[60:63], v[142:145], v[174:177], 0
	v_mfma_f32_16x16x32_bf16 v[56:59], v[150:153], v[174:177], 0
	v_mfma_f32_16x16x32_bf16 v[52:55], v[142:145], v[182:185], 0
	v_mfma_f32_16x16x32_bf16 v[48:51], v[150:153], v[182:185], 0
	v_mfma_f32_16x16x32_bf16 v[40:43], v[142:145], v[190:193], 0
	v_mfma_f32_16x16x32_bf16 v[32:35], v[150:153], v[190:193], 0
	v_mfma_f32_16x16x32_bf16 v[24:27], v[142:145], v[198:201], 0
	v_mfma_f32_16x16x32_bf16 v[16:19], v[150:153], v[198:201], 0
	v_mfma_f32_16x16x32_bf16 v[60:63], v[146:149], v[178:181], v[60:63]
	v_mfma_f32_16x16x32_bf16 v[52:55], v[146:149], v[186:189], v[52:55]
	v_mfma_f32_16x16x32_bf16 v[40:43], v[146:149], v[194:197], v[40:43]
	v_mfma_f32_16x16x32_bf16 v[24:27], v[146:149], v[202:205], v[24:27]
	v_mfma_f32_16x16x32_bf16 v[16:19], v[154:157], v[202:205], v[16:19]
	v_mfma_f32_16x16x32_bf16 v[32:35], v[154:157], v[194:197], v[32:35]
	v_mfma_f32_16x16x32_bf16 v[48:51], v[154:157], v[186:189], v[48:51]
	v_mfma_f32_16x16x32_bf16 v[56:59], v[154:157], v[178:181], v[56:59]
	s_setprio 0
	s_setprio 1
	v_mfma_f32_16x16x32_bf16 v[44:47], v[158:161], v[174:177], 0
	v_mfma_f32_16x16x32_bf16 v[36:39], v[166:169], v[174:177], 0
	v_mfma_f32_16x16x32_bf16 v[28:31], v[158:161], v[182:185], 0
	v_mfma_f32_16x16x32_bf16 v[20:23], v[166:169], v[182:185], 0
	v_mfma_f32_16x16x32_bf16 v[12:15], v[158:161], v[190:193], 0
	v_mfma_f32_16x16x32_bf16 v[8:11], v[166:169], v[190:193], 0
	v_mfma_f32_16x16x32_bf16 v[4:7], v[158:161], v[198:201], 0
	v_mfma_f32_16x16x32_bf16 v[0:3], v[166:169], v[198:201], 0
	v_mfma_f32_16x16x32_bf16 v[44:47], v[162:165], v[178:181], v[44:47]
	v_mfma_f32_16x16x32_bf16 v[28:31], v[162:165], v[186:189], v[28:31]
	v_mfma_f32_16x16x32_bf16 v[12:15], v[162:165], v[194:197], v[12:15]
	v_mfma_f32_16x16x32_bf16 v[4:7], v[162:165], v[202:205], v[4:7]
	v_mfma_f32_16x16x32_bf16 v[0:3], v[170:173], v[202:205], v[0:3]
	v_mfma_f32_16x16x32_bf16 v[8:11], v[170:173], v[194:197], v[8:11]
	v_mfma_f32_16x16x32_bf16 v[20:23], v[170:173], v[186:189], v[20:23]
	v_mfma_f32_16x16x32_bf16 v[36:39], v[170:173], v[178:181], v[36:39]
	s_setprio 0
	s_barrier
	s_add_i32 s25, 0, 0x18000
	s_add_i32 s57, 0, 0x1c000
	v_add_u32_e32 v154, s25, v244
	v_add_u32_e32 v170, s57, v244
	ds_read_b128 v[142:145], v154
	ds_read_b128 v[146:149], v154 offset:1024
	ds_read_b128 v[150:153], v154 offset:2048
	ds_read_b128 v[154:157], v154 offset:3072
	ds_read_b128 v[158:161], v170
	ds_read_b128 v[162:165], v170 offset:1024
	ds_read_b128 v[166:169], v170 offset:2048
	ds_read_b128 v[170:173], v170 offset:3072
	s_add_u32 s48, s48, s30
	s_addc_u32 s49, s49, s31
	s_mov_b32 m0, s17
	v_lshl_add_u64 v[218:219], s[48:49], 0, v[128:129]
	ds_read_b128 v[174:177], v248 offset:32768
	ds_read_b128 v[178:181], v248 offset:33792
	ds_read_b128 v[182:185], v248 offset:34816
	ds_read_b128 v[186:189], v248 offset:35840
	ds_read_b128 v[190:193], v248 offset:36864
	ds_read_b128 v[194:197], v248 offset:37888
	ds_read_b128 v[198:201], v248 offset:38912
	ds_read_b128 v[202:205], v248 offset:39936
	global_load_lds_dwordx4 v[218:219], off
	v_lshl_add_u64 v[218:219], s[48:49], 0, v[132:133]
	s_mov_b32 m0, s18
	s_nop 0
	global_load_lds_dwordx4 v[218:219], off
	s_waitcnt vmcnt(8)
	s_waitcnt lgkmcnt(0)
	s_barrier
	s_setprio 1
	s_waitcnt lgkmcnt(0)
	v_mfma_f32_16x16x32_bf16 v[124:127], v[142:145], v[174:177], v[124:127]
	v_mfma_f32_16x16x32_bf16 v[116:119], v[142:145], v[182:185], v[116:119]
	v_mfma_f32_16x16x32_bf16 v[104:107], v[142:145], v[190:193], v[104:107]
	v_mfma_f32_16x16x32_bf16 v[88:91], v[142:145], v[198:201], v[88:91]
	v_mfma_f32_16x16x32_bf16 v[80:83], v[150:153], v[198:201], v[80:83]
	v_mfma_f32_16x16x32_bf16 v[96:99], v[150:153], v[190:193], v[96:99]
	v_mfma_f32_16x16x32_bf16 v[112:115], v[150:153], v[182:185], v[112:115]
	v_mfma_f32_16x16x32_bf16 v[120:123], v[150:153], v[174:177], v[120:123]
	v_mfma_f32_16x16x32_bf16 v[124:127], v[146:149], v[178:181], v[124:127]
	v_mfma_f32_16x16x32_bf16 v[116:119], v[146:149], v[186:189], v[116:119]
	v_mfma_f32_16x16x32_bf16 v[104:107], v[146:149], v[194:197], v[104:107]
	v_mfma_f32_16x16x32_bf16 v[88:91], v[146:149], v[202:205], v[88:91]
	v_mfma_f32_16x16x32_bf16 v[80:83], v[154:157], v[202:205], v[80:83]
	v_mfma_f32_16x16x32_bf16 v[96:99], v[154:157], v[194:197], v[96:99]
	v_mfma_f32_16x16x32_bf16 v[112:115], v[154:157], v[186:189], v[112:115]
	v_mfma_f32_16x16x32_bf16 v[120:123], v[154:157], v[178:181], v[120:123]
	s_setprio 0
	s_setprio 1
	v_mfma_f32_16x16x32_bf16 v[108:111], v[158:161], v[174:177], v[108:111]
	v_mfma_f32_16x16x32_bf16 v[92:95], v[158:161], v[182:185], v[92:95]
	v_mfma_f32_16x16x32_bf16 v[76:79], v[158:161], v[190:193], v[76:79]
	v_mfma_f32_16x16x32_bf16 v[68:71], v[158:161], v[198:201], v[68:71]
	v_mfma_f32_16x16x32_bf16 v[64:67], v[166:169], v[198:201], v[64:67]
	v_mfma_f32_16x16x32_bf16 v[72:75], v[166:169], v[190:193], v[72:75]
	v_mfma_f32_16x16x32_bf16 v[84:87], v[166:169], v[182:185], v[84:87]
	v_mfma_f32_16x16x32_bf16 v[100:103], v[166:169], v[174:177], v[100:103]
	v_mfma_f32_16x16x32_bf16 v[108:111], v[162:165], v[178:181], v[108:111]
	v_mfma_f32_16x16x32_bf16 v[92:95], v[162:165], v[186:189], v[92:95]
	v_mfma_f32_16x16x32_bf16 v[76:79], v[162:165], v[194:197], v[76:79]
	v_mfma_f32_16x16x32_bf16 v[68:71], v[162:165], v[202:205], v[68:71]
	v_mfma_f32_16x16x32_bf16 v[64:67], v[170:173], v[202:205], v[64:67]
	v_mfma_f32_16x16x32_bf16 v[72:75], v[170:173], v[194:197], v[72:75]
	v_mfma_f32_16x16x32_bf16 v[84:87], v[170:173], v[186:189], v[84:87]
	v_mfma_f32_16x16x32_bf16 v[100:103], v[170:173], v[178:181], v[100:103]
	s_setprio 0
	s_barrier
; #define PG8_STAGE(bufoff, gbase, voff) do { _Pragma("unroll") for (int _i = 0; _i < 2; ++_i) \
;         __builtin_amdgcn_global_load_lds((const unsigned*)((const char*)(gbase) + (voff)[_i]), (PG8_LAS unsigned*)(lds + (bufoff) + ldsw + _i * 8192), 16, 0, 0); } while (0)
; #define PG8_LDA(dst, b, h) do { _Pragma("unroll") for (int m = 0; m < 4; ++m) _Pragma("unroll") for (int k = 0; k < 2; ++k) dst[m][k] = *(const PG8_LAS bf16x8*)(lds + PG8_SA(b, h) + aoff + m * 2048 + k * 1024); } while (0)
; #define PG8_LDB(dst, b, h) do { _Pragma("unroll") for (int n = 0; n < 2; ++n) _Pragma("unroll") for (int k = 0; k < 2; ++k) dst[n][k] = *(const PG8_LAS bf16x8*)(lds + PG8_SB(b, h) + boff + n * 2048 + k * 1024); } while (0)
; #define PG8_MMA(ai, bj, At, Bt) do { __builtin_amdgcn_s_setprio(1); _Pragma("unroll") for (int m = 0; m < 4; ++m) _Pragma("unroll") for (int n = 0; n < 2; ++n) _Pragma("unroll") for (int k = 0; k < 2; ++k) \
;         acc[ai][bj][m][n] = __builtin_amdgcn_mfma_f32_16x16x32_bf16(Bt[n][k], At[m][k], acc[ai][bj][m][n], 0, 0, 0); __builtin_amdgcn_s_setprio(0); } while (0)
; #define PG8_WAIT_V(n) asm volatile("s_waitcnt vmcnt(" #n ")" ::: "memory")
; #define PG8_WAIT_L(n) asm volatile("s_waitcnt lgkmcnt(" #n ")" ::: "memory")
; #define PG8_BAR __builtin_amdgcn_s_barrier()
; #define PG8_SCHED __builtin_amdgcn_sched_barrier(0)
; template <class Epi, class Sched, bool ALIGN_EPI = false, bool SP2 = false>
; __device__ __forceinline__ void gemm_phase(PG8_LAS unsigned char* lds, const Gemm g, const Sched& S, const Epi& E) {
;     ...
;         for (int t = 0; t < nt; t += 2) {
;             const bool last = (t == nt - 2);
;             const char* a1 = cA + (size_t)(t + 1) * kstep;
;             const char* a2 = last ? nA : cA + (size_t)(t + 2) * kstep; const char* b2 = last ? nB : cB + (size_t)(t + 2) * kstep;
;             const char* a3 = a2 + kstep; const char* b3 = b2 + kstep;
;             if (last && has_next) S.a_ready(nxt);
;             if constexpr (SP2) {
;             PG8_LDB(B0, 0, 0); PG8_LDB(B1, 0, 1); PG8_SCHED; PG8_LDA(At, 0, 0); PG8_STAGE(PG8_SA(1, 1), a1 + hstep, voffA);
;     ...
;             PG8_LDA(At, 1, 1); PG8_STAGE(PG8_SB(1, 0), b3, voffB); PG8_STAGE(PG8_SB(1, 1), b3 + hstep, voffB); PG8_STAGE(PG8_SA(1, 0), a3, voffA);
;             PG8_WAIT_V(8); PG8_WAIT_L(0); PG8_BAR; PG8_MMA(1, 0, At, B0); PG8_MMA(1, 1, At, B1); PG8_BAR; PG8_SCHED;
	s_add_i32 s25, s25, s6
	v_lshl_add_u64 v[206:207], v[206:207], 0, s[40:41]
	s_mov_b32 m0, s25
	ds_read_b128 v[174:177], v248 offset:49152
	ds_read_b128 v[178:181], v248 offset:50176
	ds_read_b128 v[182:185], v248 offset:51200
	ds_read_b128 v[186:189], v248 offset:52224
	ds_read_b128 v[190:193], v248 offset:53248
	ds_read_b128 v[194:197], v248 offset:54272
	ds_read_b128 v[198:201], v248 offset:55296
	ds_read_b128 v[202:205], v248 offset:56320
	global_load_lds_dwordx4 v[206:207], off
	v_lshl_add_u64 v[206:207], v[208:209], 0, s[40:41]
	s_add_i32 m0, s25, 0x2000
	s_add_i32 s25, s57, s6
	global_load_lds_dwordx4 v[206:207], off
	v_lshl_add_u64 v[206:207], v[210:211], 0, s[40:41]
	s_mov_b32 m0, s25
	s_nop 0
	global_load_lds_dwordx4 v[206:207], off
	v_lshl_add_u64 v[206:207], v[212:213], 0, s[40:41]
	s_add_i32 m0, s25, 0x2000
	s_nop 0
	global_load_lds_dwordx4 v[206:207], off
	v_lshl_add_u64 v[206:207], v[214:215], 0, s[40:41]
	s_mov_b32 m0, s19
	s_nop 0
	global_load_lds_dwordx4 v[206:207], off
	v_lshl_add_u64 v[206:207], v[216:217], 0, s[40:41]
	s_mov_b32 m0, s26
	s_nop 0
	global_load_lds_dwordx4 v[206:207], off
	s_waitcnt vmcnt(8)
	s_waitcnt lgkmcnt(0)
	s_barrier
	s_setprio 1
	s_waitcnt lgkmcnt(0)
	v_mfma_f32_16x16x32_bf16 v[60:63], v[142:145], v[174:177], v[60:63]
	v_mfma_f32_16x16x32_bf16 v[52:55], v[142:145], v[182:185], v[52:55]
	v_mfma_f32_16x16x32_bf16 v[40:43], v[142:145], v[190:193], v[40:43]
	v_mfma_f32_16x16x32_bf16 v[24:27], v[142:145], v[198:201], v[24:27]
	v_mfma_f32_16x16x32_bf16 v[16:19], v[150:153], v[198:201], v[16:19]
	v_mfma_f32_16x16x32_bf16 v[32:35], v[150:153], v[190:193], v[32:35]
	v_mfma_f32_16x16x32_bf16 v[48:51], v[150:153], v[182:185], v[48:51]
	v_mfma_f32_16x16x32_bf16 v[56:59], v[150:153], v[174:177], v[56:59]
	v_mfma_f32_16x16x32_bf16 v[60:63], v[146:149], v[178:181], v[60:63]
	v_mfma_f32_16x16x32_bf16 v[52:55], v[146:149], v[186:189], v[52:55]
	v_mfma_f32_16x16x32_bf16 v[40:43], v[146:149], v[194:197], v[40:43]
	v_mfma_f32_16x16x32_bf16 v[24:27], v[146:149], v[202:205], v[24:27]
	v_mfma_f32_16x16x32_bf16 v[16:19], v[154:157], v[202:205], v[16:19]
	v_mfma_f32_16x16x32_bf16 v[32:35], v[154:157], v[194:197], v[32:35]
	v_mfma_f32_16x16x32_bf16 v[48:51], v[154:157], v[186:189], v[48:51]
	v_mfma_f32_16x16x32_bf16 v[56:59], v[154:157], v[178:181], v[56:59]
	s_setprio 0
	s_setprio 1
	v_mfma_f32_16x16x32_bf16 v[44:47], v[158:161], v[174:177], v[44:47]
	v_mfma_f32_16x16x32_bf16 v[28:31], v[158:161], v[182:185], v[28:31]
	v_mfma_f32_16x16x32_bf16 v[12:15], v[158:161], v[190:193], v[12:15]
	v_mfma_f32_16x16x32_bf16 v[4:7], v[158:161], v[198:201], v[4:7]
	v_mfma_f32_16x16x32_bf16 v[0:3], v[166:169], v[198:201], v[0:3]
	v_mfma_f32_16x16x32_bf16 v[8:11], v[166:169], v[190:193], v[8:11]
	v_mfma_f32_16x16x32_bf16 v[20:23], v[166:169], v[182:185], v[20:23]
	v_mfma_f32_16x16x32_bf16 v[36:39], v[166:169], v[174:177], v[36:39]
	v_mfma_f32_16x16x32_bf16 v[44:47], v[162:165], v[178:181], v[44:47]
	v_mfma_f32_16x16x32_bf16 v[28:31], v[162:165], v[186:189], v[28:31]
	v_mfma_f32_16x16x32_bf16 v[12:15], v[162:165], v[194:197], v[12:15]
	v_mfma_f32_16x16x32_bf16 v[4:7], v[162:165], v[202:205], v[4:7]
	v_mfma_f32_16x16x32_bf16 v[0:3], v[170:173], v[202:205], v[0:3]
	v_mfma_f32_16x16x32_bf16 v[8:11], v[170:173], v[194:197], v[8:11]
	v_mfma_f32_16x16x32_bf16 v[20:23], v[170:173], v[186:189], v[20:23]
	v_mfma_f32_16x16x32_bf16 v[36:39], v[170:173], v[178:181], v[36:39]
	s_setprio 0
	s_barrier
	s_add_u32 s46, s46, 0x100
	s_addc_u32 s47, s47, 0
	s_add_u32 s2, s2, 0x100
	s_addc_u32 s24, s24, 0
	s_cmp_ge_i32 s56, s33
	s_mov_b32 s25, s56
	s_cbranch_scc1 .Lpeelx_1
.LBB0_432:
	ds_read_b128 v[142:145], v246
	ds_read_b128 v[146:149], v246 offset:1024
	ds_read_b128 v[150:153], v246 offset:2048
	ds_read_b128 v[154:157], v246 offset:3072
	ds_read_b128 v[158:161], v247
	ds_read_b128 v[162:165], v247 offset:1024
	ds_read_b128 v[166:169], v247 offset:2048
	ds_read_b128 v[170:173], v247 offset:3072
	s_add_i32 s56, s25, 2
	s_add_u32 s48, s46, 0x80
	s_addc_u32 s49, s47, 0
	s_cmp_eq_u32 s50, s25
	s_cselect_b32 s49, s15, s49
	s_cselect_b32 s48, s14, s48
	s_cselect_b32 s61, s45, s24
	s_cselect_b32 s60, s44, s2
	v_lshl_add_u64 v[206:207], s[46:47], 0, v[136:137]
	s_add_i32 m0, s7, 0xc000
	ds_read_b128 v[174:177], v248
	ds_read_b128 v[178:181], v248 offset:1024
	ds_read_b128 v[182:185], v248 offset:2048
	ds_read_b128 v[186:189], v248 offset:3072
	ds_read_b128 v[190:193], v248 offset:4096
	ds_read_b128 v[194:197], v248 offset:5120
	ds_read_b128 v[198:201], v248 offset:6144
	ds_read_b128 v[202:205], v248 offset:7168
	global_load_lds_dwordx4 v[206:207], off
	v_lshl_add_u64 v[206:207], s[46:47], 0, v[138:139]
	s_add_i32 m0, s7, 0xe000
	s_nop 0
	global_load_lds_dwordx4 v[206:207], off
	s_waitcnt vmcnt(8)
	s_waitcnt lgkmcnt(0)
	s_barrier
; #define PG8_STAGE(bufoff, gbase, voff) do { _Pragma("unroll") for (int _i = 0; _i < 2; ++_i) \
;         __builtin_amdgcn_global_load_lds((const unsigned*)((const char*)(gbase) + (voff)[_i]), (PG8_LAS unsigned*)(lds + (bufoff) + ldsw + _i * 8192), 16, 0, 0); } while (0)
; #define PG8_LDA(dst, b, h) do { _Pragma("unroll") for (int m = 0; m < 4; ++m) _Pragma("unroll") for (int k = 0; k < 2; ++k) dst[m][k] = *(const PG8_LAS bf16x8*)(lds + PG8_SA(b, h) + aoff + m * 2048 + k * 1024); } while (0)
; #define PG8_LDB(dst, b, h) do { _Pragma("unroll") for (int n = 0; n < 2; ++n) _Pragma("unroll") for (int k = 0; k < 2; ++k) dst[n][k] = *(const PG8_LAS bf16x8*)(lds + PG8_SB(b, h) + boff + n * 2048 + k * 1024); } while (0)
; #define PG8_MMA(ai, bj, At, Bt) do { __builtin_amdgcn_s_setprio(1); _Pragma("unroll") for (int m = 0; m < 4; ++m) _Pragma("unroll") for (int n = 0; n < 2; ++n) _Pragma("unroll") for (int k = 0; k < 2; ++k) \
;         acc[ai][bj][m][n] = __builtin_amdgcn_mfma_f32_16x16x32_bf16(Bt[n][k], At[m][k], acc[ai][bj][m][n], 0, 0, 0); __builtin_amdgcn_s_setprio(0); } while (0)
; #define PG8_WAIT_V(n) asm volatile("s_waitcnt vmcnt(" #n ")" ::: "memory")
; #define PG8_WAIT_L(n) asm volatile("s_waitcnt lgkmcnt(" #n ")" ::: "memory")
; #define PG8_BAR __builtin_amdgcn_s_barrier()
; #define PG8_SCHED __builtin_amdgcn_sched_barrier(0)
; template <class Epi, class Sched, bool ALIGN_EPI = false, bool SP2 = false>
; __device__ __forceinline__ void gemm_phase(PG8_LAS unsigned char* lds, const Gemm g, const Sched& S, const Epi& E) {
;     ...
;             PG8_LDB(B0, 0, 0); PG8_LDB(B1, 0, 1); PG8_SCHED; PG8_LDA(At, 0, 0); PG8_STAGE(PG8_SA(1, 1), a1 + hstep, voffA);
;             PG8_WAIT_V(8); PG8_WAIT_L(0); PG8_BAR; PG8_MMA(0, 0, At, B0); PG8_MMA(0, 1, At, B1); PG8_BAR; PG8_SCHED;
;             PG8_LDA(At, 0, 1); PG8_STAGE(PG8_SB(0, 0), b2, voffB); PG8_STAGE(PG8_SB(0, 1), b2 + hstep, voffB); PG8_STAGE(PG8_SA(0, 0), a2, voffA);
;             PG8_WAIT_V(8); PG8_WAIT_L(0); PG8_BAR; PG8_MMA(1, 0, At, B0); PG8_MMA(1, 1, At, B1); PG8_BAR; PG8_SCHED;
	s_setprio 1
	s_waitcnt lgkmcnt(0)
	v_mfma_f32_16x16x32_bf16 v[124:127], v[142:145], v[174:177], v[124:127]
	v_mfma_f32_16x16x32_bf16 v[116:119], v[142:145], v[182:185], v[116:119]
	v_mfma_f32_16x16x32_bf16 v[104:107], v[142:145], v[190:193], v[104:107]
	v_mfma_f32_16x16x32_bf16 v[88:91], v[142:145], v[198:201], v[88:91]
	v_mfma_f32_16x16x32_bf16 v[80:83], v[150:153], v[198:201], v[80:83]
	v_mfma_f32_16x16x32_bf16 v[96:99], v[150:153], v[190:193], v[96:99]
	v_mfma_f32_16x16x32_bf16 v[112:115], v[150:153], v[182:185], v[112:115]
	v_mfma_f32_16x16x32_bf16 v[120:123], v[150:153], v[174:177], v[120:123]
	v_mfma_f32_16x16x32_bf16 v[124:127], v[146:149], v[178:181], v[124:127]
	v_mfma_f32_16x16x32_bf16 v[116:119], v[146:149], v[186:189], v[116:119]
	v_mfma_f32_16x16x32_bf16 v[104:107], v[146:149], v[194:197], v[104:107]
	v_mfma_f32_16x16x32_bf16 v[88:91], v[146:149], v[202:205], v[88:91]
	v_mfma_f32_16x16x32_bf16 v[80:83], v[154:157], v[202:205], v[80:83]
	v_mfma_f32_16x16x32_bf16 v[96:99], v[154:157], v[194:197], v[96:99]
	v_mfma_f32_16x16x32_bf16 v[112:115], v[154:157], v[186:189], v[112:115]
	v_mfma_f32_16x16x32_bf16 v[120:123], v[154:157], v[178:181], v[120:123]
	s_setprio 0
	s_setprio 1
	v_mfma_f32_16x16x32_bf16 v[108:111], v[158:161], v[174:177], v[108:111]
	v_mfma_f32_16x16x32_bf16 v[92:95], v[158:161], v[182:185], v[92:95]
	v_mfma_f32_16x16x32_bf16 v[76:79], v[158:161], v[190:193], v[76:79]
	v_mfma_f32_16x16x32_bf16 v[68:71], v[158:161], v[198:201], v[68:71]
	v_mfma_f32_16x16x32_bf16 v[64:67], v[166:169], v[198:201], v[64:67]
	v_mfma_f32_16x16x32_bf16 v[72:75], v[166:169], v[190:193], v[72:75]
	v_mfma_f32_16x16x32_bf16 v[84:87], v[166:169], v[182:185], v[84:87]
	v_mfma_f32_16x16x32_bf16 v[100:103], v[166:169], v[174:177], v[100:103]
	v_mfma_f32_16x16x32_bf16 v[108:111], v[162:165], v[178:181], v[108:111]
	v_mfma_f32_16x16x32_bf16 v[92:95], v[162:165], v[186:189], v[92:95]
	v_mfma_f32_16x16x32_bf16 v[76:79], v[162:165], v[194:197], v[76:79]
	v_mfma_f32_16x16x32_bf16 v[68:71], v[162:165], v[202:205], v[68:71]
	v_mfma_f32_16x16x32_bf16 v[64:67], v[170:173], v[202:205], v[64:67]
	v_mfma_f32_16x16x32_bf16 v[72:75], v[170:173], v[194:197], v[72:75]
	v_mfma_f32_16x16x32_bf16 v[84:87], v[170:173], v[186:189], v[84:87]
	v_mfma_f32_16x16x32_bf16 v[100:103], v[170:173], v[178:181], v[100:103]
	s_setprio 0
	s_barrier
	s_add_i32 s25, s51, s6
	v_lshl_add_u64 v[206:207], s[60:61], 0, v[130:131]
	s_mov_b32 m0, s25
	ds_read_b128 v[174:177], v248 offset:16384
	ds_read_b128 v[178:181], v248 offset:17408
	ds_read_b128 v[182:185], v248 offset:18432
	ds_read_b128 v[186:189], v248 offset:19456
	ds_read_b128 v[190:193], v248 offset:20480
	ds_read_b128 v[194:197], v248 offset:21504
	ds_read_b128 v[198:201], v248 offset:22528
	ds_read_b128 v[202:205], v248 offset:23552
	global_load_lds_dwordx4 v[206:207], off
	s_add_i32 m0, s25, 0x2000
	v_lshl_add_u64 v[208:209], s[60:61], 0, v[134:135]
	s_add_u32 s60, s60, s30
	s_addc_u32 s61, s61, s31
	s_add_i32 s25, s52, s6
	global_load_lds_dwordx4 v[208:209], off
	v_lshl_add_u64 v[210:211], s[60:61], 0, v[130:131]
	s_mov_b32 m0, s25
	v_lshl_add_u64 v[212:213], s[60:61], 0, v[134:135]
	global_load_lds_dwordx4 v[210:211], off
	s_add_i32 m0, s25, 0x2000
	v_lshl_add_u64 v[214:215], s[48:49], 0, v[128:129]
	global_load_lds_dwordx4 v[212:213], off
	s_mov_b32 m0, s7
	v_lshl_add_u64 v[216:217], s[48:49], 0, v[132:133]
	global_load_lds_dwordx4 v[214:215], off
	s_mov_b32 m0, s16
	s_nop 0
	global_load_lds_dwordx4 v[216:217], off
	s_waitcnt vmcnt(8)
	s_waitcnt lgkmcnt(0)
	s_barrier
	s_setprio 1
	s_waitcnt lgkmcnt(0)
	v_mfma_f32_16x16x32_bf16 v[60:63], v[142:145], v[174:177], v[60:63]
	v_mfma_f32_16x16x32_bf16 v[52:55], v[142:145], v[182:185], v[52:55]
	v_mfma_f32_16x16x32_bf16 v[40:43], v[142:145], v[190:193], v[40:43]
	v_mfma_f32_16x16x32_bf16 v[24:27], v[142:145], v[198:201], v[24:27]
	v_mfma_f32_16x16x32_bf16 v[16:19], v[150:153], v[198:201], v[16:19]
	v_mfma_f32_16x16x32_bf16 v[32:35], v[150:153], v[190:193], v[32:35]
	v_mfma_f32_16x16x32_bf16 v[48:51], v[150:153], v[182:185], v[48:51]
	v_mfma_f32_16x16x32_bf16 v[56:59], v[150:153], v[174:177], v[56:59]
	v_mfma_f32_16x16x32_bf16 v[60:63], v[146:149], v[178:181], v[60:63]
	v_mfma_f32_16x16x32_bf16 v[52:55], v[146:149], v[186:189], v[52:55]
	v_mfma_f32_16x16x32_bf16 v[40:43], v[146:149], v[194:197], v[40:43]
	v_mfma_f32_16x16x32_bf16 v[24:27], v[146:149], v[202:205], v[24:27]
	v_mfma_f32_16x16x32_bf16 v[16:19], v[154:157], v[202:205], v[16:19]
	v_mfma_f32_16x16x32_bf16 v[32:35], v[154:157], v[194:197], v[32:35]
	v_mfma_f32_16x16x32_bf16 v[48:51], v[154:157], v[186:189], v[48:51]
	v_mfma_f32_16x16x32_bf16 v[56:59], v[154:157], v[178:181], v[56:59]
	s_setprio 0
	s_setprio 1
	v_mfma_f32_16x16x32_bf16 v[44:47], v[158:161], v[174:177], v[44:47]
	v_mfma_f32_16x16x32_bf16 v[28:31], v[158:161], v[182:185], v[28:31]
	v_mfma_f32_16x16x32_bf16 v[12:15], v[158:161], v[190:193], v[12:15]
	v_mfma_f32_16x16x32_bf16 v[4:7], v[158:161], v[198:201], v[4:7]
	v_mfma_f32_16x16x32_bf16 v[0:3], v[166:169], v[198:201], v[0:3]
	v_mfma_f32_16x16x32_bf16 v[8:11], v[166:169], v[190:193], v[8:11]
	v_mfma_f32_16x16x32_bf16 v[20:23], v[166:169], v[182:185], v[20:23]
	v_mfma_f32_16x16x32_bf16 v[36:39], v[166:169], v[174:177], v[36:39]
	v_mfma_f32_16x16x32_bf16 v[44:47], v[162:165], v[178:181], v[44:47]
	v_mfma_f32_16x16x32_bf16 v[28:31], v[162:165], v[186:189], v[28:31]
	v_mfma_f32_16x16x32_bf16 v[12:15], v[162:165], v[194:197], v[12:15]
	v_mfma_f32_16x16x32_bf16 v[4:7], v[162:165], v[202:205], v[4:7]
	v_mfma_f32_16x16x32_bf16 v[0:3], v[170:173], v[202:205], v[0:3]
	v_mfma_f32_16x16x32_bf16 v[8:11], v[170:173], v[194:197], v[8:11]
	v_mfma_f32_16x16x32_bf16 v[20:23], v[170:173], v[186:189], v[20:23]
	v_mfma_f32_16x16x32_bf16 v[36:39], v[170:173], v[178:181], v[36:39]
	s_setprio 0
	s_barrier
; #define PG8_STAGE(bufoff, gbase, voff) do { _Pragma("unroll") for (int _i = 0; _i < 2; ++_i) \
;         __builtin_amdgcn_global_load_lds((const unsigned*)((const char*)(gbase) + (voff)[_i]), (PG8_LAS unsigned*)(lds + (bufoff) + ldsw + _i * 8192), 16, 0, 0); } while (0)
; #define PG8_LDA(dst, b, h) do { _Pragma("unroll") for (int m = 0; m < 4; ++m) _Pragma("unroll") for (int k = 0; k < 2; ++k) dst[m][k] = *(const PG8_LAS bf16x8*)(lds + PG8_SA(b, h) + aoff + m * 2048 + k * 1024); } while (0)
; #define PG8_LDB(dst, b, h) do { _Pragma("unroll") for (int n = 0; n < 2; ++n) _Pragma("unroll") for (int k = 0; k < 2; ++k) dst[n][k] = *(const PG8_LAS bf16x8*)(lds + PG8_SB(b, h) + boff + n * 2048 + k * 1024); } while (0)
; #define PG8_MMA(ai, bj, At, Bt) do { __builtin_amdgcn_s_setprio(1); _Pragma("unroll") for (int m = 0; m < 4; ++m) _Pragma("unroll") for (int n = 0; n < 2; ++n) _Pragma("unroll") for (int k = 0; k < 2; ++k) \
;         acc[ai][bj][m][n] = __builtin_amdgcn_mfma_f32_16x16x32_bf16(Bt[n][k], At[m][k], acc[ai][bj][m][n], 0, 0, 0); __builtin_amdgcn_s_setprio(0); } while (0)
; #define PG8_WAIT_V(n) asm volatile("s_waitcnt vmcnt(" #n ")" ::: "memory")
; #define PG8_WAIT_L(n) asm volatile("s_waitcnt lgkmcnt(" #n ")" ::: "memory")
; #define PG8_BAR __builtin_amdgcn_s_barrier()
; #define PG8_SCHED __builtin_amdgcn_sched_barrier(0)
; template <class Epi, class Sched, bool ALIGN_EPI = false, bool SP2 = false>
; __device__ __forceinline__ void gemm_phase(PG8_LAS unsigned char* lds, const Gemm g, const Sched& S, const Epi& E) {
;     ...
;             PG8_LDB(B0, 1, 0); PG8_LDB(B1, 1, 1); PG8_SCHED; PG8_LDA(At, 1, 0); PG8_STAGE(PG8_SA(0, 1), a2 + hstep, voffA);
;             PG8_WAIT_V(8); PG8_WAIT_L(0); PG8_BAR; PG8_MMA(0, 0, At, B0); PG8_MMA(0, 1, At, B1); PG8_BAR; PG8_SCHED;
	s_add_i32 s25, 0, 0x18000
	s_add_i32 s57, 0, 0x1c000
	v_add_u32_e32 v154, s25, v244
	v_add_u32_e32 v170, s57, v244
	ds_read_b128 v[142:145], v154
	ds_read_b128 v[146:149], v154 offset:1024
	ds_read_b128 v[150:153], v154 offset:2048
	ds_read_b128 v[154:157], v154 offset:3072
	ds_read_b128 v[158:161], v170
	ds_read_b128 v[162:165], v170 offset:1024
	ds_read_b128 v[166:169], v170 offset:2048
	ds_read_b128 v[170:173], v170 offset:3072
	s_add_u32 s48, s48, s30
	s_addc_u32 s49, s49, s31
	s_mov_b32 m0, s17
	v_lshl_add_u64 v[218:219], s[48:49], 0, v[128:129]
	ds_read_b128 v[174:177], v248 offset:32768
	ds_read_b128 v[178:181], v248 offset:33792
	ds_read_b128 v[182:185], v248 offset:34816
	ds_read_b128 v[186:189], v248 offset:35840
	ds_read_b128 v[190:193], v248 offset:36864
	ds_read_b128 v[194:197], v248 offset:37888
	ds_read_b128 v[198:201], v248 offset:38912
	ds_read_b128 v[202:205], v248 offset:39936
	global_load_lds_dwordx4 v[218:219], off
	v_lshl_add_u64 v[218:219], s[48:49], 0, v[132:133]
	s_mov_b32 m0, s18
	s_nop 0
	global_load_lds_dwordx4 v[218:219], off
	s_waitcnt vmcnt(8)
	s_waitcnt lgkmcnt(0)
	s_barrier
	s_setprio 1
	s_waitcnt lgkmcnt(0)
	v_mfma_f32_16x16x32_bf16 v[124:127], v[142:145], v[174:177], v[124:127]
	v_mfma_f32_16x16x32_bf16 v[116:119], v[142:145], v[182:185], v[116:119]
	v_mfma_f32_16x16x32_bf16 v[104:107], v[142:145], v[190:193], v[104:107]
	v_mfma_f32_16x16x32_bf16 v[88:91], v[142:145], v[198:201], v[88:91]
	v_mfma_f32_16x16x32_bf16 v[80:83], v[150:153], v[198:201], v[80:83]
	v_mfma_f32_16x16x32_bf16 v[96:99], v[150:153], v[190:193], v[96:99]
	v_mfma_f32_16x16x32_bf16 v[112:115], v[150:153], v[182:185], v[112:115]
	v_mfma_f32_16x16x32_bf16 v[120:123], v[150:153], v[174:177], v[120:123]
	v_mfma_f32_16x16x32_bf16 v[124:127], v[146:149], v[178:181], v[124:127]
	v_mfma_f32_16x16x32_bf16 v[116:119], v[146:149], v[186:189], v[116:119]
	v_mfma_f32_16x16x32_bf16 v[104:107], v[146:149], v[194:197], v[104:107]
	v_mfma_f32_16x16x32_bf16 v[88:91], v[146:149], v[202:205], v[88:91]
	v_mfma_f32_16x16x32_bf16 v[80:83], v[154:157], v[202:205], v[80:83]
	v_mfma_f32_16x16x32_bf16 v[96:99], v[154:157], v[194:197], v[96:99]
	v_mfma_f32_16x16x32_bf16 v[112:115], v[154:157], v[186:189], v[112:115]
	v_mfma_f32_16x16x32_bf16 v[120:123], v[154:157], v[178:181], v[120:123]
	s_setprio 0
	s_setprio 1
	v_mfma_f32_16x16x32_bf16 v[108:111], v[158:161], v[174:177], v[108:111]
	v_mfma_f32_16x16x32_bf16 v[92:95], v[158:161], v[182:185], v[92:95]
	v_mfma_f32_16x16x32_bf16 v[76:79], v[158:161], v[190:193], v[76:79]
	v_mfma_f32_16x16x32_bf16 v[68:71], v[158:161], v[198:201], v[68:71]
	v_mfma_f32_16x16x32_bf16 v[64:67], v[166:169], v[198:201], v[64:67]
	v_mfma_f32_16x16x32_bf16 v[72:75], v[166:169], v[190:193], v[72:75]
	v_mfma_f32_16x16x32_bf16 v[84:87], v[166:169], v[182:185], v[84:87]
	v_mfma_f32_16x16x32_bf16 v[100:103], v[166:169], v[174:177], v[100:103]
	v_mfma_f32_16x16x32_bf16 v[108:111], v[162:165], v[178:181], v[108:111]
	v_mfma_f32_16x16x32_bf16 v[92:95], v[162:165], v[186:189], v[92:95]
	v_mfma_f32_16x16x32_bf16 v[76:79], v[162:165], v[194:197], v[76:79]
	v_mfma_f32_16x16x32_bf16 v[68:71], v[162:165], v[202:205], v[68:71]
	v_mfma_f32_16x16x32_bf16 v[64:67], v[170:173], v[202:205], v[64:67]
	v_mfma_f32_16x16x32_bf16 v[72:75], v[170:173], v[194:197], v[72:75]
	v_mfma_f32_16x16x32_bf16 v[84:87], v[170:173], v[186:189], v[84:87]
	v_mfma_f32_16x16x32_bf16 v[100:103], v[170:173], v[178:181], v[100:103]
	s_setprio 0
	s_barrier
; #define PG8_STAGE(bufoff, gbase, voff) do { _Pragma("unroll") for (int _i = 0; _i < 2; ++_i) \
;         __builtin_amdgcn_global_load_lds((const unsigned*)((const char*)(gbase) + (voff)[_i]), (PG8_LAS unsigned*)(lds + (bufoff) + ldsw + _i * 8192), 16, 0, 0); } while (0)
; #define PG8_LDA(dst, b, h) do { _Pragma("unroll") for (int m = 0; m < 4; ++m) _Pragma("unroll") for (int k = 0; k < 2; ++k) dst[m][k] = *(const PG8_LAS bf16x8*)(lds + PG8_SA(b, h) + aoff + m * 2048 + k * 1024); } while (0)
; #define PG8_MMA(ai, bj, At, Bt) do { __builtin_amdgcn_s_setprio(1); _Pragma("unroll") for (int m = 0; m < 4; ++m) _Pragma("unroll") for (int n = 0; n < 2; ++n) _Pragma("unroll") for (int k = 0; k < 2; ++k) \
;         acc[ai][bj][m][n] = __builtin_amdgcn_mfma_f32_16x16x32_bf16(Bt[n][k], At[m][k], acc[ai][bj][m][n], 0, 0, 0); __builtin_amdgcn_s_setprio(0); } while (0)
; #define PG8_WAIT_V(n) asm volatile("s_waitcnt vmcnt(" #n ")" ::: "memory")
; #define PG8_WAIT_L(n) asm volatile("s_waitcnt lgkmcnt(" #n ")" ::: "memory")
; #define PG8_BAR __builtin_amdgcn_s_barrier()
; #define PG8_SCHED __builtin_amdgcn_sched_barrier(0)
; template <class Epi, class Sched, bool ALIGN_EPI = false, bool SP2 = false>
; __device__ __forceinline__ void gemm_phase(PG8_LAS unsigned char* lds, const Gemm g, const Sched& S, const Epi& E) {
;     ...
;             PG8_LDA(At, 1, 1); PG8_STAGE(PG8_SB(1, 0), b3, voffB); PG8_STAGE(PG8_SB(1, 1), b3 + hstep, voffB); PG8_STAGE(PG8_SA(1, 0), a3, voffA);
;             PG8_WAIT_V(8); PG8_WAIT_L(0); PG8_BAR; PG8_MMA(1, 0, At, B0); PG8_MMA(1, 1, At, B1); PG8_BAR; PG8_SCHED;
	s_add_i32 s25, s25, s6
	v_lshl_add_u64 v[206:207], v[206:207], 0, s[40:41]
	s_mov_b32 m0, s25
	ds_read_b128 v[174:177], v248 offset:49152
	ds_read_b128 v[178:181], v248 offset:50176
	ds_read_b128 v[182:185], v248 offset:51200
	ds_read_b128 v[186:189], v248 offset:52224
	ds_read_b128 v[190:193], v248 offset:53248
	ds_read_b128 v[194:197], v248 offset:54272
	ds_read_b128 v[198:201], v248 offset:55296
	ds_read_b128 v[202:205], v248 offset:56320
	global_load_lds_dwordx4 v[206:207], off
	v_lshl_add_u64 v[206:207], v[208:209], 0, s[40:41]
	s_add_i32 m0, s25, 0x2000
	s_add_i32 s25, s57, s6
	global_load_lds_dwordx4 v[206:207], off
	v_lshl_add_u64 v[206:207], v[210:211], 0, s[40:41]
	s_mov_b32 m0, s25
	s_nop 0
	global_load_lds_dwordx4 v[206:207], off
	v_lshl_add_u64 v[206:207], v[212:213], 0, s[40:41]
	s_add_i32 m0, s25, 0x2000
	s_nop 0
	global_load_lds_dwordx4 v[206:207], off
	v_lshl_add_u64 v[206:207], v[214:215], 0, s[40:41]
	s_mov_b32 m0, s19
	s_nop 0
	global_load_lds_dwordx4 v[206:207], off
	v_lshl_add_u64 v[206:207], v[216:217], 0, s[40:41]
	s_mov_b32 m0, s26
	s_nop 0
	global_load_lds_dwordx4 v[206:207], off
	s_waitcnt vmcnt(8)
	s_waitcnt lgkmcnt(0)
	s_barrier
	s_setprio 1
	s_waitcnt lgkmcnt(0)
	v_mfma_f32_16x16x32_bf16 v[60:63], v[142:145], v[174:177], v[60:63]
	v_mfma_f32_16x16x32_bf16 v[52:55], v[142:145], v[182:185], v[52:55]
	v_mfma_f32_16x16x32_bf16 v[40:43], v[142:145], v[190:193], v[40:43]
	v_mfma_f32_16x16x32_bf16 v[24:27], v[142:145], v[198:201], v[24:27]
	v_mfma_f32_16x16x32_bf16 v[16:19], v[150:153], v[198:201], v[16:19]
	v_mfma_f32_16x16x32_bf16 v[32:35], v[150:153], v[190:193], v[32:35]
	v_mfma_f32_16x16x32_bf16 v[48:51], v[150:153], v[182:185], v[48:51]
	v_mfma_f32_16x16x32_bf16 v[56:59], v[150:153], v[174:177], v[56:59]
	v_mfma_f32_16x16x32_bf16 v[60:63], v[146:149], v[178:181], v[60:63]
	v_mfma_f32_16x16x32_bf16 v[52:55], v[146:149], v[186:189], v[52:55]
	v_mfma_f32_16x16x32_bf16 v[40:43], v[146:149], v[194:197], v[40:43]
	v_mfma_f32_16x16x32_bf16 v[24:27], v[146:149], v[202:205], v[24:27]
	v_mfma_f32_16x16x32_bf16 v[16:19], v[154:157], v[202:205], v[16:19]
	v_mfma_f32_16x16x32_bf16 v[32:35], v[154:157], v[194:197], v[32:35]
	v_mfma_f32_16x16x32_bf16 v[48:51], v[154:157], v[186:189], v[48:51]
	v_mfma_f32_16x16x32_bf16 v[56:59], v[154:157], v[178:181], v[56:59]
	s_setprio 0
	s_setprio 1
	v_mfma_f32_16x16x32_bf16 v[44:47], v[158:161], v[174:177], v[44:47]
	v_mfma_f32_16x16x32_bf16 v[28:31], v[158:161], v[182:185], v[28:31]
	v_mfma_f32_16x16x32_bf16 v[12:15], v[158:161], v[190:193], v[12:15]
	v_mfma_f32_16x16x32_bf16 v[4:7], v[158:161], v[198:201], v[4:7]
	v_mfma_f32_16x16x32_bf16 v[0:3], v[166:169], v[198:201], v[0:3]
	v_mfma_f32_16x16x32_bf16 v[8:11], v[166:169], v[190:193], v[8:11]
	v_mfma_f32_16x16x32_bf16 v[20:23], v[166:169], v[182:185], v[20:23]
	v_mfma_f32_16x16x32_bf16 v[36:39], v[166:169], v[174:177], v[36:39]
	v_mfma_f32_16x16x32_bf16 v[44:47], v[162:165], v[178:181], v[44:47]
	v_mfma_f32_16x16x32_bf16 v[28:31], v[162:165], v[186:189], v[28:31]
	v_mfma_f32_16x16x32_bf16 v[12:15], v[162:165], v[194:197], v[12:15]
	v_mfma_f32_16x16x32_bf16 v[4:7], v[162:165], v[202:205], v[4:7]
	v_mfma_f32_16x16x32_bf16 v[0:3], v[170:173], v[202:205], v[0:3]
	v_mfma_f32_16x16x32_bf16 v[8:11], v[170:173], v[194:197], v[8:11]
	v_mfma_f32_16x16x32_bf16 v[20:23], v[170:173], v[186:189], v[20:23]
	v_mfma_f32_16x16x32_bf16 v[36:39], v[170:173], v[178:181], v[36:39]
	s_setprio 0
	s_barrier
	s_add_u32 s46, s46, 0x100
	s_addc_u32 s47, s47, 0
	s_add_u32 s2, s2, 0x100
	s_addc_u32 s24, s24, 0
	s_cmp_ge_i32 s56, s33
	s_mov_b32 s25, s56
	s_cbranch_scc0 .LBB0_432

; #define PG8_STAGE(bufoff, gbase, voff) do { _Pragma("unroll") for (int _i = 0; _i < 2; ++_i) \
;         __builtin_amdgcn_global_load_lds((const unsigned*)((const char*)(gbase) + (voff)[_i]), (PG8_LAS unsigned*)(lds + (bufoff) + ldsw + _i * 8192), 16, 0, 0); } while (0)
; #define PG8_LDA(dst, b, h) do { _Pragma("unroll") for (int m = 0; m < 4; ++m) _Pragma("unroll") for (int k = 0; k < 2; ++k) dst[m][k] = *(const PG8_LAS bf16x8*)(lds + PG8_SA(b, h) + aoff + m * 2048 + k * 1024); } while (0)
; #define PG8_LDB(dst, b, h) do { _Pragma("unroll") for (int n = 0; n < 2; ++n) _Pragma("unroll") for (int k = 0; k < 2; ++k) dst[n][k] = *(const PG8_LAS bf16x8*)(lds + PG8_SB(b, h) + boff + n * 2048 + k * 1024); } while (0)
; #define PG8_MMA(ai, bj, At, Bt) do { __builtin_amdgcn_s_setprio(1); _Pragma("unroll") for (int m = 0; m < 4; ++m) _Pragma("unroll") for (int n = 0; n < 2; ++n) _Pragma("unroll") for (int k = 0; k < 2; ++k) \
;         acc[ai][bj][m][n] = __builtin_amdgcn_mfma_f32_16x16x32_bf16(Bt[n][k], At[m][k], acc[ai][bj][m][n], 0, 0, 0); __builtin_amdgcn_s_setprio(0); } while (0)
; #define PG8_WAIT_V(n) asm volatile("s_waitcnt vmcnt(" #n ")" ::: "memory")
; #define PG8_BAR __builtin_amdgcn_s_barrier()
; template <class Epi, class Sched, bool ALIGN_EPI = false, bool SP2 = false>
; __device__ __forceinline__ void gemm_phase(PG8_LAS unsigned char* lds, const Gemm g, const Sched& S, const Epi& E) {
;     ...
;         for (int t = 0; t < nt; t += 2) {
;             const bool last = (t == nt - 2);
;             const char* a1 = cA + (size_t)(t + 1) * kstep;
;             const char* a2 = last ? nA : cA + (size_t)(t + 2) * kstep; const char* b2 = last ? nB : cB + (size_t)(t + 2) * kstep;
;             const char* a3 = a2 + kstep; const char* b3 = b2 + kstep;
;             if (last && has_next) S.a_ready(nxt);
;             if constexpr (SP2) {
;             PG8_LDB(B0, 0, 0); PG8_LDB(B1, 0, 1); PG8_SCHED; PG8_LDA(At, 0, 0); PG8_STAGE(PG8_SA(1, 1), a1 + hstep, voffA);
;             PG8_WAIT_V(8); PG8_WAIT_L(0); PG8_BAR; PG8_MMA(0, 0, At, B0); PG8_MMA(0, 1, At, B1); PG8_BAR; PG8_SCHED;
;             PG8_LDA(At, 0, 1); PG8_STAGE(PG8_SB(0, 0), b2, voffB); PG8_STAGE(PG8_SB(0, 1), b2 + hstep, voffB); PG8_STAGE(PG8_SA(0, 0), a2, voffA);
;             PG8_WAIT_V(8); PG8_WAIT_L(0); PG8_BAR; PG8_MMA(1, 0, At, B0); PG8_MMA(1, 1, At, B1); PG8_BAR; PG8_SCHED;
.LBB0_532:
	s_and_b64 vcc, exec, s[8:9]
	s_cbranch_vccnz .Lcoldz_2
	s_add_u32 s54, s54, 0x80
	s_addc_u32 s55, s55, 0
	s_add_u32 s2, s56, 0x100
	s_addc_u32 s24, s57, 0
	s_mov_b32 s25, 0
	ds_read_b128 v[128:131], v209
	ds_read_b128 v[132:135], v209 offset:1024
	ds_read_b128 v[136:139], v209 offset:2048
	ds_read_b128 v[140:143], v209 offset:3072
	ds_read_b128 v[144:147], v210
	ds_read_b128 v[148:151], v210 offset:1024
	ds_read_b128 v[152:155], v210 offset:2048
	ds_read_b128 v[156:159], v210 offset:3072
	s_add_i32 s65, s25, 2
	s_add_u32 s56, s54, 0x80
	s_addc_u32 s57, s55, 0
	s_cmp_eq_u32 s34, s25
	s_cselect_b32 s57, s13, s57
	s_cselect_b32 s56, s12, s56
	s_cselect_b32 s67, s53, s24
	s_cselect_b32 s66, s52, s2
	v_lshl_add_u64 v[202:203], s[54:55], 0, v[186:187]
	s_add_i32 m0, s16, 0xc000
	ds_read_b128 v[160:163], v211
	ds_read_b128 v[164:167], v211 offset:1024
	ds_read_b128 v[168:171], v211 offset:2048
	ds_read_b128 v[172:175], v211 offset:3072
	ds_read_b128 v[194:197], v211 offset:4096
	ds_read_b128 v[198:201], v211 offset:5120
	ds_read_b128 v[214:217], v211 offset:6144
	ds_read_b128 v[218:221], v211 offset:7168
	global_load_lds_dwordx4 v[202:203], off
	v_lshl_add_u64 v[202:203], s[54:55], 0, v[188:189]
	s_add_i32 m0, s16, 0xe000
	s_nop 0
	global_load_lds_dwordx4 v[202:203], off
	s_waitcnt vmcnt(8)
	s_waitcnt lgkmcnt(0)
	s_barrier
	s_setprio 1
	s_waitcnt lgkmcnt(0)
	v_mfma_f32_16x16x32_bf16 v[124:127], v[128:131], v[160:163], 0
	v_mfma_f32_16x16x32_bf16 v[120:123], v[136:139], v[160:163], 0
	v_mfma_f32_16x16x32_bf16 v[108:111], v[128:131], v[168:171], 0
	v_mfma_f32_16x16x32_bf16 v[104:107], v[136:139], v[168:171], 0
	v_mfma_f32_16x16x32_bf16 v[92:95], v[128:131], v[194:197], 0
	v_mfma_f32_16x16x32_bf16 v[88:91], v[136:139], v[194:197], 0
	v_mfma_f32_16x16x32_bf16 v[76:79], v[128:131], v[214:217], 0
	v_mfma_f32_16x16x32_bf16 v[72:75], v[136:139], v[214:217], 0
	v_mfma_f32_16x16x32_bf16 v[124:127], v[132:135], v[164:167], v[124:127]
	v_mfma_f32_16x16x32_bf16 v[108:111], v[132:135], v[172:175], v[108:111]
	v_mfma_f32_16x16x32_bf16 v[92:95], v[132:135], v[198:201], v[92:95]
	v_mfma_f32_16x16x32_bf16 v[76:79], v[132:135], v[218:221], v[76:79]
	v_mfma_f32_16x16x32_bf16 v[72:75], v[140:143], v[218:221], v[72:75]
	v_mfma_f32_16x16x32_bf16 v[88:91], v[140:143], v[198:201], v[88:91]
	v_mfma_f32_16x16x32_bf16 v[104:107], v[140:143], v[172:175], v[104:107]
	v_mfma_f32_16x16x32_bf16 v[120:123], v[140:143], v[164:167], v[120:123]
	s_setprio 0
	s_setprio 1
	v_mfma_f32_16x16x32_bf16 v[116:119], v[144:147], v[160:163], 0
	v_mfma_f32_16x16x32_bf16 v[112:115], v[152:155], v[160:163], 0
	v_mfma_f32_16x16x32_bf16 v[100:103], v[144:147], v[168:171], 0
	v_mfma_f32_16x16x32_bf16 v[96:99], v[152:155], v[168:171], 0
	v_mfma_f32_16x16x32_bf16 v[84:87], v[144:147], v[194:197], 0
	v_mfma_f32_16x16x32_bf16 v[80:83], v[152:155], v[194:197], 0
	v_mfma_f32_16x16x32_bf16 v[68:71], v[144:147], v[214:217], 0
	v_mfma_f32_16x16x32_bf16 v[64:67], v[152:155], v[214:217], 0
	v_mfma_f32_16x16x32_bf16 v[116:119], v[148:151], v[164:167], v[116:119]
	v_mfma_f32_16x16x32_bf16 v[100:103], v[148:151], v[172:175], v[100:103]
	v_mfma_f32_16x16x32_bf16 v[84:87], v[148:151], v[198:201], v[84:87]
	v_mfma_f32_16x16x32_bf16 v[68:71], v[148:151], v[218:221], v[68:71]
	v_mfma_f32_16x16x32_bf16 v[64:67], v[156:159], v[218:221], v[64:67]
	v_mfma_f32_16x16x32_bf16 v[80:83], v[156:159], v[198:201], v[80:83]
	v_mfma_f32_16x16x32_bf16 v[96:99], v[156:159], v[172:175], v[96:99]
	v_mfma_f32_16x16x32_bf16 v[112:115], v[156:159], v[164:167], v[112:115]
	s_setprio 0
	s_barrier
	s_add_i32 s25, s3, s4
	v_lshl_add_u64 v[202:203], s[66:67], 0, v[180:181]
	s_mov_b32 m0, s25
	ds_read_b128 v[160:163], v211 offset:16384
	ds_read_b128 v[164:167], v211 offset:17408
	ds_read_b128 v[168:171], v211 offset:18432
	ds_read_b128 v[172:175], v211 offset:19456
	ds_read_b128 v[194:197], v211 offset:20480
	ds_read_b128 v[198:201], v211 offset:21504
	ds_read_b128 v[214:217], v211 offset:22528
	ds_read_b128 v[218:221], v211 offset:23552
	global_load_lds_dwordx4 v[202:203], off
	s_add_i32 m0, s25, 0x2000
	v_lshl_add_u64 v[222:223], s[66:67], 0, v[176:177]
	s_add_u32 s66, s66, s14
	s_addc_u32 s67, s67, s15
	s_add_i32 s25, s35, s4
	global_load_lds_dwordx4 v[222:223], off
	v_lshl_add_u64 v[224:225], s[66:67], 0, v[180:181]
	s_mov_b32 m0, s25
	v_lshl_add_u64 v[226:227], s[66:67], 0, v[176:177]
	global_load_lds_dwordx4 v[224:225], off
	s_add_i32 m0, s25, 0x2000
	v_lshl_add_u64 v[228:229], s[56:57], 0, v[182:183]
	global_load_lds_dwordx4 v[226:227], off
	s_mov_b32 m0, s16
	v_lshl_add_u64 v[230:231], s[56:57], 0, v[178:179]
	global_load_lds_dwordx4 v[228:229], off
	s_mov_b32 m0, s17
	s_nop 0
	global_load_lds_dwordx4 v[230:231], off
	s_waitcnt vmcnt(8)
	s_waitcnt lgkmcnt(0)
	s_barrier
; #define PG8_STAGE(bufoff, gbase, voff) do { _Pragma("unroll") for (int _i = 0; _i < 2; ++_i) \
;         __builtin_amdgcn_global_load_lds((const unsigned*)((const char*)(gbase) + (voff)[_i]), (PG8_LAS unsigned*)(lds + (bufoff) + ldsw + _i * 8192), 16, 0, 0); } while (0)
; #define PG8_LDA(dst, b, h) do { _Pragma("unroll") for (int m = 0; m < 4; ++m) _Pragma("unroll") for (int k = 0; k < 2; ++k) dst[m][k] = *(const PG8_LAS bf16x8*)(lds + PG8_SA(b, h) + aoff + m * 2048 + k * 1024); } while (0)
; #define PG8_LDB(dst, b, h) do { _Pragma("unroll") for (int n = 0; n < 2; ++n) _Pragma("unroll") for (int k = 0; k < 2; ++k) dst[n][k] = *(const PG8_LAS bf16x8*)(lds + PG8_SB(b, h) + boff + n * 2048 + k * 1024); } while (0)
; #define PG8_MMA(ai, bj, At, Bt) do { __builtin_amdgcn_s_setprio(1); _Pragma("unroll") for (int m = 0; m < 4; ++m) _Pragma("unroll") for (int n = 0; n < 2; ++n) _Pragma("unroll") for (int k = 0; k < 2; ++k) \
;         acc[ai][bj][m][n] = __builtin_amdgcn_mfma_f32_16x16x32_bf16(Bt[n][k], At[m][k], acc[ai][bj][m][n], 0, 0, 0); __builtin_amdgcn_s_setprio(0); } while (0)
; #define PG8_WAIT_V(n) asm volatile("s_waitcnt vmcnt(" #n ")" ::: "memory")
; #define PG8_WAIT_L(n) asm volatile("s_waitcnt lgkmcnt(" #n ")" ::: "memory")
; #define PG8_BAR __builtin_amdgcn_s_barrier()
; #define PG8_SCHED __builtin_amdgcn_sched_barrier(0)
; template <class Epi, class Sched, bool ALIGN_EPI = false, bool SP2 = false>
; __device__ __forceinline__ void gemm_phase(PG8_LAS unsigned char* lds, const Gemm g, const Sched& S, const Epi& E) {
;     ...
;             PG8_WAIT_V(8); PG8_WAIT_L(0); PG8_BAR; PG8_MMA(1, 0, At, B0); PG8_MMA(1, 1, At, B1); PG8_BAR; PG8_SCHED;
;             PG8_LDB(B0, 1, 0); PG8_LDB(B1, 1, 1); PG8_SCHED; PG8_LDA(At, 1, 0); PG8_STAGE(PG8_SA(0, 1), a2 + hstep, voffA);
;             PG8_WAIT_V(8); PG8_WAIT_L(0); PG8_BAR; PG8_MMA(0, 0, At, B0); PG8_MMA(0, 1, At, B1); PG8_BAR; PG8_SCHED;
	s_setprio 1
	s_waitcnt lgkmcnt(0)
	v_mfma_f32_16x16x32_bf16 v[60:63], v[128:131], v[160:163], 0
	v_mfma_f32_16x16x32_bf16 v[56:59], v[136:139], v[160:163], 0
	v_mfma_f32_16x16x32_bf16 v[44:47], v[128:131], v[168:171], 0
	v_mfma_f32_16x16x32_bf16 v[40:43], v[136:139], v[168:171], 0
	v_mfma_f32_16x16x32_bf16 v[28:31], v[128:131], v[194:197], 0
	v_mfma_f32_16x16x32_bf16 v[24:27], v[136:139], v[194:197], 0
	v_mfma_f32_16x16x32_bf16 v[12:15], v[128:131], v[214:217], 0
	v_mfma_f32_16x16x32_bf16 v[8:11], v[136:139], v[214:217], 0
	v_mfma_f32_16x16x32_bf16 v[60:63], v[132:135], v[164:167], v[60:63]
	v_mfma_f32_16x16x32_bf16 v[44:47], v[132:135], v[172:175], v[44:47]
	v_mfma_f32_16x16x32_bf16 v[28:31], v[132:135], v[198:201], v[28:31]
	v_mfma_f32_16x16x32_bf16 v[12:15], v[132:135], v[218:221], v[12:15]
	v_mfma_f32_16x16x32_bf16 v[8:11], v[140:143], v[218:221], v[8:11]
	v_mfma_f32_16x16x32_bf16 v[24:27], v[140:143], v[198:201], v[24:27]
	v_mfma_f32_16x16x32_bf16 v[40:43], v[140:143], v[172:175], v[40:43]
	v_mfma_f32_16x16x32_bf16 v[56:59], v[140:143], v[164:167], v[56:59]
	s_setprio 0
	s_setprio 1
	v_mfma_f32_16x16x32_bf16 v[52:55], v[144:147], v[160:163], 0
	v_mfma_f32_16x16x32_bf16 v[48:51], v[152:155], v[160:163], 0
	v_mfma_f32_16x16x32_bf16 v[36:39], v[144:147], v[168:171], 0
	v_mfma_f32_16x16x32_bf16 v[32:35], v[152:155], v[168:171], 0
	v_mfma_f32_16x16x32_bf16 v[20:23], v[144:147], v[194:197], 0
	v_mfma_f32_16x16x32_bf16 v[16:19], v[152:155], v[194:197], 0
	v_mfma_f32_16x16x32_bf16 v[4:7], v[144:147], v[214:217], 0
	v_mfma_f32_16x16x32_bf16 v[0:3], v[152:155], v[214:217], 0
	v_mfma_f32_16x16x32_bf16 v[52:55], v[148:151], v[164:167], v[52:55]
	v_mfma_f32_16x16x32_bf16 v[36:39], v[148:151], v[172:175], v[36:39]
	v_mfma_f32_16x16x32_bf16 v[20:23], v[148:151], v[198:201], v[20:23]
	v_mfma_f32_16x16x32_bf16 v[4:7], v[148:151], v[218:221], v[4:7]
	v_mfma_f32_16x16x32_bf16 v[0:3], v[156:159], v[218:221], v[0:3]
	v_mfma_f32_16x16x32_bf16 v[16:19], v[156:159], v[198:201], v[16:19]
	v_mfma_f32_16x16x32_bf16 v[32:35], v[156:159], v[172:175], v[32:35]
	v_mfma_f32_16x16x32_bf16 v[48:51], v[156:159], v[164:167], v[48:51]
	s_setprio 0
	s_barrier
	s_add_i32 s25, 0, 0x18000
	s_add_i32 s66, 0, 0x1c000
	v_add_u32_e32 v140, s25, v205
	v_add_u32_e32 v156, s66, v205
	ds_read_b128 v[128:131], v140
	ds_read_b128 v[132:135], v140 offset:1024
	ds_read_b128 v[136:139], v140 offset:2048
	ds_read_b128 v[140:143], v140 offset:3072
	ds_read_b128 v[144:147], v156
	ds_read_b128 v[148:151], v156 offset:1024
	ds_read_b128 v[152:155], v156 offset:2048
	ds_read_b128 v[156:159], v156 offset:3072
	s_add_u32 s56, s56, s14
	s_addc_u32 s57, s57, s15
	s_mov_b32 m0, s18
	v_lshl_add_u64 v[232:233], s[56:57], 0, v[182:183]
	ds_read_b128 v[160:163], v211 offset:32768
	ds_read_b128 v[164:167], v211 offset:33792
	ds_read_b128 v[168:171], v211 offset:34816
	ds_read_b128 v[172:175], v211 offset:35840
	ds_read_b128 v[194:197], v211 offset:36864
	ds_read_b128 v[198:201], v211 offset:37888
	ds_read_b128 v[214:217], v211 offset:38912
	ds_read_b128 v[218:221], v211 offset:39936
	global_load_lds_dwordx4 v[232:233], off
	v_lshl_add_u64 v[232:233], s[56:57], 0, v[178:179]
	s_mov_b32 m0, s19
	s_nop 0
	global_load_lds_dwordx4 v[232:233], off
	s_waitcnt vmcnt(8)
	s_waitcnt lgkmcnt(0)
	s_barrier
	s_setprio 1
	s_waitcnt lgkmcnt(0)
	v_mfma_f32_16x16x32_bf16 v[124:127], v[128:131], v[160:163], v[124:127]
	v_mfma_f32_16x16x32_bf16 v[108:111], v[128:131], v[168:171], v[108:111]
	v_mfma_f32_16x16x32_bf16 v[92:95], v[128:131], v[194:197], v[92:95]
	v_mfma_f32_16x16x32_bf16 v[76:79], v[128:131], v[214:217], v[76:79]
	v_mfma_f32_16x16x32_bf16 v[72:75], v[136:139], v[214:217], v[72:75]
	v_mfma_f32_16x16x32_bf16 v[88:91], v[136:139], v[194:197], v[88:91]
	v_mfma_f32_16x16x32_bf16 v[104:107], v[136:139], v[168:171], v[104:107]
	v_mfma_f32_16x16x32_bf16 v[120:123], v[136:139], v[160:163], v[120:123]
	v_mfma_f32_16x16x32_bf16 v[124:127], v[132:135], v[164:167], v[124:127]
	v_mfma_f32_16x16x32_bf16 v[108:111], v[132:135], v[172:175], v[108:111]
	v_mfma_f32_16x16x32_bf16 v[92:95], v[132:135], v[198:201], v[92:95]
	v_mfma_f32_16x16x32_bf16 v[76:79], v[132:135], v[218:221], v[76:79]
	v_mfma_f32_16x16x32_bf16 v[72:75], v[140:143], v[218:221], v[72:75]
	v_mfma_f32_16x16x32_bf16 v[88:91], v[140:143], v[198:201], v[88:91]
	v_mfma_f32_16x16x32_bf16 v[104:107], v[140:143], v[172:175], v[104:107]
	v_mfma_f32_16x16x32_bf16 v[120:123], v[140:143], v[164:167], v[120:123]
	s_setprio 0
	s_setprio 1
	v_mfma_f32_16x16x32_bf16 v[116:119], v[144:147], v[160:163], v[116:119]
	v_mfma_f32_16x16x32_bf16 v[100:103], v[144:147], v[168:171], v[100:103]
	v_mfma_f32_16x16x32_bf16 v[84:87], v[144:147], v[194:197], v[84:87]
	v_mfma_f32_16x16x32_bf16 v[68:71], v[144:147], v[214:217], v[68:71]
	v_mfma_f32_16x16x32_bf16 v[64:67], v[152:155], v[214:217], v[64:67]
	v_mfma_f32_16x16x32_bf16 v[80:83], v[152:155], v[194:197], v[80:83]
	v_mfma_f32_16x16x32_bf16 v[96:99], v[152:155], v[168:171], v[96:99]
	v_mfma_f32_16x16x32_bf16 v[112:115], v[152:155], v[160:163], v[112:115]
	v_mfma_f32_16x16x32_bf16 v[116:119], v[148:151], v[164:167], v[116:119]
	v_mfma_f32_16x16x32_bf16 v[100:103], v[148:151], v[172:175], v[100:103]
	v_mfma_f32_16x16x32_bf16 v[84:87], v[148:151], v[198:201], v[84:87]
	v_mfma_f32_16x16x32_bf16 v[68:71], v[148:151], v[218:221], v[68:71]
	v_mfma_f32_16x16x32_bf16 v[64:67], v[156:159], v[218:221], v[64:67]
	v_mfma_f32_16x16x32_bf16 v[80:83], v[156:159], v[198:201], v[80:83]
	v_mfma_f32_16x16x32_bf16 v[96:99], v[156:159], v[172:175], v[96:99]
	v_mfma_f32_16x16x32_bf16 v[112:115], v[156:159], v[164:167], v[112:115]
	s_setprio 0
	s_barrier
; #define PG8_STAGE(bufoff, gbase, voff) do { _Pragma("unroll") for (int _i = 0; _i < 2; ++_i) \
;         __builtin_amdgcn_global_load_lds((const unsigned*)((const char*)(gbase) + (voff)[_i]), (PG8_LAS unsigned*)(lds + (bufoff) + ldsw + _i * 8192), 16, 0, 0); } while (0)
; #define PG8_LDA(dst, b, h) do { _Pragma("unroll") for (int m = 0; m < 4; ++m) _Pragma("unroll") for (int k = 0; k < 2; ++k) dst[m][k] = *(const PG8_LAS bf16x8*)(lds + PG8_SA(b, h) + aoff + m * 2048 + k * 1024); } while (0)
; #define PG8_LDB(dst, b, h) do { _Pragma("unroll") for (int n = 0; n < 2; ++n) _Pragma("unroll") for (int k = 0; k < 2; ++k) dst[n][k] = *(const PG8_LAS bf16x8*)(lds + PG8_SB(b, h) + boff + n * 2048 + k * 1024); } while (0)
; #define PG8_MMA(ai, bj, At, Bt) do { __builtin_amdgcn_s_setprio(1); _Pragma("unroll") for (int m = 0; m < 4; ++m) _Pragma("unroll") for (int n = 0; n < 2; ++n) _Pragma("unroll") for (int k = 0; k < 2; ++k) \
;         acc[ai][bj][m][n] = __builtin_amdgcn_mfma_f32_16x16x32_bf16(Bt[n][k], At[m][k], acc[ai][bj][m][n], 0, 0, 0); __builtin_amdgcn_s_setprio(0); } while (0)
; #define PG8_WAIT_V(n) asm volatile("s_waitcnt vmcnt(" #n ")" ::: "memory")
; #define PG8_WAIT_L(n) asm volatile("s_waitcnt lgkmcnt(" #n ")" ::: "memory")
; #define PG8_BAR __builtin_amdgcn_s_barrier()
; #define PG8_SCHED __builtin_amdgcn_sched_barrier(0)
; template <class Epi, class Sched, bool ALIGN_EPI = false, bool SP2 = false>
; __device__ __forceinline__ void gemm_phase(PG8_LAS unsigned char* lds, const Gemm g, const Sched& S, const Epi& E) {
;     ...
;         for (int t = 0; t < nt; t += 2) {
;             const bool last = (t == nt - 2);
;             const char* a1 = cA + (size_t)(t + 1) * kstep;
;             const char* a2 = last ? nA : cA + (size_t)(t + 2) * kstep; const char* b2 = last ? nB : cB + (size_t)(t + 2) * kstep;
;             const char* a3 = a2 + kstep; const char* b3 = b2 + kstep;
;             if (last && has_next) S.a_ready(nxt);
;             if constexpr (SP2) {
;             PG8_LDB(B0, 0, 0); PG8_LDB(B1, 0, 1); PG8_SCHED; PG8_LDA(At, 0, 0); PG8_STAGE(PG8_SA(1, 1), a1 + hstep, voffA);
;     ...
;             PG8_LDA(At, 1, 1); PG8_STAGE(PG8_SB(1, 0), b3, voffB); PG8_STAGE(PG8_SB(1, 1), b3 + hstep, voffB); PG8_STAGE(PG8_SA(1, 0), a3, voffA);
;             PG8_WAIT_V(8); PG8_WAIT_L(0); PG8_BAR; PG8_MMA(1, 0, At, B0); PG8_MMA(1, 1, At, B1); PG8_BAR; PG8_SCHED;
	s_add_i32 s25, s25, s4
	v_lshl_add_u64 v[202:203], v[202:203], 0, s[38:39]
	s_mov_b32 m0, s25
	ds_read_b128 v[160:163], v211 offset:49152
	ds_read_b128 v[164:167], v211 offset:50176
	ds_read_b128 v[168:171], v211 offset:51200
	ds_read_b128 v[172:175], v211 offset:52224
	ds_read_b128 v[194:197], v211 offset:53248
	ds_read_b128 v[198:201], v211 offset:54272
	ds_read_b128 v[214:217], v211 offset:55296
	ds_read_b128 v[218:221], v211 offset:56320
	global_load_lds_dwordx4 v[202:203], off
	v_lshl_add_u64 v[202:203], v[222:223], 0, s[38:39]
	s_add_i32 m0, s25, 0x2000
	s_add_i32 s25, s66, s4
	global_load_lds_dwordx4 v[202:203], off
	v_lshl_add_u64 v[202:203], v[224:225], 0, s[38:39]
	s_mov_b32 m0, s25
	s_nop 0
	global_load_lds_dwordx4 v[202:203], off
	v_lshl_add_u64 v[202:203], v[226:227], 0, s[38:39]
	s_add_i32 m0, s25, 0x2000
	s_nop 0
	global_load_lds_dwordx4 v[202:203], off
	v_lshl_add_u64 v[202:203], v[228:229], 0, s[38:39]
	s_mov_b32 m0, s26
	s_nop 0
	global_load_lds_dwordx4 v[202:203], off
	v_lshl_add_u64 v[202:203], v[230:231], 0, s[38:39]
	s_mov_b32 m0, s27
	s_nop 0
	global_load_lds_dwordx4 v[202:203], off
	s_waitcnt vmcnt(8)
	s_waitcnt lgkmcnt(0)
	s_barrier
	s_setprio 1
	s_waitcnt lgkmcnt(0)
	v_mfma_f32_16x16x32_bf16 v[60:63], v[128:131], v[160:163], v[60:63]
	v_mfma_f32_16x16x32_bf16 v[44:47], v[128:131], v[168:171], v[44:47]
	v_mfma_f32_16x16x32_bf16 v[28:31], v[128:131], v[194:197], v[28:31]
	v_mfma_f32_16x16x32_bf16 v[12:15], v[128:131], v[214:217], v[12:15]
	v_mfma_f32_16x16x32_bf16 v[8:11], v[136:139], v[214:217], v[8:11]
	v_mfma_f32_16x16x32_bf16 v[24:27], v[136:139], v[194:197], v[24:27]
	v_mfma_f32_16x16x32_bf16 v[40:43], v[136:139], v[168:171], v[40:43]
	v_mfma_f32_16x16x32_bf16 v[56:59], v[136:139], v[160:163], v[56:59]
	v_mfma_f32_16x16x32_bf16 v[60:63], v[132:135], v[164:167], v[60:63]
	v_mfma_f32_16x16x32_bf16 v[44:47], v[132:135], v[172:175], v[44:47]
	v_mfma_f32_16x16x32_bf16 v[28:31], v[132:135], v[198:201], v[28:31]
	v_mfma_f32_16x16x32_bf16 v[12:15], v[132:135], v[218:221], v[12:15]
	v_mfma_f32_16x16x32_bf16 v[8:11], v[140:143], v[218:221], v[8:11]
	v_mfma_f32_16x16x32_bf16 v[24:27], v[140:143], v[198:201], v[24:27]
	v_mfma_f32_16x16x32_bf16 v[40:43], v[140:143], v[172:175], v[40:43]
	v_mfma_f32_16x16x32_bf16 v[56:59], v[140:143], v[164:167], v[56:59]
	s_setprio 0
	s_setprio 1
	v_mfma_f32_16x16x32_bf16 v[52:55], v[144:147], v[160:163], v[52:55]
	v_mfma_f32_16x16x32_bf16 v[36:39], v[144:147], v[168:171], v[36:39]
	v_mfma_f32_16x16x32_bf16 v[20:23], v[144:147], v[194:197], v[20:23]
	v_mfma_f32_16x16x32_bf16 v[4:7], v[144:147], v[214:217], v[4:7]
	v_mfma_f32_16x16x32_bf16 v[0:3], v[152:155], v[214:217], v[0:3]
	v_mfma_f32_16x16x32_bf16 v[16:19], v[152:155], v[194:197], v[16:19]
	v_mfma_f32_16x16x32_bf16 v[32:35], v[152:155], v[168:171], v[32:35]
	v_mfma_f32_16x16x32_bf16 v[48:51], v[152:155], v[160:163], v[48:51]
	v_mfma_f32_16x16x32_bf16 v[52:55], v[148:151], v[164:167], v[52:55]
	v_mfma_f32_16x16x32_bf16 v[36:39], v[148:151], v[172:175], v[36:39]
	v_mfma_f32_16x16x32_bf16 v[20:23], v[148:151], v[198:201], v[20:23]
	v_mfma_f32_16x16x32_bf16 v[4:7], v[148:151], v[218:221], v[4:7]
	v_mfma_f32_16x16x32_bf16 v[0:3], v[156:159], v[218:221], v[0:3]
	v_mfma_f32_16x16x32_bf16 v[16:19], v[156:159], v[198:201], v[16:19]
	v_mfma_f32_16x16x32_bf16 v[32:35], v[156:159], v[172:175], v[32:35]
	v_mfma_f32_16x16x32_bf16 v[48:51], v[156:159], v[164:167], v[48:51]
	s_setprio 0
	s_barrier
	s_add_u32 s54, s54, 0x100
	s_addc_u32 s55, s55, 0
	s_add_u32 s2, s2, 0x100
	s_addc_u32 s24, s24, 0
	s_cmp_ge_i32 s65, s33
	s_mov_b32 s25, s65
	s_cbranch_scc1 .Lpeelx_2
.LBB0_534:
	ds_read_b128 v[128:131], v209
	ds_read_b128 v[132:135], v209 offset:1024
	ds_read_b128 v[136:139], v209 offset:2048
	ds_read_b128 v[140:143], v209 offset:3072
	ds_read_b128 v[144:147], v210
	ds_read_b128 v[148:151], v210 offset:1024
	ds_read_b128 v[152:155], v210 offset:2048
	ds_read_b128 v[156:159], v210 offset:3072
	s_add_i32 s65, s25, 2
	s_add_u32 s56, s54, 0x80
	s_addc_u32 s57, s55, 0
	s_cmp_eq_u32 s34, s25
	s_cselect_b32 s57, s13, s57
	s_cselect_b32 s56, s12, s56
	s_cselect_b32 s67, s53, s24
	s_cselect_b32 s66, s52, s2
	v_lshl_add_u64 v[202:203], s[54:55], 0, v[186:187]
	s_add_i32 m0, s16, 0xc000
	ds_read_b128 v[160:163], v211
	ds_read_b128 v[164:167], v211 offset:1024
	ds_read_b128 v[168:171], v211 offset:2048
	ds_read_b128 v[172:175], v211 offset:3072
	ds_read_b128 v[194:197], v211 offset:4096
	ds_read_b128 v[198:201], v211 offset:5120
	ds_read_b128 v[214:217], v211 offset:6144
	ds_read_b128 v[218:221], v211 offset:7168
	global_load_lds_dwordx4 v[202:203], off
	v_lshl_add_u64 v[202:203], s[54:55], 0, v[188:189]
	s_add_i32 m0, s16, 0xe000
	s_nop 0
	global_load_lds_dwordx4 v[202:203], off
	s_waitcnt vmcnt(8)
	s_waitcnt lgkmcnt(0)
	s_barrier
; #define PG8_STAGE(bufoff, gbase, voff) do { _Pragma("unroll") for (int _i = 0; _i < 2; ++_i) \
;         __builtin_amdgcn_global_load_lds((const unsigned*)((const char*)(gbase) + (voff)[_i]), (PG8_LAS unsigned*)(lds + (bufoff) + ldsw + _i * 8192), 16, 0, 0); } while (0)
; #define PG8_LDA(dst, b, h) do { _Pragma("unroll") for (int m = 0; m < 4; ++m) _Pragma("unroll") for (int k = 0; k < 2; ++k) dst[m][k] = *(const PG8_LAS bf16x8*)(lds + PG8_SA(b, h) + aoff + m * 2048 + k * 1024); } while (0)
; #define PG8_LDB(dst, b, h) do { _Pragma("unroll") for (int n = 0; n < 2; ++n) _Pragma("unroll") for (int k = 0; k < 2; ++k) dst[n][k] = *(const PG8_LAS bf16x8*)(lds + PG8_SB(b, h) + boff + n * 2048 + k * 1024); } while (0)
; #define PG8_MMA(ai, bj, At, Bt) do { __builtin_amdgcn_s_setprio(1); _Pragma("unroll") for (int m = 0; m < 4; ++m) _Pragma("unroll") for (int n = 0; n < 2; ++n) _Pragma("unroll") for (int k = 0; k < 2; ++k) \
;         acc[ai][bj][m][n] = __builtin_amdgcn_mfma_f32_16x16x32_bf16(Bt[n][k], At[m][k], acc[ai][bj][m][n], 0, 0, 0); __builtin_amdgcn_s_setprio(0); } while (0)
; #define PG8_WAIT_V(n) asm volatile("s_waitcnt vmcnt(" #n ")" ::: "memory")
; #define PG8_WAIT_L(n) asm volatile("s_waitcnt lgkmcnt(" #n ")" ::: "memory")
; #define PG8_BAR __builtin_amdgcn_s_barrier()
; #define PG8_SCHED __builtin_amdgcn_sched_barrier(0)
; template <class Epi, class Sched, bool ALIGN_EPI = false, bool SP2 = false>
; __device__ __forceinline__ void gemm_phase(PG8_LAS unsigned char* lds, const Gemm g, const Sched& S, const Epi& E) {
;     ...
;             PG8_LDB(B0, 0, 0); PG8_LDB(B1, 0, 1); PG8_SCHED; PG8_LDA(At, 0, 0); PG8_STAGE(PG8_SA(1, 1), a1 + hstep, voffA);
;             PG8_WAIT_V(8); PG8_WAIT_L(0); PG8_BAR; PG8_MMA(0, 0, At, B0); PG8_MMA(0, 1, At, B1); PG8_BAR; PG8_SCHED;
;             PG8_LDA(At, 0, 1); PG8_STAGE(PG8_SB(0, 0), b2, voffB); PG8_STAGE(PG8_SB(0, 1), b2 + hstep, voffB); PG8_STAGE(PG8_SA(0, 0), a2, voffA);
;             PG8_WAIT_V(8); PG8_WAIT_L(0); PG8_BAR; PG8_MMA(1, 0, At, B0); PG8_MMA(1, 1, At, B1); PG8_BAR; PG8_SCHED;
	s_setprio 1
	s_waitcnt lgkmcnt(0)
	v_mfma_f32_16x16x32_bf16 v[124:127], v[128:131], v[160:163], v[124:127]
	v_mfma_f32_16x16x32_bf16 v[108:111], v[128:131], v[168:171], v[108:111]
	v_mfma_f32_16x16x32_bf16 v[92:95], v[128:131], v[194:197], v[92:95]
	v_mfma_f32_16x16x32_bf16 v[76:79], v[128:131], v[214:217], v[76:79]
	v_mfma_f32_16x16x32_bf16 v[72:75], v[136:139], v[214:217], v[72:75]
	v_mfma_f32_16x16x32_bf16 v[88:91], v[136:139], v[194:197], v[88:91]
	v_mfma_f32_16x16x32_bf16 v[104:107], v[136:139], v[168:171], v[104:107]
	v_mfma_f32_16x16x32_bf16 v[120:123], v[136:139], v[160:163], v[120:123]
	v_mfma_f32_16x16x32_bf16 v[124:127], v[132:135], v[164:167], v[124:127]
	v_mfma_f32_16x16x32_bf16 v[108:111], v[132:135], v[172:175], v[108:111]
	v_mfma_f32_16x16x32_bf16 v[92:95], v[132:135], v[198:201], v[92:95]
	v_mfma_f32_16x16x32_bf16 v[76:79], v[132:135], v[218:221], v[76:79]
	v_mfma_f32_16x16x32_bf16 v[72:75], v[140:143], v[218:221], v[72:75]
	v_mfma_f32_16x16x32_bf16 v[88:91], v[140:143], v[198:201], v[88:91]
	v_mfma_f32_16x16x32_bf16 v[104:107], v[140:143], v[172:175], v[104:107]
	v_mfma_f32_16x16x32_bf16 v[120:123], v[140:143], v[164:167], v[120:123]
	s_setprio 0
	s_setprio 1
	v_mfma_f32_16x16x32_bf16 v[116:119], v[144:147], v[160:163], v[116:119]
	v_mfma_f32_16x16x32_bf16 v[100:103], v[144:147], v[168:171], v[100:103]
	v_mfma_f32_16x16x32_bf16 v[84:87], v[144:147], v[194:197], v[84:87]
	v_mfma_f32_16x16x32_bf16 v[68:71], v[144:147], v[214:217], v[68:71]
	v_mfma_f32_16x16x32_bf16 v[64:67], v[152:155], v[214:217], v[64:67]
	v_mfma_f32_16x16x32_bf16 v[80:83], v[152:155], v[194:197], v[80:83]
	v_mfma_f32_16x16x32_bf16 v[96:99], v[152:155], v[168:171], v[96:99]
	v_mfma_f32_16x16x32_bf16 v[112:115], v[152:155], v[160:163], v[112:115]
	v_mfma_f32_16x16x32_bf16 v[116:119], v[148:151], v[164:167], v[116:119]
	v_mfma_f32_16x16x32_bf16 v[100:103], v[148:151], v[172:175], v[100:103]
	v_mfma_f32_16x16x32_bf16 v[84:87], v[148:151], v[198:201], v[84:87]
	v_mfma_f32_16x16x32_bf16 v[68:71], v[148:151], v[218:221], v[68:71]
	v_mfma_f32_16x16x32_bf16 v[64:67], v[156:159], v[218:221], v[64:67]
	v_mfma_f32_16x16x32_bf16 v[80:83], v[156:159], v[198:201], v[80:83]
	v_mfma_f32_16x16x32_bf16 v[96:99], v[156:159], v[172:175], v[96:99]
	v_mfma_f32_16x16x32_bf16 v[112:115], v[156:159], v[164:167], v[112:115]
	s_setprio 0
	s_barrier
	s_add_i32 s25, s3, s4
	v_lshl_add_u64 v[202:203], s[66:67], 0, v[180:181]
	s_mov_b32 m0, s25
	ds_read_b128 v[160:163], v211 offset:16384
	ds_read_b128 v[164:167], v211 offset:17408
	ds_read_b128 v[168:171], v211 offset:18432
	ds_read_b128 v[172:175], v211 offset:19456
	ds_read_b128 v[194:197], v211 offset:20480
	ds_read_b128 v[198:201], v211 offset:21504
	ds_read_b128 v[214:217], v211 offset:22528
	ds_read_b128 v[218:221], v211 offset:23552
	global_load_lds_dwordx4 v[202:203], off
	s_add_i32 m0, s25, 0x2000
	v_lshl_add_u64 v[222:223], s[66:67], 0, v[176:177]
	s_add_u32 s66, s66, s14
	s_addc_u32 s67, s67, s15
	s_add_i32 s25, s35, s4
	global_load_lds_dwordx4 v[222:223], off
	v_lshl_add_u64 v[224:225], s[66:67], 0, v[180:181]
	s_mov_b32 m0, s25
	v_lshl_add_u64 v[226:227], s[66:67], 0, v[176:177]
	global_load_lds_dwordx4 v[224:225], off
	s_add_i32 m0, s25, 0x2000
	v_lshl_add_u64 v[228:229], s[56:57], 0, v[182:183]
	global_load_lds_dwordx4 v[226:227], off
	s_mov_b32 m0, s16
	v_lshl_add_u64 v[230:231], s[56:57], 0, v[178:179]
	global_load_lds_dwordx4 v[228:229], off
	s_mov_b32 m0, s17
	s_nop 0
	global_load_lds_dwordx4 v[230:231], off
	s_waitcnt vmcnt(8)
	s_waitcnt lgkmcnt(0)
	s_barrier
	s_setprio 1
	s_waitcnt lgkmcnt(0)
	v_mfma_f32_16x16x32_bf16 v[60:63], v[128:131], v[160:163], v[60:63]
	v_mfma_f32_16x16x32_bf16 v[44:47], v[128:131], v[168:171], v[44:47]
	v_mfma_f32_16x16x32_bf16 v[28:31], v[128:131], v[194:197], v[28:31]
	v_mfma_f32_16x16x32_bf16 v[12:15], v[128:131], v[214:217], v[12:15]
	v_mfma_f32_16x16x32_bf16 v[8:11], v[136:139], v[214:217], v[8:11]
	v_mfma_f32_16x16x32_bf16 v[24:27], v[136:139], v[194:197], v[24:27]
	v_mfma_f32_16x16x32_bf16 v[40:43], v[136:139], v[168:171], v[40:43]
	v_mfma_f32_16x16x32_bf16 v[56:59], v[136:139], v[160:163], v[56:59]
	v_mfma_f32_16x16x32_bf16 v[60:63], v[132:135], v[164:167], v[60:63]
	v_mfma_f32_16x16x32_bf16 v[44:47], v[132:135], v[172:175], v[44:47]
	v_mfma_f32_16x16x32_bf16 v[28:31], v[132:135], v[198:201], v[28:31]
	v_mfma_f32_16x16x32_bf16 v[12:15], v[132:135], v[218:221], v[12:15]
	v_mfma_f32_16x16x32_bf16 v[8:11], v[140:143], v[218:221], v[8:11]
	v_mfma_f32_16x16x32_bf16 v[24:27], v[140:143], v[198:201], v[24:27]
	v_mfma_f32_16x16x32_bf16 v[40:43], v[140:143], v[172:175], v[40:43]
	v_mfma_f32_16x16x32_bf16 v[56:59], v[140:143], v[164:167], v[56:59]
	s_setprio 0
	s_setprio 1
	v_mfma_f32_16x16x32_bf16 v[52:55], v[144:147], v[160:163], v[52:55]
	v_mfma_f32_16x16x32_bf16 v[36:39], v[144:147], v[168:171], v[36:39]
	v_mfma_f32_16x16x32_bf16 v[20:23], v[144:147], v[194:197], v[20:23]
	v_mfma_f32_16x16x32_bf16 v[4:7], v[144:147], v[214:217], v[4:7]
	v_mfma_f32_16x16x32_bf16 v[0:3], v[152:155], v[214:217], v[0:3]
	v_mfma_f32_16x16x32_bf16 v[16:19], v[152:155], v[194:197], v[16:19]
	v_mfma_f32_16x16x32_bf16 v[32:35], v[152:155], v[168:171], v[32:35]
	v_mfma_f32_16x16x32_bf16 v[48:51], v[152:155], v[160:163], v[48:51]
	v_mfma_f32_16x16x32_bf16 v[52:55], v[148:151], v[164:167], v[52:55]
	v_mfma_f32_16x16x32_bf16 v[36:39], v[148:151], v[172:175], v[36:39]
	v_mfma_f32_16x16x32_bf16 v[20:23], v[148:151], v[198:201], v[20:23]
	v_mfma_f32_16x16x32_bf16 v[4:7], v[148:151], v[218:221], v[4:7]
	v_mfma_f32_16x16x32_bf16 v[0:3], v[156:159], v[218:221], v[0:3]
	v_mfma_f32_16x16x32_bf16 v[16:19], v[156:159], v[198:201], v[16:19]
	v_mfma_f32_16x16x32_bf16 v[32:35], v[156:159], v[172:175], v[32:35]
	v_mfma_f32_16x16x32_bf16 v[48:51], v[156:159], v[164:167], v[48:51]
	s_setprio 0
	s_barrier
; #define PG8_STAGE(bufoff, gbase, voff) do { _Pragma("unroll") for (int _i = 0; _i < 2; ++_i) \
;         __builtin_amdgcn_global_load_lds((const unsigned*)((const char*)(gbase) + (voff)[_i]), (PG8_LAS unsigned*)(lds + (bufoff) + ldsw + _i * 8192), 16, 0, 0); } while (0)
; #define PG8_LDA(dst, b, h) do { _Pragma("unroll") for (int m = 0; m < 4; ++m) _Pragma("unroll") for (int k = 0; k < 2; ++k) dst[m][k] = *(const PG8_LAS bf16x8*)(lds + PG8_SA(b, h) + aoff + m * 2048 + k * 1024); } while (0)
; #define PG8_LDB(dst, b, h) do { _Pragma("unroll") for (int n = 0; n < 2; ++n) _Pragma("unroll") for (int k = 0; k < 2; ++k) dst[n][k] = *(const PG8_LAS bf16x8*)(lds + PG8_SB(b, h) + boff + n * 2048 + k * 1024); } while (0)
; #define PG8_MMA(ai, bj, At, Bt) do { __builtin_amdgcn_s_setprio(1); _Pragma("unroll") for (int m = 0; m < 4; ++m) _Pragma("unroll") for (int n = 0; n < 2; ++n) _Pragma("unroll") for (int k = 0; k < 2; ++k) \
;         acc[ai][bj][m][n] = __builtin_amdgcn_mfma_f32_16x16x32_bf16(Bt[n][k], At[m][k], acc[ai][bj][m][n], 0, 0, 0); __builtin_amdgcn_s_setprio(0); } while (0)
; #define PG8_WAIT_V(n) asm volatile("s_waitcnt vmcnt(" #n ")" ::: "memory")
; #define PG8_WAIT_L(n) asm volatile("s_waitcnt lgkmcnt(" #n ")" ::: "memory")
; #define PG8_BAR __builtin_amdgcn_s_barrier()
; #define PG8_SCHED __builtin_amdgcn_sched_barrier(0)
; template <class Epi, class Sched, bool ALIGN_EPI = false, bool SP2 = false>
; __device__ __forceinline__ void gemm_phase(PG8_LAS unsigned char* lds, const Gemm g, const Sched& S, const Epi& E) {
;     ...
;             PG8_LDB(B0, 1, 0); PG8_LDB(B1, 1, 1); PG8_SCHED; PG8_LDA(At, 1, 0); PG8_STAGE(PG8_SA(0, 1), a2 + hstep, voffA);
;             PG8_WAIT_V(8); PG8_WAIT_L(0); PG8_BAR; PG8_MMA(0, 0, At, B0); PG8_MMA(0, 1, At, B1); PG8_BAR; PG8_SCHED;
	s_add_i32 s25, 0, 0x18000
	s_add_i32 s66, 0, 0x1c000
	v_add_u32_e32 v140, s25, v205
	v_add_u32_e32 v156, s66, v205
	ds_read_b128 v[128:131], v140
	ds_read_b128 v[132:135], v140 offset:1024
	ds_read_b128 v[136:139], v140 offset:2048
	ds_read_b128 v[140:143], v140 offset:3072
	ds_read_b128 v[144:147], v156
	ds_read_b128 v[148:151], v156 offset:1024
	ds_read_b128 v[152:155], v156 offset:2048
	ds_read_b128 v[156:159], v156 offset:3072
	s_add_u32 s56, s56, s14
	s_addc_u32 s57, s57, s15
	s_mov_b32 m0, s18
	v_lshl_add_u64 v[232:233], s[56:57], 0, v[182:183]
	ds_read_b128 v[160:163], v211 offset:32768
	ds_read_b128 v[164:167], v211 offset:33792
	ds_read_b128 v[168:171], v211 offset:34816
	ds_read_b128 v[172:175], v211 offset:35840
	ds_read_b128 v[194:197], v211 offset:36864
	ds_read_b128 v[198:201], v211 offset:37888
	ds_read_b128 v[214:217], v211 offset:38912
	ds_read_b128 v[218:221], v211 offset:39936
	global_load_lds_dwordx4 v[232:233], off
	v_lshl_add_u64 v[232:233], s[56:57], 0, v[178:179]
	s_mov_b32 m0, s19
	s_nop 0
	global_load_lds_dwordx4 v[232:233], off
	s_waitcnt vmcnt(8)
	s_waitcnt lgkmcnt(0)
	s_barrier
	s_setprio 1
	s_waitcnt lgkmcnt(0)
	v_mfma_f32_16x16x32_bf16 v[124:127], v[128:131], v[160:163], v[124:127]
	v_mfma_f32_16x16x32_bf16 v[108:111], v[128:131], v[168:171], v[108:111]
	v_mfma_f32_16x16x32_bf16 v[92:95], v[128:131], v[194:197], v[92:95]
	v_mfma_f32_16x16x32_bf16 v[76:79], v[128:131], v[214:217], v[76:79]
	v_mfma_f32_16x16x32_bf16 v[72:75], v[136:139], v[214:217], v[72:75]
	v_mfma_f32_16x16x32_bf16 v[88:91], v[136:139], v[194:197], v[88:91]
	v_mfma_f32_16x16x32_bf16 v[104:107], v[136:139], v[168:171], v[104:107]
	v_mfma_f32_16x16x32_bf16 v[120:123], v[136:139], v[160:163], v[120:123]
	v_mfma_f32_16x16x32_bf16 v[124:127], v[132:135], v[164:167], v[124:127]
	v_mfma_f32_16x16x32_bf16 v[108:111], v[132:135], v[172:175], v[108:111]
	v_mfma_f32_16x16x32_bf16 v[92:95], v[132:135], v[198:201], v[92:95]
	v_mfma_f32_16x16x32_bf16 v[76:79], v[132:135], v[218:221], v[76:79]
	v_mfma_f32_16x16x32_bf16 v[72:75], v[140:143], v[218:221], v[72:75]
	v_mfma_f32_16x16x32_bf16 v[88:91], v[140:143], v[198:201], v[88:91]
	v_mfma_f32_16x16x32_bf16 v[104:107], v[140:143], v[172:175], v[104:107]
	v_mfma_f32_16x16x32_bf16 v[120:123], v[140:143], v[164:167], v[120:123]
	s_setprio 0
	s_setprio 1
	v_mfma_f32_16x16x32_bf16 v[116:119], v[144:147], v[160:163], v[116:119]
	v_mfma_f32_16x16x32_bf16 v[100:103], v[144:147], v[168:171], v[100:103]
	v_mfma_f32_16x16x32_bf16 v[84:87], v[144:147], v[194:197], v[84:87]
	v_mfma_f32_16x16x32_bf16 v[68:71], v[144:147], v[214:217], v[68:71]
	v_mfma_f32_16x16x32_bf16 v[64:67], v[152:155], v[214:217], v[64:67]
	v_mfma_f32_16x16x32_bf16 v[80:83], v[152:155], v[194:197], v[80:83]
	v_mfma_f32_16x16x32_bf16 v[96:99], v[152:155], v[168:171], v[96:99]
	v_mfma_f32_16x16x32_bf16 v[112:115], v[152:155], v[160:163], v[112:115]
	v_mfma_f32_16x16x32_bf16 v[116:119], v[148:151], v[164:167], v[116:119]
	v_mfma_f32_16x16x32_bf16 v[100:103], v[148:151], v[172:175], v[100:103]
	v_mfma_f32_16x16x32_bf16 v[84:87], v[148:151], v[198:201], v[84:87]
	v_mfma_f32_16x16x32_bf16 v[68:71], v[148:151], v[218:221], v[68:71]
	v_mfma_f32_16x16x32_bf16 v[64:67], v[156:159], v[218:221], v[64:67]
	v_mfma_f32_16x16x32_bf16 v[80:83], v[156:159], v[198:201], v[80:83]
	v_mfma_f32_16x16x32_bf16 v[96:99], v[156:159], v[172:175], v[96:99]
	v_mfma_f32_16x16x32_bf16 v[112:115], v[156:159], v[164:167], v[112:115]
	s_setprio 0
	s_barrier
; #define PG8_STAGE(bufoff, gbase, voff) do { _Pragma("unroll") for (int _i = 0; _i < 2; ++_i) \
;         __builtin_amdgcn_global_load_lds((const unsigned*)((const char*)(gbase) + (voff)[_i]), (PG8_LAS unsigned*)(lds + (bufoff) + ldsw + _i * 8192), 16, 0, 0); } while (0)
; #define PG8_LDA(dst, b, h) do { _Pragma("unroll") for (int m = 0; m < 4; ++m) _Pragma("unroll") for (int k = 0; k < 2; ++k) dst[m][k] = *(const PG8_LAS bf16x8*)(lds + PG8_SA(b, h) + aoff + m * 2048 + k * 1024); } while (0)
; #define PG8_MMA(ai, bj, At, Bt) do { __builtin_amdgcn_s_setprio(1); _Pragma("unroll") for (int m = 0; m < 4; ++m) _Pragma("unroll") for (int n = 0; n < 2; ++n) _Pragma("unroll") for (int k = 0; k < 2; ++k) \
;         acc[ai][bj][m][n] = __builtin_amdgcn_mfma_f32_16x16x32_bf16(Bt[n][k], At[m][k], acc[ai][bj][m][n], 0, 0, 0); __builtin_amdgcn_s_setprio(0); } while (0)
; #define PG8_WAIT_V(n) asm volatile("s_waitcnt vmcnt(" #n ")" ::: "memory")
; #define PG8_WAIT_L(n) asm volatile("s_waitcnt lgkmcnt(" #n ")" ::: "memory")
; #define PG8_BAR __builtin_amdgcn_s_barrier()
; #define PG8_SCHED __builtin_amdgcn_sched_barrier(0)
; template <class Epi, class Sched, bool ALIGN_EPI = false, bool SP2 = false>
; __device__ __forceinline__ void gemm_phase(PG8_LAS unsigned char* lds, const Gemm g, const Sched& S, const Epi& E) {
;     ...
;             PG8_LDA(At, 1, 1); PG8_STAGE(PG8_SB(1, 0), b3, voffB); PG8_STAGE(PG8_SB(1, 1), b3 + hstep, voffB); PG8_STAGE(PG8_SA(1, 0), a3, voffA);
;             PG8_WAIT_V(8); PG8_WAIT_L(0); PG8_BAR; PG8_MMA(1, 0, At, B0); PG8_MMA(1, 1, At, B1); PG8_BAR; PG8_SCHED;
	s_add_i32 s25, s25, s4
	v_lshl_add_u64 v[202:203], v[202:203], 0, s[38:39]
	s_mov_b32 m0, s25
	ds_read_b128 v[160:163], v211 offset:49152
	ds_read_b128 v[164:167], v211 offset:50176
	ds_read_b128 v[168:171], v211 offset:51200
	ds_read_b128 v[172:175], v211 offset:52224
	ds_read_b128 v[194:197], v211 offset:53248
	ds_read_b128 v[198:201], v211 offset:54272
	ds_read_b128 v[214:217], v211 offset:55296
	ds_read_b128 v[218:221], v211 offset:56320
	global_load_lds_dwordx4 v[202:203], off
	v_lshl_add_u64 v[202:203], v[222:223], 0, s[38:39]
	s_add_i32 m0, s25, 0x2000
	s_add_i32 s25, s66, s4
	global_load_lds_dwordx4 v[202:203], off
	v_lshl_add_u64 v[202:203], v[224:225], 0, s[38:39]
	s_mov_b32 m0, s25
	s_nop 0
	global_load_lds_dwordx4 v[202:203], off
	v_lshl_add_u64 v[202:203], v[226:227], 0, s[38:39]
	s_add_i32 m0, s25, 0x2000
	s_nop 0
	global_load_lds_dwordx4 v[202:203], off
	v_lshl_add_u64 v[202:203], v[228:229], 0, s[38:39]
	s_mov_b32 m0, s26
	s_nop 0
	global_load_lds_dwordx4 v[202:203], off
	v_lshl_add_u64 v[202:203], v[230:231], 0, s[38:39]
	s_mov_b32 m0, s27
	s_nop 0
	global_load_lds_dwordx4 v[202:203], off
	s_waitcnt vmcnt(8)
	s_waitcnt lgkmcnt(0)
	s_barrier
	s_setprio 1
	s_waitcnt lgkmcnt(0)
	v_mfma_f32_16x16x32_bf16 v[60:63], v[128:131], v[160:163], v[60:63]
	v_mfma_f32_16x16x32_bf16 v[44:47], v[128:131], v[168:171], v[44:47]
	v_mfma_f32_16x16x32_bf16 v[28:31], v[128:131], v[194:197], v[28:31]
	v_mfma_f32_16x16x32_bf16 v[12:15], v[128:131], v[214:217], v[12:15]
	v_mfma_f32_16x16x32_bf16 v[8:11], v[136:139], v[214:217], v[8:11]
	v_mfma_f32_16x16x32_bf16 v[24:27], v[136:139], v[194:197], v[24:27]
	v_mfma_f32_16x16x32_bf16 v[40:43], v[136:139], v[168:171], v[40:43]
	v_mfma_f32_16x16x32_bf16 v[56:59], v[136:139], v[160:163], v[56:59]
	v_mfma_f32_16x16x32_bf16 v[60:63], v[132:135], v[164:167], v[60:63]
	v_mfma_f32_16x16x32_bf16 v[44:47], v[132:135], v[172:175], v[44:47]
	v_mfma_f32_16x16x32_bf16 v[28:31], v[132:135], v[198:201], v[28:31]
	v_mfma_f32_16x16x32_bf16 v[12:15], v[132:135], v[218:221], v[12:15]
	v_mfma_f32_16x16x32_bf16 v[8:11], v[140:143], v[218:221], v[8:11]
	v_mfma_f32_16x16x32_bf16 v[24:27], v[140:143], v[198:201], v[24:27]
	v_mfma_f32_16x16x32_bf16 v[40:43], v[140:143], v[172:175], v[40:43]
	v_mfma_f32_16x16x32_bf16 v[56:59], v[140:143], v[164:167], v[56:59]
	s_setprio 0
	s_setprio 1
	v_mfma_f32_16x16x32_bf16 v[52:55], v[144:147], v[160:163], v[52:55]
	v_mfma_f32_16x16x32_bf16 v[36:39], v[144:147], v[168:171], v[36:39]
	v_mfma_f32_16x16x32_bf16 v[20:23], v[144:147], v[194:197], v[20:23]
	v_mfma_f32_16x16x32_bf16 v[4:7], v[144:147], v[214:217], v[4:7]
	v_mfma_f32_16x16x32_bf16 v[0:3], v[152:155], v[214:217], v[0:3]
	v_mfma_f32_16x16x32_bf16 v[16:19], v[152:155], v[194:197], v[16:19]
	v_mfma_f32_16x16x32_bf16 v[32:35], v[152:155], v[168:171], v[32:35]
	v_mfma_f32_16x16x32_bf16 v[48:51], v[152:155], v[160:163], v[48:51]
	v_mfma_f32_16x16x32_bf16 v[52:55], v[148:151], v[164:167], v[52:55]
	v_mfma_f32_16x16x32_bf16 v[36:39], v[148:151], v[172:175], v[36:39]
	v_mfma_f32_16x16x32_bf16 v[20:23], v[148:151], v[198:201], v[20:23]
	v_mfma_f32_16x16x32_bf16 v[4:7], v[148:151], v[218:221], v[4:7]
	v_mfma_f32_16x16x32_bf16 v[0:3], v[156:159], v[218:221], v[0:3]
	v_mfma_f32_16x16x32_bf16 v[16:19], v[156:159], v[198:201], v[16:19]
	v_mfma_f32_16x16x32_bf16 v[32:35], v[156:159], v[172:175], v[32:35]
	v_mfma_f32_16x16x32_bf16 v[48:51], v[156:159], v[164:167], v[48:51]
	s_setprio 0
	s_barrier
	s_add_u32 s54, s54, 0x100
	s_addc_u32 s55, s55, 0
	s_add_u32 s2, s2, 0x100
	s_addc_u32 s24, s24, 0
	s_cmp_ge_i32 s65, s33
	s_mov_b32 s25, s65
	s_cbranch_scc0 .LBB0_534

; #define PG8_STAGE(bufoff, gbase, voff) do { _Pragma("unroll") for (int _i = 0; _i < 2; ++_i) \
;         __builtin_amdgcn_global_load_lds((const unsigned*)((const char*)(gbase) + (voff)[_i]), (PG8_LAS unsigned*)(lds + (bufoff) + ldsw + _i * 8192), 16, 0, 0); } while (0)
; #define PG8_LDA(dst, b, h) do { _Pragma("unroll") for (int m = 0; m < 4; ++m) _Pragma("unroll") for (int k = 0; k < 2; ++k) dst[m][k] = *(const PG8_LAS bf16x8*)(lds + PG8_SA(b, h) + aoff + m * 2048 + k * 1024); } while (0)
; #define PG8_LDB(dst, b, h) do { _Pragma("unroll") for (int n = 0; n < 2; ++n) _Pragma("unroll") for (int k = 0; k < 2; ++k) dst[n][k] = *(const PG8_LAS bf16x8*)(lds + PG8_SB(b, h) + boff + n * 2048 + k * 1024); } while (0)
; #define PG8_MMA(ai, bj, At, Bt) do { __builtin_amdgcn_s_setprio(1); _Pragma("unroll") for (int m = 0; m < 4; ++m) _Pragma("unroll") for (int n = 0; n < 2; ++n) _Pragma("unroll") for (int k = 0; k < 2; ++k) \
;         acc[ai][bj][m][n] = __builtin_amdgcn_mfma_f32_16x16x32_bf16(Bt[n][k], At[m][k], acc[ai][bj][m][n], 0, 0, 0); __builtin_amdgcn_s_setprio(0); } while (0)
; #define PG8_WAIT_V(n) asm volatile("s_waitcnt vmcnt(" #n ")" ::: "memory")
; #define PG8_WAIT_L(n) asm volatile("s_waitcnt lgkmcnt(" #n ")" ::: "memory")
; #define PG8_BAR __builtin_amdgcn_s_barrier()
; #define PG8_SCHED __builtin_amdgcn_sched_barrier(0)
; template <class Epi, class Sched, bool ALIGN_EPI = false, bool SP2 = false>
; __device__ __forceinline__ void gemm_phase(PG8_LAS unsigned char* lds, const Gemm g, const Sched& S, const Epi& E) {
;     ...
;             PG8_LDB(B0, 0, 0); PG8_LDB(B1, 0, 1); PG8_SCHED; PG8_LDA(At, 0, 0); PG8_STAGE(PG8_SA(1, 1), a1 + hstep, voffA);
;             PG8_WAIT_V(8); PG8_WAIT_L(0); PG8_BAR; PG8_MMA(0, 0, At, B0); PG8_MMA(0, 1, At, B1); PG8_BAR; PG8_SCHED;
;             PG8_LDA(At, 0, 1); PG8_STAGE(PG8_SB(0, 0), b2, voffB); PG8_STAGE(PG8_SB(0, 1), b2 + hstep, voffB); PG8_STAGE(PG8_SA(0, 0), a2, voffA);
;             PG8_WAIT_V(8); PG8_WAIT_L(0); PG8_BAR; PG8_MMA(1, 0, At, B0); PG8_MMA(1, 1, At, B1); PG8_BAR; PG8_SCHED;
.LBB0_1220:
	s_and_b64 vcc, exec, s[10:11]
	s_cbranch_vccnz .Lcoldz_3
	s_add_u32 s56, s56, 0x80
	s_addc_u32 s57, s57, 0
	s_add_u32 s2, s58, 0x100
	s_addc_u32 s24, s59, 0
	s_mov_b32 s25, 0
	ds_read_b128 v[120:123], v246
	ds_read_b128 v[132:135], v246 offset:1024
	ds_read_b128 v[136:139], v246 offset:2048
	ds_read_b128 v[140:143], v246 offset:3072
	ds_read_b128 v[144:147], v247
	ds_read_b128 v[148:151], v247 offset:1024
	ds_read_b128 v[152:155], v247 offset:2048
	ds_read_b128 v[156:159], v247 offset:3072
	s_add_i32 s39, s25, 2
	s_add_u32 s46, s56, 0x80
	s_addc_u32 s58, s57, 0
	s_cmp_eq_u32 s31, s25
	s_cselect_b32 s59, s15, s58
	s_cselect_b32 s58, s14, s46
	s_cselect_b32 s61, s55, s24
	s_cselect_b32 s60, s54, s2
	v_lshl_add_u64 v[206:207], s[56:57], 0, v[200:201]
	s_add_i32 m0, s7, 0xc000
	ds_read_b128 v[160:163], v248
	ds_read_b128 v[164:167], v248 offset:1024
	ds_read_b128 v[168:171], v248 offset:2048
	ds_read_b128 v[172:175], v248 offset:3072
	ds_read_b128 v[176:179], v248 offset:4096
	ds_read_b128 v[180:183], v248 offset:5120
	ds_read_b128 v[184:187], v248 offset:6144
	ds_read_b128 v[188:191], v248 offset:7168
	global_load_lds_dwordx4 v[206:207], off
	v_lshl_add_u64 v[206:207], s[56:57], 0, v[202:203]
	s_add_i32 m0, s7, 0xe000
	s_nop 0
	global_load_lds_dwordx4 v[206:207], off
	s_waitcnt vmcnt(8)
	s_waitcnt lgkmcnt(0)
	s_barrier
	s_setprio 1
	s_waitcnt lgkmcnt(0)
	v_mfma_f32_16x16x32_bf16 v[128:131], v[120:123], v[160:163], 0
	v_mfma_f32_16x16x32_bf16 v[124:127], v[136:139], v[160:163], 0
	v_mfma_f32_16x16x32_bf16 v[108:111], v[120:123], v[168:171], 0
	v_mfma_f32_16x16x32_bf16 v[104:107], v[136:139], v[168:171], 0
	v_mfma_f32_16x16x32_bf16 v[92:95], v[120:123], v[176:179], 0
	v_mfma_f32_16x16x32_bf16 v[88:91], v[136:139], v[176:179], 0
	v_mfma_f32_16x16x32_bf16 v[76:79], v[120:123], v[184:187], 0
	v_mfma_f32_16x16x32_bf16 v[72:75], v[136:139], v[184:187], 0
	v_mfma_f32_16x16x32_bf16 v[128:131], v[132:135], v[164:167], v[128:131]
	v_mfma_f32_16x16x32_bf16 v[108:111], v[132:135], v[172:175], v[108:111]
	v_mfma_f32_16x16x32_bf16 v[92:95], v[132:135], v[180:183], v[92:95]
	v_mfma_f32_16x16x32_bf16 v[76:79], v[132:135], v[188:191], v[76:79]
	v_mfma_f32_16x16x32_bf16 v[72:75], v[140:143], v[188:191], v[72:75]
	v_mfma_f32_16x16x32_bf16 v[88:91], v[140:143], v[180:183], v[88:91]
	v_mfma_f32_16x16x32_bf16 v[104:107], v[140:143], v[172:175], v[104:107]
	v_mfma_f32_16x16x32_bf16 v[124:127], v[140:143], v[164:167], v[124:127]
	s_setprio 0
	s_setprio 1
	v_mfma_f32_16x16x32_bf16 v[116:119], v[144:147], v[160:163], 0
	v_mfma_f32_16x16x32_bf16 v[112:115], v[152:155], v[160:163], 0
	v_mfma_f32_16x16x32_bf16 v[100:103], v[144:147], v[168:171], 0
	v_mfma_f32_16x16x32_bf16 v[96:99], v[152:155], v[168:171], 0
	v_mfma_f32_16x16x32_bf16 v[84:87], v[144:147], v[176:179], 0
	v_mfma_f32_16x16x32_bf16 v[80:83], v[152:155], v[176:179], 0
	v_mfma_f32_16x16x32_bf16 v[68:71], v[144:147], v[184:187], 0
	v_mfma_f32_16x16x32_bf16 v[64:67], v[152:155], v[184:187], 0
	v_mfma_f32_16x16x32_bf16 v[116:119], v[148:151], v[164:167], v[116:119]
	v_mfma_f32_16x16x32_bf16 v[100:103], v[148:151], v[172:175], v[100:103]
	v_mfma_f32_16x16x32_bf16 v[84:87], v[148:151], v[180:183], v[84:87]
	v_mfma_f32_16x16x32_bf16 v[68:71], v[148:151], v[188:191], v[68:71]
	v_mfma_f32_16x16x32_bf16 v[64:67], v[156:159], v[188:191], v[64:67]
	v_mfma_f32_16x16x32_bf16 v[80:83], v[156:159], v[180:183], v[80:83]
	v_mfma_f32_16x16x32_bf16 v[96:99], v[156:159], v[172:175], v[96:99]
	v_mfma_f32_16x16x32_bf16 v[112:115], v[156:159], v[164:167], v[112:115]
	s_setprio 0
	s_barrier
	s_add_i32 s25, s33, s6
	v_lshl_add_u64 v[206:207], s[60:61], 0, v[194:195]
	s_mov_b32 m0, s25
	ds_read_b128 v[160:163], v248 offset:16384
	ds_read_b128 v[164:167], v248 offset:17408
	ds_read_b128 v[168:171], v248 offset:18432
	ds_read_b128 v[172:175], v248 offset:19456
	ds_read_b128 v[176:179], v248 offset:20480
	ds_read_b128 v[180:183], v248 offset:21504
	ds_read_b128 v[184:187], v248 offset:22528
	ds_read_b128 v[188:191], v248 offset:23552
	global_load_lds_dwordx4 v[206:207], off
	s_add_i32 m0, s25, 0x2000
	v_lshl_add_u64 v[208:209], s[60:61], 0, v[198:199]
	s_add_u32 s60, s60, s42
	s_addc_u32 s61, s61, s43
	s_add_i32 s25, s34, s6
	global_load_lds_dwordx4 v[208:209], off
	v_lshl_add_u64 v[210:211], s[60:61], 0, v[194:195]
	s_mov_b32 m0, s25
	v_lshl_add_u64 v[212:213], s[60:61], 0, v[198:199]
	global_load_lds_dwordx4 v[210:211], off
	s_add_i32 m0, s25, 0x2000
	v_lshl_add_u64 v[214:215], s[58:59], 0, v[192:193]
	global_load_lds_dwordx4 v[212:213], off
	s_mov_b32 m0, s7
	v_lshl_add_u64 v[216:217], s[58:59], 0, v[196:197]
	global_load_lds_dwordx4 v[214:215], off
	s_mov_b32 m0, s16
	s_nop 0
	global_load_lds_dwordx4 v[216:217], off
	s_waitcnt vmcnt(8)
	s_waitcnt lgkmcnt(0)
	s_barrier
; #define PG8_STAGE(bufoff, gbase, voff) do { _Pragma("unroll") for (int _i = 0; _i < 2; ++_i) \
;         __builtin_amdgcn_global_load_lds((const unsigned*)((const char*)(gbase) + (voff)[_i]), (PG8_LAS unsigned*)(lds + (bufoff) + ldsw + _i * 8192), 16, 0, 0); } while (0)
; #define PG8_LDA(dst, b, h) do { _Pragma("unroll") for (int m = 0; m < 4; ++m) _Pragma("unroll") for (int k = 0; k < 2; ++k) dst[m][k] = *(const PG8_LAS bf16x8*)(lds + PG8_SA(b, h) + aoff + m * 2048 + k * 1024); } while (0)
; #define PG8_LDB(dst, b, h) do { _Pragma("unroll") for (int n = 0; n < 2; ++n) _Pragma("unroll") for (int k = 0; k < 2; ++k) dst[n][k] = *(const PG8_LAS bf16x8*)(lds + PG8_SB(b, h) + boff + n * 2048 + k * 1024); } while (0)
; #define PG8_MMA(ai, bj, At, Bt) do { __builtin_amdgcn_s_setprio(1); _Pragma("unroll") for (int m = 0; m < 4; ++m) _Pragma("unroll") for (int n = 0; n < 2; ++n) _Pragma("unroll") for (int k = 0; k < 2; ++k) \
;         acc[ai][bj][m][n] = __builtin_amdgcn_mfma_f32_16x16x32_bf16(Bt[n][k], At[m][k], acc[ai][bj][m][n], 0, 0, 0); __builtin_amdgcn_s_setprio(0); } while (0)
; #define PG8_WAIT_V(n) asm volatile("s_waitcnt vmcnt(" #n ")" ::: "memory")
; #define PG8_WAIT_L(n) asm volatile("s_waitcnt lgkmcnt(" #n ")" ::: "memory")
; #define PG8_BAR __builtin_amdgcn_s_barrier()
; #define PG8_SCHED __builtin_amdgcn_sched_barrier(0)
; template <class Epi, class Sched, bool ALIGN_EPI = false, bool SP2 = false>
; __device__ __forceinline__ void gemm_phase(PG8_LAS unsigned char* lds, const Gemm g, const Sched& S, const Epi& E) {
;     ...
;             PG8_WAIT_V(8); PG8_WAIT_L(0); PG8_BAR; PG8_MMA(1, 0, At, B0); PG8_MMA(1, 1, At, B1); PG8_BAR; PG8_SCHED;
;             PG8_LDB(B0, 1, 0); PG8_LDB(B1, 1, 1); PG8_SCHED; PG8_LDA(At, 1, 0); PG8_STAGE(PG8_SA(0, 1), a2 + hstep, voffA);
;             PG8_WAIT_V(8); PG8_WAIT_L(0); PG8_BAR; PG8_MMA(0, 0, At, B0); PG8_MMA(0, 1, At, B1); PG8_BAR; PG8_SCHED;
	s_setprio 1
	s_waitcnt lgkmcnt(0)
	v_mfma_f32_16x16x32_bf16 v[60:63], v[120:123], v[160:163], 0
	v_mfma_f32_16x16x32_bf16 v[56:59], v[136:139], v[160:163], 0
	v_mfma_f32_16x16x32_bf16 v[44:47], v[120:123], v[168:171], 0
	v_mfma_f32_16x16x32_bf16 v[40:43], v[136:139], v[168:171], 0
	v_mfma_f32_16x16x32_bf16 v[28:31], v[120:123], v[176:179], 0
	v_mfma_f32_16x16x32_bf16 v[24:27], v[136:139], v[176:179], 0
	v_mfma_f32_16x16x32_bf16 v[12:15], v[120:123], v[184:187], 0
	v_mfma_f32_16x16x32_bf16 v[8:11], v[136:139], v[184:187], 0
	v_mfma_f32_16x16x32_bf16 v[60:63], v[132:135], v[164:167], v[60:63]
	v_mfma_f32_16x16x32_bf16 v[44:47], v[132:135], v[172:175], v[44:47]
	v_mfma_f32_16x16x32_bf16 v[28:31], v[132:135], v[180:183], v[28:31]
	v_mfma_f32_16x16x32_bf16 v[12:15], v[132:135], v[188:191], v[12:15]
	v_mfma_f32_16x16x32_bf16 v[8:11], v[140:143], v[188:191], v[8:11]
	v_mfma_f32_16x16x32_bf16 v[24:27], v[140:143], v[180:183], v[24:27]
	v_mfma_f32_16x16x32_bf16 v[40:43], v[140:143], v[172:175], v[40:43]
	v_mfma_f32_16x16x32_bf16 v[56:59], v[140:143], v[164:167], v[56:59]
	s_setprio 0
	s_setprio 1
	v_mfma_f32_16x16x32_bf16 v[52:55], v[144:147], v[160:163], 0
	v_mfma_f32_16x16x32_bf16 v[48:51], v[152:155], v[160:163], 0
	v_mfma_f32_16x16x32_bf16 v[36:39], v[144:147], v[168:171], 0
	v_mfma_f32_16x16x32_bf16 v[32:35], v[152:155], v[168:171], 0
	v_mfma_f32_16x16x32_bf16 v[20:23], v[144:147], v[176:179], 0
	v_mfma_f32_16x16x32_bf16 v[16:19], v[152:155], v[176:179], 0
	v_mfma_f32_16x16x32_bf16 v[4:7], v[144:147], v[184:187], 0
	v_mfma_f32_16x16x32_bf16 v[0:3], v[152:155], v[184:187], 0
	v_mfma_f32_16x16x32_bf16 v[52:55], v[148:151], v[164:167], v[52:55]
	v_mfma_f32_16x16x32_bf16 v[36:39], v[148:151], v[172:175], v[36:39]
	v_mfma_f32_16x16x32_bf16 v[20:23], v[148:151], v[180:183], v[20:23]
	v_mfma_f32_16x16x32_bf16 v[4:7], v[148:151], v[188:191], v[4:7]
	v_mfma_f32_16x16x32_bf16 v[0:3], v[156:159], v[188:191], v[0:3]
	v_mfma_f32_16x16x32_bf16 v[16:19], v[156:159], v[180:183], v[16:19]
	v_mfma_f32_16x16x32_bf16 v[32:35], v[156:159], v[172:175], v[32:35]
	v_mfma_f32_16x16x32_bf16 v[48:51], v[156:159], v[164:167], v[48:51]
	s_setprio 0
	s_barrier
	s_add_i32 s25, 0, 0x18000
	s_add_i32 s46, 0, 0x1c000
	v_add_u32_e32 v140, s25, v244
	v_add_u32_e32 v156, s46, v244
	ds_read_b128 v[120:123], v140
	ds_read_b128 v[132:135], v140 offset:1024
	ds_read_b128 v[136:139], v140 offset:2048
	ds_read_b128 v[140:143], v140 offset:3072
	ds_read_b128 v[144:147], v156
	ds_read_b128 v[148:151], v156 offset:1024
	ds_read_b128 v[152:155], v156 offset:2048
	ds_read_b128 v[156:159], v156 offset:3072
	s_add_u32 s58, s58, s42
	s_addc_u32 s59, s59, s43
	s_mov_b32 m0, s17
	v_lshl_add_u64 v[218:219], s[58:59], 0, v[192:193]
	ds_read_b128 v[160:163], v248 offset:32768
	ds_read_b128 v[164:167], v248 offset:33792
	ds_read_b128 v[168:171], v248 offset:34816
	ds_read_b128 v[172:175], v248 offset:35840
	ds_read_b128 v[176:179], v248 offset:36864
	ds_read_b128 v[180:183], v248 offset:37888
	ds_read_b128 v[184:187], v248 offset:38912
	ds_read_b128 v[188:191], v248 offset:39936
	global_load_lds_dwordx4 v[218:219], off
	v_lshl_add_u64 v[218:219], s[58:59], 0, v[196:197]
	s_mov_b32 m0, s18
	s_nop 0
	global_load_lds_dwordx4 v[218:219], off
	s_waitcnt vmcnt(8)
	s_waitcnt lgkmcnt(0)
	s_barrier
	s_setprio 1
	s_waitcnt lgkmcnt(0)
	v_mfma_f32_16x16x32_bf16 v[128:131], v[120:123], v[160:163], v[128:131]
	v_mfma_f32_16x16x32_bf16 v[108:111], v[120:123], v[168:171], v[108:111]
	v_mfma_f32_16x16x32_bf16 v[92:95], v[120:123], v[176:179], v[92:95]
	v_mfma_f32_16x16x32_bf16 v[76:79], v[120:123], v[184:187], v[76:79]
	v_mfma_f32_16x16x32_bf16 v[72:75], v[136:139], v[184:187], v[72:75]
	v_mfma_f32_16x16x32_bf16 v[88:91], v[136:139], v[176:179], v[88:91]
	v_mfma_f32_16x16x32_bf16 v[104:107], v[136:139], v[168:171], v[104:107]
	v_mfma_f32_16x16x32_bf16 v[124:127], v[136:139], v[160:163], v[124:127]
	v_mfma_f32_16x16x32_bf16 v[128:131], v[132:135], v[164:167], v[128:131]
	v_mfma_f32_16x16x32_bf16 v[108:111], v[132:135], v[172:175], v[108:111]
	v_mfma_f32_16x16x32_bf16 v[92:95], v[132:135], v[180:183], v[92:95]
	v_mfma_f32_16x16x32_bf16 v[76:79], v[132:135], v[188:191], v[76:79]
	v_mfma_f32_16x16x32_bf16 v[72:75], v[140:143], v[188:191], v[72:75]
	v_mfma_f32_16x16x32_bf16 v[88:91], v[140:143], v[180:183], v[88:91]
	v_mfma_f32_16x16x32_bf16 v[104:107], v[140:143], v[172:175], v[104:107]
	v_mfma_f32_16x16x32_bf16 v[124:127], v[140:143], v[164:167], v[124:127]
	s_setprio 0
	s_setprio 1
	v_mfma_f32_16x16x32_bf16 v[116:119], v[144:147], v[160:163], v[116:119]
	v_mfma_f32_16x16x32_bf16 v[100:103], v[144:147], v[168:171], v[100:103]
	v_mfma_f32_16x16x32_bf16 v[84:87], v[144:147], v[176:179], v[84:87]
	v_mfma_f32_16x16x32_bf16 v[68:71], v[144:147], v[184:187], v[68:71]
	v_mfma_f32_16x16x32_bf16 v[64:67], v[152:155], v[184:187], v[64:67]
	v_mfma_f32_16x16x32_bf16 v[80:83], v[152:155], v[176:179], v[80:83]
	v_mfma_f32_16x16x32_bf16 v[96:99], v[152:155], v[168:171], v[96:99]
	v_mfma_f32_16x16x32_bf16 v[112:115], v[152:155], v[160:163], v[112:115]
	v_mfma_f32_16x16x32_bf16 v[116:119], v[148:151], v[164:167], v[116:119]
	v_mfma_f32_16x16x32_bf16 v[100:103], v[148:151], v[172:175], v[100:103]
	v_mfma_f32_16x16x32_bf16 v[84:87], v[148:151], v[180:183], v[84:87]
	v_mfma_f32_16x16x32_bf16 v[68:71], v[148:151], v[188:191], v[68:71]
	v_mfma_f32_16x16x32_bf16 v[64:67], v[156:159], v[188:191], v[64:67]
	v_mfma_f32_16x16x32_bf16 v[80:83], v[156:159], v[180:183], v[80:83]
	v_mfma_f32_16x16x32_bf16 v[96:99], v[156:159], v[172:175], v[96:99]
	v_mfma_f32_16x16x32_bf16 v[112:115], v[156:159], v[164:167], v[112:115]
	s_setprio 0
	s_barrier
; #define PG8_STAGE(bufoff, gbase, voff) do { _Pragma("unroll") for (int _i = 0; _i < 2; ++_i) \
;         __builtin_amdgcn_global_load_lds((const unsigned*)((const char*)(gbase) + (voff)[_i]), (PG8_LAS unsigned*)(lds + (bufoff) + ldsw + _i * 8192), 16, 0, 0); } while (0)
; #define PG8_LDA(dst, b, h) do { _Pragma("unroll") for (int m = 0; m < 4; ++m) _Pragma("unroll") for (int k = 0; k < 2; ++k) dst[m][k] = *(const PG8_LAS bf16x8*)(lds + PG8_SA(b, h) + aoff + m * 2048 + k * 1024); } while (0)
; #define PG8_LDB(dst, b, h) do { _Pragma("unroll") for (int n = 0; n < 2; ++n) _Pragma("unroll") for (int k = 0; k < 2; ++k) dst[n][k] = *(const PG8_LAS bf16x8*)(lds + PG8_SB(b, h) + boff + n * 2048 + k * 1024); } while (0)
; #define PG8_MMA(ai, bj, At, Bt) do { __builtin_amdgcn_s_setprio(1); _Pragma("unroll") for (int m = 0; m < 4; ++m) _Pragma("unroll") for (int n = 0; n < 2; ++n) _Pragma("unroll") for (int k = 0; k < 2; ++k) \
;         acc[ai][bj][m][n] = __builtin_amdgcn_mfma_f32_16x16x32_bf16(Bt[n][k], At[m][k], acc[ai][bj][m][n], 0, 0, 0); __builtin_amdgcn_s_setprio(0); } while (0)
; #define PG8_WAIT_V(n) asm volatile("s_waitcnt vmcnt(" #n ")" ::: "memory")
; #define PG8_WAIT_L(n) asm volatile("s_waitcnt lgkmcnt(" #n ")" ::: "memory")
; #define PG8_BAR __builtin_amdgcn_s_barrier()
; #define PG8_SCHED __builtin_amdgcn_sched_barrier(0)
; template <class Epi, class Sched, bool ALIGN_EPI = false, bool SP2 = false>
; __device__ __forceinline__ void gemm_phase(PG8_LAS unsigned char* lds, const Gemm g, const Sched& S, const Epi& E) {
;     ...
;             PG8_LDB(B0, 0, 0); PG8_LDB(B1, 0, 1); PG8_SCHED; PG8_LDA(At, 0, 0); PG8_STAGE(PG8_SA(1, 1), a1 + hstep, voffA);
;             PG8_WAIT_V(8); PG8_WAIT_L(0); PG8_BAR; PG8_MMA(0, 0, At, B0); PG8_MMA(0, 1, At, B1); PG8_BAR; PG8_SCHED;
;     ...
;             PG8_LDA(At, 1, 1); PG8_STAGE(PG8_SB(1, 0), b3, voffB); PG8_STAGE(PG8_SB(1, 1), b3 + hstep, voffB); PG8_STAGE(PG8_SA(1, 0), a3, voffA);
;             PG8_WAIT_V(8); PG8_WAIT_L(0); PG8_BAR; PG8_MMA(1, 0, At, B0); PG8_MMA(1, 1, At, B1); PG8_BAR; PG8_SCHED;
	s_add_i32 s25, s25, s6
	v_lshl_add_u64 v[206:207], v[206:207], 0, s[50:51]
	s_mov_b32 m0, s25
	ds_read_b128 v[160:163], v248 offset:49152
	ds_read_b128 v[164:167], v248 offset:50176
	ds_read_b128 v[168:171], v248 offset:51200
	ds_read_b128 v[172:175], v248 offset:52224
	ds_read_b128 v[176:179], v248 offset:53248
	ds_read_b128 v[180:183], v248 offset:54272
	ds_read_b128 v[184:187], v248 offset:55296
	ds_read_b128 v[188:191], v248 offset:56320
	global_load_lds_dwordx4 v[206:207], off
	v_lshl_add_u64 v[206:207], v[208:209], 0, s[50:51]
	s_add_i32 m0, s25, 0x2000
	s_add_i32 s25, s46, s6
	global_load_lds_dwordx4 v[206:207], off
	v_lshl_add_u64 v[206:207], v[210:211], 0, s[50:51]
	s_mov_b32 m0, s25
	s_nop 0
	global_load_lds_dwordx4 v[206:207], off
	v_lshl_add_u64 v[206:207], v[212:213], 0, s[50:51]
	s_add_i32 m0, s25, 0x2000
	s_nop 0
	global_load_lds_dwordx4 v[206:207], off
	v_lshl_add_u64 v[206:207], v[214:215], 0, s[50:51]
	s_mov_b32 m0, s19
	s_nop 0
	global_load_lds_dwordx4 v[206:207], off
	v_lshl_add_u64 v[206:207], v[216:217], 0, s[50:51]
	s_mov_b32 m0, s26
	s_nop 0
	global_load_lds_dwordx4 v[206:207], off
	s_waitcnt vmcnt(8)
	s_waitcnt lgkmcnt(0)
	s_barrier
	s_setprio 1
	s_waitcnt lgkmcnt(0)
	v_mfma_f32_16x16x32_bf16 v[60:63], v[120:123], v[160:163], v[60:63]
	v_mfma_f32_16x16x32_bf16 v[44:47], v[120:123], v[168:171], v[44:47]
	v_mfma_f32_16x16x32_bf16 v[28:31], v[120:123], v[176:179], v[28:31]
	v_mfma_f32_16x16x32_bf16 v[12:15], v[120:123], v[184:187], v[12:15]
	v_mfma_f32_16x16x32_bf16 v[8:11], v[136:139], v[184:187], v[8:11]
	v_mfma_f32_16x16x32_bf16 v[24:27], v[136:139], v[176:179], v[24:27]
	v_mfma_f32_16x16x32_bf16 v[40:43], v[136:139], v[168:171], v[40:43]
	v_mfma_f32_16x16x32_bf16 v[56:59], v[136:139], v[160:163], v[56:59]
	v_mfma_f32_16x16x32_bf16 v[60:63], v[132:135], v[164:167], v[60:63]
	v_mfma_f32_16x16x32_bf16 v[44:47], v[132:135], v[172:175], v[44:47]
	v_mfma_f32_16x16x32_bf16 v[28:31], v[132:135], v[180:183], v[28:31]
	v_mfma_f32_16x16x32_bf16 v[12:15], v[132:135], v[188:191], v[12:15]
	v_mfma_f32_16x16x32_bf16 v[8:11], v[140:143], v[188:191], v[8:11]
	v_mfma_f32_16x16x32_bf16 v[24:27], v[140:143], v[180:183], v[24:27]
	v_mfma_f32_16x16x32_bf16 v[40:43], v[140:143], v[172:175], v[40:43]
	v_mfma_f32_16x16x32_bf16 v[56:59], v[140:143], v[164:167], v[56:59]
	s_setprio 0
	s_setprio 1
	v_mfma_f32_16x16x32_bf16 v[52:55], v[144:147], v[160:163], v[52:55]
	v_mfma_f32_16x16x32_bf16 v[36:39], v[144:147], v[168:171], v[36:39]
	v_mfma_f32_16x16x32_bf16 v[20:23], v[144:147], v[176:179], v[20:23]
	v_mfma_f32_16x16x32_bf16 v[4:7], v[144:147], v[184:187], v[4:7]
	v_mfma_f32_16x16x32_bf16 v[0:3], v[152:155], v[184:187], v[0:3]
	v_mfma_f32_16x16x32_bf16 v[16:19], v[152:155], v[176:179], v[16:19]
	v_mfma_f32_16x16x32_bf16 v[32:35], v[152:155], v[168:171], v[32:35]
	v_mfma_f32_16x16x32_bf16 v[48:51], v[152:155], v[160:163], v[48:51]
	v_mfma_f32_16x16x32_bf16 v[52:55], v[148:151], v[164:167], v[52:55]
	v_mfma_f32_16x16x32_bf16 v[36:39], v[148:151], v[172:175], v[36:39]
	v_mfma_f32_16x16x32_bf16 v[20:23], v[148:151], v[180:183], v[20:23]
	v_mfma_f32_16x16x32_bf16 v[4:7], v[148:151], v[188:191], v[4:7]
	v_mfma_f32_16x16x32_bf16 v[0:3], v[156:159], v[188:191], v[0:3]
	v_mfma_f32_16x16x32_bf16 v[16:19], v[156:159], v[180:183], v[16:19]
	v_mfma_f32_16x16x32_bf16 v[32:35], v[156:159], v[172:175], v[32:35]
	v_mfma_f32_16x16x32_bf16 v[48:51], v[156:159], v[164:167], v[48:51]
	s_setprio 0
	s_barrier
	s_add_u32 s56, s56, 0x100
	s_addc_u32 s57, s57, 0
	s_add_u32 s2, s2, 0x100
	s_addc_u32 s24, s24, 0
	s_cmp_ge_i32 s39, s30
	s_mov_b32 s25, s39
	s_cbranch_scc1 .Lpeelx_3
.LBB0_1222:
	ds_read_b128 v[120:123], v246
	ds_read_b128 v[132:135], v246 offset:1024
	ds_read_b128 v[136:139], v246 offset:2048
	ds_read_b128 v[140:143], v246 offset:3072
	ds_read_b128 v[144:147], v247
	ds_read_b128 v[148:151], v247 offset:1024
	ds_read_b128 v[152:155], v247 offset:2048
	ds_read_b128 v[156:159], v247 offset:3072
	s_add_i32 s39, s25, 2
	s_add_u32 s46, s56, 0x80
	s_addc_u32 s58, s57, 0
	s_cmp_eq_u32 s31, s25
	s_cselect_b32 s59, s15, s58
	s_cselect_b32 s58, s14, s46
	s_cselect_b32 s61, s55, s24
	s_cselect_b32 s60, s54, s2
	v_lshl_add_u64 v[206:207], s[56:57], 0, v[200:201]
	s_add_i32 m0, s7, 0xc000
	ds_read_b128 v[160:163], v248
	ds_read_b128 v[164:167], v248 offset:1024
	ds_read_b128 v[168:171], v248 offset:2048
	ds_read_b128 v[172:175], v248 offset:3072
	ds_read_b128 v[176:179], v248 offset:4096
	ds_read_b128 v[180:183], v248 offset:5120
	ds_read_b128 v[184:187], v248 offset:6144
	ds_read_b128 v[188:191], v248 offset:7168
	global_load_lds_dwordx4 v[206:207], off
	v_lshl_add_u64 v[206:207], s[56:57], 0, v[202:203]
	s_add_i32 m0, s7, 0xe000
	s_nop 0
	global_load_lds_dwordx4 v[206:207], off
	s_waitcnt vmcnt(8)
	s_waitcnt lgkmcnt(0)
	s_barrier
; #define PG8_STAGE(bufoff, gbase, voff) do { _Pragma("unroll") for (int _i = 0; _i < 2; ++_i) \
;         __builtin_amdgcn_global_load_lds((const unsigned*)((const char*)(gbase) + (voff)[_i]), (PG8_LAS unsigned*)(lds + (bufoff) + ldsw + _i * 8192), 16, 0, 0); } while (0)
; #define PG8_LDA(dst, b, h) do { _Pragma("unroll") for (int m = 0; m < 4; ++m) _Pragma("unroll") for (int k = 0; k < 2; ++k) dst[m][k] = *(const PG8_LAS bf16x8*)(lds + PG8_SA(b, h) + aoff + m * 2048 + k * 1024); } while (0)
; #define PG8_MMA(ai, bj, At, Bt) do { __builtin_amdgcn_s_setprio(1); _Pragma("unroll") for (int m = 0; m < 4; ++m) _Pragma("unroll") for (int n = 0; n < 2; ++n) _Pragma("unroll") for (int k = 0; k < 2; ++k) \
;         acc[ai][bj][m][n] = __builtin_amdgcn_mfma_f32_16x16x32_bf16(Bt[n][k], At[m][k], acc[ai][bj][m][n], 0, 0, 0); __builtin_amdgcn_s_setprio(0); } while (0)
; #define PG8_WAIT_V(n) asm volatile("s_waitcnt vmcnt(" #n ")" ::: "memory")
; #define PG8_WAIT_L(n) asm volatile("s_waitcnt lgkmcnt(" #n ")" ::: "memory")
; #define PG8_BAR __builtin_amdgcn_s_barrier()
; #define PG8_SCHED __builtin_amdgcn_sched_barrier(0)
; template <class Epi, class Sched, bool ALIGN_EPI = false, bool SP2 = false>
; __device__ __forceinline__ void gemm_phase(PG8_LAS unsigned char* lds, const Gemm g, const Sched& S, const Epi& E) {
;     ...
;             PG8_WAIT_V(8); PG8_WAIT_L(0); PG8_BAR; PG8_MMA(0, 0, At, B0); PG8_MMA(0, 1, At, B1); PG8_BAR; PG8_SCHED;
;             PG8_LDA(At, 0, 1); PG8_STAGE(PG8_SB(0, 0), b2, voffB); PG8_STAGE(PG8_SB(0, 1), b2 + hstep, voffB); PG8_STAGE(PG8_SA(0, 0), a2, voffA);
;             PG8_WAIT_V(8); PG8_WAIT_L(0); PG8_BAR; PG8_MMA(1, 0, At, B0); PG8_MMA(1, 1, At, B1); PG8_BAR; PG8_SCHED;
	s_setprio 1
	s_waitcnt lgkmcnt(0)
	v_mfma_f32_16x16x32_bf16 v[128:131], v[120:123], v[160:163], v[128:131]
	v_mfma_f32_16x16x32_bf16 v[108:111], v[120:123], v[168:171], v[108:111]
	v_mfma_f32_16x16x32_bf16 v[92:95], v[120:123], v[176:179], v[92:95]
	v_mfma_f32_16x16x32_bf16 v[76:79], v[120:123], v[184:187], v[76:79]
	v_mfma_f32_16x16x32_bf16 v[72:75], v[136:139], v[184:187], v[72:75]
	v_mfma_f32_16x16x32_bf16 v[88:91], v[136:139], v[176:179], v[88:91]
	v_mfma_f32_16x16x32_bf16 v[104:107], v[136:139], v[168:171], v[104:107]
	v_mfma_f32_16x16x32_bf16 v[124:127], v[136:139], v[160:163], v[124:127]
	v_mfma_f32_16x16x32_bf16 v[128:131], v[132:135], v[164:167], v[128:131]
	v_mfma_f32_16x16x32_bf16 v[108:111], v[132:135], v[172:175], v[108:111]
	v_mfma_f32_16x16x32_bf16 v[92:95], v[132:135], v[180:183], v[92:95]
	v_mfma_f32_16x16x32_bf16 v[76:79], v[132:135], v[188:191], v[76:79]
	v_mfma_f32_16x16x32_bf16 v[72:75], v[140:143], v[188:191], v[72:75]
	v_mfma_f32_16x16x32_bf16 v[88:91], v[140:143], v[180:183], v[88:91]
	v_mfma_f32_16x16x32_bf16 v[104:107], v[140:143], v[172:175], v[104:107]
	v_mfma_f32_16x16x32_bf16 v[124:127], v[140:143], v[164:167], v[124:127]
	s_setprio 0
	s_setprio 1
	v_mfma_f32_16x16x32_bf16 v[116:119], v[144:147], v[160:163], v[116:119]
	v_mfma_f32_16x16x32_bf16 v[100:103], v[144:147], v[168:171], v[100:103]
	v_mfma_f32_16x16x32_bf16 v[84:87], v[144:147], v[176:179], v[84:87]
	v_mfma_f32_16x16x32_bf16 v[68:71], v[144:147], v[184:187], v[68:71]
	v_mfma_f32_16x16x32_bf16 v[64:67], v[152:155], v[184:187], v[64:67]
	v_mfma_f32_16x16x32_bf16 v[80:83], v[152:155], v[176:179], v[80:83]
	v_mfma_f32_16x16x32_bf16 v[96:99], v[152:155], v[168:171], v[96:99]
	v_mfma_f32_16x16x32_bf16 v[112:115], v[152:155], v[160:163], v[112:115]
	v_mfma_f32_16x16x32_bf16 v[116:119], v[148:151], v[164:167], v[116:119]
	v_mfma_f32_16x16x32_bf16 v[100:103], v[148:151], v[172:175], v[100:103]
	v_mfma_f32_16x16x32_bf16 v[84:87], v[148:151], v[180:183], v[84:87]
	v_mfma_f32_16x16x32_bf16 v[68:71], v[148:151], v[188:191], v[68:71]
	v_mfma_f32_16x16x32_bf16 v[64:67], v[156:159], v[188:191], v[64:67]
	v_mfma_f32_16x16x32_bf16 v[80:83], v[156:159], v[180:183], v[80:83]
	v_mfma_f32_16x16x32_bf16 v[96:99], v[156:159], v[172:175], v[96:99]
	v_mfma_f32_16x16x32_bf16 v[112:115], v[156:159], v[164:167], v[112:115]
	s_setprio 0
	s_barrier
	s_add_i32 s25, s33, s6
	v_lshl_add_u64 v[206:207], s[60:61], 0, v[194:195]
	s_mov_b32 m0, s25
	ds_read_b128 v[160:163], v248 offset:16384
	ds_read_b128 v[164:167], v248 offset:17408
	ds_read_b128 v[168:171], v248 offset:18432
	ds_read_b128 v[172:175], v248 offset:19456
	ds_read_b128 v[176:179], v248 offset:20480
	ds_read_b128 v[180:183], v248 offset:21504
	ds_read_b128 v[184:187], v248 offset:22528
	ds_read_b128 v[188:191], v248 offset:23552
	global_load_lds_dwordx4 v[206:207], off
	s_add_i32 m0, s25, 0x2000
	v_lshl_add_u64 v[208:209], s[60:61], 0, v[198:199]
	s_add_u32 s60, s60, s42
	s_addc_u32 s61, s61, s43
	s_add_i32 s25, s34, s6
	global_load_lds_dwordx4 v[208:209], off
	v_lshl_add_u64 v[210:211], s[60:61], 0, v[194:195]
	s_mov_b32 m0, s25
	v_lshl_add_u64 v[212:213], s[60:61], 0, v[198:199]
	global_load_lds_dwordx4 v[210:211], off
	s_add_i32 m0, s25, 0x2000
	v_lshl_add_u64 v[214:215], s[58:59], 0, v[192:193]
	global_load_lds_dwordx4 v[212:213], off
	s_mov_b32 m0, s7
	v_lshl_add_u64 v[216:217], s[58:59], 0, v[196:197]
	global_load_lds_dwordx4 v[214:215], off
	s_mov_b32 m0, s16
	s_nop 0
	global_load_lds_dwordx4 v[216:217], off
	s_waitcnt vmcnt(8)
	s_waitcnt lgkmcnt(0)
	s_barrier
	s_setprio 1
	s_waitcnt lgkmcnt(0)
	v_mfma_f32_16x16x32_bf16 v[60:63], v[120:123], v[160:163], v[60:63]
	v_mfma_f32_16x16x32_bf16 v[44:47], v[120:123], v[168:171], v[44:47]
	v_mfma_f32_16x16x32_bf16 v[28:31], v[120:123], v[176:179], v[28:31]
	v_mfma_f32_16x16x32_bf16 v[12:15], v[120:123], v[184:187], v[12:15]
	v_mfma_f32_16x16x32_bf16 v[8:11], v[136:139], v[184:187], v[8:11]
	v_mfma_f32_16x16x32_bf16 v[24:27], v[136:139], v[176:179], v[24:27]
	v_mfma_f32_16x16x32_bf16 v[40:43], v[136:139], v[168:171], v[40:43]
	v_mfma_f32_16x16x32_bf16 v[56:59], v[136:139], v[160:163], v[56:59]
	v_mfma_f32_16x16x32_bf16 v[60:63], v[132:135], v[164:167], v[60:63]
	v_mfma_f32_16x16x32_bf16 v[44:47], v[132:135], v[172:175], v[44:47]
	v_mfma_f32_16x16x32_bf16 v[28:31], v[132:135], v[180:183], v[28:31]
	v_mfma_f32_16x16x32_bf16 v[12:15], v[132:135], v[188:191], v[12:15]
	v_mfma_f32_16x16x32_bf16 v[8:11], v[140:143], v[188:191], v[8:11]
	v_mfma_f32_16x16x32_bf16 v[24:27], v[140:143], v[180:183], v[24:27]
	v_mfma_f32_16x16x32_bf16 v[40:43], v[140:143], v[172:175], v[40:43]
	v_mfma_f32_16x16x32_bf16 v[56:59], v[140:143], v[164:167], v[56:59]
	s_setprio 0
	s_setprio 1
	v_mfma_f32_16x16x32_bf16 v[52:55], v[144:147], v[160:163], v[52:55]
	v_mfma_f32_16x16x32_bf16 v[36:39], v[144:147], v[168:171], v[36:39]
	v_mfma_f32_16x16x32_bf16 v[20:23], v[144:147], v[176:179], v[20:23]
	v_mfma_f32_16x16x32_bf16 v[4:7], v[144:147], v[184:187], v[4:7]
	v_mfma_f32_16x16x32_bf16 v[0:3], v[152:155], v[184:187], v[0:3]
	v_mfma_f32_16x16x32_bf16 v[16:19], v[152:155], v[176:179], v[16:19]
	v_mfma_f32_16x16x32_bf16 v[32:35], v[152:155], v[168:171], v[32:35]
	v_mfma_f32_16x16x32_bf16 v[48:51], v[152:155], v[160:163], v[48:51]
	v_mfma_f32_16x16x32_bf16 v[52:55], v[148:151], v[164:167], v[52:55]
	v_mfma_f32_16x16x32_bf16 v[36:39], v[148:151], v[172:175], v[36:39]
	v_mfma_f32_16x16x32_bf16 v[20:23], v[148:151], v[180:183], v[20:23]
	v_mfma_f32_16x16x32_bf16 v[4:7], v[148:151], v[188:191], v[4:7]
	v_mfma_f32_16x16x32_bf16 v[0:3], v[156:159], v[188:191], v[0:3]
	v_mfma_f32_16x16x32_bf16 v[16:19], v[156:159], v[180:183], v[16:19]
	v_mfma_f32_16x16x32_bf16 v[32:35], v[156:159], v[172:175], v[32:35]
	v_mfma_f32_16x16x32_bf16 v[48:51], v[156:159], v[164:167], v[48:51]
	s_setprio 0
	s_barrier
; #define PG8_STAGE(bufoff, gbase, voff) do { _Pragma("unroll") for (int _i = 0; _i < 2; ++_i) \
;         __builtin_amdgcn_global_load_lds((const unsigned*)((const char*)(gbase) + (voff)[_i]), (PG8_LAS unsigned*)(lds + (bufoff) + ldsw + _i * 8192), 16, 0, 0); } while (0)
; #define PG8_LDA(dst, b, h) do { _Pragma("unroll") for (int m = 0; m < 4; ++m) _Pragma("unroll") for (int k = 0; k < 2; ++k) dst[m][k] = *(const PG8_LAS bf16x8*)(lds + PG8_SA(b, h) + aoff + m * 2048 + k * 1024); } while (0)
; #define PG8_LDB(dst, b, h) do { _Pragma("unroll") for (int n = 0; n < 2; ++n) _Pragma("unroll") for (int k = 0; k < 2; ++k) dst[n][k] = *(const PG8_LAS bf16x8*)(lds + PG8_SB(b, h) + boff + n * 2048 + k * 1024); } while (0)
; #define PG8_MMA(ai, bj, At, Bt) do { __builtin_amdgcn_s_setprio(1); _Pragma("unroll") for (int m = 0; m < 4; ++m) _Pragma("unroll") for (int n = 0; n < 2; ++n) _Pragma("unroll") for (int k = 0; k < 2; ++k) \
;         acc[ai][bj][m][n] = __builtin_amdgcn_mfma_f32_16x16x32_bf16(Bt[n][k], At[m][k], acc[ai][bj][m][n], 0, 0, 0); __builtin_amdgcn_s_setprio(0); } while (0)
; #define PG8_WAIT_V(n) asm volatile("s_waitcnt vmcnt(" #n ")" ::: "memory")
; #define PG8_WAIT_L(n) asm volatile("s_waitcnt lgkmcnt(" #n ")" ::: "memory")
; #define PG8_BAR __builtin_amdgcn_s_barrier()
; #define PG8_SCHED __builtin_amdgcn_sched_barrier(0)
; template <class Epi, class Sched, bool ALIGN_EPI = false, bool SP2 = false>
; __device__ __forceinline__ void gemm_phase(PG8_LAS unsigned char* lds, const Gemm g, const Sched& S, const Epi& E) {
;     ...
;             PG8_LDB(B0, 1, 0); PG8_LDB(B1, 1, 1); PG8_SCHED; PG8_LDA(At, 1, 0); PG8_STAGE(PG8_SA(0, 1), a2 + hstep, voffA);
;             PG8_WAIT_V(8); PG8_WAIT_L(0); PG8_BAR; PG8_MMA(0, 0, At, B0); PG8_MMA(0, 1, At, B1); PG8_BAR; PG8_SCHED;
	s_add_i32 s25, 0, 0x18000
	s_add_i32 s46, 0, 0x1c000
	v_add_u32_e32 v140, s25, v244
	v_add_u32_e32 v156, s46, v244
	ds_read_b128 v[120:123], v140
	ds_read_b128 v[132:135], v140 offset:1024
	ds_read_b128 v[136:139], v140 offset:2048
	ds_read_b128 v[140:143], v140 offset:3072
	ds_read_b128 v[144:147], v156
	ds_read_b128 v[148:151], v156 offset:1024
	ds_read_b128 v[152:155], v156 offset:2048
	ds_read_b128 v[156:159], v156 offset:3072
	s_add_u32 s58, s58, s42
	s_addc_u32 s59, s59, s43
	s_mov_b32 m0, s17
	v_lshl_add_u64 v[218:219], s[58:59], 0, v[192:193]
	ds_read_b128 v[160:163], v248 offset:32768
	ds_read_b128 v[164:167], v248 offset:33792
	ds_read_b128 v[168:171], v248 offset:34816
	ds_read_b128 v[172:175], v248 offset:35840
	ds_read_b128 v[176:179], v248 offset:36864
	ds_read_b128 v[180:183], v248 offset:37888
	ds_read_b128 v[184:187], v248 offset:38912
	ds_read_b128 v[188:191], v248 offset:39936
	global_load_lds_dwordx4 v[218:219], off
	v_lshl_add_u64 v[218:219], s[58:59], 0, v[196:197]
	s_mov_b32 m0, s18
	s_nop 0
	global_load_lds_dwordx4 v[218:219], off
	s_waitcnt vmcnt(8)
	s_waitcnt lgkmcnt(0)
	s_barrier
	s_setprio 1
	s_waitcnt lgkmcnt(0)
	v_mfma_f32_16x16x32_bf16 v[128:131], v[120:123], v[160:163], v[128:131]
	v_mfma_f32_16x16x32_bf16 v[108:111], v[120:123], v[168:171], v[108:111]
	v_mfma_f32_16x16x32_bf16 v[92:95], v[120:123], v[176:179], v[92:95]
	v_mfma_f32_16x16x32_bf16 v[76:79], v[120:123], v[184:187], v[76:79]
	v_mfma_f32_16x16x32_bf16 v[72:75], v[136:139], v[184:187], v[72:75]
	v_mfma_f32_16x16x32_bf16 v[88:91], v[136:139], v[176:179], v[88:91]
	v_mfma_f32_16x16x32_bf16 v[104:107], v[136:139], v[168:171], v[104:107]
	v_mfma_f32_16x16x32_bf16 v[124:127], v[136:139], v[160:163], v[124:127]
	v_mfma_f32_16x16x32_bf16 v[128:131], v[132:135], v[164:167], v[128:131]
	v_mfma_f32_16x16x32_bf16 v[108:111], v[132:135], v[172:175], v[108:111]
	v_mfma_f32_16x16x32_bf16 v[92:95], v[132:135], v[180:183], v[92:95]
	v_mfma_f32_16x16x32_bf16 v[76:79], v[132:135], v[188:191], v[76:79]
	v_mfma_f32_16x16x32_bf16 v[72:75], v[140:143], v[188:191], v[72:75]
	v_mfma_f32_16x16x32_bf16 v[88:91], v[140:143], v[180:183], v[88:91]
	v_mfma_f32_16x16x32_bf16 v[104:107], v[140:143], v[172:175], v[104:107]
	v_mfma_f32_16x16x32_bf16 v[124:127], v[140:143], v[164:167], v[124:127]
	s_setprio 0
	s_setprio 1
	v_mfma_f32_16x16x32_bf16 v[116:119], v[144:147], v[160:163], v[116:119]
	v_mfma_f32_16x16x32_bf16 v[100:103], v[144:147], v[168:171], v[100:103]
	v_mfma_f32_16x16x32_bf16 v[84:87], v[144:147], v[176:179], v[84:87]
	v_mfma_f32_16x16x32_bf16 v[68:71], v[144:147], v[184:187], v[68:71]
	v_mfma_f32_16x16x32_bf16 v[64:67], v[152:155], v[184:187], v[64:67]
	v_mfma_f32_16x16x32_bf16 v[80:83], v[152:155], v[176:179], v[80:83]
	v_mfma_f32_16x16x32_bf16 v[96:99], v[152:155], v[168:171], v[96:99]
	v_mfma_f32_16x16x32_bf16 v[112:115], v[152:155], v[160:163], v[112:115]
	v_mfma_f32_16x16x32_bf16 v[116:119], v[148:151], v[164:167], v[116:119]
	v_mfma_f32_16x16x32_bf16 v[100:103], v[148:151], v[172:175], v[100:103]
	v_mfma_f32_16x16x32_bf16 v[84:87], v[148:151], v[180:183], v[84:87]
	v_mfma_f32_16x16x32_bf16 v[68:71], v[148:151], v[188:191], v[68:71]
	v_mfma_f32_16x16x32_bf16 v[64:67], v[156:159], v[188:191], v[64:67]
	v_mfma_f32_16x16x32_bf16 v[80:83], v[156:159], v[180:183], v[80:83]
	v_mfma_f32_16x16x32_bf16 v[96:99], v[156:159], v[172:175], v[96:99]
	v_mfma_f32_16x16x32_bf16 v[112:115], v[156:159], v[164:167], v[112:115]
	s_setprio 0
	s_barrier
; #define PG8_STAGE(bufoff, gbase, voff) do { _Pragma("unroll") for (int _i = 0; _i < 2; ++_i) \
;         __builtin_amdgcn_global_load_lds((const unsigned*)((const char*)(gbase) + (voff)[_i]), (PG8_LAS unsigned*)(lds + (bufoff) + ldsw + _i * 8192), 16, 0, 0); } while (0)
; #define PG8_LDA(dst, b, h) do { _Pragma("unroll") for (int m = 0; m < 4; ++m) _Pragma("unroll") for (int k = 0; k < 2; ++k) dst[m][k] = *(const PG8_LAS bf16x8*)(lds + PG8_SA(b, h) + aoff + m * 2048 + k * 1024); } while (0)
; #define PG8_MMA(ai, bj, At, Bt) do { __builtin_amdgcn_s_setprio(1); _Pragma("unroll") for (int m = 0; m < 4; ++m) _Pragma("unroll") for (int n = 0; n < 2; ++n) _Pragma("unroll") for (int k = 0; k < 2; ++k) \
;         acc[ai][bj][m][n] = __builtin_amdgcn_mfma_f32_16x16x32_bf16(Bt[n][k], At[m][k], acc[ai][bj][m][n], 0, 0, 0); __builtin_amdgcn_s_setprio(0); } while (0)
; #define PG8_WAIT_V(n) asm volatile("s_waitcnt vmcnt(" #n ")" ::: "memory")
; #define PG8_WAIT_L(n) asm volatile("s_waitcnt lgkmcnt(" #n ")" ::: "memory")
; #define PG8_BAR __builtin_amdgcn_s_barrier()
; #define PG8_SCHED __builtin_amdgcn_sched_barrier(0)
; template <class Epi, class Sched, bool ALIGN_EPI = false, bool SP2 = false>
; __device__ __forceinline__ void gemm_phase(PG8_LAS unsigned char* lds, const Gemm g, const Sched& S, const Epi& E) {
;     ...
;             PG8_LDA(At, 1, 1); PG8_STAGE(PG8_SB(1, 0), b3, voffB); PG8_STAGE(PG8_SB(1, 1), b3 + hstep, voffB); PG8_STAGE(PG8_SA(1, 0), a3, voffA);
;             PG8_WAIT_V(8); PG8_WAIT_L(0); PG8_BAR; PG8_MMA(1, 0, At, B0); PG8_MMA(1, 1, At, B1); PG8_BAR; PG8_SCHED;
	s_add_i32 s25, s25, s6
	v_lshl_add_u64 v[206:207], v[206:207], 0, s[50:51]
	s_mov_b32 m0, s25
	ds_read_b128 v[160:163], v248 offset:49152
	ds_read_b128 v[164:167], v248 offset:50176
	ds_read_b128 v[168:171], v248 offset:51200
	ds_read_b128 v[172:175], v248 offset:52224
	ds_read_b128 v[176:179], v248 offset:53248
	ds_read_b128 v[180:183], v248 offset:54272
	ds_read_b128 v[184:187], v248 offset:55296
	ds_read_b128 v[188:191], v248 offset:56320
	global_load_lds_dwordx4 v[206:207], off
	v_lshl_add_u64 v[206:207], v[208:209], 0, s[50:51]
	s_add_i32 m0, s25, 0x2000
	s_add_i32 s25, s46, s6
	global_load_lds_dwordx4 v[206:207], off
	v_lshl_add_u64 v[206:207], v[210:211], 0, s[50:51]
	s_mov_b32 m0, s25
	s_nop 0
	global_load_lds_dwordx4 v[206:207], off
	v_lshl_add_u64 v[206:207], v[212:213], 0, s[50:51]
	s_add_i32 m0, s25, 0x2000
	s_nop 0
	global_load_lds_dwordx4 v[206:207], off
	v_lshl_add_u64 v[206:207], v[214:215], 0, s[50:51]
	s_mov_b32 m0, s19
	s_nop 0
	global_load_lds_dwordx4 v[206:207], off
	v_lshl_add_u64 v[206:207], v[216:217], 0, s[50:51]
	s_mov_b32 m0, s26
	s_nop 0
	global_load_lds_dwordx4 v[206:207], off
	s_waitcnt vmcnt(8)
	s_waitcnt lgkmcnt(0)
	s_barrier
	s_setprio 1
	s_waitcnt lgkmcnt(0)
	v_mfma_f32_16x16x32_bf16 v[60:63], v[120:123], v[160:163], v[60:63]
	v_mfma_f32_16x16x32_bf16 v[44:47], v[120:123], v[168:171], v[44:47]
	v_mfma_f32_16x16x32_bf16 v[28:31], v[120:123], v[176:179], v[28:31]
	v_mfma_f32_16x16x32_bf16 v[12:15], v[120:123], v[184:187], v[12:15]
	v_mfma_f32_16x16x32_bf16 v[8:11], v[136:139], v[184:187], v[8:11]
	v_mfma_f32_16x16x32_bf16 v[24:27], v[136:139], v[176:179], v[24:27]
	v_mfma_f32_16x16x32_bf16 v[40:43], v[136:139], v[168:171], v[40:43]
	v_mfma_f32_16x16x32_bf16 v[56:59], v[136:139], v[160:163], v[56:59]
	v_mfma_f32_16x16x32_bf16 v[60:63], v[132:135], v[164:167], v[60:63]
	v_mfma_f32_16x16x32_bf16 v[44:47], v[132:135], v[172:175], v[44:47]
	v_mfma_f32_16x16x32_bf16 v[28:31], v[132:135], v[180:183], v[28:31]
	v_mfma_f32_16x16x32_bf16 v[12:15], v[132:135], v[188:191], v[12:15]
	v_mfma_f32_16x16x32_bf16 v[8:11], v[140:143], v[188:191], v[8:11]
	v_mfma_f32_16x16x32_bf16 v[24:27], v[140:143], v[180:183], v[24:27]
	v_mfma_f32_16x16x32_bf16 v[40:43], v[140:143], v[172:175], v[40:43]
	v_mfma_f32_16x16x32_bf16 v[56:59], v[140:143], v[164:167], v[56:59]
	s_setprio 0
	s_setprio 1
	v_mfma_f32_16x16x32_bf16 v[52:55], v[144:147], v[160:163], v[52:55]
	v_mfma_f32_16x16x32_bf16 v[36:39], v[144:147], v[168:171], v[36:39]
	v_mfma_f32_16x16x32_bf16 v[20:23], v[144:147], v[176:179], v[20:23]
	v_mfma_f32_16x16x32_bf16 v[4:7], v[144:147], v[184:187], v[4:7]
	v_mfma_f32_16x16x32_bf16 v[0:3], v[152:155], v[184:187], v[0:3]
	v_mfma_f32_16x16x32_bf16 v[16:19], v[152:155], v[176:179], v[16:19]
	v_mfma_f32_16x16x32_bf16 v[32:35], v[152:155], v[168:171], v[32:35]
	v_mfma_f32_16x16x32_bf16 v[48:51], v[152:155], v[160:163], v[48:51]
	v_mfma_f32_16x16x32_bf16 v[52:55], v[148:151], v[164:167], v[52:55]
	v_mfma_f32_16x16x32_bf16 v[36:39], v[148:151], v[172:175], v[36:39]
	v_mfma_f32_16x16x32_bf16 v[20:23], v[148:151], v[180:183], v[20:23]
	v_mfma_f32_16x16x32_bf16 v[4:7], v[148:151], v[188:191], v[4:7]
	v_mfma_f32_16x16x32_bf16 v[0:3], v[156:159], v[188:191], v[0:3]
	v_mfma_f32_16x16x32_bf16 v[16:19], v[156:159], v[180:183], v[16:19]
	v_mfma_f32_16x16x32_bf16 v[32:35], v[156:159], v[172:175], v[32:35]
	v_mfma_f32_16x16x32_bf16 v[48:51], v[156:159], v[164:167], v[48:51]
	s_setprio 0
	s_barrier
	s_add_u32 s56, s56, 0x100
	s_addc_u32 s57, s57, 0
	s_add_u32 s2, s2, 0x100
	s_addc_u32 s24, s24, 0
	s_cmp_ge_i32 s39, s30
	s_mov_b32 s25, s39
	s_cbranch_scc0 .LBB0_1222

; #define PG8_STAGE(bufoff, gbase, voff) do { _Pragma("unroll") for (int _i = 0; _i < 2; ++_i) \
;         __builtin_amdgcn_global_load_lds((const unsigned*)((const char*)(gbase) + (voff)[_i]), (PG8_LAS unsigned*)(lds + (bufoff) + ldsw + _i * 8192), 16, 0, 0); } while (0)
; #define PG8_LDA(dst, b, h) do { _Pragma("unroll") for (int m = 0; m < 4; ++m) _Pragma("unroll") for (int k = 0; k < 2; ++k) dst[m][k] = *(const PG8_LAS bf16x8*)(lds + PG8_SA(b, h) + aoff + m * 2048 + k * 1024); } while (0)
; #define PG8_LDB(dst, b, h) do { _Pragma("unroll") for (int n = 0; n < 2; ++n) _Pragma("unroll") for (int k = 0; k < 2; ++k) dst[n][k] = *(const PG8_LAS bf16x8*)(lds + PG8_SB(b, h) + boff + n * 2048 + k * 1024); } while (0)
; #define PG8_MMA(ai, bj, At, Bt) do { __builtin_amdgcn_s_setprio(1); _Pragma("unroll") for (int m = 0; m < 4; ++m) _Pragma("unroll") for (int n = 0; n < 2; ++n) _Pragma("unroll") for (int k = 0; k < 2; ++k) \
;         acc[ai][bj][m][n] = __builtin_amdgcn_mfma_f32_16x16x32_bf16(Bt[n][k], At[m][k], acc[ai][bj][m][n], 0, 0, 0); __builtin_amdgcn_s_setprio(0); } while (0)
; #define PG8_WAIT_V(n) asm volatile("s_waitcnt vmcnt(" #n ")" ::: "memory")
; #define PG8_WAIT_L(n) asm volatile("s_waitcnt lgkmcnt(" #n ")" ::: "memory")
; #define PG8_BAR __builtin_amdgcn_s_barrier()
; #define PG8_SCHED __builtin_amdgcn_sched_barrier(0)
; template <class Epi, class Sched, bool ALIGN_EPI = false, bool SP2 = false>
; __device__ __forceinline__ void gemm_phase(PG8_LAS unsigned char* lds, const Gemm g, const Sched& S, const Epi& E) {
;     ...
;             PG8_LDB(B0, 0, 0); PG8_LDB(B1, 0, 1); PG8_SCHED; PG8_LDA(At, 0, 0); PG8_STAGE(PG8_SA(1, 1), a1 + hstep, voffA);
;             PG8_WAIT_V(8); PG8_WAIT_L(0); PG8_BAR; PG8_MMA(0, 0, At, B0); PG8_MMA(0, 1, At, B1); PG8_BAR; PG8_SCHED;
;             PG8_LDA(At, 0, 1); PG8_STAGE(PG8_SB(0, 0), b2, voffB); PG8_STAGE(PG8_SB(0, 1), b2 + hstep, voffB); PG8_STAGE(PG8_SA(0, 0), a2, voffA);
;             PG8_WAIT_V(8); PG8_WAIT_L(0); PG8_BAR; PG8_MMA(1, 0, At, B0); PG8_MMA(1, 1, At, B1); PG8_BAR; PG8_SCHED;
.LBB0_1321:
	s_and_b64 vcc, exec, s[10:11]
	s_cbranch_vccnz .Lcoldz_4
	s_add_u32 s50, s50, 0x80
	s_addc_u32 s51, s51, 0
	s_add_u32 s24, s52, 0x100
	s_addc_u32 s25, s53, 0
	s_mov_b32 s52, 0
	ds_read_b128 v[152:155], v148
	ds_read_b128 v[156:159], v148 offset:1024
	ds_read_b128 v[160:163], v148 offset:2048
	ds_read_b128 v[164:167], v148 offset:3072
	ds_read_b128 v[168:171], v149
	ds_read_b128 v[172:175], v149 offset:1024
	ds_read_b128 v[176:179], v149 offset:2048
	ds_read_b128 v[180:183], v149 offset:3072
	s_add_i32 s58, s52, 2
	s_add_u32 s59, s50, 0x80
	s_addc_u32 s53, s51, 0
	s_cmp_eq_u32 s33, s52
	s_cselect_b32 s52, s14, s59
	s_cselect_b32 s53, s15, s53
	s_cselect_b32 s61, s49, s25
	s_cselect_b32 s60, s48, s24
	s_mov_b32 m0, s37
	v_lshl_add_u64 v[216:217], s[50:51], 0, v[136:137]
	ds_read_b128 v[184:187], v150
	ds_read_b128 v[188:191], v150 offset:1024
	ds_read_b128 v[192:195], v150 offset:2048
	ds_read_b128 v[196:199], v150 offset:3072
	ds_read_b128 v[200:203], v150 offset:4096
	ds_read_b128 v[204:207], v150 offset:5120
	ds_read_b128 v[208:211], v150 offset:6144
	ds_read_b128 v[212:215], v150 offset:7168
	global_load_lds_dwordx4 v[216:217], off
	v_lshl_add_u64 v[216:217], s[50:51], 0, v[138:139]
	s_mov_b32 m0, s38
	s_nop 0
	global_load_lds_dwordx4 v[216:217], off
	s_waitcnt vmcnt(8)
	s_waitcnt lgkmcnt(0)
	s_barrier
	s_setprio 1
	s_waitcnt lgkmcnt(0)
	v_mfma_f32_16x16x32_bf16 v[120:123], v[152:155], v[184:187], 0
	v_mfma_f32_16x16x32_bf16 v[116:119], v[160:163], v[184:187], 0
	v_mfma_f32_16x16x32_bf16 v[108:111], v[152:155], v[192:195], 0
	v_mfma_f32_16x16x32_bf16 v[100:103], v[160:163], v[192:195], 0
	v_mfma_f32_16x16x32_bf16 v[92:95], v[152:155], v[200:203], 0
	v_mfma_f32_16x16x32_bf16 v[84:87], v[160:163], v[200:203], 0
	v_mfma_f32_16x16x32_bf16 v[76:79], v[152:155], v[208:211], 0
	v_mfma_f32_16x16x32_bf16 v[68:71], v[160:163], v[208:211], 0
	v_mfma_f32_16x16x32_bf16 v[120:123], v[156:159], v[188:191], v[120:123]
	v_mfma_f32_16x16x32_bf16 v[108:111], v[156:159], v[196:199], v[108:111]
	v_mfma_f32_16x16x32_bf16 v[92:95], v[156:159], v[204:207], v[92:95]
	v_mfma_f32_16x16x32_bf16 v[76:79], v[156:159], v[212:215], v[76:79]
	v_mfma_f32_16x16x32_bf16 v[68:71], v[164:167], v[212:215], v[68:71]
	v_mfma_f32_16x16x32_bf16 v[84:87], v[164:167], v[204:207], v[84:87]
	v_mfma_f32_16x16x32_bf16 v[100:103], v[164:167], v[196:199], v[100:103]
	v_mfma_f32_16x16x32_bf16 v[116:119], v[164:167], v[188:191], v[116:119]
	s_setprio 0
	s_setprio 1
	v_mfma_f32_16x16x32_bf16 v[124:127], v[168:171], v[184:187], 0
	v_mfma_f32_16x16x32_bf16 v[112:115], v[176:179], v[184:187], 0
	v_mfma_f32_16x16x32_bf16 v[104:107], v[168:171], v[192:195], 0
	v_mfma_f32_16x16x32_bf16 v[96:99], v[176:179], v[192:195], 0
	v_mfma_f32_16x16x32_bf16 v[88:91], v[168:171], v[200:203], 0
	v_mfma_f32_16x16x32_bf16 v[80:83], v[176:179], v[200:203], 0
	v_mfma_f32_16x16x32_bf16 v[72:75], v[168:171], v[208:211], 0
	v_mfma_f32_16x16x32_bf16 v[64:67], v[176:179], v[208:211], 0
	v_mfma_f32_16x16x32_bf16 v[124:127], v[172:175], v[188:191], v[124:127]
	v_mfma_f32_16x16x32_bf16 v[104:107], v[172:175], v[196:199], v[104:107]
	v_mfma_f32_16x16x32_bf16 v[88:91], v[172:175], v[204:207], v[88:91]
	v_mfma_f32_16x16x32_bf16 v[72:75], v[172:175], v[212:215], v[72:75]
	v_mfma_f32_16x16x32_bf16 v[64:67], v[180:183], v[212:215], v[64:67]
	v_mfma_f32_16x16x32_bf16 v[80:83], v[180:183], v[204:207], v[80:83]
	v_mfma_f32_16x16x32_bf16 v[96:99], v[180:183], v[196:199], v[96:99]
	v_mfma_f32_16x16x32_bf16 v[112:115], v[180:183], v[188:191], v[112:115]
	s_setprio 0
	s_barrier
	s_add_i32 s59, s34, s3
	v_lshl_add_u64 v[216:217], s[60:61], 0, v[132:133]
	s_mov_b32 m0, s59
	ds_read_b128 v[184:187], v150 offset:16384
	ds_read_b128 v[188:191], v150 offset:17408
	ds_read_b128 v[192:195], v150 offset:18432
	ds_read_b128 v[196:199], v150 offset:19456
	ds_read_b128 v[200:203], v150 offset:20480
	ds_read_b128 v[204:207], v150 offset:21504
	ds_read_b128 v[208:211], v150 offset:22528
	ds_read_b128 v[212:215], v150 offset:23552
	global_load_lds_dwordx4 v[216:217], off
	s_add_i32 m0, s59, 0x2000
	v_lshl_add_u64 v[218:219], s[60:61], 0, v[128:129]
	s_add_u32 s60, s60, s16
	s_addc_u32 s61, s61, s17
	s_add_i32 s59, s35, s3
	global_load_lds_dwordx4 v[218:219], off
	v_lshl_add_u64 v[220:221], s[60:61], 0, v[132:133]
	s_mov_b32 m0, s59
	v_lshl_add_u64 v[222:223], s[60:61], 0, v[128:129]
	global_load_lds_dwordx4 v[220:221], off
	s_add_i32 m0, s59, 0x2000
	v_lshl_add_u64 v[224:225], s[52:53], 0, v[134:135]
	global_load_lds_dwordx4 v[222:223], off
	s_mov_b32 m0, s7
	v_lshl_add_u64 v[226:227], s[52:53], 0, v[130:131]
	global_load_lds_dwordx4 v[224:225], off
	s_mov_b32 m0, s18
	s_nop 0
	global_load_lds_dwordx4 v[226:227], off
	s_waitcnt vmcnt(8)
	s_waitcnt lgkmcnt(0)
	s_barrier
; #define PG8_STAGE(bufoff, gbase, voff) do { _Pragma("unroll") for (int _i = 0; _i < 2; ++_i) \
;         __builtin_amdgcn_global_load_lds((const unsigned*)((const char*)(gbase) + (voff)[_i]), (PG8_LAS unsigned*)(lds + (bufoff) + ldsw + _i * 8192), 16, 0, 0); } while (0)
; #define PG8_LDA(dst, b, h) do { _Pragma("unroll") for (int m = 0; m < 4; ++m) _Pragma("unroll") for (int k = 0; k < 2; ++k) dst[m][k] = *(const PG8_LAS bf16x8*)(lds + PG8_SA(b, h) + aoff + m * 2048 + k * 1024); } while (0)
; #define PG8_LDB(dst, b, h) do { _Pragma("unroll") for (int n = 0; n < 2; ++n) _Pragma("unroll") for (int k = 0; k < 2; ++k) dst[n][k] = *(const PG8_LAS bf16x8*)(lds + PG8_SB(b, h) + boff + n * 2048 + k * 1024); } while (0)
; #define PG8_MMA(ai, bj, At, Bt) do { __builtin_amdgcn_s_setprio(1); _Pragma("unroll") for (int m = 0; m < 4; ++m) _Pragma("unroll") for (int n = 0; n < 2; ++n) _Pragma("unroll") for (int k = 0; k < 2; ++k) \
;         acc[ai][bj][m][n] = __builtin_amdgcn_mfma_f32_16x16x32_bf16(Bt[n][k], At[m][k], acc[ai][bj][m][n], 0, 0, 0); __builtin_amdgcn_s_setprio(0); } while (0)
; #define PG8_WAIT_V(n) asm volatile("s_waitcnt vmcnt(" #n ")" ::: "memory")
; #define PG8_WAIT_L(n) asm volatile("s_waitcnt lgkmcnt(" #n ")" ::: "memory")
; #define PG8_BAR __builtin_amdgcn_s_barrier()
; #define PG8_SCHED __builtin_amdgcn_sched_barrier(0)
; template <class Epi, class Sched, bool ALIGN_EPI = false, bool SP2 = false>
; __device__ __forceinline__ void gemm_phase(PG8_LAS unsigned char* lds, const Gemm g, const Sched& S, const Epi& E) {
;     ...
;             PG8_WAIT_V(8); PG8_WAIT_L(0); PG8_BAR; PG8_MMA(1, 0, At, B0); PG8_MMA(1, 1, At, B1); PG8_BAR; PG8_SCHED;
;             PG8_LDB(B0, 1, 0); PG8_LDB(B1, 1, 1); PG8_SCHED; PG8_LDA(At, 1, 0); PG8_STAGE(PG8_SA(0, 1), a2 + hstep, voffA);
;             PG8_WAIT_V(8); PG8_WAIT_L(0); PG8_BAR; PG8_MMA(0, 0, At, B0); PG8_MMA(0, 1, At, B1); PG8_BAR; PG8_SCHED;
	s_setprio 1
	s_waitcnt lgkmcnt(0)
	v_mfma_f32_16x16x32_bf16 v[60:63], v[152:155], v[184:187], 0
	v_mfma_f32_16x16x32_bf16 v[52:55], v[160:163], v[184:187], 0
	v_mfma_f32_16x16x32_bf16 v[44:47], v[152:155], v[192:195], 0
	v_mfma_f32_16x16x32_bf16 v[36:39], v[160:163], v[192:195], 0
	v_mfma_f32_16x16x32_bf16 v[28:31], v[152:155], v[200:203], 0
	v_mfma_f32_16x16x32_bf16 v[20:23], v[160:163], v[200:203], 0
	v_mfma_f32_16x16x32_bf16 v[12:15], v[152:155], v[208:211], 0
	v_mfma_f32_16x16x32_bf16 v[4:7], v[160:163], v[208:211], 0
	v_mfma_f32_16x16x32_bf16 v[60:63], v[156:159], v[188:191], v[60:63]
	v_mfma_f32_16x16x32_bf16 v[44:47], v[156:159], v[196:199], v[44:47]
	v_mfma_f32_16x16x32_bf16 v[28:31], v[156:159], v[204:207], v[28:31]
	v_mfma_f32_16x16x32_bf16 v[12:15], v[156:159], v[212:215], v[12:15]
	v_mfma_f32_16x16x32_bf16 v[4:7], v[164:167], v[212:215], v[4:7]
	v_mfma_f32_16x16x32_bf16 v[20:23], v[164:167], v[204:207], v[20:23]
	v_mfma_f32_16x16x32_bf16 v[36:39], v[164:167], v[196:199], v[36:39]
	v_mfma_f32_16x16x32_bf16 v[52:55], v[164:167], v[188:191], v[52:55]
	s_setprio 0
	s_setprio 1
	v_mfma_f32_16x16x32_bf16 v[56:59], v[168:171], v[184:187], 0
	v_mfma_f32_16x16x32_bf16 v[48:51], v[176:179], v[184:187], 0
	v_mfma_f32_16x16x32_bf16 v[40:43], v[168:171], v[192:195], 0
	v_mfma_f32_16x16x32_bf16 v[32:35], v[176:179], v[192:195], 0
	v_mfma_f32_16x16x32_bf16 v[24:27], v[168:171], v[200:203], 0
	v_mfma_f32_16x16x32_bf16 v[16:19], v[176:179], v[200:203], 0
	v_mfma_f32_16x16x32_bf16 v[8:11], v[168:171], v[208:211], 0
	v_mfma_f32_16x16x32_bf16 v[0:3], v[176:179], v[208:211], 0
	v_mfma_f32_16x16x32_bf16 v[56:59], v[172:175], v[188:191], v[56:59]
	v_mfma_f32_16x16x32_bf16 v[40:43], v[172:175], v[196:199], v[40:43]
	v_mfma_f32_16x16x32_bf16 v[24:27], v[172:175], v[204:207], v[24:27]
	v_mfma_f32_16x16x32_bf16 v[8:11], v[172:175], v[212:215], v[8:11]
	v_mfma_f32_16x16x32_bf16 v[0:3], v[180:183], v[212:215], v[0:3]
	v_mfma_f32_16x16x32_bf16 v[16:19], v[180:183], v[204:207], v[16:19]
	v_mfma_f32_16x16x32_bf16 v[32:35], v[180:183], v[196:199], v[32:35]
	v_mfma_f32_16x16x32_bf16 v[48:51], v[180:183], v[188:191], v[48:51]
	s_setprio 0
	s_barrier
	s_add_i32 s59, 0, 0x18000
	v_add_u32_e32 v151, s59, v145
	s_add_i32 s60, 0, 0x1c000
	ds_read_b128 v[152:155], v151
	ds_read_b128 v[156:159], v151 offset:1024
	ds_read_b128 v[160:163], v151 offset:2048
	ds_read_b128 v[164:167], v151 offset:3072
	v_add_u32_e32 v151, s60, v145
	ds_read_b128 v[168:171], v151
	ds_read_b128 v[172:175], v151 offset:1024
	ds_read_b128 v[176:179], v151 offset:2048
	ds_read_b128 v[180:183], v151 offset:3072
	s_add_u32 s52, s52, s16
	s_addc_u32 s53, s53, s17
	s_mov_b32 m0, s19
	v_lshl_add_u64 v[228:229], s[52:53], 0, v[134:135]
	ds_read_b128 v[184:187], v150 offset:32768
	ds_read_b128 v[188:191], v150 offset:33792
	ds_read_b128 v[192:195], v150 offset:34816
	ds_read_b128 v[196:199], v150 offset:35840
	ds_read_b128 v[200:203], v150 offset:36864
	ds_read_b128 v[204:207], v150 offset:37888
	ds_read_b128 v[208:211], v150 offset:38912
	ds_read_b128 v[212:215], v150 offset:39936
	global_load_lds_dwordx4 v[228:229], off
	v_lshl_add_u64 v[228:229], s[52:53], 0, v[130:131]
	s_mov_b32 m0, s26
	s_nop 0
	global_load_lds_dwordx4 v[228:229], off
	s_waitcnt vmcnt(8)
	s_waitcnt lgkmcnt(0)
	s_barrier
	s_setprio 1
	s_waitcnt lgkmcnt(0)
	v_mfma_f32_16x16x32_bf16 v[120:123], v[152:155], v[184:187], v[120:123]
	v_mfma_f32_16x16x32_bf16 v[108:111], v[152:155], v[192:195], v[108:111]
	v_mfma_f32_16x16x32_bf16 v[92:95], v[152:155], v[200:203], v[92:95]
	v_mfma_f32_16x16x32_bf16 v[76:79], v[152:155], v[208:211], v[76:79]
	v_mfma_f32_16x16x32_bf16 v[68:71], v[160:163], v[208:211], v[68:71]
	v_mfma_f32_16x16x32_bf16 v[84:87], v[160:163], v[200:203], v[84:87]
	v_mfma_f32_16x16x32_bf16 v[100:103], v[160:163], v[192:195], v[100:103]
	v_mfma_f32_16x16x32_bf16 v[116:119], v[160:163], v[184:187], v[116:119]
	v_mfma_f32_16x16x32_bf16 v[120:123], v[156:159], v[188:191], v[120:123]
	v_mfma_f32_16x16x32_bf16 v[108:111], v[156:159], v[196:199], v[108:111]
	v_mfma_f32_16x16x32_bf16 v[92:95], v[156:159], v[204:207], v[92:95]
	v_mfma_f32_16x16x32_bf16 v[76:79], v[156:159], v[212:215], v[76:79]
	v_mfma_f32_16x16x32_bf16 v[68:71], v[164:167], v[212:215], v[68:71]
	v_mfma_f32_16x16x32_bf16 v[84:87], v[164:167], v[204:207], v[84:87]
	v_mfma_f32_16x16x32_bf16 v[100:103], v[164:167], v[196:199], v[100:103]
	v_mfma_f32_16x16x32_bf16 v[116:119], v[164:167], v[188:191], v[116:119]
	s_setprio 0
	s_setprio 1
	v_mfma_f32_16x16x32_bf16 v[124:127], v[168:171], v[184:187], v[124:127]
	v_mfma_f32_16x16x32_bf16 v[104:107], v[168:171], v[192:195], v[104:107]
	v_mfma_f32_16x16x32_bf16 v[88:91], v[168:171], v[200:203], v[88:91]
	v_mfma_f32_16x16x32_bf16 v[72:75], v[168:171], v[208:211], v[72:75]
	v_mfma_f32_16x16x32_bf16 v[64:67], v[176:179], v[208:211], v[64:67]
	v_mfma_f32_16x16x32_bf16 v[80:83], v[176:179], v[200:203], v[80:83]
	v_mfma_f32_16x16x32_bf16 v[96:99], v[176:179], v[192:195], v[96:99]
	v_mfma_f32_16x16x32_bf16 v[112:115], v[176:179], v[184:187], v[112:115]
	v_mfma_f32_16x16x32_bf16 v[124:127], v[172:175], v[188:191], v[124:127]
	v_mfma_f32_16x16x32_bf16 v[104:107], v[172:175], v[196:199], v[104:107]
	v_mfma_f32_16x16x32_bf16 v[88:91], v[172:175], v[204:207], v[88:91]
	v_mfma_f32_16x16x32_bf16 v[72:75], v[172:175], v[212:215], v[72:75]
	v_mfma_f32_16x16x32_bf16 v[64:67], v[180:183], v[212:215], v[64:67]
	v_mfma_f32_16x16x32_bf16 v[80:83], v[180:183], v[204:207], v[80:83]
	v_mfma_f32_16x16x32_bf16 v[96:99], v[180:183], v[196:199], v[96:99]
	v_mfma_f32_16x16x32_bf16 v[112:115], v[180:183], v[188:191], v[112:115]
	s_setprio 0
	s_barrier
; #define PG8_STAGE(bufoff, gbase, voff) do { _Pragma("unroll") for (int _i = 0; _i < 2; ++_i) \
;         __builtin_amdgcn_global_load_lds((const unsigned*)((const char*)(gbase) + (voff)[_i]), (PG8_LAS unsigned*)(lds + (bufoff) + ldsw + _i * 8192), 16, 0, 0); } while (0)
; #define PG8_LDA(dst, b, h) do { _Pragma("unroll") for (int m = 0; m < 4; ++m) _Pragma("unroll") for (int k = 0; k < 2; ++k) dst[m][k] = *(const PG8_LAS bf16x8*)(lds + PG8_SA(b, h) + aoff + m * 2048 + k * 1024); } while (0)
; #define PG8_LDB(dst, b, h) do { _Pragma("unroll") for (int n = 0; n < 2; ++n) _Pragma("unroll") for (int k = 0; k < 2; ++k) dst[n][k] = *(const PG8_LAS bf16x8*)(lds + PG8_SB(b, h) + boff + n * 2048 + k * 1024); } while (0)
; #define PG8_MMA(ai, bj, At, Bt) do { __builtin_amdgcn_s_setprio(1); _Pragma("unroll") for (int m = 0; m < 4; ++m) _Pragma("unroll") for (int n = 0; n < 2; ++n) _Pragma("unroll") for (int k = 0; k < 2; ++k) \
;         acc[ai][bj][m][n] = __builtin_amdgcn_mfma_f32_16x16x32_bf16(Bt[n][k], At[m][k], acc[ai][bj][m][n], 0, 0, 0); __builtin_amdgcn_s_setprio(0); } while (0)
; #define PG8_WAIT_V(n) asm volatile("s_waitcnt vmcnt(" #n ")" ::: "memory")
; #define PG8_WAIT_L(n) asm volatile("s_waitcnt lgkmcnt(" #n ")" ::: "memory")
; #define PG8_BAR __builtin_amdgcn_s_barrier()
; #define PG8_SCHED __builtin_amdgcn_sched_barrier(0)
; template <class Epi, class Sched, bool ALIGN_EPI = false, bool SP2 = false>
; __device__ __forceinline__ void gemm_phase(PG8_LAS unsigned char* lds, const Gemm g, const Sched& S, const Epi& E) {
;     ...
;             PG8_LDB(B0, 0, 0); PG8_LDB(B1, 0, 1); PG8_SCHED; PG8_LDA(At, 0, 0); PG8_STAGE(PG8_SA(1, 1), a1 + hstep, voffA);
;             PG8_WAIT_V(8); PG8_WAIT_L(0); PG8_BAR; PG8_MMA(0, 0, At, B0); PG8_MMA(0, 1, At, B1); PG8_BAR; PG8_SCHED;
;     ...
;             PG8_LDA(At, 1, 1); PG8_STAGE(PG8_SB(1, 0), b3, voffB); PG8_STAGE(PG8_SB(1, 1), b3 + hstep, voffB); PG8_STAGE(PG8_SA(1, 0), a3, voffA);
;             PG8_WAIT_V(8); PG8_WAIT_L(0); PG8_BAR; PG8_MMA(1, 0, At, B0); PG8_MMA(1, 1, At, B1); PG8_BAR; PG8_SCHED;
	s_add_i32 s52, s59, s3
	v_lshl_add_u64 v[216:217], v[216:217], 0, s[44:45]
	s_mov_b32 m0, s52
	ds_read_b128 v[184:187], v150 offset:49152
	ds_read_b128 v[188:191], v150 offset:50176
	ds_read_b128 v[192:195], v150 offset:51200
	ds_read_b128 v[196:199], v150 offset:52224
	ds_read_b128 v[200:203], v150 offset:53248
	ds_read_b128 v[204:207], v150 offset:54272
	ds_read_b128 v[208:211], v150 offset:55296
	ds_read_b128 v[212:215], v150 offset:56320
	global_load_lds_dwordx4 v[216:217], off
	v_lshl_add_u64 v[216:217], v[218:219], 0, s[44:45]
	s_add_i32 m0, s52, 0x2000
	s_add_i32 s52, s60, s3
	global_load_lds_dwordx4 v[216:217], off
	v_lshl_add_u64 v[216:217], v[220:221], 0, s[44:45]
	s_mov_b32 m0, s52
	s_nop 0
	global_load_lds_dwordx4 v[216:217], off
	v_lshl_add_u64 v[216:217], v[222:223], 0, s[44:45]
	s_add_i32 m0, s52, 0x2000
	s_nop 0
	global_load_lds_dwordx4 v[216:217], off
	v_lshl_add_u64 v[216:217], v[224:225], 0, s[44:45]
	s_mov_b32 m0, s27
	s_nop 0
	global_load_lds_dwordx4 v[216:217], off
	v_lshl_add_u64 v[216:217], v[226:227], 0, s[44:45]
	s_mov_b32 m0, s30
	s_nop 0
	global_load_lds_dwordx4 v[216:217], off
	s_waitcnt vmcnt(8)
	s_waitcnt lgkmcnt(0)
	s_barrier
	s_setprio 1
	s_waitcnt lgkmcnt(0)
	v_mfma_f32_16x16x32_bf16 v[60:63], v[152:155], v[184:187], v[60:63]
	v_mfma_f32_16x16x32_bf16 v[44:47], v[152:155], v[192:195], v[44:47]
	v_mfma_f32_16x16x32_bf16 v[28:31], v[152:155], v[200:203], v[28:31]
	v_mfma_f32_16x16x32_bf16 v[12:15], v[152:155], v[208:211], v[12:15]
	v_mfma_f32_16x16x32_bf16 v[4:7], v[160:163], v[208:211], v[4:7]
	v_mfma_f32_16x16x32_bf16 v[20:23], v[160:163], v[200:203], v[20:23]
	v_mfma_f32_16x16x32_bf16 v[36:39], v[160:163], v[192:195], v[36:39]
	v_mfma_f32_16x16x32_bf16 v[52:55], v[160:163], v[184:187], v[52:55]
	v_mfma_f32_16x16x32_bf16 v[60:63], v[156:159], v[188:191], v[60:63]
	v_mfma_f32_16x16x32_bf16 v[44:47], v[156:159], v[196:199], v[44:47]
	v_mfma_f32_16x16x32_bf16 v[28:31], v[156:159], v[204:207], v[28:31]
	v_mfma_f32_16x16x32_bf16 v[12:15], v[156:159], v[212:215], v[12:15]
	v_mfma_f32_16x16x32_bf16 v[4:7], v[164:167], v[212:215], v[4:7]
	v_mfma_f32_16x16x32_bf16 v[20:23], v[164:167], v[204:207], v[20:23]
	v_mfma_f32_16x16x32_bf16 v[36:39], v[164:167], v[196:199], v[36:39]
	v_mfma_f32_16x16x32_bf16 v[52:55], v[164:167], v[188:191], v[52:55]
	s_setprio 0
	s_setprio 1
	v_mfma_f32_16x16x32_bf16 v[56:59], v[168:171], v[184:187], v[56:59]
	v_mfma_f32_16x16x32_bf16 v[40:43], v[168:171], v[192:195], v[40:43]
	v_mfma_f32_16x16x32_bf16 v[24:27], v[168:171], v[200:203], v[24:27]
	v_mfma_f32_16x16x32_bf16 v[8:11], v[168:171], v[208:211], v[8:11]
	v_mfma_f32_16x16x32_bf16 v[0:3], v[176:179], v[208:211], v[0:3]
	v_mfma_f32_16x16x32_bf16 v[16:19], v[176:179], v[200:203], v[16:19]
	v_mfma_f32_16x16x32_bf16 v[32:35], v[176:179], v[192:195], v[32:35]
	v_mfma_f32_16x16x32_bf16 v[48:51], v[176:179], v[184:187], v[48:51]
	v_mfma_f32_16x16x32_bf16 v[56:59], v[172:175], v[188:191], v[56:59]
	v_mfma_f32_16x16x32_bf16 v[40:43], v[172:175], v[196:199], v[40:43]
	v_mfma_f32_16x16x32_bf16 v[24:27], v[172:175], v[204:207], v[24:27]
	v_mfma_f32_16x16x32_bf16 v[8:11], v[172:175], v[212:215], v[8:11]
	v_mfma_f32_16x16x32_bf16 v[0:3], v[180:183], v[212:215], v[0:3]
	v_mfma_f32_16x16x32_bf16 v[16:19], v[180:183], v[204:207], v[16:19]
	v_mfma_f32_16x16x32_bf16 v[32:35], v[180:183], v[196:199], v[32:35]
	v_mfma_f32_16x16x32_bf16 v[48:51], v[180:183], v[188:191], v[48:51]
	s_setprio 0
	s_barrier
	s_add_u32 s50, s50, 0x100
	s_addc_u32 s51, s51, 0
	s_add_u32 s24, s24, 0x100
	s_addc_u32 s25, s25, 0
	s_cmp_ge_i32 s58, s31
	s_mov_b32 s52, s58
	s_cbranch_scc1 .Lpeelx_4
.LBB0_1323:
	ds_read_b128 v[152:155], v148
	ds_read_b128 v[156:159], v148 offset:1024
	ds_read_b128 v[160:163], v148 offset:2048
	ds_read_b128 v[164:167], v148 offset:3072
	ds_read_b128 v[168:171], v149
	ds_read_b128 v[172:175], v149 offset:1024
	ds_read_b128 v[176:179], v149 offset:2048
	ds_read_b128 v[180:183], v149 offset:3072
	s_add_i32 s58, s52, 2
	s_add_u32 s59, s50, 0x80
	s_addc_u32 s53, s51, 0
	s_cmp_eq_u32 s33, s52
	s_cselect_b32 s52, s14, s59
	s_cselect_b32 s53, s15, s53
	s_cselect_b32 s61, s49, s25
	s_cselect_b32 s60, s48, s24
	s_mov_b32 m0, s37
	v_lshl_add_u64 v[216:217], s[50:51], 0, v[136:137]
	ds_read_b128 v[184:187], v150
	ds_read_b128 v[188:191], v150 offset:1024
	ds_read_b128 v[192:195], v150 offset:2048
	ds_read_b128 v[196:199], v150 offset:3072
	ds_read_b128 v[200:203], v150 offset:4096
	ds_read_b128 v[204:207], v150 offset:5120
	ds_read_b128 v[208:211], v150 offset:6144
	ds_read_b128 v[212:215], v150 offset:7168
	global_load_lds_dwordx4 v[216:217], off
	v_lshl_add_u64 v[216:217], s[50:51], 0, v[138:139]
	s_mov_b32 m0, s38
	s_nop 0
	global_load_lds_dwordx4 v[216:217], off
	s_waitcnt vmcnt(8)
	s_waitcnt lgkmcnt(0)
	s_barrier
; #define PG8_STAGE(bufoff, gbase, voff) do { _Pragma("unroll") for (int _i = 0; _i < 2; ++_i) \
;         __builtin_amdgcn_global_load_lds((const unsigned*)((const char*)(gbase) + (voff)[_i]), (PG8_LAS unsigned*)(lds + (bufoff) + ldsw + _i * 8192), 16, 0, 0); } while (0)
; #define PG8_LDA(dst, b, h) do { _Pragma("unroll") for (int m = 0; m < 4; ++m) _Pragma("unroll") for (int k = 0; k < 2; ++k) dst[m][k] = *(const PG8_LAS bf16x8*)(lds + PG8_SA(b, h) + aoff + m * 2048 + k * 1024); } while (0)
; #define PG8_MMA(ai, bj, At, Bt) do { __builtin_amdgcn_s_setprio(1); _Pragma("unroll") for (int m = 0; m < 4; ++m) _Pragma("unroll") for (int n = 0; n < 2; ++n) _Pragma("unroll") for (int k = 0; k < 2; ++k) \
;         acc[ai][bj][m][n] = __builtin_amdgcn_mfma_f32_16x16x32_bf16(Bt[n][k], At[m][k], acc[ai][bj][m][n], 0, 0, 0); __builtin_amdgcn_s_setprio(0); } while (0)
; #define PG8_WAIT_V(n) asm volatile("s_waitcnt vmcnt(" #n ")" ::: "memory")
; #define PG8_WAIT_L(n) asm volatile("s_waitcnt lgkmcnt(" #n ")" ::: "memory")
; #define PG8_BAR __builtin_amdgcn_s_barrier()
; #define PG8_SCHED __builtin_amdgcn_sched_barrier(0)
; template <class Epi, class Sched, bool ALIGN_EPI = false, bool SP2 = false>
; __device__ __forceinline__ void gemm_phase(PG8_LAS unsigned char* lds, const Gemm g, const Sched& S, const Epi& E) {
;     ...
;             PG8_WAIT_V(8); PG8_WAIT_L(0); PG8_BAR; PG8_MMA(0, 0, At, B0); PG8_MMA(0, 1, At, B1); PG8_BAR; PG8_SCHED;
;             PG8_LDA(At, 0, 1); PG8_STAGE(PG8_SB(0, 0), b2, voffB); PG8_STAGE(PG8_SB(0, 1), b2 + hstep, voffB); PG8_STAGE(PG8_SA(0, 0), a2, voffA);
;             PG8_WAIT_V(8); PG8_WAIT_L(0); PG8_BAR; PG8_MMA(1, 0, At, B0); PG8_MMA(1, 1, At, B1); PG8_BAR; PG8_SCHED;
	s_setprio 1
	s_waitcnt lgkmcnt(0)
	v_mfma_f32_16x16x32_bf16 v[120:123], v[152:155], v[184:187], v[120:123]
	v_mfma_f32_16x16x32_bf16 v[108:111], v[152:155], v[192:195], v[108:111]
	v_mfma_f32_16x16x32_bf16 v[92:95], v[152:155], v[200:203], v[92:95]
	v_mfma_f32_16x16x32_bf16 v[76:79], v[152:155], v[208:211], v[76:79]
	v_mfma_f32_16x16x32_bf16 v[68:71], v[160:163], v[208:211], v[68:71]
	v_mfma_f32_16x16x32_bf16 v[84:87], v[160:163], v[200:203], v[84:87]
	v_mfma_f32_16x16x32_bf16 v[100:103], v[160:163], v[192:195], v[100:103]
	v_mfma_f32_16x16x32_bf16 v[116:119], v[160:163], v[184:187], v[116:119]
	v_mfma_f32_16x16x32_bf16 v[120:123], v[156:159], v[188:191], v[120:123]
	v_mfma_f32_16x16x32_bf16 v[108:111], v[156:159], v[196:199], v[108:111]
	v_mfma_f32_16x16x32_bf16 v[92:95], v[156:159], v[204:207], v[92:95]
	v_mfma_f32_16x16x32_bf16 v[76:79], v[156:159], v[212:215], v[76:79]
	v_mfma_f32_16x16x32_bf16 v[68:71], v[164:167], v[212:215], v[68:71]
	v_mfma_f32_16x16x32_bf16 v[84:87], v[164:167], v[204:207], v[84:87]
	v_mfma_f32_16x16x32_bf16 v[100:103], v[164:167], v[196:199], v[100:103]
	v_mfma_f32_16x16x32_bf16 v[116:119], v[164:167], v[188:191], v[116:119]
	s_setprio 0
	s_setprio 1
	v_mfma_f32_16x16x32_bf16 v[124:127], v[168:171], v[184:187], v[124:127]
	v_mfma_f32_16x16x32_bf16 v[104:107], v[168:171], v[192:195], v[104:107]
	v_mfma_f32_16x16x32_bf16 v[88:91], v[168:171], v[200:203], v[88:91]
	v_mfma_f32_16x16x32_bf16 v[72:75], v[168:171], v[208:211], v[72:75]
	v_mfma_f32_16x16x32_bf16 v[64:67], v[176:179], v[208:211], v[64:67]
	v_mfma_f32_16x16x32_bf16 v[80:83], v[176:179], v[200:203], v[80:83]
	v_mfma_f32_16x16x32_bf16 v[96:99], v[176:179], v[192:195], v[96:99]
	v_mfma_f32_16x16x32_bf16 v[112:115], v[176:179], v[184:187], v[112:115]
	v_mfma_f32_16x16x32_bf16 v[124:127], v[172:175], v[188:191], v[124:127]
	v_mfma_f32_16x16x32_bf16 v[104:107], v[172:175], v[196:199], v[104:107]
	v_mfma_f32_16x16x32_bf16 v[88:91], v[172:175], v[204:207], v[88:91]
	v_mfma_f32_16x16x32_bf16 v[72:75], v[172:175], v[212:215], v[72:75]
	v_mfma_f32_16x16x32_bf16 v[64:67], v[180:183], v[212:215], v[64:67]
	v_mfma_f32_16x16x32_bf16 v[80:83], v[180:183], v[204:207], v[80:83]
	v_mfma_f32_16x16x32_bf16 v[96:99], v[180:183], v[196:199], v[96:99]
	v_mfma_f32_16x16x32_bf16 v[112:115], v[180:183], v[188:191], v[112:115]
	s_setprio 0
	s_barrier
	s_add_i32 s59, s34, s3
	v_lshl_add_u64 v[216:217], s[60:61], 0, v[132:133]
	s_mov_b32 m0, s59
	ds_read_b128 v[184:187], v150 offset:16384
	ds_read_b128 v[188:191], v150 offset:17408
	ds_read_b128 v[192:195], v150 offset:18432
	ds_read_b128 v[196:199], v150 offset:19456
	ds_read_b128 v[200:203], v150 offset:20480
	ds_read_b128 v[204:207], v150 offset:21504
	ds_read_b128 v[208:211], v150 offset:22528
	ds_read_b128 v[212:215], v150 offset:23552
	global_load_lds_dwordx4 v[216:217], off
	s_add_i32 m0, s59, 0x2000
	v_lshl_add_u64 v[218:219], s[60:61], 0, v[128:129]
	s_add_u32 s60, s60, s16
	s_addc_u32 s61, s61, s17
	s_add_i32 s59, s35, s3
	global_load_lds_dwordx4 v[218:219], off
	v_lshl_add_u64 v[220:221], s[60:61], 0, v[132:133]
	s_mov_b32 m0, s59
	v_lshl_add_u64 v[222:223], s[60:61], 0, v[128:129]
	global_load_lds_dwordx4 v[220:221], off
	s_add_i32 m0, s59, 0x2000
	v_lshl_add_u64 v[224:225], s[52:53], 0, v[134:135]
	global_load_lds_dwordx4 v[222:223], off
	s_mov_b32 m0, s7
	v_lshl_add_u64 v[226:227], s[52:53], 0, v[130:131]
	global_load_lds_dwordx4 v[224:225], off
	s_mov_b32 m0, s18
	s_nop 0
	global_load_lds_dwordx4 v[226:227], off
	s_waitcnt vmcnt(8)
	s_waitcnt lgkmcnt(0)
	s_barrier
	s_setprio 1
	s_waitcnt lgkmcnt(0)
	v_mfma_f32_16x16x32_bf16 v[60:63], v[152:155], v[184:187], v[60:63]
	v_mfma_f32_16x16x32_bf16 v[44:47], v[152:155], v[192:195], v[44:47]
	v_mfma_f32_16x16x32_bf16 v[28:31], v[152:155], v[200:203], v[28:31]
	v_mfma_f32_16x16x32_bf16 v[12:15], v[152:155], v[208:211], v[12:15]
	v_mfma_f32_16x16x32_bf16 v[4:7], v[160:163], v[208:211], v[4:7]
	v_mfma_f32_16x16x32_bf16 v[20:23], v[160:163], v[200:203], v[20:23]
	v_mfma_f32_16x16x32_bf16 v[36:39], v[160:163], v[192:195], v[36:39]
	v_mfma_f32_16x16x32_bf16 v[52:55], v[160:163], v[184:187], v[52:55]
	v_mfma_f32_16x16x32_bf16 v[60:63], v[156:159], v[188:191], v[60:63]
	v_mfma_f32_16x16x32_bf16 v[44:47], v[156:159], v[196:199], v[44:47]
	v_mfma_f32_16x16x32_bf16 v[28:31], v[156:159], v[204:207], v[28:31]
	v_mfma_f32_16x16x32_bf16 v[12:15], v[156:159], v[212:215], v[12:15]
	v_mfma_f32_16x16x32_bf16 v[4:7], v[164:167], v[212:215], v[4:7]
	v_mfma_f32_16x16x32_bf16 v[20:23], v[164:167], v[204:207], v[20:23]
	v_mfma_f32_16x16x32_bf16 v[36:39], v[164:167], v[196:199], v[36:39]
	v_mfma_f32_16x16x32_bf16 v[52:55], v[164:167], v[188:191], v[52:55]
	s_setprio 0
	s_setprio 1
	v_mfma_f32_16x16x32_bf16 v[56:59], v[168:171], v[184:187], v[56:59]
	v_mfma_f32_16x16x32_bf16 v[40:43], v[168:171], v[192:195], v[40:43]
	v_mfma_f32_16x16x32_bf16 v[24:27], v[168:171], v[200:203], v[24:27]
	v_mfma_f32_16x16x32_bf16 v[8:11], v[168:171], v[208:211], v[8:11]
	v_mfma_f32_16x16x32_bf16 v[0:3], v[176:179], v[208:211], v[0:3]
	v_mfma_f32_16x16x32_bf16 v[16:19], v[176:179], v[200:203], v[16:19]
	v_mfma_f32_16x16x32_bf16 v[32:35], v[176:179], v[192:195], v[32:35]
	v_mfma_f32_16x16x32_bf16 v[48:51], v[176:179], v[184:187], v[48:51]
	v_mfma_f32_16x16x32_bf16 v[56:59], v[172:175], v[188:191], v[56:59]
	v_mfma_f32_16x16x32_bf16 v[40:43], v[172:175], v[196:199], v[40:43]
	v_mfma_f32_16x16x32_bf16 v[24:27], v[172:175], v[204:207], v[24:27]
	v_mfma_f32_16x16x32_bf16 v[8:11], v[172:175], v[212:215], v[8:11]
	v_mfma_f32_16x16x32_bf16 v[0:3], v[180:183], v[212:215], v[0:3]
	v_mfma_f32_16x16x32_bf16 v[16:19], v[180:183], v[204:207], v[16:19]
	v_mfma_f32_16x16x32_bf16 v[32:35], v[180:183], v[196:199], v[32:35]
	v_mfma_f32_16x16x32_bf16 v[48:51], v[180:183], v[188:191], v[48:51]
	s_setprio 0
	s_barrier
; #define PG8_STAGE(bufoff, gbase, voff) do { _Pragma("unroll") for (int _i = 0; _i < 2; ++_i) \
;         __builtin_amdgcn_global_load_lds((const unsigned*)((const char*)(gbase) + (voff)[_i]), (PG8_LAS unsigned*)(lds + (bufoff) + ldsw + _i * 8192), 16, 0, 0); } while (0)
; #define PG8_LDA(dst, b, h) do { _Pragma("unroll") for (int m = 0; m < 4; ++m) _Pragma("unroll") for (int k = 0; k < 2; ++k) dst[m][k] = *(const PG8_LAS bf16x8*)(lds + PG8_SA(b, h) + aoff + m * 2048 + k * 1024); } while (0)
; #define PG8_LDB(dst, b, h) do { _Pragma("unroll") for (int n = 0; n < 2; ++n) _Pragma("unroll") for (int k = 0; k < 2; ++k) dst[n][k] = *(const PG8_LAS bf16x8*)(lds + PG8_SB(b, h) + boff + n * 2048 + k * 1024); } while (0)
; #define PG8_MMA(ai, bj, At, Bt) do { __builtin_amdgcn_s_setprio(1); _Pragma("unroll") for (int m = 0; m < 4; ++m) _Pragma("unroll") for (int n = 0; n < 2; ++n) _Pragma("unroll") for (int k = 0; k < 2; ++k) \
;         acc[ai][bj][m][n] = __builtin_amdgcn_mfma_f32_16x16x32_bf16(Bt[n][k], At[m][k], acc[ai][bj][m][n], 0, 0, 0); __builtin_amdgcn_s_setprio(0); } while (0)
; #define PG8_WAIT_V(n) asm volatile("s_waitcnt vmcnt(" #n ")" ::: "memory")
; #define PG8_WAIT_L(n) asm volatile("s_waitcnt lgkmcnt(" #n ")" ::: "memory")
; #define PG8_BAR __builtin_amdgcn_s_barrier()
; #define PG8_SCHED __builtin_amdgcn_sched_barrier(0)
; template <class Epi, class Sched, bool ALIGN_EPI = false, bool SP2 = false>
; __device__ __forceinline__ void gemm_phase(PG8_LAS unsigned char* lds, const Gemm g, const Sched& S, const Epi& E) {
;     ...
;             PG8_LDB(B0, 1, 0); PG8_LDB(B1, 1, 1); PG8_SCHED; PG8_LDA(At, 1, 0); PG8_STAGE(PG8_SA(0, 1), a2 + hstep, voffA);
;             PG8_WAIT_V(8); PG8_WAIT_L(0); PG8_BAR; PG8_MMA(0, 0, At, B0); PG8_MMA(0, 1, At, B1); PG8_BAR; PG8_SCHED;
	s_add_i32 s59, 0, 0x18000
	v_add_u32_e32 v151, s59, v145
	s_add_i32 s60, 0, 0x1c000
	ds_read_b128 v[152:155], v151
	ds_read_b128 v[156:159], v151 offset:1024
	ds_read_b128 v[160:163], v151 offset:2048
	ds_read_b128 v[164:167], v151 offset:3072
	v_add_u32_e32 v151, s60, v145
	ds_read_b128 v[168:171], v151
	ds_read_b128 v[172:175], v151 offset:1024
	ds_read_b128 v[176:179], v151 offset:2048
	ds_read_b128 v[180:183], v151 offset:3072
	s_add_u32 s52, s52, s16
	s_addc_u32 s53, s53, s17
	s_mov_b32 m0, s19
	v_lshl_add_u64 v[228:229], s[52:53], 0, v[134:135]
	ds_read_b128 v[184:187], v150 offset:32768
	ds_read_b128 v[188:191], v150 offset:33792
	ds_read_b128 v[192:195], v150 offset:34816
	ds_read_b128 v[196:199], v150 offset:35840
	ds_read_b128 v[200:203], v150 offset:36864
	ds_read_b128 v[204:207], v150 offset:37888
	ds_read_b128 v[208:211], v150 offset:38912
	ds_read_b128 v[212:215], v150 offset:39936
	global_load_lds_dwordx4 v[228:229], off
	v_lshl_add_u64 v[228:229], s[52:53], 0, v[130:131]
	s_mov_b32 m0, s26
	s_nop 0
	global_load_lds_dwordx4 v[228:229], off
	s_waitcnt vmcnt(8)
	s_waitcnt lgkmcnt(0)
	s_barrier
	s_setprio 1
	s_waitcnt lgkmcnt(0)
	v_mfma_f32_16x16x32_bf16 v[120:123], v[152:155], v[184:187], v[120:123]
	v_mfma_f32_16x16x32_bf16 v[108:111], v[152:155], v[192:195], v[108:111]
	v_mfma_f32_16x16x32_bf16 v[92:95], v[152:155], v[200:203], v[92:95]
	v_mfma_f32_16x16x32_bf16 v[76:79], v[152:155], v[208:211], v[76:79]
	v_mfma_f32_16x16x32_bf16 v[68:71], v[160:163], v[208:211], v[68:71]
	v_mfma_f32_16x16x32_bf16 v[84:87], v[160:163], v[200:203], v[84:87]
	v_mfma_f32_16x16x32_bf16 v[100:103], v[160:163], v[192:195], v[100:103]
	v_mfma_f32_16x16x32_bf16 v[116:119], v[160:163], v[184:187], v[116:119]
	v_mfma_f32_16x16x32_bf16 v[120:123], v[156:159], v[188:191], v[120:123]
	v_mfma_f32_16x16x32_bf16 v[108:111], v[156:159], v[196:199], v[108:111]
	v_mfma_f32_16x16x32_bf16 v[92:95], v[156:159], v[204:207], v[92:95]
	v_mfma_f32_16x16x32_bf16 v[76:79], v[156:159], v[212:215], v[76:79]
	v_mfma_f32_16x16x32_bf16 v[68:71], v[164:167], v[212:215], v[68:71]
	v_mfma_f32_16x16x32_bf16 v[84:87], v[164:167], v[204:207], v[84:87]
	v_mfma_f32_16x16x32_bf16 v[100:103], v[164:167], v[196:199], v[100:103]
	v_mfma_f32_16x16x32_bf16 v[116:119], v[164:167], v[188:191], v[116:119]
	s_setprio 0
	s_setprio 1
	v_mfma_f32_16x16x32_bf16 v[124:127], v[168:171], v[184:187], v[124:127]
	v_mfma_f32_16x16x32_bf16 v[104:107], v[168:171], v[192:195], v[104:107]
	v_mfma_f32_16x16x32_bf16 v[88:91], v[168:171], v[200:203], v[88:91]
	v_mfma_f32_16x16x32_bf16 v[72:75], v[168:171], v[208:211], v[72:75]
	v_mfma_f32_16x16x32_bf16 v[64:67], v[176:179], v[208:211], v[64:67]
	v_mfma_f32_16x16x32_bf16 v[80:83], v[176:179], v[200:203], v[80:83]
	v_mfma_f32_16x16x32_bf16 v[96:99], v[176:179], v[192:195], v[96:99]
	v_mfma_f32_16x16x32_bf16 v[112:115], v[176:179], v[184:187], v[112:115]
	v_mfma_f32_16x16x32_bf16 v[124:127], v[172:175], v[188:191], v[124:127]
	v_mfma_f32_16x16x32_bf16 v[104:107], v[172:175], v[196:199], v[104:107]
	v_mfma_f32_16x16x32_bf16 v[88:91], v[172:175], v[204:207], v[88:91]
	v_mfma_f32_16x16x32_bf16 v[72:75], v[172:175], v[212:215], v[72:75]
	v_mfma_f32_16x16x32_bf16 v[64:67], v[180:183], v[212:215], v[64:67]
	v_mfma_f32_16x16x32_bf16 v[80:83], v[180:183], v[204:207], v[80:83]
	v_mfma_f32_16x16x32_bf16 v[96:99], v[180:183], v[196:199], v[96:99]
	v_mfma_f32_16x16x32_bf16 v[112:115], v[180:183], v[188:191], v[112:115]
	s_setprio 0
	s_barrier
; #define PG8_STAGE(bufoff, gbase, voff) do { _Pragma("unroll") for (int _i = 0; _i < 2; ++_i) \
;         __builtin_amdgcn_global_load_lds((const unsigned*)((const char*)(gbase) + (voff)[_i]), (PG8_LAS unsigned*)(lds + (bufoff) + ldsw + _i * 8192), 16, 0, 0); } while (0)
; #define PG8_LDA(dst, b, h) do { _Pragma("unroll") for (int m = 0; m < 4; ++m) _Pragma("unroll") for (int k = 0; k < 2; ++k) dst[m][k] = *(const PG8_LAS bf16x8*)(lds + PG8_SA(b, h) + aoff + m * 2048 + k * 1024); } while (0)
; #define PG8_MMA(ai, bj, At, Bt) do { __builtin_amdgcn_s_setprio(1); _Pragma("unroll") for (int m = 0; m < 4; ++m) _Pragma("unroll") for (int n = 0; n < 2; ++n) _Pragma("unroll") for (int k = 0; k < 2; ++k) \
;         acc[ai][bj][m][n] = __builtin_amdgcn_mfma_f32_16x16x32_bf16(Bt[n][k], At[m][k], acc[ai][bj][m][n], 0, 0, 0); __builtin_amdgcn_s_setprio(0); } while (0)
; #define PG8_WAIT_V(n) asm volatile("s_waitcnt vmcnt(" #n ")" ::: "memory")
; #define PG8_WAIT_L(n) asm volatile("s_waitcnt lgkmcnt(" #n ")" ::: "memory")
; #define PG8_BAR __builtin_amdgcn_s_barrier()
; #define PG8_SCHED __builtin_amdgcn_sched_barrier(0)
; template <class Epi, class Sched, bool ALIGN_EPI = false, bool SP2 = false>
; __device__ __forceinline__ void gemm_phase(PG8_LAS unsigned char* lds, const Gemm g, const Sched& S, const Epi& E) {
;     ...
;             PG8_LDA(At, 1, 1); PG8_STAGE(PG8_SB(1, 0), b3, voffB); PG8_STAGE(PG8_SB(1, 1), b3 + hstep, voffB); PG8_STAGE(PG8_SA(1, 0), a3, voffA);
;             PG8_WAIT_V(8); PG8_WAIT_L(0); PG8_BAR; PG8_MMA(1, 0, At, B0); PG8_MMA(1, 1, At, B1); PG8_BAR; PG8_SCHED;
	s_add_i32 s52, s59, s3
	v_lshl_add_u64 v[216:217], v[216:217], 0, s[44:45]
	s_mov_b32 m0, s52
	ds_read_b128 v[184:187], v150 offset:49152
	ds_read_b128 v[188:191], v150 offset:50176
	ds_read_b128 v[192:195], v150 offset:51200
	ds_read_b128 v[196:199], v150 offset:52224
	ds_read_b128 v[200:203], v150 offset:53248
	ds_read_b128 v[204:207], v150 offset:54272
	ds_read_b128 v[208:211], v150 offset:55296
	ds_read_b128 v[212:215], v150 offset:56320
	global_load_lds_dwordx4 v[216:217], off
	v_lshl_add_u64 v[216:217], v[218:219], 0, s[44:45]
	s_add_i32 m0, s52, 0x2000
	s_add_i32 s52, s60, s3
	global_load_lds_dwordx4 v[216:217], off
	v_lshl_add_u64 v[216:217], v[220:221], 0, s[44:45]
	s_mov_b32 m0, s52
	s_nop 0
	global_load_lds_dwordx4 v[216:217], off
	v_lshl_add_u64 v[216:217], v[222:223], 0, s[44:45]
	s_add_i32 m0, s52, 0x2000
	s_nop 0
	global_load_lds_dwordx4 v[216:217], off
	v_lshl_add_u64 v[216:217], v[224:225], 0, s[44:45]
	s_mov_b32 m0, s27
	s_nop 0
	global_load_lds_dwordx4 v[216:217], off
	v_lshl_add_u64 v[216:217], v[226:227], 0, s[44:45]
	s_mov_b32 m0, s30
	s_nop 0
	global_load_lds_dwordx4 v[216:217], off
	s_waitcnt vmcnt(8)
	s_waitcnt lgkmcnt(0)
	s_barrier
	s_setprio 1
	s_waitcnt lgkmcnt(0)
	v_mfma_f32_16x16x32_bf16 v[60:63], v[152:155], v[184:187], v[60:63]
	v_mfma_f32_16x16x32_bf16 v[44:47], v[152:155], v[192:195], v[44:47]
	v_mfma_f32_16x16x32_bf16 v[28:31], v[152:155], v[200:203], v[28:31]
	v_mfma_f32_16x16x32_bf16 v[12:15], v[152:155], v[208:211], v[12:15]
	v_mfma_f32_16x16x32_bf16 v[4:7], v[160:163], v[208:211], v[4:7]
	v_mfma_f32_16x16x32_bf16 v[20:23], v[160:163], v[200:203], v[20:23]
	v_mfma_f32_16x16x32_bf16 v[36:39], v[160:163], v[192:195], v[36:39]
	v_mfma_f32_16x16x32_bf16 v[52:55], v[160:163], v[184:187], v[52:55]
	v_mfma_f32_16x16x32_bf16 v[60:63], v[156:159], v[188:191], v[60:63]
	v_mfma_f32_16x16x32_bf16 v[44:47], v[156:159], v[196:199], v[44:47]
	v_mfma_f32_16x16x32_bf16 v[28:31], v[156:159], v[204:207], v[28:31]
	v_mfma_f32_16x16x32_bf16 v[12:15], v[156:159], v[212:215], v[12:15]
	v_mfma_f32_16x16x32_bf16 v[4:7], v[164:167], v[212:215], v[4:7]
	v_mfma_f32_16x16x32_bf16 v[20:23], v[164:167], v[204:207], v[20:23]
	v_mfma_f32_16x16x32_bf16 v[36:39], v[164:167], v[196:199], v[36:39]
	v_mfma_f32_16x16x32_bf16 v[52:55], v[164:167], v[188:191], v[52:55]
	s_setprio 0
	s_setprio 1
	v_mfma_f32_16x16x32_bf16 v[56:59], v[168:171], v[184:187], v[56:59]
	v_mfma_f32_16x16x32_bf16 v[40:43], v[168:171], v[192:195], v[40:43]
	v_mfma_f32_16x16x32_bf16 v[24:27], v[168:171], v[200:203], v[24:27]
	v_mfma_f32_16x16x32_bf16 v[8:11], v[168:171], v[208:211], v[8:11]
	v_mfma_f32_16x16x32_bf16 v[0:3], v[176:179], v[208:211], v[0:3]
	v_mfma_f32_16x16x32_bf16 v[16:19], v[176:179], v[200:203], v[16:19]
	v_mfma_f32_16x16x32_bf16 v[32:35], v[176:179], v[192:195], v[32:35]
	v_mfma_f32_16x16x32_bf16 v[48:51], v[176:179], v[184:187], v[48:51]
	v_mfma_f32_16x16x32_bf16 v[56:59], v[172:175], v[188:191], v[56:59]
	v_mfma_f32_16x16x32_bf16 v[40:43], v[172:175], v[196:199], v[40:43]
	v_mfma_f32_16x16x32_bf16 v[24:27], v[172:175], v[204:207], v[24:27]
	v_mfma_f32_16x16x32_bf16 v[8:11], v[172:175], v[212:215], v[8:11]
	v_mfma_f32_16x16x32_bf16 v[0:3], v[180:183], v[212:215], v[0:3]
	v_mfma_f32_16x16x32_bf16 v[16:19], v[180:183], v[204:207], v[16:19]
	v_mfma_f32_16x16x32_bf16 v[32:35], v[180:183], v[196:199], v[32:35]
	v_mfma_f32_16x16x32_bf16 v[48:51], v[180:183], v[188:191], v[48:51]
	s_setprio 0
	s_barrier
	s_add_u32 s50, s50, 0x100
	s_addc_u32 s51, s51, 0
	s_add_u32 s24, s24, 0x100
	s_addc_u32 s25, s25, 0
	s_cmp_ge_i32 s58, s31
	s_mov_b32 s52, s58
	s_cbranch_scc0 .LBB0_1323

; #define PG8_STAGE(bufoff, gbase, voff) do { _Pragma("unroll") for (int _i = 0; _i < 2; ++_i) \
;         __builtin_amdgcn_global_load_lds((const unsigned*)((const char*)(gbase) + (voff)[_i]), (PG8_LAS unsigned*)(lds + (bufoff) + ldsw + _i * 8192), 16, 0, 0); } while (0)
; #define PG8_LDA(dst, b, h) do { _Pragma("unroll") for (int m = 0; m < 4; ++m) _Pragma("unroll") for (int k = 0; k < 2; ++k) dst[m][k] = *(const PG8_LAS bf16x8*)(lds + PG8_SA(b, h) + aoff + m * 2048 + k * 1024); } while (0)
; #define PG8_LDB(dst, b, h) do { _Pragma("unroll") for (int n = 0; n < 2; ++n) _Pragma("unroll") for (int k = 0; k < 2; ++k) dst[n][k] = *(const PG8_LAS bf16x8*)(lds + PG8_SB(b, h) + boff + n * 2048 + k * 1024); } while (0)
; #define PG8_MMA(ai, bj, At, Bt) do { __builtin_amdgcn_s_setprio(1); _Pragma("unroll") for (int m = 0; m < 4; ++m) _Pragma("unroll") for (int n = 0; n < 2; ++n) _Pragma("unroll") for (int k = 0; k < 2; ++k) \
;         acc[ai][bj][m][n] = __builtin_amdgcn_mfma_f32_16x16x32_bf16(Bt[n][k], At[m][k], acc[ai][bj][m][n], 0, 0, 0); __builtin_amdgcn_s_setprio(0); } while (0)
; #define PG8_WAIT_V(n) asm volatile("s_waitcnt vmcnt(" #n ")" ::: "memory")
; #define PG8_WAIT_L(n) asm volatile("s_waitcnt lgkmcnt(" #n ")" ::: "memory")
; #define PG8_BAR __builtin_amdgcn_s_barrier()
; #define PG8_SCHED __builtin_amdgcn_sched_barrier(0)
; template <class Epi, class Sched, bool ALIGN_EPI = false, bool SP2 = false>
; __device__ __forceinline__ void gemm_phase(PG8_LAS unsigned char* lds, const Gemm g, const Sched& S, const Epi& E) {
;     ...
;             PG8_LDB(B0, 0, 0); PG8_LDB(B1, 0, 1); PG8_SCHED; PG8_LDA(At, 0, 0); PG8_STAGE(PG8_SA(1, 1), a1 + hstep, voffA);
;             PG8_WAIT_V(8); PG8_WAIT_L(0); PG8_BAR; PG8_MMA(0, 0, At, B0); PG8_MMA(0, 1, At, B1); PG8_BAR; PG8_SCHED;
;             PG8_LDA(At, 0, 1); PG8_STAGE(PG8_SB(0, 0), b2, voffB); PG8_STAGE(PG8_SB(0, 1), b2 + hstep, voffB); PG8_STAGE(PG8_SA(0, 0), a2, voffA);
;             PG8_WAIT_V(8); PG8_WAIT_L(0); PG8_BAR; PG8_MMA(1, 0, At, B0); PG8_MMA(1, 1, At, B1); PG8_BAR; PG8_SCHED;
.LBB0_1404:
	s_and_b64 vcc, exec, s[12:13]
	s_cbranch_vccnz .Lcoldz_5
	s_add_u32 s56, s56, 0x80
	s_addc_u32 s57, s57, 0
	s_add_u32 s2, s58, 0x100
	s_addc_u32 s24, s59, 0
	s_mov_b32 s25, 0
	ds_read_b128 v[142:145], v246
	ds_read_b128 v[146:149], v246 offset:1024
	ds_read_b128 v[150:153], v246 offset:2048
	ds_read_b128 v[154:157], v246 offset:3072
	ds_read_b128 v[158:161], v247
	ds_read_b128 v[162:165], v247 offset:1024
	ds_read_b128 v[166:169], v247 offset:2048
	ds_read_b128 v[170:173], v247 offset:3072
	s_add_i32 s60, s25, 2
	s_add_u32 s58, s56, 0x80
	s_addc_u32 s59, s57, 0
	s_cmp_eq_u32 s34, s25
	s_cselect_b32 s59, s17, s59
	s_cselect_b32 s58, s16, s58
	s_cselect_b32 s63, s55, s24
	s_cselect_b32 s62, s54, s2
	v_lshl_add_u64 v[206:207], s[56:57], 0, v[136:137]
	s_add_i32 m0, s7, 0xc000
	ds_read_b128 v[174:177], v248
	ds_read_b128 v[178:181], v248 offset:1024
	ds_read_b128 v[182:185], v248 offset:2048
	ds_read_b128 v[186:189], v248 offset:3072
	ds_read_b128 v[190:193], v248 offset:4096
	ds_read_b128 v[194:197], v248 offset:5120
	ds_read_b128 v[198:201], v248 offset:6144
	ds_read_b128 v[202:205], v248 offset:7168
	global_load_lds_dwordx4 v[206:207], off
	v_lshl_add_u64 v[206:207], s[56:57], 0, v[138:139]
	s_add_i32 m0, s7, 0xe000
	s_nop 0
	global_load_lds_dwordx4 v[206:207], off
	s_waitcnt vmcnt(8)
	s_waitcnt lgkmcnt(0)
	s_barrier
	s_setprio 1
	s_waitcnt lgkmcnt(0)
	v_mfma_f32_16x16x32_bf16 v[124:127], v[142:145], v[174:177], 0
	v_mfma_f32_16x16x32_bf16 v[120:123], v[150:153], v[174:177], 0
	v_mfma_f32_16x16x32_bf16 v[116:119], v[142:145], v[182:185], 0
	v_mfma_f32_16x16x32_bf16 v[112:115], v[150:153], v[182:185], 0
	v_mfma_f32_16x16x32_bf16 v[104:107], v[142:145], v[190:193], 0
	v_mfma_f32_16x16x32_bf16 v[96:99], v[150:153], v[190:193], 0
	v_mfma_f32_16x16x32_bf16 v[88:91], v[142:145], v[198:201], 0
	v_mfma_f32_16x16x32_bf16 v[80:83], v[150:153], v[198:201], 0
	v_mfma_f32_16x16x32_bf16 v[124:127], v[146:149], v[178:181], v[124:127]
	v_mfma_f32_16x16x32_bf16 v[116:119], v[146:149], v[186:189], v[116:119]
	v_mfma_f32_16x16x32_bf16 v[104:107], v[146:149], v[194:197], v[104:107]
	v_mfma_f32_16x16x32_bf16 v[88:91], v[146:149], v[202:205], v[88:91]
	v_mfma_f32_16x16x32_bf16 v[80:83], v[154:157], v[202:205], v[80:83]
	v_mfma_f32_16x16x32_bf16 v[96:99], v[154:157], v[194:197], v[96:99]
	v_mfma_f32_16x16x32_bf16 v[112:115], v[154:157], v[186:189], v[112:115]
	v_mfma_f32_16x16x32_bf16 v[120:123], v[154:157], v[178:181], v[120:123]
	s_setprio 0
	s_setprio 1
	v_mfma_f32_16x16x32_bf16 v[108:111], v[158:161], v[174:177], 0
	v_mfma_f32_16x16x32_bf16 v[100:103], v[166:169], v[174:177], 0
	v_mfma_f32_16x16x32_bf16 v[92:95], v[158:161], v[182:185], 0
	v_mfma_f32_16x16x32_bf16 v[84:87], v[166:169], v[182:185], 0
	v_mfma_f32_16x16x32_bf16 v[76:79], v[158:161], v[190:193], 0
	v_mfma_f32_16x16x32_bf16 v[72:75], v[166:169], v[190:193], 0
	v_mfma_f32_16x16x32_bf16 v[68:71], v[158:161], v[198:201], 0
	v_mfma_f32_16x16x32_bf16 v[64:67], v[166:169], v[198:201], 0
	v_mfma_f32_16x16x32_bf16 v[108:111], v[162:165], v[178:181], v[108:111]
	v_mfma_f32_16x16x32_bf16 v[92:95], v[162:165], v[186:189], v[92:95]
	v_mfma_f32_16x16x32_bf16 v[76:79], v[162:165], v[194:197], v[76:79]
	v_mfma_f32_16x16x32_bf16 v[68:71], v[162:165], v[202:205], v[68:71]
	v_mfma_f32_16x16x32_bf16 v[64:67], v[170:173], v[202:205], v[64:67]
	v_mfma_f32_16x16x32_bf16 v[72:75], v[170:173], v[194:197], v[72:75]
	v_mfma_f32_16x16x32_bf16 v[84:87], v[170:173], v[186:189], v[84:87]
	v_mfma_f32_16x16x32_bf16 v[100:103], v[170:173], v[178:181], v[100:103]
	s_setprio 0
	s_barrier
	s_add_i32 s25, s35, s6
	v_lshl_add_u64 v[206:207], s[62:63], 0, v[130:131]
	s_mov_b32 m0, s25
	ds_read_b128 v[174:177], v248 offset:16384
	ds_read_b128 v[178:181], v248 offset:17408
	ds_read_b128 v[182:185], v248 offset:18432
	ds_read_b128 v[186:189], v248 offset:19456
	ds_read_b128 v[190:193], v248 offset:20480
	ds_read_b128 v[194:197], v248 offset:21504
	ds_read_b128 v[198:201], v248 offset:22528
	ds_read_b128 v[202:205], v248 offset:23552
	global_load_lds_dwordx4 v[206:207], off
	s_add_i32 m0, s25, 0x2000
	v_lshl_add_u64 v[208:209], s[62:63], 0, v[134:135]
	s_add_u32 s62, s62, s42
	s_addc_u32 s63, s63, s43
	s_add_i32 s25, s36, s6
	global_load_lds_dwordx4 v[208:209], off
	v_lshl_add_u64 v[210:211], s[62:63], 0, v[130:131]
	s_mov_b32 m0, s25
	v_lshl_add_u64 v[212:213], s[62:63], 0, v[134:135]
	global_load_lds_dwordx4 v[210:211], off
	s_add_i32 m0, s25, 0x2000
	v_lshl_add_u64 v[214:215], s[58:59], 0, v[128:129]
	global_load_lds_dwordx4 v[212:213], off
	s_mov_b32 m0, s7
	v_lshl_add_u64 v[216:217], s[58:59], 0, v[132:133]
	global_load_lds_dwordx4 v[214:215], off
	s_mov_b32 m0, s18
	s_nop 0
	global_load_lds_dwordx4 v[216:217], off
	s_waitcnt vmcnt(8)
	s_waitcnt lgkmcnt(0)
	s_barrier
; #define PG8_STAGE(bufoff, gbase, voff) do { _Pragma("unroll") for (int _i = 0; _i < 2; ++_i) \
;         __builtin_amdgcn_global_load_lds((const unsigned*)((const char*)(gbase) + (voff)[_i]), (PG8_LAS unsigned*)(lds + (bufoff) + ldsw + _i * 8192), 16, 0, 0); } while (0)
; #define PG8_LDA(dst, b, h) do { _Pragma("unroll") for (int m = 0; m < 4; ++m) _Pragma("unroll") for (int k = 0; k < 2; ++k) dst[m][k] = *(const PG8_LAS bf16x8*)(lds + PG8_SA(b, h) + aoff + m * 2048 + k * 1024); } while (0)
; #define PG8_LDB(dst, b, h) do { _Pragma("unroll") for (int n = 0; n < 2; ++n) _Pragma("unroll") for (int k = 0; k < 2; ++k) dst[n][k] = *(const PG8_LAS bf16x8*)(lds + PG8_SB(b, h) + boff + n * 2048 + k * 1024); } while (0)
; #define PG8_MMA(ai, bj, At, Bt) do { __builtin_amdgcn_s_setprio(1); _Pragma("unroll") for (int m = 0; m < 4; ++m) _Pragma("unroll") for (int n = 0; n < 2; ++n) _Pragma("unroll") for (int k = 0; k < 2; ++k) \
;         acc[ai][bj][m][n] = __builtin_amdgcn_mfma_f32_16x16x32_bf16(Bt[n][k], At[m][k], acc[ai][bj][m][n], 0, 0, 0); __builtin_amdgcn_s_setprio(0); } while (0)
; #define PG8_WAIT_V(n) asm volatile("s_waitcnt vmcnt(" #n ")" ::: "memory")
; #define PG8_WAIT_L(n) asm volatile("s_waitcnt lgkmcnt(" #n ")" ::: "memory")
; #define PG8_BAR __builtin_amdgcn_s_barrier()
; #define PG8_SCHED __builtin_amdgcn_sched_barrier(0)
; template <class Epi, class Sched, bool ALIGN_EPI = false, bool SP2 = false>
; __device__ __forceinline__ void gemm_phase(PG8_LAS unsigned char* lds, const Gemm g, const Sched& S, const Epi& E) {
;     ...
;             PG8_WAIT_V(8); PG8_WAIT_L(0); PG8_BAR; PG8_MMA(1, 0, At, B0); PG8_MMA(1, 1, At, B1); PG8_BAR; PG8_SCHED;
;             PG8_LDB(B0, 1, 0); PG8_LDB(B1, 1, 1); PG8_SCHED; PG8_LDA(At, 1, 0); PG8_STAGE(PG8_SA(0, 1), a2 + hstep, voffA);
;             PG8_WAIT_V(8); PG8_WAIT_L(0); PG8_BAR; PG8_MMA(0, 0, At, B0); PG8_MMA(0, 1, At, B1); PG8_BAR; PG8_SCHED;
	s_setprio 1
	s_waitcnt lgkmcnt(0)
	v_mfma_f32_16x16x32_bf16 v[60:63], v[142:145], v[174:177], 0
	v_mfma_f32_16x16x32_bf16 v[56:59], v[150:153], v[174:177], 0
	v_mfma_f32_16x16x32_bf16 v[52:55], v[142:145], v[182:185], 0
	v_mfma_f32_16x16x32_bf16 v[48:51], v[150:153], v[182:185], 0
	v_mfma_f32_16x16x32_bf16 v[40:43], v[142:145], v[190:193], 0
	v_mfma_f32_16x16x32_bf16 v[32:35], v[150:153], v[190:193], 0
	v_mfma_f32_16x16x32_bf16 v[24:27], v[142:145], v[198:201], 0
	v_mfma_f32_16x16x32_bf16 v[16:19], v[150:153], v[198:201], 0
	v_mfma_f32_16x16x32_bf16 v[60:63], v[146:149], v[178:181], v[60:63]
	v_mfma_f32_16x16x32_bf16 v[52:55], v[146:149], v[186:189], v[52:55]
	v_mfma_f32_16x16x32_bf16 v[40:43], v[146:149], v[194:197], v[40:43]
	v_mfma_f32_16x16x32_bf16 v[24:27], v[146:149], v[202:205], v[24:27]
	v_mfma_f32_16x16x32_bf16 v[16:19], v[154:157], v[202:205], v[16:19]
	v_mfma_f32_16x16x32_bf16 v[32:35], v[154:157], v[194:197], v[32:35]
	v_mfma_f32_16x16x32_bf16 v[48:51], v[154:157], v[186:189], v[48:51]
	v_mfma_f32_16x16x32_bf16 v[56:59], v[154:157], v[178:181], v[56:59]
	s_setprio 0
	s_setprio 1
	v_mfma_f32_16x16x32_bf16 v[44:47], v[158:161], v[174:177], 0
	v_mfma_f32_16x16x32_bf16 v[36:39], v[166:169], v[174:177], 0
	v_mfma_f32_16x16x32_bf16 v[28:31], v[158:161], v[182:185], 0
	v_mfma_f32_16x16x32_bf16 v[20:23], v[166:169], v[182:185], 0
	v_mfma_f32_16x16x32_bf16 v[12:15], v[158:161], v[190:193], 0
	v_mfma_f32_16x16x32_bf16 v[8:11], v[166:169], v[190:193], 0
	v_mfma_f32_16x16x32_bf16 v[4:7], v[158:161], v[198:201], 0
	v_mfma_f32_16x16x32_bf16 v[0:3], v[166:169], v[198:201], 0
	v_mfma_f32_16x16x32_bf16 v[44:47], v[162:165], v[178:181], v[44:47]
	v_mfma_f32_16x16x32_bf16 v[28:31], v[162:165], v[186:189], v[28:31]
	v_mfma_f32_16x16x32_bf16 v[12:15], v[162:165], v[194:197], v[12:15]
	v_mfma_f32_16x16x32_bf16 v[4:7], v[162:165], v[202:205], v[4:7]
	v_mfma_f32_16x16x32_bf16 v[0:3], v[170:173], v[202:205], v[0:3]
	v_mfma_f32_16x16x32_bf16 v[8:11], v[170:173], v[194:197], v[8:11]
	v_mfma_f32_16x16x32_bf16 v[20:23], v[170:173], v[186:189], v[20:23]
	v_mfma_f32_16x16x32_bf16 v[36:39], v[170:173], v[178:181], v[36:39]
	s_setprio 0
	s_barrier
	s_add_i32 s25, 0, 0x18000
	s_add_i32 s61, 0, 0x1c000
	v_add_u32_e32 v154, s25, v244
	v_add_u32_e32 v170, s61, v244
	ds_read_b128 v[142:145], v154
	ds_read_b128 v[146:149], v154 offset:1024
	ds_read_b128 v[150:153], v154 offset:2048
	ds_read_b128 v[154:157], v154 offset:3072
	ds_read_b128 v[158:161], v170
	ds_read_b128 v[162:165], v170 offset:1024
	ds_read_b128 v[166:169], v170 offset:2048
	ds_read_b128 v[170:173], v170 offset:3072
	s_add_u32 s58, s58, s42
	s_addc_u32 s59, s59, s43
	s_mov_b32 m0, s19
	v_lshl_add_u64 v[218:219], s[58:59], 0, v[128:129]
	ds_read_b128 v[174:177], v248 offset:32768
	ds_read_b128 v[178:181], v248 offset:33792
	ds_read_b128 v[182:185], v248 offset:34816
	ds_read_b128 v[186:189], v248 offset:35840
	ds_read_b128 v[190:193], v248 offset:36864
	ds_read_b128 v[194:197], v248 offset:37888
	ds_read_b128 v[198:201], v248 offset:38912
	ds_read_b128 v[202:205], v248 offset:39936
	global_load_lds_dwordx4 v[218:219], off
	v_lshl_add_u64 v[218:219], s[58:59], 0, v[132:133]
	s_mov_b32 m0, s26
	s_nop 0
	global_load_lds_dwordx4 v[218:219], off
	s_waitcnt vmcnt(8)
	s_waitcnt lgkmcnt(0)
	s_barrier
	s_setprio 1
	s_waitcnt lgkmcnt(0)
	v_mfma_f32_16x16x32_bf16 v[124:127], v[142:145], v[174:177], v[124:127]
	v_mfma_f32_16x16x32_bf16 v[116:119], v[142:145], v[182:185], v[116:119]
	v_mfma_f32_16x16x32_bf16 v[104:107], v[142:145], v[190:193], v[104:107]
	v_mfma_f32_16x16x32_bf16 v[88:91], v[142:145], v[198:201], v[88:91]
	v_mfma_f32_16x16x32_bf16 v[80:83], v[150:153], v[198:201], v[80:83]
	v_mfma_f32_16x16x32_bf16 v[96:99], v[150:153], v[190:193], v[96:99]
	v_mfma_f32_16x16x32_bf16 v[112:115], v[150:153], v[182:185], v[112:115]
	v_mfma_f32_16x16x32_bf16 v[120:123], v[150:153], v[174:177], v[120:123]
	v_mfma_f32_16x16x32_bf16 v[124:127], v[146:149], v[178:181], v[124:127]
	v_mfma_f32_16x16x32_bf16 v[116:119], v[146:149], v[186:189], v[116:119]
	v_mfma_f32_16x16x32_bf16 v[104:107], v[146:149], v[194:197], v[104:107]
	v_mfma_f32_16x16x32_bf16 v[88:91], v[146:149], v[202:205], v[88:91]
	v_mfma_f32_16x16x32_bf16 v[80:83], v[154:157], v[202:205], v[80:83]
	v_mfma_f32_16x16x32_bf16 v[96:99], v[154:157], v[194:197], v[96:99]
	v_mfma_f32_16x16x32_bf16 v[112:115], v[154:157], v[186:189], v[112:115]
	v_mfma_f32_16x16x32_bf16 v[120:123], v[154:157], v[178:181], v[120:123]
	s_setprio 0
	s_setprio 1
	v_mfma_f32_16x16x32_bf16 v[108:111], v[158:161], v[174:177], v[108:111]
	v_mfma_f32_16x16x32_bf16 v[92:95], v[158:161], v[182:185], v[92:95]
	v_mfma_f32_16x16x32_bf16 v[76:79], v[158:161], v[190:193], v[76:79]
	v_mfma_f32_16x16x32_bf16 v[68:71], v[158:161], v[198:201], v[68:71]
	v_mfma_f32_16x16x32_bf16 v[64:67], v[166:169], v[198:201], v[64:67]
	v_mfma_f32_16x16x32_bf16 v[72:75], v[166:169], v[190:193], v[72:75]
	v_mfma_f32_16x16x32_bf16 v[84:87], v[166:169], v[182:185], v[84:87]
	v_mfma_f32_16x16x32_bf16 v[100:103], v[166:169], v[174:177], v[100:103]
	v_mfma_f32_16x16x32_bf16 v[108:111], v[162:165], v[178:181], v[108:111]
	v_mfma_f32_16x16x32_bf16 v[92:95], v[162:165], v[186:189], v[92:95]
	v_mfma_f32_16x16x32_bf16 v[76:79], v[162:165], v[194:197], v[76:79]
	v_mfma_f32_16x16x32_bf16 v[68:71], v[162:165], v[202:205], v[68:71]
	v_mfma_f32_16x16x32_bf16 v[64:67], v[170:173], v[202:205], v[64:67]
	v_mfma_f32_16x16x32_bf16 v[72:75], v[170:173], v[194:197], v[72:75]
	v_mfma_f32_16x16x32_bf16 v[84:87], v[170:173], v[186:189], v[84:87]
	v_mfma_f32_16x16x32_bf16 v[100:103], v[170:173], v[178:181], v[100:103]
	s_setprio 0
	s_barrier
; #define PG8_STAGE(bufoff, gbase, voff) do { _Pragma("unroll") for (int _i = 0; _i < 2; ++_i) \
;         __builtin_amdgcn_global_load_lds((const unsigned*)((const char*)(gbase) + (voff)[_i]), (PG8_LAS unsigned*)(lds + (bufoff) + ldsw + _i * 8192), 16, 0, 0); } while (0)
; #define PG8_LDA(dst, b, h) do { _Pragma("unroll") for (int m = 0; m < 4; ++m) _Pragma("unroll") for (int k = 0; k < 2; ++k) dst[m][k] = *(const PG8_LAS bf16x8*)(lds + PG8_SA(b, h) + aoff + m * 2048 + k * 1024); } while (0)
; #define PG8_LDB(dst, b, h) do { _Pragma("unroll") for (int n = 0; n < 2; ++n) _Pragma("unroll") for (int k = 0; k < 2; ++k) dst[n][k] = *(const PG8_LAS bf16x8*)(lds + PG8_SB(b, h) + boff + n * 2048 + k * 1024); } while (0)
; #define PG8_MMA(ai, bj, At, Bt) do { __builtin_amdgcn_s_setprio(1); _Pragma("unroll") for (int m = 0; m < 4; ++m) _Pragma("unroll") for (int n = 0; n < 2; ++n) _Pragma("unroll") for (int k = 0; k < 2; ++k) \
;         acc[ai][bj][m][n] = __builtin_amdgcn_mfma_f32_16x16x32_bf16(Bt[n][k], At[m][k], acc[ai][bj][m][n], 0, 0, 0); __builtin_amdgcn_s_setprio(0); } while (0)
; #define PG8_WAIT_V(n) asm volatile("s_waitcnt vmcnt(" #n ")" ::: "memory")
; #define PG8_WAIT_L(n) asm volatile("s_waitcnt lgkmcnt(" #n ")" ::: "memory")
; #define PG8_BAR __builtin_amdgcn_s_barrier()
; #define PG8_SCHED __builtin_amdgcn_sched_barrier(0)
; template <class Epi, class Sched, bool ALIGN_EPI = false, bool SP2 = false>
; __device__ __forceinline__ void gemm_phase(PG8_LAS unsigned char* lds, const Gemm g, const Sched& S, const Epi& E) {
;     ...
;             PG8_LDB(B0, 0, 0); PG8_LDB(B1, 0, 1); PG8_SCHED; PG8_LDA(At, 0, 0); PG8_STAGE(PG8_SA(1, 1), a1 + hstep, voffA);
;             PG8_WAIT_V(8); PG8_WAIT_L(0); PG8_BAR; PG8_MMA(0, 0, At, B0); PG8_MMA(0, 1, At, B1); PG8_BAR; PG8_SCHED;
;     ...
;             PG8_LDA(At, 1, 1); PG8_STAGE(PG8_SB(1, 0), b3, voffB); PG8_STAGE(PG8_SB(1, 1), b3 + hstep, voffB); PG8_STAGE(PG8_SA(1, 0), a3, voffA);
;             PG8_WAIT_V(8); PG8_WAIT_L(0); PG8_BAR; PG8_MMA(1, 0, At, B0); PG8_MMA(1, 1, At, B1); PG8_BAR; PG8_SCHED;
	s_add_i32 s25, s25, s6
	v_lshl_add_u64 v[206:207], v[206:207], 0, s[50:51]
	s_mov_b32 m0, s25
	ds_read_b128 v[174:177], v248 offset:49152
	ds_read_b128 v[178:181], v248 offset:50176
	ds_read_b128 v[182:185], v248 offset:51200
	ds_read_b128 v[186:189], v248 offset:52224
	ds_read_b128 v[190:193], v248 offset:53248
	ds_read_b128 v[194:197], v248 offset:54272
	ds_read_b128 v[198:201], v248 offset:55296
	ds_read_b128 v[202:205], v248 offset:56320
	global_load_lds_dwordx4 v[206:207], off
	v_lshl_add_u64 v[206:207], v[208:209], 0, s[50:51]
	s_add_i32 m0, s25, 0x2000
	s_add_i32 s25, s61, s6
	global_load_lds_dwordx4 v[206:207], off
	v_lshl_add_u64 v[206:207], v[210:211], 0, s[50:51]
	s_mov_b32 m0, s25
	s_nop 0
	global_load_lds_dwordx4 v[206:207], off
	v_lshl_add_u64 v[206:207], v[212:213], 0, s[50:51]
	s_add_i32 m0, s25, 0x2000
	s_nop 0
	global_load_lds_dwordx4 v[206:207], off
	v_lshl_add_u64 v[206:207], v[214:215], 0, s[50:51]
	s_mov_b32 m0, s27
	s_nop 0
	global_load_lds_dwordx4 v[206:207], off
	v_lshl_add_u64 v[206:207], v[216:217], 0, s[50:51]
	s_mov_b32 m0, s30
	s_nop 0
	global_load_lds_dwordx4 v[206:207], off
	s_waitcnt vmcnt(8)
	s_waitcnt lgkmcnt(0)
	s_barrier
	s_setprio 1
	s_waitcnt lgkmcnt(0)
	v_mfma_f32_16x16x32_bf16 v[60:63], v[142:145], v[174:177], v[60:63]
	v_mfma_f32_16x16x32_bf16 v[52:55], v[142:145], v[182:185], v[52:55]
	v_mfma_f32_16x16x32_bf16 v[40:43], v[142:145], v[190:193], v[40:43]
	v_mfma_f32_16x16x32_bf16 v[24:27], v[142:145], v[198:201], v[24:27]
	v_mfma_f32_16x16x32_bf16 v[16:19], v[150:153], v[198:201], v[16:19]
	v_mfma_f32_16x16x32_bf16 v[32:35], v[150:153], v[190:193], v[32:35]
	v_mfma_f32_16x16x32_bf16 v[48:51], v[150:153], v[182:185], v[48:51]
	v_mfma_f32_16x16x32_bf16 v[56:59], v[150:153], v[174:177], v[56:59]
	v_mfma_f32_16x16x32_bf16 v[60:63], v[146:149], v[178:181], v[60:63]
	v_mfma_f32_16x16x32_bf16 v[52:55], v[146:149], v[186:189], v[52:55]
	v_mfma_f32_16x16x32_bf16 v[40:43], v[146:149], v[194:197], v[40:43]
	v_mfma_f32_16x16x32_bf16 v[24:27], v[146:149], v[202:205], v[24:27]
	v_mfma_f32_16x16x32_bf16 v[16:19], v[154:157], v[202:205], v[16:19]
	v_mfma_f32_16x16x32_bf16 v[32:35], v[154:157], v[194:197], v[32:35]
	v_mfma_f32_16x16x32_bf16 v[48:51], v[154:157], v[186:189], v[48:51]
	v_mfma_f32_16x16x32_bf16 v[56:59], v[154:157], v[178:181], v[56:59]
	s_setprio 0
	s_setprio 1
	v_mfma_f32_16x16x32_bf16 v[44:47], v[158:161], v[174:177], v[44:47]
	v_mfma_f32_16x16x32_bf16 v[28:31], v[158:161], v[182:185], v[28:31]
	v_mfma_f32_16x16x32_bf16 v[12:15], v[158:161], v[190:193], v[12:15]
	v_mfma_f32_16x16x32_bf16 v[4:7], v[158:161], v[198:201], v[4:7]
	v_mfma_f32_16x16x32_bf16 v[0:3], v[166:169], v[198:201], v[0:3]
	v_mfma_f32_16x16x32_bf16 v[8:11], v[166:169], v[190:193], v[8:11]
	v_mfma_f32_16x16x32_bf16 v[20:23], v[166:169], v[182:185], v[20:23]
	v_mfma_f32_16x16x32_bf16 v[36:39], v[166:169], v[174:177], v[36:39]
	v_mfma_f32_16x16x32_bf16 v[44:47], v[162:165], v[178:181], v[44:47]
	v_mfma_f32_16x16x32_bf16 v[28:31], v[162:165], v[186:189], v[28:31]
	v_mfma_f32_16x16x32_bf16 v[12:15], v[162:165], v[194:197], v[12:15]
	v_mfma_f32_16x16x32_bf16 v[4:7], v[162:165], v[202:205], v[4:7]
	v_mfma_f32_16x16x32_bf16 v[0:3], v[170:173], v[202:205], v[0:3]
	v_mfma_f32_16x16x32_bf16 v[8:11], v[170:173], v[194:197], v[8:11]
	v_mfma_f32_16x16x32_bf16 v[20:23], v[170:173], v[186:189], v[20:23]
	v_mfma_f32_16x16x32_bf16 v[36:39], v[170:173], v[178:181], v[36:39]
	s_setprio 0
	s_barrier
	s_add_u32 s56, s56, 0x100
	s_addc_u32 s57, s57, 0
	s_add_u32 s2, s2, 0x100
	s_addc_u32 s24, s24, 0
	s_cmp_ge_i32 s60, s33
	s_mov_b32 s25, s60
	s_cbranch_scc1 .Lpeelx_5
.LBB0_1406:
	ds_read_b128 v[142:145], v246
	ds_read_b128 v[146:149], v246 offset:1024
	ds_read_b128 v[150:153], v246 offset:2048
	ds_read_b128 v[154:157], v246 offset:3072
	ds_read_b128 v[158:161], v247
	ds_read_b128 v[162:165], v247 offset:1024
	ds_read_b128 v[166:169], v247 offset:2048
	ds_read_b128 v[170:173], v247 offset:3072
	s_add_i32 s60, s25, 2
	s_add_u32 s58, s56, 0x80
	s_addc_u32 s59, s57, 0
	s_cmp_eq_u32 s34, s25
	s_cselect_b32 s59, s17, s59
	s_cselect_b32 s58, s16, s58
	s_cselect_b32 s63, s55, s24
	s_cselect_b32 s62, s54, s2
	v_lshl_add_u64 v[206:207], s[56:57], 0, v[136:137]
	s_add_i32 m0, s7, 0xc000
	ds_read_b128 v[174:177], v248
	ds_read_b128 v[178:181], v248 offset:1024
	ds_read_b128 v[182:185], v248 offset:2048
	ds_read_b128 v[186:189], v248 offset:3072
	ds_read_b128 v[190:193], v248 offset:4096
	ds_read_b128 v[194:197], v248 offset:5120
	ds_read_b128 v[198:201], v248 offset:6144
	ds_read_b128 v[202:205], v248 offset:7168
	global_load_lds_dwordx4 v[206:207], off
	v_lshl_add_u64 v[206:207], s[56:57], 0, v[138:139]
	s_add_i32 m0, s7, 0xe000
	s_nop 0
	global_load_lds_dwordx4 v[206:207], off
	s_waitcnt vmcnt(8)
	s_waitcnt lgkmcnt(0)
	s_barrier
; #define PG8_STAGE(bufoff, gbase, voff) do { _Pragma("unroll") for (int _i = 0; _i < 2; ++_i) \
;         __builtin_amdgcn_global_load_lds((const unsigned*)((const char*)(gbase) + (voff)[_i]), (PG8_LAS unsigned*)(lds + (bufoff) + ldsw + _i * 8192), 16, 0, 0); } while (0)
; #define PG8_LDA(dst, b, h) do { _Pragma("unroll") for (int m = 0; m < 4; ++m) _Pragma("unroll") for (int k = 0; k < 2; ++k) dst[m][k] = *(const PG8_LAS bf16x8*)(lds + PG8_SA(b, h) + aoff + m * 2048 + k * 1024); } while (0)
; #define PG8_MMA(ai, bj, At, Bt) do { __builtin_amdgcn_s_setprio(1); _Pragma("unroll") for (int m = 0; m < 4; ++m) _Pragma("unroll") for (int n = 0; n < 2; ++n) _Pragma("unroll") for (int k = 0; k < 2; ++k) \
;         acc[ai][bj][m][n] = __builtin_amdgcn_mfma_f32_16x16x32_bf16(Bt[n][k], At[m][k], acc[ai][bj][m][n], 0, 0, 0); __builtin_amdgcn_s_setprio(0); } while (0)
; #define PG8_WAIT_V(n) asm volatile("s_waitcnt vmcnt(" #n ")" ::: "memory")
; #define PG8_WAIT_L(n) asm volatile("s_waitcnt lgkmcnt(" #n ")" ::: "memory")
; #define PG8_BAR __builtin_amdgcn_s_barrier()
; #define PG8_SCHED __builtin_amdgcn_sched_barrier(0)
; template <class Epi, class Sched, bool ALIGN_EPI = false, bool SP2 = false>
; __device__ __forceinline__ void gemm_phase(PG8_LAS unsigned char* lds, const Gemm g, const Sched& S, const Epi& E) {
;     ...
;             PG8_WAIT_V(8); PG8_WAIT_L(0); PG8_BAR; PG8_MMA(0, 0, At, B0); PG8_MMA(0, 1, At, B1); PG8_BAR; PG8_SCHED;
;             PG8_LDA(At, 0, 1); PG8_STAGE(PG8_SB(0, 0), b2, voffB); PG8_STAGE(PG8_SB(0, 1), b2 + hstep, voffB); PG8_STAGE(PG8_SA(0, 0), a2, voffA);
;             PG8_WAIT_V(8); PG8_WAIT_L(0); PG8_BAR; PG8_MMA(1, 0, At, B0); PG8_MMA(1, 1, At, B1); PG8_BAR; PG8_SCHED;
	s_setprio 1
	s_waitcnt lgkmcnt(0)
	v_mfma_f32_16x16x32_bf16 v[124:127], v[142:145], v[174:177], v[124:127]
	v_mfma_f32_16x16x32_bf16 v[116:119], v[142:145], v[182:185], v[116:119]
	v_mfma_f32_16x16x32_bf16 v[104:107], v[142:145], v[190:193], v[104:107]
	v_mfma_f32_16x16x32_bf16 v[88:91], v[142:145], v[198:201], v[88:91]
	v_mfma_f32_16x16x32_bf16 v[80:83], v[150:153], v[198:201], v[80:83]
	v_mfma_f32_16x16x32_bf16 v[96:99], v[150:153], v[190:193], v[96:99]
	v_mfma_f32_16x16x32_bf16 v[112:115], v[150:153], v[182:185], v[112:115]
	v_mfma_f32_16x16x32_bf16 v[120:123], v[150:153], v[174:177], v[120:123]
	v_mfma_f32_16x16x32_bf16 v[124:127], v[146:149], v[178:181], v[124:127]
	v_mfma_f32_16x16x32_bf16 v[116:119], v[146:149], v[186:189], v[116:119]
	v_mfma_f32_16x16x32_bf16 v[104:107], v[146:149], v[194:197], v[104:107]
	v_mfma_f32_16x16x32_bf16 v[88:91], v[146:149], v[202:205], v[88:91]
	v_mfma_f32_16x16x32_bf16 v[80:83], v[154:157], v[202:205], v[80:83]
	v_mfma_f32_16x16x32_bf16 v[96:99], v[154:157], v[194:197], v[96:99]
	v_mfma_f32_16x16x32_bf16 v[112:115], v[154:157], v[186:189], v[112:115]
	v_mfma_f32_16x16x32_bf16 v[120:123], v[154:157], v[178:181], v[120:123]
	s_setprio 0
	s_setprio 1
	v_mfma_f32_16x16x32_bf16 v[108:111], v[158:161], v[174:177], v[108:111]
	v_mfma_f32_16x16x32_bf16 v[92:95], v[158:161], v[182:185], v[92:95]
	v_mfma_f32_16x16x32_bf16 v[76:79], v[158:161], v[190:193], v[76:79]
	v_mfma_f32_16x16x32_bf16 v[68:71], v[158:161], v[198:201], v[68:71]
	v_mfma_f32_16x16x32_bf16 v[64:67], v[166:169], v[198:201], v[64:67]
	v_mfma_f32_16x16x32_bf16 v[72:75], v[166:169], v[190:193], v[72:75]
	v_mfma_f32_16x16x32_bf16 v[84:87], v[166:169], v[182:185], v[84:87]
	v_mfma_f32_16x16x32_bf16 v[100:103], v[166:169], v[174:177], v[100:103]
	v_mfma_f32_16x16x32_bf16 v[108:111], v[162:165], v[178:181], v[108:111]
	v_mfma_f32_16x16x32_bf16 v[92:95], v[162:165], v[186:189], v[92:95]
	v_mfma_f32_16x16x32_bf16 v[76:79], v[162:165], v[194:197], v[76:79]
	v_mfma_f32_16x16x32_bf16 v[68:71], v[162:165], v[202:205], v[68:71]
	v_mfma_f32_16x16x32_bf16 v[64:67], v[170:173], v[202:205], v[64:67]
	v_mfma_f32_16x16x32_bf16 v[72:75], v[170:173], v[194:197], v[72:75]
	v_mfma_f32_16x16x32_bf16 v[84:87], v[170:173], v[186:189], v[84:87]
	v_mfma_f32_16x16x32_bf16 v[100:103], v[170:173], v[178:181], v[100:103]
	s_setprio 0
	s_barrier
	s_add_i32 s25, s35, s6
	v_lshl_add_u64 v[206:207], s[62:63], 0, v[130:131]
	s_mov_b32 m0, s25
	ds_read_b128 v[174:177], v248 offset:16384
	ds_read_b128 v[178:181], v248 offset:17408
	ds_read_b128 v[182:185], v248 offset:18432
	ds_read_b128 v[186:189], v248 offset:19456
	ds_read_b128 v[190:193], v248 offset:20480
	ds_read_b128 v[194:197], v248 offset:21504
	ds_read_b128 v[198:201], v248 offset:22528
	ds_read_b128 v[202:205], v248 offset:23552
	global_load_lds_dwordx4 v[206:207], off
	s_add_i32 m0, s25, 0x2000
	v_lshl_add_u64 v[208:209], s[62:63], 0, v[134:135]
	s_add_u32 s62, s62, s42
	s_addc_u32 s63, s63, s43
	s_add_i32 s25, s36, s6
	global_load_lds_dwordx4 v[208:209], off
	v_lshl_add_u64 v[210:211], s[62:63], 0, v[130:131]
	s_mov_b32 m0, s25
	v_lshl_add_u64 v[212:213], s[62:63], 0, v[134:135]
	global_load_lds_dwordx4 v[210:211], off
	s_add_i32 m0, s25, 0x2000
	v_lshl_add_u64 v[214:215], s[58:59], 0, v[128:129]
	global_load_lds_dwordx4 v[212:213], off
	s_mov_b32 m0, s7
	v_lshl_add_u64 v[216:217], s[58:59], 0, v[132:133]
	global_load_lds_dwordx4 v[214:215], off
	s_mov_b32 m0, s18
	s_nop 0
	global_load_lds_dwordx4 v[216:217], off
	s_waitcnt vmcnt(8)
	s_waitcnt lgkmcnt(0)
	s_barrier
	s_setprio 1
	s_waitcnt lgkmcnt(0)
	v_mfma_f32_16x16x32_bf16 v[60:63], v[142:145], v[174:177], v[60:63]
	v_mfma_f32_16x16x32_bf16 v[52:55], v[142:145], v[182:185], v[52:55]
	v_mfma_f32_16x16x32_bf16 v[40:43], v[142:145], v[190:193], v[40:43]
	v_mfma_f32_16x16x32_bf16 v[24:27], v[142:145], v[198:201], v[24:27]
	v_mfma_f32_16x16x32_bf16 v[16:19], v[150:153], v[198:201], v[16:19]
	v_mfma_f32_16x16x32_bf16 v[32:35], v[150:153], v[190:193], v[32:35]
	v_mfma_f32_16x16x32_bf16 v[48:51], v[150:153], v[182:185], v[48:51]
	v_mfma_f32_16x16x32_bf16 v[56:59], v[150:153], v[174:177], v[56:59]
	v_mfma_f32_16x16x32_bf16 v[60:63], v[146:149], v[178:181], v[60:63]
	v_mfma_f32_16x16x32_bf16 v[52:55], v[146:149], v[186:189], v[52:55]
	v_mfma_f32_16x16x32_bf16 v[40:43], v[146:149], v[194:197], v[40:43]
	v_mfma_f32_16x16x32_bf16 v[24:27], v[146:149], v[202:205], v[24:27]
	v_mfma_f32_16x16x32_bf16 v[16:19], v[154:157], v[202:205], v[16:19]
	v_mfma_f32_16x16x32_bf16 v[32:35], v[154:157], v[194:197], v[32:35]
	v_mfma_f32_16x16x32_bf16 v[48:51], v[154:157], v[186:189], v[48:51]
	v_mfma_f32_16x16x32_bf16 v[56:59], v[154:157], v[178:181], v[56:59]
	s_setprio 0
	s_setprio 1
	v_mfma_f32_16x16x32_bf16 v[44:47], v[158:161], v[174:177], v[44:47]
	v_mfma_f32_16x16x32_bf16 v[28:31], v[158:161], v[182:185], v[28:31]
	v_mfma_f32_16x16x32_bf16 v[12:15], v[158:161], v[190:193], v[12:15]
	v_mfma_f32_16x16x32_bf16 v[4:7], v[158:161], v[198:201], v[4:7]
	v_mfma_f32_16x16x32_bf16 v[0:3], v[166:169], v[198:201], v[0:3]
	v_mfma_f32_16x16x32_bf16 v[8:11], v[166:169], v[190:193], v[8:11]
	v_mfma_f32_16x16x32_bf16 v[20:23], v[166:169], v[182:185], v[20:23]
	v_mfma_f32_16x16x32_bf16 v[36:39], v[166:169], v[174:177], v[36:39]
	v_mfma_f32_16x16x32_bf16 v[44:47], v[162:165], v[178:181], v[44:47]
	v_mfma_f32_16x16x32_bf16 v[28:31], v[162:165], v[186:189], v[28:31]
	v_mfma_f32_16x16x32_bf16 v[12:15], v[162:165], v[194:197], v[12:15]
	v_mfma_f32_16x16x32_bf16 v[4:7], v[162:165], v[202:205], v[4:7]
	v_mfma_f32_16x16x32_bf16 v[0:3], v[170:173], v[202:205], v[0:3]
	v_mfma_f32_16x16x32_bf16 v[8:11], v[170:173], v[194:197], v[8:11]
	v_mfma_f32_16x16x32_bf16 v[20:23], v[170:173], v[186:189], v[20:23]
	v_mfma_f32_16x16x32_bf16 v[36:39], v[170:173], v[178:181], v[36:39]
	s_setprio 0
	s_barrier
; #define PG8_STAGE(bufoff, gbase, voff) do { _Pragma("unroll") for (int _i = 0; _i < 2; ++_i) \
;         __builtin_amdgcn_global_load_lds((const unsigned*)((const char*)(gbase) + (voff)[_i]), (PG8_LAS unsigned*)(lds + (bufoff) + ldsw + _i * 8192), 16, 0, 0); } while (0)
; #define PG8_LDA(dst, b, h) do { _Pragma("unroll") for (int m = 0; m < 4; ++m) _Pragma("unroll") for (int k = 0; k < 2; ++k) dst[m][k] = *(const PG8_LAS bf16x8*)(lds + PG8_SA(b, h) + aoff + m * 2048 + k * 1024); } while (0)
; #define PG8_LDB(dst, b, h) do { _Pragma("unroll") for (int n = 0; n < 2; ++n) _Pragma("unroll") for (int k = 0; k < 2; ++k) dst[n][k] = *(const PG8_LAS bf16x8*)(lds + PG8_SB(b, h) + boff + n * 2048 + k * 1024); } while (0)
; #define PG8_MMA(ai, bj, At, Bt) do { __builtin_amdgcn_s_setprio(1); _Pragma("unroll") for (int m = 0; m < 4; ++m) _Pragma("unroll") for (int n = 0; n < 2; ++n) _Pragma("unroll") for (int k = 0; k < 2; ++k) \
;         acc[ai][bj][m][n] = __builtin_amdgcn_mfma_f32_16x16x32_bf16(Bt[n][k], At[m][k], acc[ai][bj][m][n], 0, 0, 0); __builtin_amdgcn_s_setprio(0); } while (0)
; #define PG8_WAIT_V(n) asm volatile("s_waitcnt vmcnt(" #n ")" ::: "memory")
; #define PG8_WAIT_L(n) asm volatile("s_waitcnt lgkmcnt(" #n ")" ::: "memory")
; #define PG8_BAR __builtin_amdgcn_s_barrier()
; #define PG8_SCHED __builtin_amdgcn_sched_barrier(0)
; template <class Epi, class Sched, bool ALIGN_EPI = false, bool SP2 = false>
; __device__ __forceinline__ void gemm_phase(PG8_LAS unsigned char* lds, const Gemm g, const Sched& S, const Epi& E) {
;     ...
;             PG8_LDB(B0, 1, 0); PG8_LDB(B1, 1, 1); PG8_SCHED; PG8_LDA(At, 1, 0); PG8_STAGE(PG8_SA(0, 1), a2 + hstep, voffA);
;             PG8_WAIT_V(8); PG8_WAIT_L(0); PG8_BAR; PG8_MMA(0, 0, At, B0); PG8_MMA(0, 1, At, B1); PG8_BAR; PG8_SCHED;
	s_add_i32 s25, 0, 0x18000
	s_add_i32 s61, 0, 0x1c000
	v_add_u32_e32 v154, s25, v244
	v_add_u32_e32 v170, s61, v244
	ds_read_b128 v[142:145], v154
	ds_read_b128 v[146:149], v154 offset:1024
	ds_read_b128 v[150:153], v154 offset:2048
	ds_read_b128 v[154:157], v154 offset:3072
	ds_read_b128 v[158:161], v170
	ds_read_b128 v[162:165], v170 offset:1024
	ds_read_b128 v[166:169], v170 offset:2048
	ds_read_b128 v[170:173], v170 offset:3072
	s_add_u32 s58, s58, s42
	s_addc_u32 s59, s59, s43
	s_mov_b32 m0, s19
	v_lshl_add_u64 v[218:219], s[58:59], 0, v[128:129]
	ds_read_b128 v[174:177], v248 offset:32768
	ds_read_b128 v[178:181], v248 offset:33792
	ds_read_b128 v[182:185], v248 offset:34816
	ds_read_b128 v[186:189], v248 offset:35840
	ds_read_b128 v[190:193], v248 offset:36864
	ds_read_b128 v[194:197], v248 offset:37888
	ds_read_b128 v[198:201], v248 offset:38912
	ds_read_b128 v[202:205], v248 offset:39936
	global_load_lds_dwordx4 v[218:219], off
	v_lshl_add_u64 v[218:219], s[58:59], 0, v[132:133]
	s_mov_b32 m0, s26
	s_nop 0
	global_load_lds_dwordx4 v[218:219], off
	s_waitcnt vmcnt(8)
	s_waitcnt lgkmcnt(0)
	s_barrier
	s_setprio 1
	s_waitcnt lgkmcnt(0)
	v_mfma_f32_16x16x32_bf16 v[124:127], v[142:145], v[174:177], v[124:127]
	v_mfma_f32_16x16x32_bf16 v[116:119], v[142:145], v[182:185], v[116:119]
	v_mfma_f32_16x16x32_bf16 v[104:107], v[142:145], v[190:193], v[104:107]
	v_mfma_f32_16x16x32_bf16 v[88:91], v[142:145], v[198:201], v[88:91]
	v_mfma_f32_16x16x32_bf16 v[80:83], v[150:153], v[198:201], v[80:83]
	v_mfma_f32_16x16x32_bf16 v[96:99], v[150:153], v[190:193], v[96:99]
	v_mfma_f32_16x16x32_bf16 v[112:115], v[150:153], v[182:185], v[112:115]
	v_mfma_f32_16x16x32_bf16 v[120:123], v[150:153], v[174:177], v[120:123]
	v_mfma_f32_16x16x32_bf16 v[124:127], v[146:149], v[178:181], v[124:127]
	v_mfma_f32_16x16x32_bf16 v[116:119], v[146:149], v[186:189], v[116:119]
	v_mfma_f32_16x16x32_bf16 v[104:107], v[146:149], v[194:197], v[104:107]
	v_mfma_f32_16x16x32_bf16 v[88:91], v[146:149], v[202:205], v[88:91]
	v_mfma_f32_16x16x32_bf16 v[80:83], v[154:157], v[202:205], v[80:83]
	v_mfma_f32_16x16x32_bf16 v[96:99], v[154:157], v[194:197], v[96:99]
	v_mfma_f32_16x16x32_bf16 v[112:115], v[154:157], v[186:189], v[112:115]
	v_mfma_f32_16x16x32_bf16 v[120:123], v[154:157], v[178:181], v[120:123]
	s_setprio 0
	s_setprio 1
	v_mfma_f32_16x16x32_bf16 v[108:111], v[158:161], v[174:177], v[108:111]
	v_mfma_f32_16x16x32_bf16 v[92:95], v[158:161], v[182:185], v[92:95]
	v_mfma_f32_16x16x32_bf16 v[76:79], v[158:161], v[190:193], v[76:79]
	v_mfma_f32_16x16x32_bf16 v[68:71], v[158:161], v[198:201], v[68:71]
	v_mfma_f32_16x16x32_bf16 v[64:67], v[166:169], v[198:201], v[64:67]
	v_mfma_f32_16x16x32_bf16 v[72:75], v[166:169], v[190:193], v[72:75]
	v_mfma_f32_16x16x32_bf16 v[84:87], v[166:169], v[182:185], v[84:87]
	v_mfma_f32_16x16x32_bf16 v[100:103], v[166:169], v[174:177], v[100:103]
	v_mfma_f32_16x16x32_bf16 v[108:111], v[162:165], v[178:181], v[108:111]
	v_mfma_f32_16x16x32_bf16 v[92:95], v[162:165], v[186:189], v[92:95]
	v_mfma_f32_16x16x32_bf16 v[76:79], v[162:165], v[194:197], v[76:79]
	v_mfma_f32_16x16x32_bf16 v[68:71], v[162:165], v[202:205], v[68:71]
	v_mfma_f32_16x16x32_bf16 v[64:67], v[170:173], v[202:205], v[64:67]
	v_mfma_f32_16x16x32_bf16 v[72:75], v[170:173], v[194:197], v[72:75]
	v_mfma_f32_16x16x32_bf16 v[84:87], v[170:173], v[186:189], v[84:87]
	v_mfma_f32_16x16x32_bf16 v[100:103], v[170:173], v[178:181], v[100:103]
	s_setprio 0
	s_barrier
; #define PG8_STAGE(bufoff, gbase, voff) do { _Pragma("unroll") for (int _i = 0; _i < 2; ++_i) \
;         __builtin_amdgcn_global_load_lds((const unsigned*)((const char*)(gbase) + (voff)[_i]), (PG8_LAS unsigned*)(lds + (bufoff) + ldsw + _i * 8192), 16, 0, 0); } while (0)
; #define PG8_LDA(dst, b, h) do { _Pragma("unroll") for (int m = 0; m < 4; ++m) _Pragma("unroll") for (int k = 0; k < 2; ++k) dst[m][k] = *(const PG8_LAS bf16x8*)(lds + PG8_SA(b, h) + aoff + m * 2048 + k * 1024); } while (0)
; #define PG8_MMA(ai, bj, At, Bt) do { __builtin_amdgcn_s_setprio(1); _Pragma("unroll") for (int m = 0; m < 4; ++m) _Pragma("unroll") for (int n = 0; n < 2; ++n) _Pragma("unroll") for (int k = 0; k < 2; ++k) \
;         acc[ai][bj][m][n] = __builtin_amdgcn_mfma_f32_16x16x32_bf16(Bt[n][k], At[m][k], acc[ai][bj][m][n], 0, 0, 0); __builtin_amdgcn_s_setprio(0); } while (0)
; #define PG8_WAIT_V(n) asm volatile("s_waitcnt vmcnt(" #n ")" ::: "memory")
; #define PG8_WAIT_L(n) asm volatile("s_waitcnt lgkmcnt(" #n ")" ::: "memory")
; #define PG8_BAR __builtin_amdgcn_s_barrier()
; #define PG8_SCHED __builtin_amdgcn_sched_barrier(0)
; template <class Epi, class Sched, bool ALIGN_EPI = false, bool SP2 = false>
; __device__ __forceinline__ void gemm_phase(PG8_LAS unsigned char* lds, const Gemm g, const Sched& S, const Epi& E) {
;     ...
;             PG8_LDA(At, 1, 1); PG8_STAGE(PG8_SB(1, 0), b3, voffB); PG8_STAGE(PG8_SB(1, 1), b3 + hstep, voffB); PG8_STAGE(PG8_SA(1, 0), a3, voffA);
;             PG8_WAIT_V(8); PG8_WAIT_L(0); PG8_BAR; PG8_MMA(1, 0, At, B0); PG8_MMA(1, 1, At, B1); PG8_BAR; PG8_SCHED;
	s_add_i32 s25, s25, s6
	v_lshl_add_u64 v[206:207], v[206:207], 0, s[50:51]
	s_mov_b32 m0, s25
	ds_read_b128 v[174:177], v248 offset:49152
	ds_read_b128 v[178:181], v248 offset:50176
	ds_read_b128 v[182:185], v248 offset:51200
	ds_read_b128 v[186:189], v248 offset:52224
	ds_read_b128 v[190:193], v248 offset:53248
	ds_read_b128 v[194:197], v248 offset:54272
	ds_read_b128 v[198:201], v248 offset:55296
	ds_read_b128 v[202:205], v248 offset:56320
	global_load_lds_dwordx4 v[206:207], off
	v_lshl_add_u64 v[206:207], v[208:209], 0, s[50:51]
	s_add_i32 m0, s25, 0x2000
	s_add_i32 s25, s61, s6
	global_load_lds_dwordx4 v[206:207], off
	v_lshl_add_u64 v[206:207], v[210:211], 0, s[50:51]
	s_mov_b32 m0, s25
	s_nop 0
	global_load_lds_dwordx4 v[206:207], off
	v_lshl_add_u64 v[206:207], v[212:213], 0, s[50:51]
	s_add_i32 m0, s25, 0x2000
	s_nop 0
	global_load_lds_dwordx4 v[206:207], off
	v_lshl_add_u64 v[206:207], v[214:215], 0, s[50:51]
	s_mov_b32 m0, s27
	s_nop 0
	global_load_lds_dwordx4 v[206:207], off
	v_lshl_add_u64 v[206:207], v[216:217], 0, s[50:51]
	s_mov_b32 m0, s30
	s_nop 0
	global_load_lds_dwordx4 v[206:207], off
	s_waitcnt vmcnt(8)
	s_waitcnt lgkmcnt(0)
	s_barrier
	s_setprio 1
	s_waitcnt lgkmcnt(0)
	v_mfma_f32_16x16x32_bf16 v[60:63], v[142:145], v[174:177], v[60:63]
	v_mfma_f32_16x16x32_bf16 v[52:55], v[142:145], v[182:185], v[52:55]
	v_mfma_f32_16x16x32_bf16 v[40:43], v[142:145], v[190:193], v[40:43]
	v_mfma_f32_16x16x32_bf16 v[24:27], v[142:145], v[198:201], v[24:27]
	v_mfma_f32_16x16x32_bf16 v[16:19], v[150:153], v[198:201], v[16:19]
	v_mfma_f32_16x16x32_bf16 v[32:35], v[150:153], v[190:193], v[32:35]
	v_mfma_f32_16x16x32_bf16 v[48:51], v[150:153], v[182:185], v[48:51]
	v_mfma_f32_16x16x32_bf16 v[56:59], v[150:153], v[174:177], v[56:59]
	v_mfma_f32_16x16x32_bf16 v[60:63], v[146:149], v[178:181], v[60:63]
	v_mfma_f32_16x16x32_bf16 v[52:55], v[146:149], v[186:189], v[52:55]
	v_mfma_f32_16x16x32_bf16 v[40:43], v[146:149], v[194:197], v[40:43]
	v_mfma_f32_16x16x32_bf16 v[24:27], v[146:149], v[202:205], v[24:27]
	v_mfma_f32_16x16x32_bf16 v[16:19], v[154:157], v[202:205], v[16:19]
	v_mfma_f32_16x16x32_bf16 v[32:35], v[154:157], v[194:197], v[32:35]
	v_mfma_f32_16x16x32_bf16 v[48:51], v[154:157], v[186:189], v[48:51]
	v_mfma_f32_16x16x32_bf16 v[56:59], v[154:157], v[178:181], v[56:59]
	s_setprio 0
	s_setprio 1
	v_mfma_f32_16x16x32_bf16 v[44:47], v[158:161], v[174:177], v[44:47]
	v_mfma_f32_16x16x32_bf16 v[28:31], v[158:161], v[182:185], v[28:31]
	v_mfma_f32_16x16x32_bf16 v[12:15], v[158:161], v[190:193], v[12:15]
	v_mfma_f32_16x16x32_bf16 v[4:7], v[158:161], v[198:201], v[4:7]
	v_mfma_f32_16x16x32_bf16 v[0:3], v[166:169], v[198:201], v[0:3]
	v_mfma_f32_16x16x32_bf16 v[8:11], v[166:169], v[190:193], v[8:11]
	v_mfma_f32_16x16x32_bf16 v[20:23], v[166:169], v[182:185], v[20:23]
	v_mfma_f32_16x16x32_bf16 v[36:39], v[166:169], v[174:177], v[36:39]
	v_mfma_f32_16x16x32_bf16 v[44:47], v[162:165], v[178:181], v[44:47]
	v_mfma_f32_16x16x32_bf16 v[28:31], v[162:165], v[186:189], v[28:31]
	v_mfma_f32_16x16x32_bf16 v[12:15], v[162:165], v[194:197], v[12:15]
	v_mfma_f32_16x16x32_bf16 v[4:7], v[162:165], v[202:205], v[4:7]
	v_mfma_f32_16x16x32_bf16 v[0:3], v[170:173], v[202:205], v[0:3]
	v_mfma_f32_16x16x32_bf16 v[8:11], v[170:173], v[194:197], v[8:11]
	v_mfma_f32_16x16x32_bf16 v[20:23], v[170:173], v[186:189], v[20:23]
	v_mfma_f32_16x16x32_bf16 v[36:39], v[170:173], v[178:181], v[36:39]
	s_setprio 0
	s_barrier
	s_add_u32 s56, s56, 0x100
	s_addc_u32 s57, s57, 0
	s_add_u32 s2, s2, 0x100
	s_addc_u32 s24, s24, 0
	s_cmp_ge_i32 s60, s33
	s_mov_b32 s25, s60
	s_cbranch_scc0 .LBB0_1406

; #define PG8_STAGE(bufoff, gbase, voff) do { _Pragma("unroll") for (int _i = 0; _i < 2; ++_i) \
;         __builtin_amdgcn_global_load_lds((const unsigned*)((const char*)(gbase) + (voff)[_i]), (PG8_LAS unsigned*)(lds + (bufoff) + ldsw + _i * 8192), 16, 0, 0); } while (0)
; #define PG8_LDA(dst, b, h) do { _Pragma("unroll") for (int m = 0; m < 4; ++m) _Pragma("unroll") for (int k = 0; k < 2; ++k) dst[m][k] = *(const PG8_LAS bf16x8*)(lds + PG8_SA(b, h) + aoff + m * 2048 + k * 1024); } while (0)
; #define PG8_LDB(dst, b, h) do { _Pragma("unroll") for (int n = 0; n < 2; ++n) _Pragma("unroll") for (int k = 0; k < 2; ++k) dst[n][k] = *(const PG8_LAS bf16x8*)(lds + PG8_SB(b, h) + boff + n * 2048 + k * 1024); } while (0)
; #define PG8_MMA(ai, bj, At, Bt) do { __builtin_amdgcn_s_setprio(1); _Pragma("unroll") for (int m = 0; m < 4; ++m) _Pragma("unroll") for (int n = 0; n < 2; ++n) _Pragma("unroll") for (int k = 0; k < 2; ++k) \
;         acc[ai][bj][m][n] = __builtin_amdgcn_mfma_f32_16x16x32_bf16(Bt[n][k], At[m][k], acc[ai][bj][m][n], 0, 0, 0); __builtin_amdgcn_s_setprio(0); } while (0)
; #define PG8_WAIT_V(n) asm volatile("s_waitcnt vmcnt(" #n ")" ::: "memory")
; #define PG8_WAIT_L(n) asm volatile("s_waitcnt lgkmcnt(" #n ")" ::: "memory")
; #define PG8_BAR __builtin_amdgcn_s_barrier()
; #define PG8_SCHED __builtin_amdgcn_sched_barrier(0)
; template <class Epi, class Sched, bool ALIGN_EPI = false, bool SP2 = false>
; __device__ __forceinline__ void gemm_phase(PG8_LAS unsigned char* lds, const Gemm g, const Sched& S, const Epi& E) {
;     ...
;             PG8_LDB(B0, 0, 0); PG8_LDB(B1, 0, 1); PG8_SCHED; PG8_LDA(At, 0, 0); PG8_STAGE(PG8_SA(1, 1), a1 + hstep, voffA);
;             PG8_WAIT_V(8); PG8_WAIT_L(0); PG8_BAR; PG8_MMA(0, 0, At, B0); PG8_MMA(0, 1, At, B1); PG8_BAR; PG8_SCHED;
;             PG8_LDA(At, 0, 1); PG8_STAGE(PG8_SB(0, 0), b2, voffB); PG8_STAGE(PG8_SB(0, 1), b2 + hstep, voffB); PG8_STAGE(PG8_SA(0, 0), a2, voffA);
;             PG8_WAIT_V(8); PG8_WAIT_L(0); PG8_BAR; PG8_MMA(1, 0, At, B0); PG8_MMA(1, 1, At, B1); PG8_BAR; PG8_SCHED;
.LBB0_1695:
	ds_read_b128 v[128:131], v179
	ds_read_b128 v[132:135], v179 offset:1024
	ds_read_b128 v[166:169], v179 offset:2048
	ds_read_b128 v[170:173], v179 offset:3072
	ds_read_b128 v[174:177], v180
	ds_read_b128 v[184:187], v180 offset:1024
	ds_read_b128 v[188:191], v180 offset:2048
	ds_read_b128 v[192:195], v180 offset:3072
	s_add_i32 s70, s48, 2
	s_add_u32 s68, s14, 0x80
	s_addc_u32 s69, s15, 0
	s_cmp_eq_u32 s35, s48
	s_cselect_b32 s69, s65, s69
	s_cselect_b32 s68, s64, s68
	s_cselect_b32 s73, s67, s25
	s_cselect_b32 s72, s66, s24
	v_lshl_add_u64 v[162:163], s[14:15], 0, v[154:155]
	s_add_i32 m0, s18, 0xc000
	ds_read_b128 v[196:199], v181
	ds_read_b128 v[200:203], v181 offset:1024
	ds_read_b128 v[204:207], v181 offset:2048
	ds_read_b128 v[208:211], v181 offset:3072
	ds_read_b128 v[212:215], v181 offset:4096
	ds_read_b128 v[216:219], v181 offset:5120
	ds_read_b128 v[220:223], v181 offset:6144
	ds_read_b128 v[224:227], v181 offset:7168
	global_load_lds_dwordx4 v[162:163], off
	v_lshl_add_u64 v[162:163], s[14:15], 0, v[156:157]
	s_add_i32 m0, s18, 0xe000
	s_nop 0
	global_load_lds_dwordx4 v[162:163], off
	s_waitcnt vmcnt(8)
	s_waitcnt lgkmcnt(0)
	s_barrier
	s_setprio 1
	s_waitcnt lgkmcnt(0)
	v_mfma_f32_16x16x32_bf16 v[124:127], v[128:131], v[196:199], v[124:127]
	v_mfma_f32_16x16x32_bf16 v[108:111], v[128:131], v[204:207], v[108:111]
	v_mfma_f32_16x16x32_bf16 v[92:95], v[128:131], v[212:215], v[92:95]
	v_mfma_f32_16x16x32_bf16 v[76:79], v[128:131], v[220:223], v[76:79]
	v_mfma_f32_16x16x32_bf16 v[68:71], v[166:169], v[220:223], v[68:71]
	v_mfma_f32_16x16x32_bf16 v[84:87], v[166:169], v[212:215], v[84:87]
	v_mfma_f32_16x16x32_bf16 v[100:103], v[166:169], v[204:207], v[100:103]
	v_mfma_f32_16x16x32_bf16 v[116:119], v[166:169], v[196:199], v[116:119]
	v_mfma_f32_16x16x32_bf16 v[124:127], v[132:135], v[200:203], v[124:127]
	v_mfma_f32_16x16x32_bf16 v[108:111], v[132:135], v[208:211], v[108:111]
	v_mfma_f32_16x16x32_bf16 v[92:95], v[132:135], v[216:219], v[92:95]
	v_mfma_f32_16x16x32_bf16 v[76:79], v[132:135], v[224:227], v[76:79]
	v_mfma_f32_16x16x32_bf16 v[68:71], v[170:173], v[224:227], v[68:71]
	v_mfma_f32_16x16x32_bf16 v[84:87], v[170:173], v[216:219], v[84:87]
	v_mfma_f32_16x16x32_bf16 v[100:103], v[170:173], v[208:211], v[100:103]
	v_mfma_f32_16x16x32_bf16 v[116:119], v[170:173], v[200:203], v[116:119]
	s_setprio 0
	s_setprio 1
	v_mfma_f32_16x16x32_bf16 v[120:123], v[174:177], v[196:199], v[120:123]
	v_mfma_f32_16x16x32_bf16 v[104:107], v[174:177], v[204:207], v[104:107]
	v_mfma_f32_16x16x32_bf16 v[88:91], v[174:177], v[212:215], v[88:91]
	v_mfma_f32_16x16x32_bf16 v[72:75], v[174:177], v[220:223], v[72:75]
	v_mfma_f32_16x16x32_bf16 v[64:67], v[188:191], v[220:223], v[64:67]
	v_mfma_f32_16x16x32_bf16 v[80:83], v[188:191], v[212:215], v[80:83]
	v_mfma_f32_16x16x32_bf16 v[96:99], v[188:191], v[204:207], v[96:99]
	v_mfma_f32_16x16x32_bf16 v[112:115], v[188:191], v[196:199], v[112:115]
	v_mfma_f32_16x16x32_bf16 v[120:123], v[184:187], v[200:203], v[120:123]
	v_mfma_f32_16x16x32_bf16 v[104:107], v[184:187], v[208:211], v[104:107]
	v_mfma_f32_16x16x32_bf16 v[88:91], v[184:187], v[216:219], v[88:91]
	v_mfma_f32_16x16x32_bf16 v[72:75], v[184:187], v[224:227], v[72:75]
	v_mfma_f32_16x16x32_bf16 v[64:67], v[192:195], v[224:227], v[64:67]
	v_mfma_f32_16x16x32_bf16 v[80:83], v[192:195], v[216:219], v[80:83]
	v_mfma_f32_16x16x32_bf16 v[96:99], v[192:195], v[208:211], v[96:99]
	v_mfma_f32_16x16x32_bf16 v[112:115], v[192:195], v[200:203], v[112:115]
	s_setprio 0
	s_barrier
	s_add_i32 s48, s36, s5
	v_lshl_add_u64 v[162:163], s[72:73], 0, v[138:139]
	s_mov_b32 m0, s48
	ds_read_b128 v[196:199], v181 offset:16384
	ds_read_b128 v[200:203], v181 offset:17408
	ds_read_b128 v[204:207], v181 offset:18432
	ds_read_b128 v[208:211], v181 offset:19456
	ds_read_b128 v[212:215], v181 offset:20480
	ds_read_b128 v[216:219], v181 offset:21504
	ds_read_b128 v[220:223], v181 offset:22528
	ds_read_b128 v[224:227], v181 offset:23552
	global_load_lds_dwordx4 v[162:163], off
	s_add_i32 m0, s48, 0x2000
	v_lshl_add_u64 v[228:229], s[72:73], 0, v[142:143]
	s_add_u32 s72, s72, s44
	s_addc_u32 s73, s73, s45
	s_add_i32 s48, s37, s5
	global_load_lds_dwordx4 v[228:229], off
	v_lshl_add_u64 v[230:231], s[72:73], 0, v[138:139]
	s_mov_b32 m0, s48
	v_lshl_add_u64 v[232:233], s[72:73], 0, v[142:143]
	global_load_lds_dwordx4 v[230:231], off
	s_add_i32 m0, s48, 0x2000
	v_lshl_add_u64 v[234:235], s[68:69], 0, v[136:137]
	global_load_lds_dwordx4 v[232:233], off
	s_mov_b32 m0, s18
	v_lshl_add_u64 v[236:237], s[68:69], 0, v[140:141]
	global_load_lds_dwordx4 v[234:235], off
	s_mov_b32 m0, s19
	s_nop 0
	global_load_lds_dwordx4 v[236:237], off
	s_waitcnt vmcnt(8)
	s_waitcnt lgkmcnt(0)
	s_barrier
; #define PG8_STAGE(bufoff, gbase, voff) do { _Pragma("unroll") for (int _i = 0; _i < 2; ++_i) \
;         __builtin_amdgcn_global_load_lds((const unsigned*)((const char*)(gbase) + (voff)[_i]), (PG8_LAS unsigned*)(lds + (bufoff) + ldsw + _i * 8192), 16, 0, 0); } while (0)
; #define PG8_LDA(dst, b, h) do { _Pragma("unroll") for (int m = 0; m < 4; ++m) _Pragma("unroll") for (int k = 0; k < 2; ++k) dst[m][k] = *(const PG8_LAS bf16x8*)(lds + PG8_SA(b, h) + aoff + m * 2048 + k * 1024); } while (0)
; #define PG8_LDB(dst, b, h) do { _Pragma("unroll") for (int n = 0; n < 2; ++n) _Pragma("unroll") for (int k = 0; k < 2; ++k) dst[n][k] = *(const PG8_LAS bf16x8*)(lds + PG8_SB(b, h) + boff + n * 2048 + k * 1024); } while (0)
; #define PG8_MMA(ai, bj, At, Bt) do { __builtin_amdgcn_s_setprio(1); _Pragma("unroll") for (int m = 0; m < 4; ++m) _Pragma("unroll") for (int n = 0; n < 2; ++n) _Pragma("unroll") for (int k = 0; k < 2; ++k) \
;         acc[ai][bj][m][n] = __builtin_amdgcn_mfma_f32_16x16x32_bf16(Bt[n][k], At[m][k], acc[ai][bj][m][n], 0, 0, 0); __builtin_amdgcn_s_setprio(0); } while (0)
; #define PG8_WAIT_V(n) asm volatile("s_waitcnt vmcnt(" #n ")" ::: "memory")
; #define PG8_WAIT_L(n) asm volatile("s_waitcnt lgkmcnt(" #n ")" ::: "memory")
; #define PG8_BAR __builtin_amdgcn_s_barrier()
; #define PG8_SCHED __builtin_amdgcn_sched_barrier(0)
; template <class Epi, class Sched, bool ALIGN_EPI = false, bool SP2 = false>
; __device__ __forceinline__ void gemm_phase(PG8_LAS unsigned char* lds, const Gemm g, const Sched& S, const Epi& E) {
;     ...
;             PG8_WAIT_V(8); PG8_WAIT_L(0); PG8_BAR; PG8_MMA(1, 0, At, B0); PG8_MMA(1, 1, At, B1); PG8_BAR; PG8_SCHED;
;             PG8_LDB(B0, 1, 0); PG8_LDB(B1, 1, 1); PG8_SCHED; PG8_LDA(At, 1, 0); PG8_STAGE(PG8_SA(0, 1), a2 + hstep, voffA);
;             PG8_WAIT_V(8); PG8_WAIT_L(0); PG8_BAR; PG8_MMA(0, 0, At, B0); PG8_MMA(0, 1, At, B1); PG8_BAR; PG8_SCHED;
	s_setprio 1
	s_waitcnt lgkmcnt(0)
	v_mfma_f32_16x16x32_bf16 v[60:63], v[128:131], v[196:199], v[60:63]
	v_mfma_f32_16x16x32_bf16 v[44:47], v[128:131], v[204:207], v[44:47]
	v_mfma_f32_16x16x32_bf16 v[28:31], v[128:131], v[212:215], v[28:31]
	v_mfma_f32_16x16x32_bf16 v[12:15], v[128:131], v[220:223], v[12:15]
	v_mfma_f32_16x16x32_bf16 v[4:7], v[166:169], v[220:223], v[4:7]
	v_mfma_f32_16x16x32_bf16 v[20:23], v[166:169], v[212:215], v[20:23]
	v_mfma_f32_16x16x32_bf16 v[36:39], v[166:169], v[204:207], v[36:39]
	v_mfma_f32_16x16x32_bf16 v[52:55], v[166:169], v[196:199], v[52:55]
	v_mfma_f32_16x16x32_bf16 v[60:63], v[132:135], v[200:203], v[60:63]
	v_mfma_f32_16x16x32_bf16 v[44:47], v[132:135], v[208:211], v[44:47]
	v_mfma_f32_16x16x32_bf16 v[28:31], v[132:135], v[216:219], v[28:31]
	v_mfma_f32_16x16x32_bf16 v[12:15], v[132:135], v[224:227], v[12:15]
	v_mfma_f32_16x16x32_bf16 v[4:7], v[170:173], v[224:227], v[4:7]
	v_mfma_f32_16x16x32_bf16 v[20:23], v[170:173], v[216:219], v[20:23]
	v_mfma_f32_16x16x32_bf16 v[36:39], v[170:173], v[208:211], v[36:39]
	v_mfma_f32_16x16x32_bf16 v[52:55], v[170:173], v[200:203], v[52:55]
	s_setprio 0
	s_setprio 1
	v_mfma_f32_16x16x32_bf16 v[56:59], v[174:177], v[196:199], v[56:59]
	v_mfma_f32_16x16x32_bf16 v[40:43], v[174:177], v[204:207], v[40:43]
	v_mfma_f32_16x16x32_bf16 v[24:27], v[174:177], v[212:215], v[24:27]
	v_mfma_f32_16x16x32_bf16 v[8:11], v[174:177], v[220:223], v[8:11]
	v_mfma_f32_16x16x32_bf16 v[0:3], v[188:191], v[220:223], v[0:3]
	v_mfma_f32_16x16x32_bf16 v[16:19], v[188:191], v[212:215], v[16:19]
	v_mfma_f32_16x16x32_bf16 v[32:35], v[188:191], v[204:207], v[32:35]
	v_mfma_f32_16x16x32_bf16 v[48:51], v[188:191], v[196:199], v[48:51]
	v_mfma_f32_16x16x32_bf16 v[56:59], v[184:187], v[200:203], v[56:59]
	v_mfma_f32_16x16x32_bf16 v[40:43], v[184:187], v[208:211], v[40:43]
	v_mfma_f32_16x16x32_bf16 v[24:27], v[184:187], v[216:219], v[24:27]
	v_mfma_f32_16x16x32_bf16 v[8:11], v[184:187], v[224:227], v[8:11]
	v_mfma_f32_16x16x32_bf16 v[0:3], v[192:195], v[224:227], v[0:3]
	v_mfma_f32_16x16x32_bf16 v[16:19], v[192:195], v[216:219], v[16:19]
	v_mfma_f32_16x16x32_bf16 v[32:35], v[192:195], v[208:211], v[32:35]
	v_mfma_f32_16x16x32_bf16 v[48:51], v[192:195], v[200:203], v[48:51]
	s_setprio 0
	s_barrier
	s_add_i32 s48, 0, 0x18000
	v_add_u32_e32 v144, s48, v165
	s_add_i32 s71, 0, 0x1c000
	ds_read_b128 v[128:131], v144
	ds_read_b128 v[132:135], v144 offset:1024
	ds_read_b128 v[166:169], v144 offset:2048
	ds_read_b128 v[170:173], v144 offset:3072
	v_add_u32_e32 v144, s71, v165
	ds_read_b128 v[174:177], v144
	ds_read_b128 v[184:187], v144 offset:1024
	ds_read_b128 v[188:191], v144 offset:2048
	ds_read_b128 v[192:195], v144 offset:3072
	s_add_u32 s68, s68, s44
	s_addc_u32 s69, s69, s45
	s_mov_b32 m0, s26
	v_lshl_add_u64 v[238:239], s[68:69], 0, v[136:137]
	ds_read_b128 v[196:199], v181 offset:32768
	ds_read_b128 v[200:203], v181 offset:33792
	ds_read_b128 v[204:207], v181 offset:34816
	ds_read_b128 v[208:211], v181 offset:35840
	ds_read_b128 v[212:215], v181 offset:36864
	ds_read_b128 v[216:219], v181 offset:37888
	ds_read_b128 v[220:223], v181 offset:38912
	ds_read_b128 v[224:227], v181 offset:39936
	global_load_lds_dwordx4 v[238:239], off
	v_lshl_add_u64 v[238:239], s[68:69], 0, v[140:141]
	s_mov_b32 m0, s27
	s_nop 0
	global_load_lds_dwordx4 v[238:239], off
	s_waitcnt vmcnt(8)
	s_waitcnt lgkmcnt(0)
	s_barrier
	s_setprio 1
	s_waitcnt lgkmcnt(0)
	v_mfma_f32_16x16x32_bf16 v[124:127], v[128:131], v[196:199], v[124:127]
	v_mfma_f32_16x16x32_bf16 v[108:111], v[128:131], v[204:207], v[108:111]
	v_mfma_f32_16x16x32_bf16 v[92:95], v[128:131], v[212:215], v[92:95]
	v_mfma_f32_16x16x32_bf16 v[76:79], v[128:131], v[220:223], v[76:79]
	v_mfma_f32_16x16x32_bf16 v[68:71], v[166:169], v[220:223], v[68:71]
	v_mfma_f32_16x16x32_bf16 v[84:87], v[166:169], v[212:215], v[84:87]
	v_mfma_f32_16x16x32_bf16 v[100:103], v[166:169], v[204:207], v[100:103]
	v_mfma_f32_16x16x32_bf16 v[116:119], v[166:169], v[196:199], v[116:119]
	v_mfma_f32_16x16x32_bf16 v[124:127], v[132:135], v[200:203], v[124:127]
	v_mfma_f32_16x16x32_bf16 v[108:111], v[132:135], v[208:211], v[108:111]
	v_mfma_f32_16x16x32_bf16 v[92:95], v[132:135], v[216:219], v[92:95]
	v_mfma_f32_16x16x32_bf16 v[76:79], v[132:135], v[224:227], v[76:79]
	v_mfma_f32_16x16x32_bf16 v[68:71], v[170:173], v[224:227], v[68:71]
	v_mfma_f32_16x16x32_bf16 v[84:87], v[170:173], v[216:219], v[84:87]
	v_mfma_f32_16x16x32_bf16 v[100:103], v[170:173], v[208:211], v[100:103]
	v_mfma_f32_16x16x32_bf16 v[116:119], v[170:173], v[200:203], v[116:119]
	s_setprio 0
	s_setprio 1
	v_mfma_f32_16x16x32_bf16 v[120:123], v[174:177], v[196:199], v[120:123]
	v_mfma_f32_16x16x32_bf16 v[104:107], v[174:177], v[204:207], v[104:107]
	v_mfma_f32_16x16x32_bf16 v[88:91], v[174:177], v[212:215], v[88:91]
	v_mfma_f32_16x16x32_bf16 v[72:75], v[174:177], v[220:223], v[72:75]
	v_mfma_f32_16x16x32_bf16 v[64:67], v[188:191], v[220:223], v[64:67]
	v_mfma_f32_16x16x32_bf16 v[80:83], v[188:191], v[212:215], v[80:83]
	v_mfma_f32_16x16x32_bf16 v[96:99], v[188:191], v[204:207], v[96:99]
	v_mfma_f32_16x16x32_bf16 v[112:115], v[188:191], v[196:199], v[112:115]
	v_mfma_f32_16x16x32_bf16 v[120:123], v[184:187], v[200:203], v[120:123]
	v_mfma_f32_16x16x32_bf16 v[104:107], v[184:187], v[208:211], v[104:107]
	v_mfma_f32_16x16x32_bf16 v[88:91], v[184:187], v[216:219], v[88:91]
	v_mfma_f32_16x16x32_bf16 v[72:75], v[184:187], v[224:227], v[72:75]
	v_mfma_f32_16x16x32_bf16 v[64:67], v[192:195], v[224:227], v[64:67]
	v_mfma_f32_16x16x32_bf16 v[80:83], v[192:195], v[216:219], v[80:83]
	v_mfma_f32_16x16x32_bf16 v[96:99], v[192:195], v[208:211], v[96:99]
	v_mfma_f32_16x16x32_bf16 v[112:115], v[192:195], v[200:203], v[112:115]
	s_setprio 0
	s_barrier
; #define PG8_STAGE(bufoff, gbase, voff) do { _Pragma("unroll") for (int _i = 0; _i < 2; ++_i) \
;         __builtin_amdgcn_global_load_lds((const unsigned*)((const char*)(gbase) + (voff)[_i]), (PG8_LAS unsigned*)(lds + (bufoff) + ldsw + _i * 8192), 16, 0, 0); } while (0)
; #define PG8_LDA(dst, b, h) do { _Pragma("unroll") for (int m = 0; m < 4; ++m) _Pragma("unroll") for (int k = 0; k < 2; ++k) dst[m][k] = *(const PG8_LAS bf16x8*)(lds + PG8_SA(b, h) + aoff + m * 2048 + k * 1024); } while (0)
; #define PG8_MMA(ai, bj, At, Bt) do { __builtin_amdgcn_s_setprio(1); _Pragma("unroll") for (int m = 0; m < 4; ++m) _Pragma("unroll") for (int n = 0; n < 2; ++n) _Pragma("unroll") for (int k = 0; k < 2; ++k) \
;         acc[ai][bj][m][n] = __builtin_amdgcn_mfma_f32_16x16x32_bf16(Bt[n][k], At[m][k], acc[ai][bj][m][n], 0, 0, 0); __builtin_amdgcn_s_setprio(0); } while (0)
; #define PG8_WAIT_V(n) asm volatile("s_waitcnt vmcnt(" #n ")" ::: "memory")
; #define PG8_WAIT_L(n) asm volatile("s_waitcnt lgkmcnt(" #n ")" ::: "memory")
; #define PG8_BAR __builtin_amdgcn_s_barrier()
; #define PG8_SCHED __builtin_amdgcn_sched_barrier(0)
; template <class Epi, class Sched, bool ALIGN_EPI = false, bool SP2 = false>
; __device__ __forceinline__ void gemm_phase(PG8_LAS unsigned char* lds, const Gemm g, const Sched& S, const Epi& E) {
;     ...
;         for (int t = 0; t < nt; t += 2) {
;             const bool last = (t == nt - 2);
;             const char* a1 = cA + (size_t)(t + 1) * kstep;
;             const char* a2 = last ? nA : cA + (size_t)(t + 2) * kstep; const char* b2 = last ? nB : cB + (size_t)(t + 2) * kstep;
;     ...
;             PG8_LDA(At, 1, 1); PG8_STAGE(PG8_SB(1, 0), b3, voffB); PG8_STAGE(PG8_SB(1, 1), b3 + hstep, voffB); PG8_STAGE(PG8_SA(1, 0), a3, voffA);
;             PG8_WAIT_V(8); PG8_WAIT_L(0); PG8_BAR; PG8_MMA(1, 0, At, B0); PG8_MMA(1, 1, At, B1); PG8_BAR; PG8_SCHED;
	s_add_i32 s48, s48, s5
	v_lshl_add_u64 v[162:163], v[162:163], 0, s[52:53]
	s_mov_b32 m0, s48
	ds_read_b128 v[196:199], v181 offset:49152
	ds_read_b128 v[200:203], v181 offset:50176
	ds_read_b128 v[204:207], v181 offset:51200
	ds_read_b128 v[208:211], v181 offset:52224
	ds_read_b128 v[212:215], v181 offset:53248
	ds_read_b128 v[216:219], v181 offset:54272
	ds_read_b128 v[220:223], v181 offset:55296
	ds_read_b128 v[224:227], v181 offset:56320
	global_load_lds_dwordx4 v[162:163], off
	v_lshl_add_u64 v[162:163], v[228:229], 0, s[52:53]
	s_add_i32 m0, s48, 0x2000
	s_add_i32 s48, s71, s5
	global_load_lds_dwordx4 v[162:163], off
	v_lshl_add_u64 v[162:163], v[230:231], 0, s[52:53]
	s_mov_b32 m0, s48
	s_nop 0
	global_load_lds_dwordx4 v[162:163], off
	v_lshl_add_u64 v[162:163], v[232:233], 0, s[52:53]
	s_add_i32 m0, s48, 0x2000
	s_nop 0
	global_load_lds_dwordx4 v[162:163], off
	v_lshl_add_u64 v[162:163], v[234:235], 0, s[52:53]
	s_mov_b32 m0, s30
	s_nop 0
	global_load_lds_dwordx4 v[162:163], off
	v_lshl_add_u64 v[162:163], v[236:237], 0, s[52:53]
	s_mov_b32 m0, s31
	s_nop 0
	global_load_lds_dwordx4 v[162:163], off
	s_waitcnt vmcnt(8)
	s_waitcnt lgkmcnt(0)
	s_barrier
	s_setprio 1
	s_waitcnt lgkmcnt(0)
	v_mfma_f32_16x16x32_bf16 v[60:63], v[128:131], v[196:199], v[60:63]
	v_mfma_f32_16x16x32_bf16 v[44:47], v[128:131], v[204:207], v[44:47]
	v_mfma_f32_16x16x32_bf16 v[28:31], v[128:131], v[212:215], v[28:31]
	v_mfma_f32_16x16x32_bf16 v[12:15], v[128:131], v[220:223], v[12:15]
	v_mfma_f32_16x16x32_bf16 v[4:7], v[166:169], v[220:223], v[4:7]
	v_mfma_f32_16x16x32_bf16 v[20:23], v[166:169], v[212:215], v[20:23]
	v_mfma_f32_16x16x32_bf16 v[36:39], v[166:169], v[204:207], v[36:39]
	v_mfma_f32_16x16x32_bf16 v[52:55], v[166:169], v[196:199], v[52:55]
	v_mfma_f32_16x16x32_bf16 v[60:63], v[132:135], v[200:203], v[60:63]
	v_mfma_f32_16x16x32_bf16 v[44:47], v[132:135], v[208:211], v[44:47]
	v_mfma_f32_16x16x32_bf16 v[28:31], v[132:135], v[216:219], v[28:31]
	v_mfma_f32_16x16x32_bf16 v[12:15], v[132:135], v[224:227], v[12:15]
	v_mfma_f32_16x16x32_bf16 v[4:7], v[170:173], v[224:227], v[4:7]
	v_mfma_f32_16x16x32_bf16 v[20:23], v[170:173], v[216:219], v[20:23]
	v_mfma_f32_16x16x32_bf16 v[36:39], v[170:173], v[208:211], v[36:39]
	v_mfma_f32_16x16x32_bf16 v[52:55], v[170:173], v[200:203], v[52:55]
	s_setprio 0
	s_setprio 1
	v_mfma_f32_16x16x32_bf16 v[56:59], v[174:177], v[196:199], v[56:59]
	v_mfma_f32_16x16x32_bf16 v[40:43], v[174:177], v[204:207], v[40:43]
	v_mfma_f32_16x16x32_bf16 v[24:27], v[174:177], v[212:215], v[24:27]
	v_mfma_f32_16x16x32_bf16 v[8:11], v[174:177], v[220:223], v[8:11]
	v_mfma_f32_16x16x32_bf16 v[0:3], v[188:191], v[220:223], v[0:3]
	v_mfma_f32_16x16x32_bf16 v[16:19], v[188:191], v[212:215], v[16:19]
	v_mfma_f32_16x16x32_bf16 v[32:35], v[188:191], v[204:207], v[32:35]
	v_mfma_f32_16x16x32_bf16 v[48:51], v[188:191], v[196:199], v[48:51]
	v_mfma_f32_16x16x32_bf16 v[56:59], v[184:187], v[200:203], v[56:59]
	v_mfma_f32_16x16x32_bf16 v[40:43], v[184:187], v[208:211], v[40:43]
	v_mfma_f32_16x16x32_bf16 v[24:27], v[184:187], v[216:219], v[24:27]
	v_mfma_f32_16x16x32_bf16 v[8:11], v[184:187], v[224:227], v[8:11]
	v_mfma_f32_16x16x32_bf16 v[0:3], v[192:195], v[224:227], v[0:3]
	v_mfma_f32_16x16x32_bf16 v[16:19], v[192:195], v[216:219], v[16:19]
	v_mfma_f32_16x16x32_bf16 v[32:35], v[192:195], v[208:211], v[32:35]
	v_mfma_f32_16x16x32_bf16 v[48:51], v[192:195], v[200:203], v[48:51]
	s_setprio 0
	s_barrier
	s_add_u32 s14, s14, 0x100
	s_addc_u32 s15, s15, 0
	s_add_u32 s24, s24, 0x100
	s_addc_u32 s25, s25, 0
	s_cmp_ge_i32 s70, s33
	s_mov_b32 s48, s70
	s_cbranch_scc0 .LBB0_1695

; #define PG8_STAGE(bufoff, gbase, voff) do { _Pragma("unroll") for (int _i = 0; _i < 2; ++_i) \
;         __builtin_amdgcn_global_load_lds((const unsigned*)((const char*)(gbase) + (voff)[_i]), (PG8_LAS unsigned*)(lds + (bufoff) + ldsw + _i * 8192), 16, 0, 0); } while (0)
; #define PG8_LDA(dst, b, h) do { _Pragma("unroll") for (int m = 0; m < 4; ++m) _Pragma("unroll") for (int k = 0; k < 2; ++k) dst[m][k] = *(const PG8_LAS bf16x8*)(lds + PG8_SA(b, h) + aoff + m * 2048 + k * 1024); } while (0)
; #define PG8_LDB(dst, b, h) do { _Pragma("unroll") for (int n = 0; n < 2; ++n) _Pragma("unroll") for (int k = 0; k < 2; ++k) dst[n][k] = *(const PG8_LAS bf16x8*)(lds + PG8_SB(b, h) + boff + n * 2048 + k * 1024); } while (0)
; #define PG8_MMA(ai, bj, At, Bt) do { __builtin_amdgcn_s_setprio(1); _Pragma("unroll") for (int m = 0; m < 4; ++m) _Pragma("unroll") for (int n = 0; n < 2; ++n) _Pragma("unroll") for (int k = 0; k < 2; ++k) \
;         acc[ai][bj][m][n] = __builtin_amdgcn_mfma_f32_16x16x32_bf16(Bt[n][k], At[m][k], acc[ai][bj][m][n], 0, 0, 0); __builtin_amdgcn_s_setprio(0); } while (0)
; #define PG8_WAIT_V(n) asm volatile("s_waitcnt vmcnt(" #n ")" ::: "memory")
; #define PG8_WAIT_L(n) asm volatile("s_waitcnt lgkmcnt(" #n ")" ::: "memory")
; #define PG8_BAR __builtin_amdgcn_s_barrier()
; #define PG8_SCHED __builtin_amdgcn_sched_barrier(0)
; template <class Epi, class Sched, bool ALIGN_EPI = false, bool SP2 = false>
; __device__ __forceinline__ void gemm_phase(PG8_LAS unsigned char* lds, const Gemm g, const Sched& S, const Epi& E) {
;     ...
;             PG8_LDB(B0, 0, 0); PG8_LDB(B1, 0, 1); PG8_SCHED; PG8_LDA(At, 0, 0); PG8_STAGE(PG8_SA(1, 1), a1 + hstep, voffA);
;             PG8_WAIT_V(8); PG8_WAIT_L(0); PG8_BAR; PG8_MMA(0, 0, At, B0); PG8_MMA(0, 1, At, B1); PG8_BAR; PG8_SCHED;
;             PG8_LDA(At, 0, 1); PG8_STAGE(PG8_SB(0, 0), b2, voffB); PG8_STAGE(PG8_SB(0, 1), b2 + hstep, voffB); PG8_STAGE(PG8_SA(0, 0), a2, voffA);
;             PG8_WAIT_V(8); PG8_WAIT_L(0); PG8_BAR; PG8_MMA(1, 0, At, B0); PG8_MMA(1, 1, At, B1); PG8_BAR; PG8_SCHED;
.LBB0_1994:
	s_and_b64 vcc, exec, s[10:11]
	s_cbranch_vccnz .Lcoldz_8
	s_add_u32 s58, s58, 0x80
	s_addc_u32 s59, s59, 0
	s_add_u32 s24, s60, 0x100
	s_addc_u32 s25, s61, 0
	s_mov_b32 s60, 0
	ds_read_b128 v[128:131], v216
	ds_read_b128 v[132:135], v216 offset:1024
	ds_read_b128 v[136:139], v216 offset:2048
	ds_read_b128 v[140:143], v216 offset:3072
	ds_read_b128 v[144:147], v217
	ds_read_b128 v[148:151], v217 offset:1024
	ds_read_b128 v[152:155], v217 offset:2048
	ds_read_b128 v[156:159], v217 offset:3072
	s_add_i32 s65, s60, 2
	s_add_u32 s66, s58, 0x80
	s_addc_u32 s61, s59, 0
	s_cmp_eq_u32 s34, s60
	s_cselect_b32 s60, s14, s66
	s_cselect_b32 s61, s15, s61
	s_cselect_b32 s67, s57, s25
	s_cselect_b32 s66, s56, s24
	v_lshl_add_u64 v[212:213], s[58:59], 0, v[188:189]
	s_add_i32 m0, s18, 0xc000
	ds_read_b128 v[160:163], v218
	ds_read_b128 v[164:167], v218 offset:1024
	ds_read_b128 v[168:171], v218 offset:2048
	ds_read_b128 v[172:175], v218 offset:3072
	ds_read_b128 v[196:199], v218 offset:4096
	ds_read_b128 v[200:203], v218 offset:5120
	ds_read_b128 v[204:207], v218 offset:6144
	ds_read_b128 v[208:211], v218 offset:7168
	global_load_lds_dwordx4 v[212:213], off
	v_lshl_add_u64 v[212:213], s[58:59], 0, v[190:191]
	s_add_i32 m0, s18, 0xe000
	s_nop 0
	global_load_lds_dwordx4 v[212:213], off
	s_waitcnt vmcnt(8)
	s_waitcnt lgkmcnt(0)
	s_barrier
	s_setprio 1
	s_waitcnt lgkmcnt(0)
	v_mfma_f32_16x16x32_bf16 v[124:127], v[128:131], v[160:163], 0
	v_mfma_f32_16x16x32_bf16 v[120:123], v[136:139], v[160:163], 0
	v_mfma_f32_16x16x32_bf16 v[108:111], v[128:131], v[168:171], 0
	v_mfma_f32_16x16x32_bf16 v[104:107], v[136:139], v[168:171], 0
	v_mfma_f32_16x16x32_bf16 v[92:95], v[128:131], v[196:199], 0
	v_mfma_f32_16x16x32_bf16 v[88:91], v[136:139], v[196:199], 0
	v_mfma_f32_16x16x32_bf16 v[76:79], v[128:131], v[204:207], 0
	v_mfma_f32_16x16x32_bf16 v[72:75], v[136:139], v[204:207], 0
	v_mfma_f32_16x16x32_bf16 v[124:127], v[132:135], v[164:167], v[124:127]
	v_mfma_f32_16x16x32_bf16 v[108:111], v[132:135], v[172:175], v[108:111]
	v_mfma_f32_16x16x32_bf16 v[92:95], v[132:135], v[200:203], v[92:95]
	v_mfma_f32_16x16x32_bf16 v[76:79], v[132:135], v[208:211], v[76:79]
	v_mfma_f32_16x16x32_bf16 v[72:75], v[140:143], v[208:211], v[72:75]
	v_mfma_f32_16x16x32_bf16 v[88:91], v[140:143], v[200:203], v[88:91]
	v_mfma_f32_16x16x32_bf16 v[104:107], v[140:143], v[172:175], v[104:107]
	v_mfma_f32_16x16x32_bf16 v[120:123], v[140:143], v[164:167], v[120:123]
	s_setprio 0
	s_setprio 1
	v_mfma_f32_16x16x32_bf16 v[116:119], v[144:147], v[160:163], 0
	v_mfma_f32_16x16x32_bf16 v[112:115], v[152:155], v[160:163], 0
	v_mfma_f32_16x16x32_bf16 v[100:103], v[144:147], v[168:171], 0
	v_mfma_f32_16x16x32_bf16 v[96:99], v[152:155], v[168:171], 0
	v_mfma_f32_16x16x32_bf16 v[84:87], v[144:147], v[196:199], 0
	v_mfma_f32_16x16x32_bf16 v[80:83], v[152:155], v[196:199], 0
	v_mfma_f32_16x16x32_bf16 v[68:71], v[144:147], v[204:207], 0
	v_mfma_f32_16x16x32_bf16 v[64:67], v[152:155], v[204:207], 0
	v_mfma_f32_16x16x32_bf16 v[116:119], v[148:151], v[164:167], v[116:119]
	v_mfma_f32_16x16x32_bf16 v[100:103], v[148:151], v[172:175], v[100:103]
	v_mfma_f32_16x16x32_bf16 v[84:87], v[148:151], v[200:203], v[84:87]
	v_mfma_f32_16x16x32_bf16 v[68:71], v[148:151], v[208:211], v[68:71]
	v_mfma_f32_16x16x32_bf16 v[64:67], v[156:159], v[208:211], v[64:67]
	v_mfma_f32_16x16x32_bf16 v[80:83], v[156:159], v[200:203], v[80:83]
	v_mfma_f32_16x16x32_bf16 v[96:99], v[156:159], v[172:175], v[96:99]
	v_mfma_f32_16x16x32_bf16 v[112:115], v[156:159], v[164:167], v[112:115]
	s_setprio 0
	s_barrier
	s_add_i32 s68, s35, s4
	v_lshl_add_u64 v[212:213], s[66:67], 0, v[180:181]
	s_mov_b32 m0, s68
	ds_read_b128 v[160:163], v218 offset:16384
	ds_read_b128 v[164:167], v218 offset:17408
	ds_read_b128 v[168:171], v218 offset:18432
	ds_read_b128 v[172:175], v218 offset:19456
	ds_read_b128 v[196:199], v218 offset:20480
	ds_read_b128 v[200:203], v218 offset:21504
	ds_read_b128 v[204:207], v218 offset:22528
	ds_read_b128 v[208:211], v218 offset:23552
	global_load_lds_dwordx4 v[212:213], off
	s_add_i32 m0, s68, 0x2000
	v_lshl_add_u64 v[220:221], s[66:67], 0, v[176:177]
	s_add_u32 s66, s66, s44
	s_addc_u32 s67, s67, s45
	s_add_i32 s68, s36, s4
	global_load_lds_dwordx4 v[220:221], off
	v_lshl_add_u64 v[222:223], s[66:67], 0, v[180:181]
	s_mov_b32 m0, s68
	v_lshl_add_u64 v[224:225], s[66:67], 0, v[176:177]
	global_load_lds_dwordx4 v[222:223], off
	s_add_i32 m0, s68, 0x2000
	v_lshl_add_u64 v[226:227], s[60:61], 0, v[182:183]
	global_load_lds_dwordx4 v[224:225], off
	s_mov_b32 m0, s18
	v_lshl_add_u64 v[228:229], s[60:61], 0, v[178:179]
	global_load_lds_dwordx4 v[226:227], off
	s_mov_b32 m0, s19
	s_nop 0
	global_load_lds_dwordx4 v[228:229], off
	s_waitcnt vmcnt(8)
	s_waitcnt lgkmcnt(0)
	s_barrier
; #define PG8_STAGE(bufoff, gbase, voff) do { _Pragma("unroll") for (int _i = 0; _i < 2; ++_i) \
;         __builtin_amdgcn_global_load_lds((const unsigned*)((const char*)(gbase) + (voff)[_i]), (PG8_LAS unsigned*)(lds + (bufoff) + ldsw + _i * 8192), 16, 0, 0); } while (0)
; #define PG8_LDA(dst, b, h) do { _Pragma("unroll") for (int m = 0; m < 4; ++m) _Pragma("unroll") for (int k = 0; k < 2; ++k) dst[m][k] = *(const PG8_LAS bf16x8*)(lds + PG8_SA(b, h) + aoff + m * 2048 + k * 1024); } while (0)
; #define PG8_LDB(dst, b, h) do { _Pragma("unroll") for (int n = 0; n < 2; ++n) _Pragma("unroll") for (int k = 0; k < 2; ++k) dst[n][k] = *(const PG8_LAS bf16x8*)(lds + PG8_SB(b, h) + boff + n * 2048 + k * 1024); } while (0)
; #define PG8_MMA(ai, bj, At, Bt) do { __builtin_amdgcn_s_setprio(1); _Pragma("unroll") for (int m = 0; m < 4; ++m) _Pragma("unroll") for (int n = 0; n < 2; ++n) _Pragma("unroll") for (int k = 0; k < 2; ++k) \
;         acc[ai][bj][m][n] = __builtin_amdgcn_mfma_f32_16x16x32_bf16(Bt[n][k], At[m][k], acc[ai][bj][m][n], 0, 0, 0); __builtin_amdgcn_s_setprio(0); } while (0)
; #define PG8_WAIT_V(n) asm volatile("s_waitcnt vmcnt(" #n ")" ::: "memory")
; #define PG8_WAIT_L(n) asm volatile("s_waitcnt lgkmcnt(" #n ")" ::: "memory")
; #define PG8_BAR __builtin_amdgcn_s_barrier()
; #define PG8_SCHED __builtin_amdgcn_sched_barrier(0)
; template <class Epi, class Sched, bool ALIGN_EPI = false, bool SP2 = false>
; __device__ __forceinline__ void gemm_phase(PG8_LAS unsigned char* lds, const Gemm g, const Sched& S, const Epi& E) {
;     ...
;             PG8_WAIT_V(8); PG8_WAIT_L(0); PG8_BAR; PG8_MMA(1, 0, At, B0); PG8_MMA(1, 1, At, B1); PG8_BAR; PG8_SCHED;
;             PG8_LDB(B0, 1, 0); PG8_LDB(B1, 1, 1); PG8_SCHED; PG8_LDA(At, 1, 0); PG8_STAGE(PG8_SA(0, 1), a2 + hstep, voffA);
;             PG8_WAIT_V(8); PG8_WAIT_L(0); PG8_BAR; PG8_MMA(0, 0, At, B0); PG8_MMA(0, 1, At, B1); PG8_BAR; PG8_SCHED;
	s_setprio 1
	s_waitcnt lgkmcnt(0)
	v_mfma_f32_16x16x32_bf16 v[60:63], v[128:131], v[160:163], 0
	v_mfma_f32_16x16x32_bf16 v[56:59], v[136:139], v[160:163], 0
	v_mfma_f32_16x16x32_bf16 v[44:47], v[128:131], v[168:171], 0
	v_mfma_f32_16x16x32_bf16 v[40:43], v[136:139], v[168:171], 0
	v_mfma_f32_16x16x32_bf16 v[28:31], v[128:131], v[196:199], 0
	v_mfma_f32_16x16x32_bf16 v[24:27], v[136:139], v[196:199], 0
	v_mfma_f32_16x16x32_bf16 v[12:15], v[128:131], v[204:207], 0
	v_mfma_f32_16x16x32_bf16 v[8:11], v[136:139], v[204:207], 0
	v_mfma_f32_16x16x32_bf16 v[60:63], v[132:135], v[164:167], v[60:63]
	v_mfma_f32_16x16x32_bf16 v[44:47], v[132:135], v[172:175], v[44:47]
	v_mfma_f32_16x16x32_bf16 v[28:31], v[132:135], v[200:203], v[28:31]
	v_mfma_f32_16x16x32_bf16 v[12:15], v[132:135], v[208:211], v[12:15]
	v_mfma_f32_16x16x32_bf16 v[8:11], v[140:143], v[208:211], v[8:11]
	v_mfma_f32_16x16x32_bf16 v[24:27], v[140:143], v[200:203], v[24:27]
	v_mfma_f32_16x16x32_bf16 v[40:43], v[140:143], v[172:175], v[40:43]
	v_mfma_f32_16x16x32_bf16 v[56:59], v[140:143], v[164:167], v[56:59]
	s_setprio 0
	s_setprio 1
	v_mfma_f32_16x16x32_bf16 v[52:55], v[144:147], v[160:163], 0
	v_mfma_f32_16x16x32_bf16 v[48:51], v[152:155], v[160:163], 0
	v_mfma_f32_16x16x32_bf16 v[36:39], v[144:147], v[168:171], 0
	v_mfma_f32_16x16x32_bf16 v[32:35], v[152:155], v[168:171], 0
	v_mfma_f32_16x16x32_bf16 v[20:23], v[144:147], v[196:199], 0
	v_mfma_f32_16x16x32_bf16 v[16:19], v[152:155], v[196:199], 0
	v_mfma_f32_16x16x32_bf16 v[4:7], v[144:147], v[204:207], 0
	v_mfma_f32_16x16x32_bf16 v[0:3], v[152:155], v[204:207], 0
	v_mfma_f32_16x16x32_bf16 v[52:55], v[148:151], v[164:167], v[52:55]
	v_mfma_f32_16x16x32_bf16 v[36:39], v[148:151], v[172:175], v[36:39]
	v_mfma_f32_16x16x32_bf16 v[20:23], v[148:151], v[200:203], v[20:23]
	v_mfma_f32_16x16x32_bf16 v[4:7], v[148:151], v[208:211], v[4:7]
	v_mfma_f32_16x16x32_bf16 v[0:3], v[156:159], v[208:211], v[0:3]
	v_mfma_f32_16x16x32_bf16 v[16:19], v[156:159], v[200:203], v[16:19]
	v_mfma_f32_16x16x32_bf16 v[32:35], v[156:159], v[172:175], v[32:35]
	v_mfma_f32_16x16x32_bf16 v[48:51], v[156:159], v[164:167], v[48:51]
	s_setprio 0
	s_barrier
	s_add_i32 s66, 0, 0x18000
	s_add_i32 s67, 0, 0x1c000
	v_add_u32_e32 v140, s66, v214
	v_add_u32_e32 v156, s67, v214
	ds_read_b128 v[128:131], v140
	ds_read_b128 v[132:135], v140 offset:1024
	ds_read_b128 v[136:139], v140 offset:2048
	ds_read_b128 v[140:143], v140 offset:3072
	ds_read_b128 v[144:147], v156
	ds_read_b128 v[148:151], v156 offset:1024
	ds_read_b128 v[152:155], v156 offset:2048
	ds_read_b128 v[156:159], v156 offset:3072
	s_add_u32 s60, s60, s44
	s_addc_u32 s61, s61, s45
	s_mov_b32 m0, s26
	v_lshl_add_u64 v[230:231], s[60:61], 0, v[182:183]
	ds_read_b128 v[160:163], v218 offset:32768
	ds_read_b128 v[164:167], v218 offset:33792
	ds_read_b128 v[168:171], v218 offset:34816
	ds_read_b128 v[172:175], v218 offset:35840
	ds_read_b128 v[196:199], v218 offset:36864
	ds_read_b128 v[200:203], v218 offset:37888
	ds_read_b128 v[204:207], v218 offset:38912
	ds_read_b128 v[208:211], v218 offset:39936
	global_load_lds_dwordx4 v[230:231], off
	v_lshl_add_u64 v[230:231], s[60:61], 0, v[178:179]
	s_mov_b32 m0, s27
	s_nop 0
	global_load_lds_dwordx4 v[230:231], off
	s_waitcnt vmcnt(8)
	s_waitcnt lgkmcnt(0)
	s_barrier
	s_setprio 1
	s_waitcnt lgkmcnt(0)
	v_mfma_f32_16x16x32_bf16 v[124:127], v[128:131], v[160:163], v[124:127]
	v_mfma_f32_16x16x32_bf16 v[108:111], v[128:131], v[168:171], v[108:111]
	v_mfma_f32_16x16x32_bf16 v[92:95], v[128:131], v[196:199], v[92:95]
	v_mfma_f32_16x16x32_bf16 v[76:79], v[128:131], v[204:207], v[76:79]
	v_mfma_f32_16x16x32_bf16 v[72:75], v[136:139], v[204:207], v[72:75]
	v_mfma_f32_16x16x32_bf16 v[88:91], v[136:139], v[196:199], v[88:91]
	v_mfma_f32_16x16x32_bf16 v[104:107], v[136:139], v[168:171], v[104:107]
	v_mfma_f32_16x16x32_bf16 v[120:123], v[136:139], v[160:163], v[120:123]
	v_mfma_f32_16x16x32_bf16 v[124:127], v[132:135], v[164:167], v[124:127]
	v_mfma_f32_16x16x32_bf16 v[108:111], v[132:135], v[172:175], v[108:111]
	v_mfma_f32_16x16x32_bf16 v[92:95], v[132:135], v[200:203], v[92:95]
	v_mfma_f32_16x16x32_bf16 v[76:79], v[132:135], v[208:211], v[76:79]
	v_mfma_f32_16x16x32_bf16 v[72:75], v[140:143], v[208:211], v[72:75]
	v_mfma_f32_16x16x32_bf16 v[88:91], v[140:143], v[200:203], v[88:91]
	v_mfma_f32_16x16x32_bf16 v[104:107], v[140:143], v[172:175], v[104:107]
	v_mfma_f32_16x16x32_bf16 v[120:123], v[140:143], v[164:167], v[120:123]
	s_setprio 0
	s_setprio 1
	v_mfma_f32_16x16x32_bf16 v[116:119], v[144:147], v[160:163], v[116:119]
	v_mfma_f32_16x16x32_bf16 v[100:103], v[144:147], v[168:171], v[100:103]
	v_mfma_f32_16x16x32_bf16 v[84:87], v[144:147], v[196:199], v[84:87]
	v_mfma_f32_16x16x32_bf16 v[68:71], v[144:147], v[204:207], v[68:71]
	v_mfma_f32_16x16x32_bf16 v[64:67], v[152:155], v[204:207], v[64:67]
	v_mfma_f32_16x16x32_bf16 v[80:83], v[152:155], v[196:199], v[80:83]
	v_mfma_f32_16x16x32_bf16 v[96:99], v[152:155], v[168:171], v[96:99]
	v_mfma_f32_16x16x32_bf16 v[112:115], v[152:155], v[160:163], v[112:115]
	v_mfma_f32_16x16x32_bf16 v[116:119], v[148:151], v[164:167], v[116:119]
	v_mfma_f32_16x16x32_bf16 v[100:103], v[148:151], v[172:175], v[100:103]
	v_mfma_f32_16x16x32_bf16 v[84:87], v[148:151], v[200:203], v[84:87]
	v_mfma_f32_16x16x32_bf16 v[68:71], v[148:151], v[208:211], v[68:71]
	v_mfma_f32_16x16x32_bf16 v[64:67], v[156:159], v[208:211], v[64:67]
	v_mfma_f32_16x16x32_bf16 v[80:83], v[156:159], v[200:203], v[80:83]
	v_mfma_f32_16x16x32_bf16 v[96:99], v[156:159], v[172:175], v[96:99]
	v_mfma_f32_16x16x32_bf16 v[112:115], v[156:159], v[164:167], v[112:115]
	s_setprio 0
	s_barrier
; #define PG8_STAGE(bufoff, gbase, voff) do { _Pragma("unroll") for (int _i = 0; _i < 2; ++_i) \
;         __builtin_amdgcn_global_load_lds((const unsigned*)((const char*)(gbase) + (voff)[_i]), (PG8_LAS unsigned*)(lds + (bufoff) + ldsw + _i * 8192), 16, 0, 0); } while (0)
; #define PG8_LDA(dst, b, h) do { _Pragma("unroll") for (int m = 0; m < 4; ++m) _Pragma("unroll") for (int k = 0; k < 2; ++k) dst[m][k] = *(const PG8_LAS bf16x8*)(lds + PG8_SA(b, h) + aoff + m * 2048 + k * 1024); } while (0)
; #define PG8_LDB(dst, b, h) do { _Pragma("unroll") for (int n = 0; n < 2; ++n) _Pragma("unroll") for (int k = 0; k < 2; ++k) dst[n][k] = *(const PG8_LAS bf16x8*)(lds + PG8_SB(b, h) + boff + n * 2048 + k * 1024); } while (0)
; #define PG8_MMA(ai, bj, At, Bt) do { __builtin_amdgcn_s_setprio(1); _Pragma("unroll") for (int m = 0; m < 4; ++m) _Pragma("unroll") for (int n = 0; n < 2; ++n) _Pragma("unroll") for (int k = 0; k < 2; ++k) \
;         acc[ai][bj][m][n] = __builtin_amdgcn_mfma_f32_16x16x32_bf16(Bt[n][k], At[m][k], acc[ai][bj][m][n], 0, 0, 0); __builtin_amdgcn_s_setprio(0); } while (0)
; #define PG8_WAIT_V(n) asm volatile("s_waitcnt vmcnt(" #n ")" ::: "memory")
; #define PG8_WAIT_L(n) asm volatile("s_waitcnt lgkmcnt(" #n ")" ::: "memory")
; #define PG8_BAR __builtin_amdgcn_s_barrier()
; #define PG8_SCHED __builtin_amdgcn_sched_barrier(0)
; template <class Epi, class Sched, bool ALIGN_EPI = false, bool SP2 = false>
; __device__ __forceinline__ void gemm_phase(PG8_LAS unsigned char* lds, const Gemm g, const Sched& S, const Epi& E) {
;     ...
;         for (int t = 0; t < nt; t += 2) {
;             const bool last = (t == nt - 2);
;             const char* a1 = cA + (size_t)(t + 1) * kstep;
;             const char* a2 = last ? nA : cA + (size_t)(t + 2) * kstep; const char* b2 = last ? nB : cB + (size_t)(t + 2) * kstep;
;     ...
;             PG8_LDB(B0, 0, 0); PG8_LDB(B1, 0, 1); PG8_SCHED; PG8_LDA(At, 0, 0); PG8_STAGE(PG8_SA(1, 1), a1 + hstep, voffA);
;             PG8_WAIT_V(8); PG8_WAIT_L(0); PG8_BAR; PG8_MMA(0, 0, At, B0); PG8_MMA(0, 1, At, B1); PG8_BAR; PG8_SCHED;
;     ...
;             PG8_LDA(At, 1, 1); PG8_STAGE(PG8_SB(1, 0), b3, voffB); PG8_STAGE(PG8_SB(1, 1), b3 + hstep, voffB); PG8_STAGE(PG8_SA(1, 0), a3, voffA);
;             PG8_WAIT_V(8); PG8_WAIT_L(0); PG8_BAR; PG8_MMA(1, 0, At, B0); PG8_MMA(1, 1, At, B1); PG8_BAR; PG8_SCHED;
	s_add_i32 s60, s66, s4
	v_lshl_add_u64 v[212:213], v[212:213], 0, s[52:53]
	s_mov_b32 m0, s60
	ds_read_b128 v[160:163], v218 offset:49152
	ds_read_b128 v[164:167], v218 offset:50176
	ds_read_b128 v[168:171], v218 offset:51200
	ds_read_b128 v[172:175], v218 offset:52224
	ds_read_b128 v[196:199], v218 offset:53248
	ds_read_b128 v[200:203], v218 offset:54272
	ds_read_b128 v[204:207], v218 offset:55296
	ds_read_b128 v[208:211], v218 offset:56320
	global_load_lds_dwordx4 v[212:213], off
	v_lshl_add_u64 v[212:213], v[220:221], 0, s[52:53]
	s_add_i32 m0, s60, 0x2000
	s_add_i32 s60, s67, s4
	global_load_lds_dwordx4 v[212:213], off
	v_lshl_add_u64 v[212:213], v[222:223], 0, s[52:53]
	s_mov_b32 m0, s60
	s_nop 0
	global_load_lds_dwordx4 v[212:213], off
	v_lshl_add_u64 v[212:213], v[224:225], 0, s[52:53]
	s_add_i32 m0, s60, 0x2000
	s_nop 0
	global_load_lds_dwordx4 v[212:213], off
	v_lshl_add_u64 v[212:213], v[226:227], 0, s[52:53]
	s_mov_b32 m0, s3
	s_nop 0
	global_load_lds_dwordx4 v[212:213], off
	v_lshl_add_u64 v[212:213], v[228:229], 0, s[52:53]
	s_mov_b32 m0, s30
	s_nop 0
	global_load_lds_dwordx4 v[212:213], off
	s_waitcnt vmcnt(8)
	s_waitcnt lgkmcnt(0)
	s_barrier
	s_setprio 1
	s_waitcnt lgkmcnt(0)
	v_mfma_f32_16x16x32_bf16 v[60:63], v[128:131], v[160:163], v[60:63]
	v_mfma_f32_16x16x32_bf16 v[44:47], v[128:131], v[168:171], v[44:47]
	v_mfma_f32_16x16x32_bf16 v[28:31], v[128:131], v[196:199], v[28:31]
	v_mfma_f32_16x16x32_bf16 v[12:15], v[128:131], v[204:207], v[12:15]
	v_mfma_f32_16x16x32_bf16 v[8:11], v[136:139], v[204:207], v[8:11]
	v_mfma_f32_16x16x32_bf16 v[24:27], v[136:139], v[196:199], v[24:27]
	v_mfma_f32_16x16x32_bf16 v[40:43], v[136:139], v[168:171], v[40:43]
	v_mfma_f32_16x16x32_bf16 v[56:59], v[136:139], v[160:163], v[56:59]
	v_mfma_f32_16x16x32_bf16 v[60:63], v[132:135], v[164:167], v[60:63]
	v_mfma_f32_16x16x32_bf16 v[44:47], v[132:135], v[172:175], v[44:47]
	v_mfma_f32_16x16x32_bf16 v[28:31], v[132:135], v[200:203], v[28:31]
	v_mfma_f32_16x16x32_bf16 v[12:15], v[132:135], v[208:211], v[12:15]
	v_mfma_f32_16x16x32_bf16 v[8:11], v[140:143], v[208:211], v[8:11]
	v_mfma_f32_16x16x32_bf16 v[24:27], v[140:143], v[200:203], v[24:27]
	v_mfma_f32_16x16x32_bf16 v[40:43], v[140:143], v[172:175], v[40:43]
	v_mfma_f32_16x16x32_bf16 v[56:59], v[140:143], v[164:167], v[56:59]
	s_setprio 0
	s_setprio 1
	v_mfma_f32_16x16x32_bf16 v[52:55], v[144:147], v[160:163], v[52:55]
	v_mfma_f32_16x16x32_bf16 v[36:39], v[144:147], v[168:171], v[36:39]
	v_mfma_f32_16x16x32_bf16 v[20:23], v[144:147], v[196:199], v[20:23]
	v_mfma_f32_16x16x32_bf16 v[4:7], v[144:147], v[204:207], v[4:7]
	v_mfma_f32_16x16x32_bf16 v[0:3], v[152:155], v[204:207], v[0:3]
	v_mfma_f32_16x16x32_bf16 v[16:19], v[152:155], v[196:199], v[16:19]
	v_mfma_f32_16x16x32_bf16 v[32:35], v[152:155], v[168:171], v[32:35]
	v_mfma_f32_16x16x32_bf16 v[48:51], v[152:155], v[160:163], v[48:51]
	v_mfma_f32_16x16x32_bf16 v[52:55], v[148:151], v[164:167], v[52:55]
	v_mfma_f32_16x16x32_bf16 v[36:39], v[148:151], v[172:175], v[36:39]
	v_mfma_f32_16x16x32_bf16 v[20:23], v[148:151], v[200:203], v[20:23]
	v_mfma_f32_16x16x32_bf16 v[4:7], v[148:151], v[208:211], v[4:7]
	v_mfma_f32_16x16x32_bf16 v[0:3], v[156:159], v[208:211], v[0:3]
	v_mfma_f32_16x16x32_bf16 v[16:19], v[156:159], v[200:203], v[16:19]
	v_mfma_f32_16x16x32_bf16 v[32:35], v[156:159], v[172:175], v[32:35]
	v_mfma_f32_16x16x32_bf16 v[48:51], v[156:159], v[164:167], v[48:51]
	s_setprio 0
	s_barrier
	s_add_u32 s58, s58, 0x100
	s_addc_u32 s59, s59, 0
	s_add_u32 s24, s24, 0x100
	s_addc_u32 s25, s25, 0
	s_cmp_ge_i32 s65, s31
	s_mov_b32 s60, s65
	s_cbranch_scc1 .Lpeelx_8
.LBB0_1996:
	ds_read_b128 v[128:131], v216
	ds_read_b128 v[132:135], v216 offset:1024
	ds_read_b128 v[136:139], v216 offset:2048
	ds_read_b128 v[140:143], v216 offset:3072
	ds_read_b128 v[144:147], v217
	ds_read_b128 v[148:151], v217 offset:1024
	ds_read_b128 v[152:155], v217 offset:2048
	ds_read_b128 v[156:159], v217 offset:3072
	s_add_i32 s65, s60, 2
	s_add_u32 s66, s58, 0x80
	s_addc_u32 s61, s59, 0
	s_cmp_eq_u32 s34, s60
	s_cselect_b32 s60, s14, s66
	s_cselect_b32 s61, s15, s61
	s_cselect_b32 s67, s57, s25
	s_cselect_b32 s66, s56, s24
	v_lshl_add_u64 v[212:213], s[58:59], 0, v[188:189]
	s_add_i32 m0, s18, 0xc000
	ds_read_b128 v[160:163], v218
	ds_read_b128 v[164:167], v218 offset:1024
	ds_read_b128 v[168:171], v218 offset:2048
	ds_read_b128 v[172:175], v218 offset:3072
	ds_read_b128 v[196:199], v218 offset:4096
	ds_read_b128 v[200:203], v218 offset:5120
	ds_read_b128 v[204:207], v218 offset:6144
	ds_read_b128 v[208:211], v218 offset:7168
	global_load_lds_dwordx4 v[212:213], off
	v_lshl_add_u64 v[212:213], s[58:59], 0, v[190:191]
	s_add_i32 m0, s18, 0xe000
	s_nop 0
	global_load_lds_dwordx4 v[212:213], off
	s_waitcnt vmcnt(8)
	s_waitcnt lgkmcnt(0)
	s_barrier
; #define PG8_STAGE(bufoff, gbase, voff) do { _Pragma("unroll") for (int _i = 0; _i < 2; ++_i) \
;         __builtin_amdgcn_global_load_lds((const unsigned*)((const char*)(gbase) + (voff)[_i]), (PG8_LAS unsigned*)(lds + (bufoff) + ldsw + _i * 8192), 16, 0, 0); } while (0)
; #define PG8_LDA(dst, b, h) do { _Pragma("unroll") for (int m = 0; m < 4; ++m) _Pragma("unroll") for (int k = 0; k < 2; ++k) dst[m][k] = *(const PG8_LAS bf16x8*)(lds + PG8_SA(b, h) + aoff + m * 2048 + k * 1024); } while (0)
; #define PG8_LDB(dst, b, h) do { _Pragma("unroll") for (int n = 0; n < 2; ++n) _Pragma("unroll") for (int k = 0; k < 2; ++k) dst[n][k] = *(const PG8_LAS bf16x8*)(lds + PG8_SB(b, h) + boff + n * 2048 + k * 1024); } while (0)
; #define PG8_MMA(ai, bj, At, Bt) do { __builtin_amdgcn_s_setprio(1); _Pragma("unroll") for (int m = 0; m < 4; ++m) _Pragma("unroll") for (int n = 0; n < 2; ++n) _Pragma("unroll") for (int k = 0; k < 2; ++k) \
;         acc[ai][bj][m][n] = __builtin_amdgcn_mfma_f32_16x16x32_bf16(Bt[n][k], At[m][k], acc[ai][bj][m][n], 0, 0, 0); __builtin_amdgcn_s_setprio(0); } while (0)
; #define PG8_WAIT_V(n) asm volatile("s_waitcnt vmcnt(" #n ")" ::: "memory")
; #define PG8_WAIT_L(n) asm volatile("s_waitcnt lgkmcnt(" #n ")" ::: "memory")
; #define PG8_BAR __builtin_amdgcn_s_barrier()
; #define PG8_SCHED __builtin_amdgcn_sched_barrier(0)
; template <class Epi, class Sched, bool ALIGN_EPI = false, bool SP2 = false>
; __device__ __forceinline__ void gemm_phase(PG8_LAS unsigned char* lds, const Gemm g, const Sched& S, const Epi& E) {
;     ...
;             PG8_WAIT_V(8); PG8_WAIT_L(0); PG8_BAR; PG8_MMA(0, 0, At, B0); PG8_MMA(0, 1, At, B1); PG8_BAR; PG8_SCHED;
;             PG8_LDA(At, 0, 1); PG8_STAGE(PG8_SB(0, 0), b2, voffB); PG8_STAGE(PG8_SB(0, 1), b2 + hstep, voffB); PG8_STAGE(PG8_SA(0, 0), a2, voffA);
;             PG8_WAIT_V(8); PG8_WAIT_L(0); PG8_BAR; PG8_MMA(1, 0, At, B0); PG8_MMA(1, 1, At, B1); PG8_BAR; PG8_SCHED;
;             PG8_LDB(B0, 1, 0); PG8_LDB(B1, 1, 1); PG8_SCHED; PG8_LDA(At, 1, 0); PG8_STAGE(PG8_SA(0, 1), a2 + hstep, voffA);
;             PG8_WAIT_V(8); PG8_WAIT_L(0); PG8_BAR; PG8_MMA(0, 0, At, B0); PG8_MMA(0, 1, At, B1); PG8_BAR; PG8_SCHED;
	s_setprio 1
	s_waitcnt lgkmcnt(0)
	v_mfma_f32_16x16x32_bf16 v[124:127], v[128:131], v[160:163], v[124:127]
	v_mfma_f32_16x16x32_bf16 v[108:111], v[128:131], v[168:171], v[108:111]
	v_mfma_f32_16x16x32_bf16 v[92:95], v[128:131], v[196:199], v[92:95]
	v_mfma_f32_16x16x32_bf16 v[76:79], v[128:131], v[204:207], v[76:79]
	v_mfma_f32_16x16x32_bf16 v[72:75], v[136:139], v[204:207], v[72:75]
	v_mfma_f32_16x16x32_bf16 v[88:91], v[136:139], v[196:199], v[88:91]
	v_mfma_f32_16x16x32_bf16 v[104:107], v[136:139], v[168:171], v[104:107]
	v_mfma_f32_16x16x32_bf16 v[120:123], v[136:139], v[160:163], v[120:123]
	v_mfma_f32_16x16x32_bf16 v[124:127], v[132:135], v[164:167], v[124:127]
	v_mfma_f32_16x16x32_bf16 v[108:111], v[132:135], v[172:175], v[108:111]
	v_mfma_f32_16x16x32_bf16 v[92:95], v[132:135], v[200:203], v[92:95]
	v_mfma_f32_16x16x32_bf16 v[76:79], v[132:135], v[208:211], v[76:79]
	v_mfma_f32_16x16x32_bf16 v[72:75], v[140:143], v[208:211], v[72:75]
	v_mfma_f32_16x16x32_bf16 v[88:91], v[140:143], v[200:203], v[88:91]
	v_mfma_f32_16x16x32_bf16 v[104:107], v[140:143], v[172:175], v[104:107]
	v_mfma_f32_16x16x32_bf16 v[120:123], v[140:143], v[164:167], v[120:123]
	s_setprio 0
	s_setprio 1
	v_mfma_f32_16x16x32_bf16 v[116:119], v[144:147], v[160:163], v[116:119]
	v_mfma_f32_16x16x32_bf16 v[100:103], v[144:147], v[168:171], v[100:103]
	v_mfma_f32_16x16x32_bf16 v[84:87], v[144:147], v[196:199], v[84:87]
	v_mfma_f32_16x16x32_bf16 v[68:71], v[144:147], v[204:207], v[68:71]
	v_mfma_f32_16x16x32_bf16 v[64:67], v[152:155], v[204:207], v[64:67]
	v_mfma_f32_16x16x32_bf16 v[80:83], v[152:155], v[196:199], v[80:83]
	v_mfma_f32_16x16x32_bf16 v[96:99], v[152:155], v[168:171], v[96:99]
	v_mfma_f32_16x16x32_bf16 v[112:115], v[152:155], v[160:163], v[112:115]
	v_mfma_f32_16x16x32_bf16 v[116:119], v[148:151], v[164:167], v[116:119]
	v_mfma_f32_16x16x32_bf16 v[100:103], v[148:151], v[172:175], v[100:103]
	v_mfma_f32_16x16x32_bf16 v[84:87], v[148:151], v[200:203], v[84:87]
	v_mfma_f32_16x16x32_bf16 v[68:71], v[148:151], v[208:211], v[68:71]
	v_mfma_f32_16x16x32_bf16 v[64:67], v[156:159], v[208:211], v[64:67]
	v_mfma_f32_16x16x32_bf16 v[80:83], v[156:159], v[200:203], v[80:83]
	v_mfma_f32_16x16x32_bf16 v[96:99], v[156:159], v[172:175], v[96:99]
	v_mfma_f32_16x16x32_bf16 v[112:115], v[156:159], v[164:167], v[112:115]
	s_setprio 0
	s_barrier
	s_add_i32 s68, s35, s4
	v_lshl_add_u64 v[212:213], s[66:67], 0, v[180:181]
	s_mov_b32 m0, s68
	ds_read_b128 v[160:163], v218 offset:16384
	ds_read_b128 v[164:167], v218 offset:17408
	ds_read_b128 v[168:171], v218 offset:18432
	ds_read_b128 v[172:175], v218 offset:19456
	ds_read_b128 v[196:199], v218 offset:20480
	ds_read_b128 v[200:203], v218 offset:21504
	ds_read_b128 v[204:207], v218 offset:22528
	ds_read_b128 v[208:211], v218 offset:23552
	global_load_lds_dwordx4 v[212:213], off
	s_add_i32 m0, s68, 0x2000
	v_lshl_add_u64 v[220:221], s[66:67], 0, v[176:177]
	s_add_u32 s66, s66, s44
	s_addc_u32 s67, s67, s45
	s_add_i32 s68, s36, s4
	global_load_lds_dwordx4 v[220:221], off
	v_lshl_add_u64 v[222:223], s[66:67], 0, v[180:181]
	s_mov_b32 m0, s68
	v_lshl_add_u64 v[224:225], s[66:67], 0, v[176:177]
	global_load_lds_dwordx4 v[222:223], off
	s_add_i32 m0, s68, 0x2000
	v_lshl_add_u64 v[226:227], s[60:61], 0, v[182:183]
	global_load_lds_dwordx4 v[224:225], off
	s_mov_b32 m0, s18
	v_lshl_add_u64 v[228:229], s[60:61], 0, v[178:179]
	global_load_lds_dwordx4 v[226:227], off
	s_mov_b32 m0, s19
	s_nop 0
	global_load_lds_dwordx4 v[228:229], off
	s_waitcnt vmcnt(8)
	s_waitcnt lgkmcnt(0)
	s_barrier
	s_setprio 1
	s_waitcnt lgkmcnt(0)
	v_mfma_f32_16x16x32_bf16 v[60:63], v[128:131], v[160:163], v[60:63]
	v_mfma_f32_16x16x32_bf16 v[44:47], v[128:131], v[168:171], v[44:47]
	v_mfma_f32_16x16x32_bf16 v[28:31], v[128:131], v[196:199], v[28:31]
	v_mfma_f32_16x16x32_bf16 v[12:15], v[128:131], v[204:207], v[12:15]
	v_mfma_f32_16x16x32_bf16 v[8:11], v[136:139], v[204:207], v[8:11]
	v_mfma_f32_16x16x32_bf16 v[24:27], v[136:139], v[196:199], v[24:27]
	v_mfma_f32_16x16x32_bf16 v[40:43], v[136:139], v[168:171], v[40:43]
	v_mfma_f32_16x16x32_bf16 v[56:59], v[136:139], v[160:163], v[56:59]
	v_mfma_f32_16x16x32_bf16 v[60:63], v[132:135], v[164:167], v[60:63]
	v_mfma_f32_16x16x32_bf16 v[44:47], v[132:135], v[172:175], v[44:47]
	v_mfma_f32_16x16x32_bf16 v[28:31], v[132:135], v[200:203], v[28:31]
	v_mfma_f32_16x16x32_bf16 v[12:15], v[132:135], v[208:211], v[12:15]
	v_mfma_f32_16x16x32_bf16 v[8:11], v[140:143], v[208:211], v[8:11]
	v_mfma_f32_16x16x32_bf16 v[24:27], v[140:143], v[200:203], v[24:27]
	v_mfma_f32_16x16x32_bf16 v[40:43], v[140:143], v[172:175], v[40:43]
	v_mfma_f32_16x16x32_bf16 v[56:59], v[140:143], v[164:167], v[56:59]
	s_setprio 0
	s_setprio 1
	v_mfma_f32_16x16x32_bf16 v[52:55], v[144:147], v[160:163], v[52:55]
	v_mfma_f32_16x16x32_bf16 v[36:39], v[144:147], v[168:171], v[36:39]
	v_mfma_f32_16x16x32_bf16 v[20:23], v[144:147], v[196:199], v[20:23]
	v_mfma_f32_16x16x32_bf16 v[4:7], v[144:147], v[204:207], v[4:7]
	v_mfma_f32_16x16x32_bf16 v[0:3], v[152:155], v[204:207], v[0:3]
	v_mfma_f32_16x16x32_bf16 v[16:19], v[152:155], v[196:199], v[16:19]
	v_mfma_f32_16x16x32_bf16 v[32:35], v[152:155], v[168:171], v[32:35]
	v_mfma_f32_16x16x32_bf16 v[48:51], v[152:155], v[160:163], v[48:51]
	v_mfma_f32_16x16x32_bf16 v[52:55], v[148:151], v[164:167], v[52:55]
	v_mfma_f32_16x16x32_bf16 v[36:39], v[148:151], v[172:175], v[36:39]
	v_mfma_f32_16x16x32_bf16 v[20:23], v[148:151], v[200:203], v[20:23]
	v_mfma_f32_16x16x32_bf16 v[4:7], v[148:151], v[208:211], v[4:7]
	v_mfma_f32_16x16x32_bf16 v[0:3], v[156:159], v[208:211], v[0:3]
	v_mfma_f32_16x16x32_bf16 v[16:19], v[156:159], v[200:203], v[16:19]
	v_mfma_f32_16x16x32_bf16 v[32:35], v[156:159], v[172:175], v[32:35]
	v_mfma_f32_16x16x32_bf16 v[48:51], v[156:159], v[164:167], v[48:51]
	s_setprio 0
	s_barrier
; #define PG8_STAGE(bufoff, gbase, voff) do { _Pragma("unroll") for (int _i = 0; _i < 2; ++_i) \
;         __builtin_amdgcn_global_load_lds((const unsigned*)((const char*)(gbase) + (voff)[_i]), (PG8_LAS unsigned*)(lds + (bufoff) + ldsw + _i * 8192), 16, 0, 0); } while (0)
; #define PG8_LDA(dst, b, h) do { _Pragma("unroll") for (int m = 0; m < 4; ++m) _Pragma("unroll") for (int k = 0; k < 2; ++k) dst[m][k] = *(const PG8_LAS bf16x8*)(lds + PG8_SA(b, h) + aoff + m * 2048 + k * 1024); } while (0)
; #define PG8_LDB(dst, b, h) do { _Pragma("unroll") for (int n = 0; n < 2; ++n) _Pragma("unroll") for (int k = 0; k < 2; ++k) dst[n][k] = *(const PG8_LAS bf16x8*)(lds + PG8_SB(b, h) + boff + n * 2048 + k * 1024); } while (0)
; #define PG8_MMA(ai, bj, At, Bt) do { __builtin_amdgcn_s_setprio(1); _Pragma("unroll") for (int m = 0; m < 4; ++m) _Pragma("unroll") for (int n = 0; n < 2; ++n) _Pragma("unroll") for (int k = 0; k < 2; ++k) \
;         acc[ai][bj][m][n] = __builtin_amdgcn_mfma_f32_16x16x32_bf16(Bt[n][k], At[m][k], acc[ai][bj][m][n], 0, 0, 0); __builtin_amdgcn_s_setprio(0); } while (0)
; #define PG8_WAIT_V(n) asm volatile("s_waitcnt vmcnt(" #n ")" ::: "memory")
; #define PG8_WAIT_L(n) asm volatile("s_waitcnt lgkmcnt(" #n ")" ::: "memory")
; #define PG8_BAR __builtin_amdgcn_s_barrier()
; #define PG8_SCHED __builtin_amdgcn_sched_barrier(0)
; template <class Epi, class Sched, bool ALIGN_EPI = false, bool SP2 = false>
; __device__ __forceinline__ void gemm_phase(PG8_LAS unsigned char* lds, const Gemm g, const Sched& S, const Epi& E) {
;     ...
;             PG8_LDB(B0, 1, 0); PG8_LDB(B1, 1, 1); PG8_SCHED; PG8_LDA(At, 1, 0); PG8_STAGE(PG8_SA(0, 1), a2 + hstep, voffA);
;             PG8_WAIT_V(8); PG8_WAIT_L(0); PG8_BAR; PG8_MMA(0, 0, At, B0); PG8_MMA(0, 1, At, B1); PG8_BAR; PG8_SCHED;
	s_add_i32 s66, 0, 0x18000
	s_add_i32 s67, 0, 0x1c000
	v_add_u32_e32 v140, s66, v214
	v_add_u32_e32 v156, s67, v214
	ds_read_b128 v[128:131], v140
	ds_read_b128 v[132:135], v140 offset:1024
	ds_read_b128 v[136:139], v140 offset:2048
	ds_read_b128 v[140:143], v140 offset:3072
	ds_read_b128 v[144:147], v156
	ds_read_b128 v[148:151], v156 offset:1024
	ds_read_b128 v[152:155], v156 offset:2048
	ds_read_b128 v[156:159], v156 offset:3072
	s_add_u32 s60, s60, s44
	s_addc_u32 s61, s61, s45
	s_mov_b32 m0, s26
	v_lshl_add_u64 v[230:231], s[60:61], 0, v[182:183]
	ds_read_b128 v[160:163], v218 offset:32768
	ds_read_b128 v[164:167], v218 offset:33792
	ds_read_b128 v[168:171], v218 offset:34816
	ds_read_b128 v[172:175], v218 offset:35840
	ds_read_b128 v[196:199], v218 offset:36864
	ds_read_b128 v[200:203], v218 offset:37888
	ds_read_b128 v[204:207], v218 offset:38912
	ds_read_b128 v[208:211], v218 offset:39936
	global_load_lds_dwordx4 v[230:231], off
	v_lshl_add_u64 v[230:231], s[60:61], 0, v[178:179]
	s_mov_b32 m0, s27
	s_nop 0
	global_load_lds_dwordx4 v[230:231], off
	s_waitcnt vmcnt(8)
	s_waitcnt lgkmcnt(0)
	s_barrier
	s_setprio 1
	s_waitcnt lgkmcnt(0)
	v_mfma_f32_16x16x32_bf16 v[124:127], v[128:131], v[160:163], v[124:127]
	v_mfma_f32_16x16x32_bf16 v[108:111], v[128:131], v[168:171], v[108:111]
	v_mfma_f32_16x16x32_bf16 v[92:95], v[128:131], v[196:199], v[92:95]
	v_mfma_f32_16x16x32_bf16 v[76:79], v[128:131], v[204:207], v[76:79]
	v_mfma_f32_16x16x32_bf16 v[72:75], v[136:139], v[204:207], v[72:75]
	v_mfma_f32_16x16x32_bf16 v[88:91], v[136:139], v[196:199], v[88:91]
	v_mfma_f32_16x16x32_bf16 v[104:107], v[136:139], v[168:171], v[104:107]
	v_mfma_f32_16x16x32_bf16 v[120:123], v[136:139], v[160:163], v[120:123]
	v_mfma_f32_16x16x32_bf16 v[124:127], v[132:135], v[164:167], v[124:127]
	v_mfma_f32_16x16x32_bf16 v[108:111], v[132:135], v[172:175], v[108:111]
	v_mfma_f32_16x16x32_bf16 v[92:95], v[132:135], v[200:203], v[92:95]
	v_mfma_f32_16x16x32_bf16 v[76:79], v[132:135], v[208:211], v[76:79]
	v_mfma_f32_16x16x32_bf16 v[72:75], v[140:143], v[208:211], v[72:75]
	v_mfma_f32_16x16x32_bf16 v[88:91], v[140:143], v[200:203], v[88:91]
	v_mfma_f32_16x16x32_bf16 v[104:107], v[140:143], v[172:175], v[104:107]
	v_mfma_f32_16x16x32_bf16 v[120:123], v[140:143], v[164:167], v[120:123]
	s_setprio 0
	s_setprio 1
	v_mfma_f32_16x16x32_bf16 v[116:119], v[144:147], v[160:163], v[116:119]
	v_mfma_f32_16x16x32_bf16 v[100:103], v[144:147], v[168:171], v[100:103]
	v_mfma_f32_16x16x32_bf16 v[84:87], v[144:147], v[196:199], v[84:87]
	v_mfma_f32_16x16x32_bf16 v[68:71], v[144:147], v[204:207], v[68:71]
	v_mfma_f32_16x16x32_bf16 v[64:67], v[152:155], v[204:207], v[64:67]
	v_mfma_f32_16x16x32_bf16 v[80:83], v[152:155], v[196:199], v[80:83]
	v_mfma_f32_16x16x32_bf16 v[96:99], v[152:155], v[168:171], v[96:99]
	v_mfma_f32_16x16x32_bf16 v[112:115], v[152:155], v[160:163], v[112:115]
	v_mfma_f32_16x16x32_bf16 v[116:119], v[148:151], v[164:167], v[116:119]
	v_mfma_f32_16x16x32_bf16 v[100:103], v[148:151], v[172:175], v[100:103]
	v_mfma_f32_16x16x32_bf16 v[84:87], v[148:151], v[200:203], v[84:87]
	v_mfma_f32_16x16x32_bf16 v[68:71], v[148:151], v[208:211], v[68:71]
	v_mfma_f32_16x16x32_bf16 v[64:67], v[156:159], v[208:211], v[64:67]
	v_mfma_f32_16x16x32_bf16 v[80:83], v[156:159], v[200:203], v[80:83]
	v_mfma_f32_16x16x32_bf16 v[96:99], v[156:159], v[172:175], v[96:99]
	v_mfma_f32_16x16x32_bf16 v[112:115], v[156:159], v[164:167], v[112:115]
	s_setprio 0
	s_barrier
; #define PG8_STAGE(bufoff, gbase, voff) do { _Pragma("unroll") for (int _i = 0; _i < 2; ++_i) \
;         __builtin_amdgcn_global_load_lds((const unsigned*)((const char*)(gbase) + (voff)[_i]), (PG8_LAS unsigned*)(lds + (bufoff) + ldsw + _i * 8192), 16, 0, 0); } while (0)
; #define PG8_LDA(dst, b, h) do { _Pragma("unroll") for (int m = 0; m < 4; ++m) _Pragma("unroll") for (int k = 0; k < 2; ++k) dst[m][k] = *(const PG8_LAS bf16x8*)(lds + PG8_SA(b, h) + aoff + m * 2048 + k * 1024); } while (0)
; #define PG8_MMA(ai, bj, At, Bt) do { __builtin_amdgcn_s_setprio(1); _Pragma("unroll") for (int m = 0; m < 4; ++m) _Pragma("unroll") for (int n = 0; n < 2; ++n) _Pragma("unroll") for (int k = 0; k < 2; ++k) \
;         acc[ai][bj][m][n] = __builtin_amdgcn_mfma_f32_16x16x32_bf16(Bt[n][k], At[m][k], acc[ai][bj][m][n], 0, 0, 0); __builtin_amdgcn_s_setprio(0); } while (0)
; #define PG8_WAIT_V(n) asm volatile("s_waitcnt vmcnt(" #n ")" ::: "memory")
; #define PG8_WAIT_L(n) asm volatile("s_waitcnt lgkmcnt(" #n ")" ::: "memory")
; #define PG8_BAR __builtin_amdgcn_s_barrier()
; #define PG8_SCHED __builtin_amdgcn_sched_barrier(0)
; template <class Epi, class Sched, bool ALIGN_EPI = false, bool SP2 = false>
; __device__ __forceinline__ void gemm_phase(PG8_LAS unsigned char* lds, const Gemm g, const Sched& S, const Epi& E) {
;     ...
;         for (int t = 0; t < nt; t += 2) {
;             const bool last = (t == nt - 2);
;             const char* a1 = cA + (size_t)(t + 1) * kstep;
;             const char* a2 = last ? nA : cA + (size_t)(t + 2) * kstep; const char* b2 = last ? nB : cB + (size_t)(t + 2) * kstep;
;     ...
;             PG8_LDA(At, 1, 1); PG8_STAGE(PG8_SB(1, 0), b3, voffB); PG8_STAGE(PG8_SB(1, 1), b3 + hstep, voffB); PG8_STAGE(PG8_SA(1, 0), a3, voffA);
;             PG8_WAIT_V(8); PG8_WAIT_L(0); PG8_BAR; PG8_MMA(1, 0, At, B0); PG8_MMA(1, 1, At, B1); PG8_BAR; PG8_SCHED;
	s_add_i32 s60, s66, s4
	v_lshl_add_u64 v[212:213], v[212:213], 0, s[52:53]
	s_mov_b32 m0, s60
	ds_read_b128 v[160:163], v218 offset:49152
	ds_read_b128 v[164:167], v218 offset:50176
	ds_read_b128 v[168:171], v218 offset:51200
	ds_read_b128 v[172:175], v218 offset:52224
	ds_read_b128 v[196:199], v218 offset:53248
	ds_read_b128 v[200:203], v218 offset:54272
	ds_read_b128 v[204:207], v218 offset:55296
	ds_read_b128 v[208:211], v218 offset:56320
	global_load_lds_dwordx4 v[212:213], off
	v_lshl_add_u64 v[212:213], v[220:221], 0, s[52:53]
	s_add_i32 m0, s60, 0x2000
	s_add_i32 s60, s67, s4
	global_load_lds_dwordx4 v[212:213], off
	v_lshl_add_u64 v[212:213], v[222:223], 0, s[52:53]
	s_mov_b32 m0, s60
	s_nop 0
	global_load_lds_dwordx4 v[212:213], off
	v_lshl_add_u64 v[212:213], v[224:225], 0, s[52:53]
	s_add_i32 m0, s60, 0x2000
	s_nop 0
	global_load_lds_dwordx4 v[212:213], off
	v_lshl_add_u64 v[212:213], v[226:227], 0, s[52:53]
	s_mov_b32 m0, s3
	s_nop 0
	global_load_lds_dwordx4 v[212:213], off
	v_lshl_add_u64 v[212:213], v[228:229], 0, s[52:53]
	s_mov_b32 m0, s30
	s_nop 0
	global_load_lds_dwordx4 v[212:213], off
	s_waitcnt vmcnt(8)
	s_waitcnt lgkmcnt(0)
	s_barrier
	s_setprio 1
	s_waitcnt lgkmcnt(0)
	v_mfma_f32_16x16x32_bf16 v[60:63], v[128:131], v[160:163], v[60:63]
	v_mfma_f32_16x16x32_bf16 v[44:47], v[128:131], v[168:171], v[44:47]
	v_mfma_f32_16x16x32_bf16 v[28:31], v[128:131], v[196:199], v[28:31]
	v_mfma_f32_16x16x32_bf16 v[12:15], v[128:131], v[204:207], v[12:15]
	v_mfma_f32_16x16x32_bf16 v[8:11], v[136:139], v[204:207], v[8:11]
	v_mfma_f32_16x16x32_bf16 v[24:27], v[136:139], v[196:199], v[24:27]
	v_mfma_f32_16x16x32_bf16 v[40:43], v[136:139], v[168:171], v[40:43]
	v_mfma_f32_16x16x32_bf16 v[56:59], v[136:139], v[160:163], v[56:59]
	v_mfma_f32_16x16x32_bf16 v[60:63], v[132:135], v[164:167], v[60:63]
	v_mfma_f32_16x16x32_bf16 v[44:47], v[132:135], v[172:175], v[44:47]
	v_mfma_f32_16x16x32_bf16 v[28:31], v[132:135], v[200:203], v[28:31]
	v_mfma_f32_16x16x32_bf16 v[12:15], v[132:135], v[208:211], v[12:15]
	v_mfma_f32_16x16x32_bf16 v[8:11], v[140:143], v[208:211], v[8:11]
	v_mfma_f32_16x16x32_bf16 v[24:27], v[140:143], v[200:203], v[24:27]
	v_mfma_f32_16x16x32_bf16 v[40:43], v[140:143], v[172:175], v[40:43]
	v_mfma_f32_16x16x32_bf16 v[56:59], v[140:143], v[164:167], v[56:59]
	s_setprio 0
	s_setprio 1
	v_mfma_f32_16x16x32_bf16 v[52:55], v[144:147], v[160:163], v[52:55]
	v_mfma_f32_16x16x32_bf16 v[36:39], v[144:147], v[168:171], v[36:39]
	v_mfma_f32_16x16x32_bf16 v[20:23], v[144:147], v[196:199], v[20:23]
	v_mfma_f32_16x16x32_bf16 v[4:7], v[144:147], v[204:207], v[4:7]
	v_mfma_f32_16x16x32_bf16 v[0:3], v[152:155], v[204:207], v[0:3]
	v_mfma_f32_16x16x32_bf16 v[16:19], v[152:155], v[196:199], v[16:19]
	v_mfma_f32_16x16x32_bf16 v[32:35], v[152:155], v[168:171], v[32:35]
	v_mfma_f32_16x16x32_bf16 v[48:51], v[152:155], v[160:163], v[48:51]
	v_mfma_f32_16x16x32_bf16 v[52:55], v[148:151], v[164:167], v[52:55]
	v_mfma_f32_16x16x32_bf16 v[36:39], v[148:151], v[172:175], v[36:39]
	v_mfma_f32_16x16x32_bf16 v[20:23], v[148:151], v[200:203], v[20:23]
	v_mfma_f32_16x16x32_bf16 v[4:7], v[148:151], v[208:211], v[4:7]
	v_mfma_f32_16x16x32_bf16 v[0:3], v[156:159], v[208:211], v[0:3]
	v_mfma_f32_16x16x32_bf16 v[16:19], v[156:159], v[200:203], v[16:19]
	v_mfma_f32_16x16x32_bf16 v[32:35], v[156:159], v[172:175], v[32:35]
	v_mfma_f32_16x16x32_bf16 v[48:51], v[156:159], v[164:167], v[48:51]
	s_setprio 0
	s_barrier
	s_add_u32 s58, s58, 0x100
	s_addc_u32 s59, s59, 0
	s_add_u32 s24, s24, 0x100
	s_addc_u32 s25, s25, 0
	s_cmp_ge_i32 s65, s31
	s_mov_b32 s60, s65
	s_cbranch_scc0 .LBB0_1996

; #define PG8_STAGE(bufoff, gbase, voff) do { _Pragma("unroll") for (int _i = 0; _i < 2; ++_i) \
;         __builtin_amdgcn_global_load_lds((const unsigned*)((const char*)(gbase) + (voff)[_i]), (PG8_LAS unsigned*)(lds + (bufoff) + ldsw + _i * 8192), 16, 0, 0); } while (0)
; #define PG8_LDA(dst, b, h) do { _Pragma("unroll") for (int m = 0; m < 4; ++m) _Pragma("unroll") for (int k = 0; k < 2; ++k) dst[m][k] = *(const PG8_LAS bf16x8*)(lds + PG8_SA(b, h) + aoff + m * 2048 + k * 1024); } while (0)
; #define PG8_LDB(dst, b, h) do { _Pragma("unroll") for (int n = 0; n < 2; ++n) _Pragma("unroll") for (int k = 0; k < 2; ++k) dst[n][k] = *(const PG8_LAS bf16x8*)(lds + PG8_SB(b, h) + boff + n * 2048 + k * 1024); } while (0)
; #define PG8_MMA(ai, bj, At, Bt) do { __builtin_amdgcn_s_setprio(1); _Pragma("unroll") for (int m = 0; m < 4; ++m) _Pragma("unroll") for (int n = 0; n < 2; ++n) _Pragma("unroll") for (int k = 0; k < 2; ++k) \
;         acc[ai][bj][m][n] = __builtin_amdgcn_mfma_f32_16x16x32_bf16(Bt[n][k], At[m][k], acc[ai][bj][m][n], 0, 0, 0); __builtin_amdgcn_s_setprio(0); } while (0)
; #define PG8_WAIT_V(n) asm volatile("s_waitcnt vmcnt(" #n ")" ::: "memory")
; #define PG8_WAIT_L(n) asm volatile("s_waitcnt lgkmcnt(" #n ")" ::: "memory")
; #define PG8_BAR __builtin_amdgcn_s_barrier()
; #define PG8_SCHED __builtin_amdgcn_sched_barrier(0)
; template <class Epi, class Sched, bool ALIGN_EPI = false, bool SP2 = false>
; __device__ __forceinline__ void gemm_phase(PG8_LAS unsigned char* lds, const Gemm g, const Sched& S, const Epi& E) {
;     ...
;             PG8_LDB(B0, 0, 0); PG8_LDB(B1, 0, 1); PG8_SCHED; PG8_LDA(At, 0, 0); PG8_STAGE(PG8_SA(1, 1), a1 + hstep, voffA);
;             PG8_WAIT_V(8); PG8_WAIT_L(0); PG8_BAR; PG8_MMA(0, 0, At, B0); PG8_MMA(0, 1, At, B1); PG8_BAR; PG8_SCHED;
;             PG8_LDA(At, 0, 1); PG8_STAGE(PG8_SB(0, 0), b2, voffB); PG8_STAGE(PG8_SB(0, 1), b2 + hstep, voffB); PG8_STAGE(PG8_SA(0, 0), a2, voffA);
;             PG8_WAIT_V(8); PG8_WAIT_L(0); PG8_BAR; PG8_MMA(1, 0, At, B0); PG8_MMA(1, 1, At, B1); PG8_BAR; PG8_SCHED;
.LBB0_2069:
	s_and_b64 vcc, exec, s[10:11]
	s_cbranch_vccnz .Lcoldz_9
	s_add_u32 s50, s50, 0x80
	s_addc_u32 s51, s51, 0
	s_add_u32 s2, s52, 0x100
	s_addc_u32 s24, s53, 0
	s_mov_b32 s25, 0
	ds_read_b128 v[154:157], v151
	ds_read_b128 v[158:161], v151 offset:1024
	ds_read_b128 v[162:165], v151 offset:2048
	ds_read_b128 v[166:169], v151 offset:3072
	ds_read_b128 v[170:173], v152
	ds_read_b128 v[174:177], v152 offset:1024
	ds_read_b128 v[178:181], v152 offset:2048
	ds_read_b128 v[182:185], v152 offset:3072
	s_add_i32 s60, s25, 2
	s_add_u32 s52, s50, 0x80
	s_addc_u32 s53, s51, 0
	s_cmp_eq_u32 s31, s25
	s_cselect_b32 s53, s15, s53
	s_cselect_b32 s52, s14, s52
	s_cselect_b32 s63, s49, s24
	s_cselect_b32 s62, s48, s2
	v_lshl_add_u64 v[146:147], s[50:51], 0, v[138:139]
	s_add_i32 m0, s6, 0xc000
	ds_read_b128 v[186:189], v153
	ds_read_b128 v[190:193], v153 offset:1024
	ds_read_b128 v[194:197], v153 offset:2048
	ds_read_b128 v[198:201], v153 offset:3072
	ds_read_b128 v[202:205], v153 offset:4096
	ds_read_b128 v[206:209], v153 offset:5120
	ds_read_b128 v[210:213], v153 offset:6144
	ds_read_b128 v[214:217], v153 offset:7168
	global_load_lds_dwordx4 v[146:147], off
	v_lshl_add_u64 v[146:147], s[50:51], 0, v[140:141]
	s_add_i32 m0, s6, 0xe000
	s_nop 0
	global_load_lds_dwordx4 v[146:147], off
	s_waitcnt vmcnt(8)
	s_waitcnt lgkmcnt(0)
	s_barrier
	s_setprio 1
	s_waitcnt lgkmcnt(0)
	v_mfma_f32_16x16x32_bf16 v[124:127], v[154:157], v[186:189], 0
	v_mfma_f32_16x16x32_bf16 v[120:123], v[162:165], v[186:189], 0
	v_mfma_f32_16x16x32_bf16 v[108:111], v[154:157], v[194:197], 0
	v_mfma_f32_16x16x32_bf16 v[104:107], v[162:165], v[194:197], 0
	v_mfma_f32_16x16x32_bf16 v[92:95], v[154:157], v[202:205], 0
	v_mfma_f32_16x16x32_bf16 v[88:91], v[162:165], v[202:205], 0
	v_mfma_f32_16x16x32_bf16 v[76:79], v[154:157], v[210:213], 0
	v_mfma_f32_16x16x32_bf16 v[72:75], v[162:165], v[210:213], 0
	v_mfma_f32_16x16x32_bf16 v[124:127], v[158:161], v[190:193], v[124:127]
	v_mfma_f32_16x16x32_bf16 v[108:111], v[158:161], v[198:201], v[108:111]
	v_mfma_f32_16x16x32_bf16 v[92:95], v[158:161], v[206:209], v[92:95]
	v_mfma_f32_16x16x32_bf16 v[76:79], v[158:161], v[214:217], v[76:79]
	v_mfma_f32_16x16x32_bf16 v[72:75], v[166:169], v[214:217], v[72:75]
	v_mfma_f32_16x16x32_bf16 v[88:91], v[166:169], v[206:209], v[88:91]
	v_mfma_f32_16x16x32_bf16 v[104:107], v[166:169], v[198:201], v[104:107]
	v_mfma_f32_16x16x32_bf16 v[120:123], v[166:169], v[190:193], v[120:123]
	s_setprio 0
	s_setprio 1
	v_mfma_f32_16x16x32_bf16 v[116:119], v[170:173], v[186:189], 0
	v_mfma_f32_16x16x32_bf16 v[112:115], v[178:181], v[186:189], 0
	v_mfma_f32_16x16x32_bf16 v[100:103], v[170:173], v[194:197], 0
	v_mfma_f32_16x16x32_bf16 v[96:99], v[178:181], v[194:197], 0
	v_mfma_f32_16x16x32_bf16 v[84:87], v[170:173], v[202:205], 0
	v_mfma_f32_16x16x32_bf16 v[80:83], v[178:181], v[202:205], 0
	v_mfma_f32_16x16x32_bf16 v[68:71], v[170:173], v[210:213], 0
	v_mfma_f32_16x16x32_bf16 v[64:67], v[178:181], v[210:213], 0
	v_mfma_f32_16x16x32_bf16 v[116:119], v[174:177], v[190:193], v[116:119]
	v_mfma_f32_16x16x32_bf16 v[100:103], v[174:177], v[198:201], v[100:103]
	v_mfma_f32_16x16x32_bf16 v[84:87], v[174:177], v[206:209], v[84:87]
	v_mfma_f32_16x16x32_bf16 v[68:71], v[174:177], v[214:217], v[68:71]
	v_mfma_f32_16x16x32_bf16 v[64:67], v[182:185], v[214:217], v[64:67]
	v_mfma_f32_16x16x32_bf16 v[80:83], v[182:185], v[206:209], v[80:83]
	v_mfma_f32_16x16x32_bf16 v[96:99], v[182:185], v[198:201], v[96:99]
	v_mfma_f32_16x16x32_bf16 v[112:115], v[182:185], v[190:193], v[112:115]
	s_setprio 0
	s_barrier
	s_add_i32 s25, s33, s3
	v_lshl_add_u64 v[146:147], s[62:63], 0, v[130:131]
	s_mov_b32 m0, s25
	ds_read_b128 v[186:189], v153 offset:16384
	ds_read_b128 v[190:193], v153 offset:17408
	ds_read_b128 v[194:197], v153 offset:18432
	ds_read_b128 v[198:201], v153 offset:19456
	ds_read_b128 v[202:205], v153 offset:20480
	ds_read_b128 v[206:209], v153 offset:21504
	ds_read_b128 v[210:213], v153 offset:22528
	ds_read_b128 v[214:217], v153 offset:23552
	global_load_lds_dwordx4 v[146:147], off
	s_add_i32 m0, s25, 0x2000
	v_lshl_add_u64 v[218:219], s[62:63], 0, v[134:135]
	s_add_u32 s62, s62, s34
	s_addc_u32 s63, s63, s35
	s_add_i32 s25, s38, s3
	global_load_lds_dwordx4 v[218:219], off
	v_lshl_add_u64 v[220:221], s[62:63], 0, v[130:131]
	s_mov_b32 m0, s25
	v_lshl_add_u64 v[222:223], s[62:63], 0, v[134:135]
	global_load_lds_dwordx4 v[220:221], off
	s_add_i32 m0, s25, 0x2000
	v_lshl_add_u64 v[224:225], s[52:53], 0, v[128:129]
	global_load_lds_dwordx4 v[222:223], off
	s_mov_b32 m0, s6
	v_lshl_add_u64 v[226:227], s[52:53], 0, v[132:133]
	global_load_lds_dwordx4 v[224:225], off
	s_mov_b32 m0, s7
	s_nop 0
	global_load_lds_dwordx4 v[226:227], off
	s_waitcnt vmcnt(8)
	s_waitcnt lgkmcnt(0)
	s_barrier
; #define PG8_STAGE(bufoff, gbase, voff) do { _Pragma("unroll") for (int _i = 0; _i < 2; ++_i) \
;         __builtin_amdgcn_global_load_lds((const unsigned*)((const char*)(gbase) + (voff)[_i]), (PG8_LAS unsigned*)(lds + (bufoff) + ldsw + _i * 8192), 16, 0, 0); } while (0)
; #define PG8_LDA(dst, b, h) do { _Pragma("unroll") for (int m = 0; m < 4; ++m) _Pragma("unroll") for (int k = 0; k < 2; ++k) dst[m][k] = *(const PG8_LAS bf16x8*)(lds + PG8_SA(b, h) + aoff + m * 2048 + k * 1024); } while (0)
; #define PG8_LDB(dst, b, h) do { _Pragma("unroll") for (int n = 0; n < 2; ++n) _Pragma("unroll") for (int k = 0; k < 2; ++k) dst[n][k] = *(const PG8_LAS bf16x8*)(lds + PG8_SB(b, h) + boff + n * 2048 + k * 1024); } while (0)
; #define PG8_MMA(ai, bj, At, Bt) do { __builtin_amdgcn_s_setprio(1); _Pragma("unroll") for (int m = 0; m < 4; ++m) _Pragma("unroll") for (int n = 0; n < 2; ++n) _Pragma("unroll") for (int k = 0; k < 2; ++k) \
;         acc[ai][bj][m][n] = __builtin_amdgcn_mfma_f32_16x16x32_bf16(Bt[n][k], At[m][k], acc[ai][bj][m][n], 0, 0, 0); __builtin_amdgcn_s_setprio(0); } while (0)
; #define PG8_WAIT_V(n) asm volatile("s_waitcnt vmcnt(" #n ")" ::: "memory")
; #define PG8_WAIT_L(n) asm volatile("s_waitcnt lgkmcnt(" #n ")" ::: "memory")
; #define PG8_BAR __builtin_amdgcn_s_barrier()
; #define PG8_SCHED __builtin_amdgcn_sched_barrier(0)
; template <class Epi, class Sched, bool ALIGN_EPI = false, bool SP2 = false>
; __device__ __forceinline__ void gemm_phase(PG8_LAS unsigned char* lds, const Gemm g, const Sched& S, const Epi& E) {
;     ...
;             PG8_WAIT_V(8); PG8_WAIT_L(0); PG8_BAR; PG8_MMA(1, 0, At, B0); PG8_MMA(1, 1, At, B1); PG8_BAR; PG8_SCHED;
;             PG8_LDB(B0, 1, 0); PG8_LDB(B1, 1, 1); PG8_SCHED; PG8_LDA(At, 1, 0); PG8_STAGE(PG8_SA(0, 1), a2 + hstep, voffA);
;             PG8_WAIT_V(8); PG8_WAIT_L(0); PG8_BAR; PG8_MMA(0, 0, At, B0); PG8_MMA(0, 1, At, B1); PG8_BAR; PG8_SCHED;
	s_setprio 1
	s_waitcnt lgkmcnt(0)
	v_mfma_f32_16x16x32_bf16 v[60:63], v[154:157], v[186:189], 0
	v_mfma_f32_16x16x32_bf16 v[56:59], v[162:165], v[186:189], 0
	v_mfma_f32_16x16x32_bf16 v[44:47], v[154:157], v[194:197], 0
	v_mfma_f32_16x16x32_bf16 v[40:43], v[162:165], v[194:197], 0
	v_mfma_f32_16x16x32_bf16 v[28:31], v[154:157], v[202:205], 0
	v_mfma_f32_16x16x32_bf16 v[24:27], v[162:165], v[202:205], 0
	v_mfma_f32_16x16x32_bf16 v[12:15], v[154:157], v[210:213], 0
	v_mfma_f32_16x16x32_bf16 v[8:11], v[162:165], v[210:213], 0
	v_mfma_f32_16x16x32_bf16 v[60:63], v[158:161], v[190:193], v[60:63]
	v_mfma_f32_16x16x32_bf16 v[44:47], v[158:161], v[198:201], v[44:47]
	v_mfma_f32_16x16x32_bf16 v[28:31], v[158:161], v[206:209], v[28:31]
	v_mfma_f32_16x16x32_bf16 v[12:15], v[158:161], v[214:217], v[12:15]
	v_mfma_f32_16x16x32_bf16 v[8:11], v[166:169], v[214:217], v[8:11]
	v_mfma_f32_16x16x32_bf16 v[24:27], v[166:169], v[206:209], v[24:27]
	v_mfma_f32_16x16x32_bf16 v[40:43], v[166:169], v[198:201], v[40:43]
	v_mfma_f32_16x16x32_bf16 v[56:59], v[166:169], v[190:193], v[56:59]
	s_setprio 0
	s_setprio 1
	v_mfma_f32_16x16x32_bf16 v[52:55], v[170:173], v[186:189], 0
	v_mfma_f32_16x16x32_bf16 v[48:51], v[178:181], v[186:189], 0
	v_mfma_f32_16x16x32_bf16 v[36:39], v[170:173], v[194:197], 0
	v_mfma_f32_16x16x32_bf16 v[32:35], v[178:181], v[194:197], 0
	v_mfma_f32_16x16x32_bf16 v[20:23], v[170:173], v[202:205], 0
	v_mfma_f32_16x16x32_bf16 v[16:19], v[178:181], v[202:205], 0
	v_mfma_f32_16x16x32_bf16 v[4:7], v[170:173], v[210:213], 0
	v_mfma_f32_16x16x32_bf16 v[0:3], v[178:181], v[210:213], 0
	v_mfma_f32_16x16x32_bf16 v[52:55], v[174:177], v[190:193], v[52:55]
	v_mfma_f32_16x16x32_bf16 v[36:39], v[174:177], v[198:201], v[36:39]
	v_mfma_f32_16x16x32_bf16 v[20:23], v[174:177], v[206:209], v[20:23]
	v_mfma_f32_16x16x32_bf16 v[4:7], v[174:177], v[214:217], v[4:7]
	v_mfma_f32_16x16x32_bf16 v[0:3], v[182:185], v[214:217], v[0:3]
	v_mfma_f32_16x16x32_bf16 v[16:19], v[182:185], v[206:209], v[16:19]
	v_mfma_f32_16x16x32_bf16 v[32:35], v[182:185], v[198:201], v[32:35]
	v_mfma_f32_16x16x32_bf16 v[48:51], v[182:185], v[190:193], v[48:51]
	s_setprio 0
	s_barrier
	s_add_i32 s25, 0, 0x18000
	s_add_i32 s61, 0, 0x1c000
	v_add_u32_e32 v166, s25, v149
	v_add_u32_e32 v182, s61, v149
	ds_read_b128 v[154:157], v166
	ds_read_b128 v[158:161], v166 offset:1024
	ds_read_b128 v[162:165], v166 offset:2048
	ds_read_b128 v[166:169], v166 offset:3072
	ds_read_b128 v[170:173], v182
	ds_read_b128 v[174:177], v182 offset:1024
	ds_read_b128 v[178:181], v182 offset:2048
	ds_read_b128 v[182:185], v182 offset:3072
	s_add_u32 s52, s52, s34
	s_addc_u32 s53, s53, s35
	s_mov_b32 m0, s18
	v_lshl_add_u64 v[228:229], s[52:53], 0, v[128:129]
	ds_read_b128 v[186:189], v153 offset:32768
	ds_read_b128 v[190:193], v153 offset:33792
	ds_read_b128 v[194:197], v153 offset:34816
	ds_read_b128 v[198:201], v153 offset:35840
	ds_read_b128 v[202:205], v153 offset:36864
	ds_read_b128 v[206:209], v153 offset:37888
	ds_read_b128 v[210:213], v153 offset:38912
	ds_read_b128 v[214:217], v153 offset:39936
	global_load_lds_dwordx4 v[228:229], off
	v_lshl_add_u64 v[228:229], s[52:53], 0, v[132:133]
	s_mov_b32 m0, s19
	s_nop 0
	global_load_lds_dwordx4 v[228:229], off
	s_waitcnt vmcnt(8)
	s_waitcnt lgkmcnt(0)
	s_barrier
	s_setprio 1
	s_waitcnt lgkmcnt(0)
	v_mfma_f32_16x16x32_bf16 v[124:127], v[154:157], v[186:189], v[124:127]
	v_mfma_f32_16x16x32_bf16 v[108:111], v[154:157], v[194:197], v[108:111]
	v_mfma_f32_16x16x32_bf16 v[92:95], v[154:157], v[202:205], v[92:95]
	v_mfma_f32_16x16x32_bf16 v[76:79], v[154:157], v[210:213], v[76:79]
	v_mfma_f32_16x16x32_bf16 v[72:75], v[162:165], v[210:213], v[72:75]
	v_mfma_f32_16x16x32_bf16 v[88:91], v[162:165], v[202:205], v[88:91]
	v_mfma_f32_16x16x32_bf16 v[104:107], v[162:165], v[194:197], v[104:107]
	v_mfma_f32_16x16x32_bf16 v[120:123], v[162:165], v[186:189], v[120:123]
	v_mfma_f32_16x16x32_bf16 v[124:127], v[158:161], v[190:193], v[124:127]
	v_mfma_f32_16x16x32_bf16 v[108:111], v[158:161], v[198:201], v[108:111]
	v_mfma_f32_16x16x32_bf16 v[92:95], v[158:161], v[206:209], v[92:95]
	v_mfma_f32_16x16x32_bf16 v[76:79], v[158:161], v[214:217], v[76:79]
	v_mfma_f32_16x16x32_bf16 v[72:75], v[166:169], v[214:217], v[72:75]
	v_mfma_f32_16x16x32_bf16 v[88:91], v[166:169], v[206:209], v[88:91]
	v_mfma_f32_16x16x32_bf16 v[104:107], v[166:169], v[198:201], v[104:107]
	v_mfma_f32_16x16x32_bf16 v[120:123], v[166:169], v[190:193], v[120:123]
	s_setprio 0
	s_setprio 1
	v_mfma_f32_16x16x32_bf16 v[116:119], v[170:173], v[186:189], v[116:119]
	v_mfma_f32_16x16x32_bf16 v[100:103], v[170:173], v[194:197], v[100:103]
	v_mfma_f32_16x16x32_bf16 v[84:87], v[170:173], v[202:205], v[84:87]
	v_mfma_f32_16x16x32_bf16 v[68:71], v[170:173], v[210:213], v[68:71]
	v_mfma_f32_16x16x32_bf16 v[64:67], v[178:181], v[210:213], v[64:67]
	v_mfma_f32_16x16x32_bf16 v[80:83], v[178:181], v[202:205], v[80:83]
	v_mfma_f32_16x16x32_bf16 v[96:99], v[178:181], v[194:197], v[96:99]
	v_mfma_f32_16x16x32_bf16 v[112:115], v[178:181], v[186:189], v[112:115]
	v_mfma_f32_16x16x32_bf16 v[116:119], v[174:177], v[190:193], v[116:119]
	v_mfma_f32_16x16x32_bf16 v[100:103], v[174:177], v[198:201], v[100:103]
	v_mfma_f32_16x16x32_bf16 v[84:87], v[174:177], v[206:209], v[84:87]
	v_mfma_f32_16x16x32_bf16 v[68:71], v[174:177], v[214:217], v[68:71]
	v_mfma_f32_16x16x32_bf16 v[64:67], v[182:185], v[214:217], v[64:67]
	v_mfma_f32_16x16x32_bf16 v[80:83], v[182:185], v[206:209], v[80:83]
	v_mfma_f32_16x16x32_bf16 v[96:99], v[182:185], v[198:201], v[96:99]
	v_mfma_f32_16x16x32_bf16 v[112:115], v[182:185], v[190:193], v[112:115]
	s_setprio 0
	s_barrier
; #define PG8_STAGE(bufoff, gbase, voff) do { _Pragma("unroll") for (int _i = 0; _i < 2; ++_i) \
;         __builtin_amdgcn_global_load_lds((const unsigned*)((const char*)(gbase) + (voff)[_i]), (PG8_LAS unsigned*)(lds + (bufoff) + ldsw + _i * 8192), 16, 0, 0); } while (0)
; #define PG8_LDA(dst, b, h) do { _Pragma("unroll") for (int m = 0; m < 4; ++m) _Pragma("unroll") for (int k = 0; k < 2; ++k) dst[m][k] = *(const PG8_LAS bf16x8*)(lds + PG8_SA(b, h) + aoff + m * 2048 + k * 1024); } while (0)
; #define PG8_LDB(dst, b, h) do { _Pragma("unroll") for (int n = 0; n < 2; ++n) _Pragma("unroll") for (int k = 0; k < 2; ++k) dst[n][k] = *(const PG8_LAS bf16x8*)(lds + PG8_SB(b, h) + boff + n * 2048 + k * 1024); } while (0)
; #define PG8_MMA(ai, bj, At, Bt) do { __builtin_amdgcn_s_setprio(1); _Pragma("unroll") for (int m = 0; m < 4; ++m) _Pragma("unroll") for (int n = 0; n < 2; ++n) _Pragma("unroll") for (int k = 0; k < 2; ++k) \
;         acc[ai][bj][m][n] = __builtin_amdgcn_mfma_f32_16x16x32_bf16(Bt[n][k], At[m][k], acc[ai][bj][m][n], 0, 0, 0); __builtin_amdgcn_s_setprio(0); } while (0)
; #define PG8_WAIT_V(n) asm volatile("s_waitcnt vmcnt(" #n ")" ::: "memory")
; #define PG8_WAIT_L(n) asm volatile("s_waitcnt lgkmcnt(" #n ")" ::: "memory")
; #define PG8_BAR __builtin_amdgcn_s_barrier()
; #define PG8_SCHED __builtin_amdgcn_sched_barrier(0)
; template <class Epi, class Sched, bool ALIGN_EPI = false, bool SP2 = false>
; __device__ __forceinline__ void gemm_phase(PG8_LAS unsigned char* lds, const Gemm g, const Sched& S, const Epi& E) {
;     ...
;         for (int t = 0; t < nt; t += 2) {
;             const bool last = (t == nt - 2);
;             const char* a1 = cA + (size_t)(t + 1) * kstep;
;             const char* a2 = last ? nA : cA + (size_t)(t + 2) * kstep; const char* b2 = last ? nB : cB + (size_t)(t + 2) * kstep;
;     ...
;             PG8_LDB(B0, 0, 0); PG8_LDB(B1, 0, 1); PG8_SCHED; PG8_LDA(At, 0, 0); PG8_STAGE(PG8_SA(1, 1), a1 + hstep, voffA);
;             PG8_WAIT_V(8); PG8_WAIT_L(0); PG8_BAR; PG8_MMA(0, 0, At, B0); PG8_MMA(0, 1, At, B1); PG8_BAR; PG8_SCHED;
;     ...
;             PG8_LDA(At, 1, 1); PG8_STAGE(PG8_SB(1, 0), b3, voffB); PG8_STAGE(PG8_SB(1, 1), b3 + hstep, voffB); PG8_STAGE(PG8_SA(1, 0), a3, voffA);
;             PG8_WAIT_V(8); PG8_WAIT_L(0); PG8_BAR; PG8_MMA(1, 0, At, B0); PG8_MMA(1, 1, At, B1); PG8_BAR; PG8_SCHED;
	s_add_i32 s25, s25, s3
	v_lshl_add_u64 v[146:147], v[146:147], 0, s[44:45]
	s_mov_b32 m0, s25
	ds_read_b128 v[186:189], v153 offset:49152
	ds_read_b128 v[190:193], v153 offset:50176
	ds_read_b128 v[194:197], v153 offset:51200
	ds_read_b128 v[198:201], v153 offset:52224
	ds_read_b128 v[202:205], v153 offset:53248
	ds_read_b128 v[206:209], v153 offset:54272
	ds_read_b128 v[210:213], v153 offset:55296
	ds_read_b128 v[214:217], v153 offset:56320
	global_load_lds_dwordx4 v[146:147], off
	v_lshl_add_u64 v[146:147], v[218:219], 0, s[44:45]
	s_add_i32 m0, s25, 0x2000
	s_add_i32 s25, s61, s3
	global_load_lds_dwordx4 v[146:147], off
	v_lshl_add_u64 v[146:147], v[220:221], 0, s[44:45]
	s_mov_b32 m0, s25
	s_nop 0
	global_load_lds_dwordx4 v[146:147], off
	v_lshl_add_u64 v[146:147], v[222:223], 0, s[44:45]
	s_add_i32 m0, s25, 0x2000
	s_nop 0
	global_load_lds_dwordx4 v[146:147], off
	v_lshl_add_u64 v[146:147], v[224:225], 0, s[44:45]
	s_mov_b32 m0, s26
	s_nop 0
	global_load_lds_dwordx4 v[146:147], off
	v_lshl_add_u64 v[146:147], v[226:227], 0, s[44:45]
	s_mov_b32 m0, s27
	s_nop 0
	global_load_lds_dwordx4 v[146:147], off
	s_waitcnt vmcnt(8)
	s_waitcnt lgkmcnt(0)
	s_barrier
	s_setprio 1
	s_waitcnt lgkmcnt(0)
	v_mfma_f32_16x16x32_bf16 v[60:63], v[154:157], v[186:189], v[60:63]
	v_mfma_f32_16x16x32_bf16 v[44:47], v[154:157], v[194:197], v[44:47]
	v_mfma_f32_16x16x32_bf16 v[28:31], v[154:157], v[202:205], v[28:31]
	v_mfma_f32_16x16x32_bf16 v[12:15], v[154:157], v[210:213], v[12:15]
	v_mfma_f32_16x16x32_bf16 v[8:11], v[162:165], v[210:213], v[8:11]
	v_mfma_f32_16x16x32_bf16 v[24:27], v[162:165], v[202:205], v[24:27]
	v_mfma_f32_16x16x32_bf16 v[40:43], v[162:165], v[194:197], v[40:43]
	v_mfma_f32_16x16x32_bf16 v[56:59], v[162:165], v[186:189], v[56:59]
	v_mfma_f32_16x16x32_bf16 v[60:63], v[158:161], v[190:193], v[60:63]
	v_mfma_f32_16x16x32_bf16 v[44:47], v[158:161], v[198:201], v[44:47]
	v_mfma_f32_16x16x32_bf16 v[28:31], v[158:161], v[206:209], v[28:31]
	v_mfma_f32_16x16x32_bf16 v[12:15], v[158:161], v[214:217], v[12:15]
	v_mfma_f32_16x16x32_bf16 v[8:11], v[166:169], v[214:217], v[8:11]
	v_mfma_f32_16x16x32_bf16 v[24:27], v[166:169], v[206:209], v[24:27]
	v_mfma_f32_16x16x32_bf16 v[40:43], v[166:169], v[198:201], v[40:43]
	v_mfma_f32_16x16x32_bf16 v[56:59], v[166:169], v[190:193], v[56:59]
	s_setprio 0
	s_setprio 1
	v_mfma_f32_16x16x32_bf16 v[52:55], v[170:173], v[186:189], v[52:55]
	v_mfma_f32_16x16x32_bf16 v[36:39], v[170:173], v[194:197], v[36:39]
	v_mfma_f32_16x16x32_bf16 v[20:23], v[170:173], v[202:205], v[20:23]
	v_mfma_f32_16x16x32_bf16 v[4:7], v[170:173], v[210:213], v[4:7]
	v_mfma_f32_16x16x32_bf16 v[0:3], v[178:181], v[210:213], v[0:3]
	v_mfma_f32_16x16x32_bf16 v[16:19], v[178:181], v[202:205], v[16:19]
	v_mfma_f32_16x16x32_bf16 v[32:35], v[178:181], v[194:197], v[32:35]
	v_mfma_f32_16x16x32_bf16 v[48:51], v[178:181], v[186:189], v[48:51]
	v_mfma_f32_16x16x32_bf16 v[52:55], v[174:177], v[190:193], v[52:55]
	v_mfma_f32_16x16x32_bf16 v[36:39], v[174:177], v[198:201], v[36:39]
	v_mfma_f32_16x16x32_bf16 v[20:23], v[174:177], v[206:209], v[20:23]
	v_mfma_f32_16x16x32_bf16 v[4:7], v[174:177], v[214:217], v[4:7]
	v_mfma_f32_16x16x32_bf16 v[0:3], v[182:185], v[214:217], v[0:3]
	v_mfma_f32_16x16x32_bf16 v[16:19], v[182:185], v[206:209], v[16:19]
	v_mfma_f32_16x16x32_bf16 v[32:35], v[182:185], v[198:201], v[32:35]
	v_mfma_f32_16x16x32_bf16 v[48:51], v[182:185], v[190:193], v[48:51]
	s_setprio 0
	s_barrier
	s_add_u32 s50, s50, 0x100
	s_addc_u32 s51, s51, 0
	s_add_u32 s2, s2, 0x100
	s_addc_u32 s24, s24, 0
	s_cmp_ge_i32 s60, s30
	s_mov_b32 s25, s60
	s_cbranch_scc1 .Lpeelx_9
.LBB0_2071:
	ds_read_b128 v[154:157], v151
	ds_read_b128 v[158:161], v151 offset:1024
	ds_read_b128 v[162:165], v151 offset:2048
	ds_read_b128 v[166:169], v151 offset:3072
	ds_read_b128 v[170:173], v152
	ds_read_b128 v[174:177], v152 offset:1024
	ds_read_b128 v[178:181], v152 offset:2048
	ds_read_b128 v[182:185], v152 offset:3072
	s_add_i32 s60, s25, 2
	s_add_u32 s52, s50, 0x80
	s_addc_u32 s53, s51, 0
	s_cmp_eq_u32 s31, s25
	s_cselect_b32 s53, s15, s53
	s_cselect_b32 s52, s14, s52
	s_cselect_b32 s63, s49, s24
	s_cselect_b32 s62, s48, s2
	v_lshl_add_u64 v[146:147], s[50:51], 0, v[138:139]
	s_add_i32 m0, s6, 0xc000
	ds_read_b128 v[186:189], v153
	ds_read_b128 v[190:193], v153 offset:1024
	ds_read_b128 v[194:197], v153 offset:2048
	ds_read_b128 v[198:201], v153 offset:3072
	ds_read_b128 v[202:205], v153 offset:4096
	ds_read_b128 v[206:209], v153 offset:5120
	ds_read_b128 v[210:213], v153 offset:6144
	ds_read_b128 v[214:217], v153 offset:7168
	global_load_lds_dwordx4 v[146:147], off
	v_lshl_add_u64 v[146:147], s[50:51], 0, v[140:141]
	s_add_i32 m0, s6, 0xe000
	s_nop 0
	global_load_lds_dwordx4 v[146:147], off
	s_waitcnt vmcnt(8)
	s_waitcnt lgkmcnt(0)
	s_barrier
; #define PG8_STAGE(bufoff, gbase, voff) do { _Pragma("unroll") for (int _i = 0; _i < 2; ++_i) \
;         __builtin_amdgcn_global_load_lds((const unsigned*)((const char*)(gbase) + (voff)[_i]), (PG8_LAS unsigned*)(lds + (bufoff) + ldsw + _i * 8192), 16, 0, 0); } while (0)
; #define PG8_LDA(dst, b, h) do { _Pragma("unroll") for (int m = 0; m < 4; ++m) _Pragma("unroll") for (int k = 0; k < 2; ++k) dst[m][k] = *(const PG8_LAS bf16x8*)(lds + PG8_SA(b, h) + aoff + m * 2048 + k * 1024); } while (0)
; #define PG8_LDB(dst, b, h) do { _Pragma("unroll") for (int n = 0; n < 2; ++n) _Pragma("unroll") for (int k = 0; k < 2; ++k) dst[n][k] = *(const PG8_LAS bf16x8*)(lds + PG8_SB(b, h) + boff + n * 2048 + k * 1024); } while (0)
; #define PG8_MMA(ai, bj, At, Bt) do { __builtin_amdgcn_s_setprio(1); _Pragma("unroll") for (int m = 0; m < 4; ++m) _Pragma("unroll") for (int n = 0; n < 2; ++n) _Pragma("unroll") for (int k = 0; k < 2; ++k) \
;         acc[ai][bj][m][n] = __builtin_amdgcn_mfma_f32_16x16x32_bf16(Bt[n][k], At[m][k], acc[ai][bj][m][n], 0, 0, 0); __builtin_amdgcn_s_setprio(0); } while (0)
; #define PG8_WAIT_V(n) asm volatile("s_waitcnt vmcnt(" #n ")" ::: "memory")
; #define PG8_WAIT_L(n) asm volatile("s_waitcnt lgkmcnt(" #n ")" ::: "memory")
; #define PG8_BAR __builtin_amdgcn_s_barrier()
; #define PG8_SCHED __builtin_amdgcn_sched_barrier(0)
; template <class Epi, class Sched, bool ALIGN_EPI = false, bool SP2 = false>
; __device__ __forceinline__ void gemm_phase(PG8_LAS unsigned char* lds, const Gemm g, const Sched& S, const Epi& E) {
;     ...
;             PG8_WAIT_V(8); PG8_WAIT_L(0); PG8_BAR; PG8_MMA(0, 0, At, B0); PG8_MMA(0, 1, At, B1); PG8_BAR; PG8_SCHED;
;             PG8_LDA(At, 0, 1); PG8_STAGE(PG8_SB(0, 0), b2, voffB); PG8_STAGE(PG8_SB(0, 1), b2 + hstep, voffB); PG8_STAGE(PG8_SA(0, 0), a2, voffA);
;             PG8_WAIT_V(8); PG8_WAIT_L(0); PG8_BAR; PG8_MMA(1, 0, At, B0); PG8_MMA(1, 1, At, B1); PG8_BAR; PG8_SCHED;
;             PG8_LDB(B0, 1, 0); PG8_LDB(B1, 1, 1); PG8_SCHED; PG8_LDA(At, 1, 0); PG8_STAGE(PG8_SA(0, 1), a2 + hstep, voffA);
;             PG8_WAIT_V(8); PG8_WAIT_L(0); PG8_BAR; PG8_MMA(0, 0, At, B0); PG8_MMA(0, 1, At, B1); PG8_BAR; PG8_SCHED;
	s_setprio 1
	s_waitcnt lgkmcnt(0)
	v_mfma_f32_16x16x32_bf16 v[124:127], v[154:157], v[186:189], v[124:127]
	v_mfma_f32_16x16x32_bf16 v[108:111], v[154:157], v[194:197], v[108:111]
	v_mfma_f32_16x16x32_bf16 v[92:95], v[154:157], v[202:205], v[92:95]
	v_mfma_f32_16x16x32_bf16 v[76:79], v[154:157], v[210:213], v[76:79]
	v_mfma_f32_16x16x32_bf16 v[72:75], v[162:165], v[210:213], v[72:75]
	v_mfma_f32_16x16x32_bf16 v[88:91], v[162:165], v[202:205], v[88:91]
	v_mfma_f32_16x16x32_bf16 v[104:107], v[162:165], v[194:197], v[104:107]
	v_mfma_f32_16x16x32_bf16 v[120:123], v[162:165], v[186:189], v[120:123]
	v_mfma_f32_16x16x32_bf16 v[124:127], v[158:161], v[190:193], v[124:127]
	v_mfma_f32_16x16x32_bf16 v[108:111], v[158:161], v[198:201], v[108:111]
	v_mfma_f32_16x16x32_bf16 v[92:95], v[158:161], v[206:209], v[92:95]
	v_mfma_f32_16x16x32_bf16 v[76:79], v[158:161], v[214:217], v[76:79]
	v_mfma_f32_16x16x32_bf16 v[72:75], v[166:169], v[214:217], v[72:75]
	v_mfma_f32_16x16x32_bf16 v[88:91], v[166:169], v[206:209], v[88:91]
	v_mfma_f32_16x16x32_bf16 v[104:107], v[166:169], v[198:201], v[104:107]
	v_mfma_f32_16x16x32_bf16 v[120:123], v[166:169], v[190:193], v[120:123]
	s_setprio 0
	s_setprio 1
	v_mfma_f32_16x16x32_bf16 v[116:119], v[170:173], v[186:189], v[116:119]
	v_mfma_f32_16x16x32_bf16 v[100:103], v[170:173], v[194:197], v[100:103]
	v_mfma_f32_16x16x32_bf16 v[84:87], v[170:173], v[202:205], v[84:87]
	v_mfma_f32_16x16x32_bf16 v[68:71], v[170:173], v[210:213], v[68:71]
	v_mfma_f32_16x16x32_bf16 v[64:67], v[178:181], v[210:213], v[64:67]
	v_mfma_f32_16x16x32_bf16 v[80:83], v[178:181], v[202:205], v[80:83]
	v_mfma_f32_16x16x32_bf16 v[96:99], v[178:181], v[194:197], v[96:99]
	v_mfma_f32_16x16x32_bf16 v[112:115], v[178:181], v[186:189], v[112:115]
	v_mfma_f32_16x16x32_bf16 v[116:119], v[174:177], v[190:193], v[116:119]
	v_mfma_f32_16x16x32_bf16 v[100:103], v[174:177], v[198:201], v[100:103]
	v_mfma_f32_16x16x32_bf16 v[84:87], v[174:177], v[206:209], v[84:87]
	v_mfma_f32_16x16x32_bf16 v[68:71], v[174:177], v[214:217], v[68:71]
	v_mfma_f32_16x16x32_bf16 v[64:67], v[182:185], v[214:217], v[64:67]
	v_mfma_f32_16x16x32_bf16 v[80:83], v[182:185], v[206:209], v[80:83]
	v_mfma_f32_16x16x32_bf16 v[96:99], v[182:185], v[198:201], v[96:99]
	v_mfma_f32_16x16x32_bf16 v[112:115], v[182:185], v[190:193], v[112:115]
	s_setprio 0
	s_barrier
	s_add_i32 s25, s33, s3
	v_lshl_add_u64 v[146:147], s[62:63], 0, v[130:131]
	s_mov_b32 m0, s25
	ds_read_b128 v[186:189], v153 offset:16384
	ds_read_b128 v[190:193], v153 offset:17408
	ds_read_b128 v[194:197], v153 offset:18432
	ds_read_b128 v[198:201], v153 offset:19456
	ds_read_b128 v[202:205], v153 offset:20480
	ds_read_b128 v[206:209], v153 offset:21504
	ds_read_b128 v[210:213], v153 offset:22528
	ds_read_b128 v[214:217], v153 offset:23552
	global_load_lds_dwordx4 v[146:147], off
	s_add_i32 m0, s25, 0x2000
	v_lshl_add_u64 v[218:219], s[62:63], 0, v[134:135]
	s_add_u32 s62, s62, s34
	s_addc_u32 s63, s63, s35
	s_add_i32 s25, s38, s3
	global_load_lds_dwordx4 v[218:219], off
	v_lshl_add_u64 v[220:221], s[62:63], 0, v[130:131]
	s_mov_b32 m0, s25
	v_lshl_add_u64 v[222:223], s[62:63], 0, v[134:135]
	global_load_lds_dwordx4 v[220:221], off
	s_add_i32 m0, s25, 0x2000
	v_lshl_add_u64 v[224:225], s[52:53], 0, v[128:129]
	global_load_lds_dwordx4 v[222:223], off
	s_mov_b32 m0, s6
	v_lshl_add_u64 v[226:227], s[52:53], 0, v[132:133]
	global_load_lds_dwordx4 v[224:225], off
	s_mov_b32 m0, s7
	s_nop 0
	global_load_lds_dwordx4 v[226:227], off
	s_waitcnt vmcnt(8)
	s_waitcnt lgkmcnt(0)
	s_barrier
	s_setprio 1
	s_waitcnt lgkmcnt(0)
	v_mfma_f32_16x16x32_bf16 v[60:63], v[154:157], v[186:189], v[60:63]
	v_mfma_f32_16x16x32_bf16 v[44:47], v[154:157], v[194:197], v[44:47]
	v_mfma_f32_16x16x32_bf16 v[28:31], v[154:157], v[202:205], v[28:31]
	v_mfma_f32_16x16x32_bf16 v[12:15], v[154:157], v[210:213], v[12:15]
	v_mfma_f32_16x16x32_bf16 v[8:11], v[162:165], v[210:213], v[8:11]
	v_mfma_f32_16x16x32_bf16 v[24:27], v[162:165], v[202:205], v[24:27]
	v_mfma_f32_16x16x32_bf16 v[40:43], v[162:165], v[194:197], v[40:43]
	v_mfma_f32_16x16x32_bf16 v[56:59], v[162:165], v[186:189], v[56:59]
	v_mfma_f32_16x16x32_bf16 v[60:63], v[158:161], v[190:193], v[60:63]
	v_mfma_f32_16x16x32_bf16 v[44:47], v[158:161], v[198:201], v[44:47]
	v_mfma_f32_16x16x32_bf16 v[28:31], v[158:161], v[206:209], v[28:31]
	v_mfma_f32_16x16x32_bf16 v[12:15], v[158:161], v[214:217], v[12:15]
	v_mfma_f32_16x16x32_bf16 v[8:11], v[166:169], v[214:217], v[8:11]
	v_mfma_f32_16x16x32_bf16 v[24:27], v[166:169], v[206:209], v[24:27]
	v_mfma_f32_16x16x32_bf16 v[40:43], v[166:169], v[198:201], v[40:43]
	v_mfma_f32_16x16x32_bf16 v[56:59], v[166:169], v[190:193], v[56:59]
	s_setprio 0
	s_setprio 1
	v_mfma_f32_16x16x32_bf16 v[52:55], v[170:173], v[186:189], v[52:55]
	v_mfma_f32_16x16x32_bf16 v[36:39], v[170:173], v[194:197], v[36:39]
	v_mfma_f32_16x16x32_bf16 v[20:23], v[170:173], v[202:205], v[20:23]
	v_mfma_f32_16x16x32_bf16 v[4:7], v[170:173], v[210:213], v[4:7]
	v_mfma_f32_16x16x32_bf16 v[0:3], v[178:181], v[210:213], v[0:3]
	v_mfma_f32_16x16x32_bf16 v[16:19], v[178:181], v[202:205], v[16:19]
	v_mfma_f32_16x16x32_bf16 v[32:35], v[178:181], v[194:197], v[32:35]
	v_mfma_f32_16x16x32_bf16 v[48:51], v[178:181], v[186:189], v[48:51]
	v_mfma_f32_16x16x32_bf16 v[52:55], v[174:177], v[190:193], v[52:55]
	v_mfma_f32_16x16x32_bf16 v[36:39], v[174:177], v[198:201], v[36:39]
	v_mfma_f32_16x16x32_bf16 v[20:23], v[174:177], v[206:209], v[20:23]
	v_mfma_f32_16x16x32_bf16 v[4:7], v[174:177], v[214:217], v[4:7]
	v_mfma_f32_16x16x32_bf16 v[0:3], v[182:185], v[214:217], v[0:3]
	v_mfma_f32_16x16x32_bf16 v[16:19], v[182:185], v[206:209], v[16:19]
	v_mfma_f32_16x16x32_bf16 v[32:35], v[182:185], v[198:201], v[32:35]
	v_mfma_f32_16x16x32_bf16 v[48:51], v[182:185], v[190:193], v[48:51]
	s_setprio 0
	s_barrier
; #define PG8_STAGE(bufoff, gbase, voff) do { _Pragma("unroll") for (int _i = 0; _i < 2; ++_i) \
;         __builtin_amdgcn_global_load_lds((const unsigned*)((const char*)(gbase) + (voff)[_i]), (PG8_LAS unsigned*)(lds + (bufoff) + ldsw + _i * 8192), 16, 0, 0); } while (0)
; #define PG8_LDA(dst, b, h) do { _Pragma("unroll") for (int m = 0; m < 4; ++m) _Pragma("unroll") for (int k = 0; k < 2; ++k) dst[m][k] = *(const PG8_LAS bf16x8*)(lds + PG8_SA(b, h) + aoff + m * 2048 + k * 1024); } while (0)
; #define PG8_LDB(dst, b, h) do { _Pragma("unroll") for (int n = 0; n < 2; ++n) _Pragma("unroll") for (int k = 0; k < 2; ++k) dst[n][k] = *(const PG8_LAS bf16x8*)(lds + PG8_SB(b, h) + boff + n * 2048 + k * 1024); } while (0)
; #define PG8_MMA(ai, bj, At, Bt) do { __builtin_amdgcn_s_setprio(1); _Pragma("unroll") for (int m = 0; m < 4; ++m) _Pragma("unroll") for (int n = 0; n < 2; ++n) _Pragma("unroll") for (int k = 0; k < 2; ++k) \
;         acc[ai][bj][m][n] = __builtin_amdgcn_mfma_f32_16x16x32_bf16(Bt[n][k], At[m][k], acc[ai][bj][m][n], 0, 0, 0); __builtin_amdgcn_s_setprio(0); } while (0)
; #define PG8_WAIT_V(n) asm volatile("s_waitcnt vmcnt(" #n ")" ::: "memory")
; #define PG8_WAIT_L(n) asm volatile("s_waitcnt lgkmcnt(" #n ")" ::: "memory")
; #define PG8_BAR __builtin_amdgcn_s_barrier()
; #define PG8_SCHED __builtin_amdgcn_sched_barrier(0)
; template <class Epi, class Sched, bool ALIGN_EPI = false, bool SP2 = false>
; __device__ __forceinline__ void gemm_phase(PG8_LAS unsigned char* lds, const Gemm g, const Sched& S, const Epi& E) {
;     ...
;             PG8_LDB(B0, 1, 0); PG8_LDB(B1, 1, 1); PG8_SCHED; PG8_LDA(At, 1, 0); PG8_STAGE(PG8_SA(0, 1), a2 + hstep, voffA);
;             PG8_WAIT_V(8); PG8_WAIT_L(0); PG8_BAR; PG8_MMA(0, 0, At, B0); PG8_MMA(0, 1, At, B1); PG8_BAR; PG8_SCHED;
	s_add_i32 s25, 0, 0x18000
	s_add_i32 s61, 0, 0x1c000
	v_add_u32_e32 v166, s25, v149
	v_add_u32_e32 v182, s61, v149
	ds_read_b128 v[154:157], v166
	ds_read_b128 v[158:161], v166 offset:1024
	ds_read_b128 v[162:165], v166 offset:2048
	ds_read_b128 v[166:169], v166 offset:3072
	ds_read_b128 v[170:173], v182
	ds_read_b128 v[174:177], v182 offset:1024
	ds_read_b128 v[178:181], v182 offset:2048
	ds_read_b128 v[182:185], v182 offset:3072
	s_add_u32 s52, s52, s34
	s_addc_u32 s53, s53, s35
	s_mov_b32 m0, s18
	v_lshl_add_u64 v[228:229], s[52:53], 0, v[128:129]
	ds_read_b128 v[186:189], v153 offset:32768
	ds_read_b128 v[190:193], v153 offset:33792
	ds_read_b128 v[194:197], v153 offset:34816
	ds_read_b128 v[198:201], v153 offset:35840
	ds_read_b128 v[202:205], v153 offset:36864
	ds_read_b128 v[206:209], v153 offset:37888
	ds_read_b128 v[210:213], v153 offset:38912
	ds_read_b128 v[214:217], v153 offset:39936
	global_load_lds_dwordx4 v[228:229], off
	v_lshl_add_u64 v[228:229], s[52:53], 0, v[132:133]
	s_mov_b32 m0, s19
	s_nop 0
	global_load_lds_dwordx4 v[228:229], off
	s_waitcnt vmcnt(8)
	s_waitcnt lgkmcnt(0)
	s_barrier
	s_setprio 1
	s_waitcnt lgkmcnt(0)
	v_mfma_f32_16x16x32_bf16 v[124:127], v[154:157], v[186:189], v[124:127]
	v_mfma_f32_16x16x32_bf16 v[108:111], v[154:157], v[194:197], v[108:111]
	v_mfma_f32_16x16x32_bf16 v[92:95], v[154:157], v[202:205], v[92:95]
	v_mfma_f32_16x16x32_bf16 v[76:79], v[154:157], v[210:213], v[76:79]
	v_mfma_f32_16x16x32_bf16 v[72:75], v[162:165], v[210:213], v[72:75]
	v_mfma_f32_16x16x32_bf16 v[88:91], v[162:165], v[202:205], v[88:91]
	v_mfma_f32_16x16x32_bf16 v[104:107], v[162:165], v[194:197], v[104:107]
	v_mfma_f32_16x16x32_bf16 v[120:123], v[162:165], v[186:189], v[120:123]
	v_mfma_f32_16x16x32_bf16 v[124:127], v[158:161], v[190:193], v[124:127]
	v_mfma_f32_16x16x32_bf16 v[108:111], v[158:161], v[198:201], v[108:111]
	v_mfma_f32_16x16x32_bf16 v[92:95], v[158:161], v[206:209], v[92:95]
	v_mfma_f32_16x16x32_bf16 v[76:79], v[158:161], v[214:217], v[76:79]
	v_mfma_f32_16x16x32_bf16 v[72:75], v[166:169], v[214:217], v[72:75]
	v_mfma_f32_16x16x32_bf16 v[88:91], v[166:169], v[206:209], v[88:91]
	v_mfma_f32_16x16x32_bf16 v[104:107], v[166:169], v[198:201], v[104:107]
	v_mfma_f32_16x16x32_bf16 v[120:123], v[166:169], v[190:193], v[120:123]
	s_setprio 0
	s_setprio 1
	v_mfma_f32_16x16x32_bf16 v[116:119], v[170:173], v[186:189], v[116:119]
	v_mfma_f32_16x16x32_bf16 v[100:103], v[170:173], v[194:197], v[100:103]
	v_mfma_f32_16x16x32_bf16 v[84:87], v[170:173], v[202:205], v[84:87]
	v_mfma_f32_16x16x32_bf16 v[68:71], v[170:173], v[210:213], v[68:71]
	v_mfma_f32_16x16x32_bf16 v[64:67], v[178:181], v[210:213], v[64:67]
	v_mfma_f32_16x16x32_bf16 v[80:83], v[178:181], v[202:205], v[80:83]
	v_mfma_f32_16x16x32_bf16 v[96:99], v[178:181], v[194:197], v[96:99]
	v_mfma_f32_16x16x32_bf16 v[112:115], v[178:181], v[186:189], v[112:115]
	v_mfma_f32_16x16x32_bf16 v[116:119], v[174:177], v[190:193], v[116:119]
	v_mfma_f32_16x16x32_bf16 v[100:103], v[174:177], v[198:201], v[100:103]
	v_mfma_f32_16x16x32_bf16 v[84:87], v[174:177], v[206:209], v[84:87]
	v_mfma_f32_16x16x32_bf16 v[68:71], v[174:177], v[214:217], v[68:71]
	v_mfma_f32_16x16x32_bf16 v[64:67], v[182:185], v[214:217], v[64:67]
	v_mfma_f32_16x16x32_bf16 v[80:83], v[182:185], v[206:209], v[80:83]
	v_mfma_f32_16x16x32_bf16 v[96:99], v[182:185], v[198:201], v[96:99]
	v_mfma_f32_16x16x32_bf16 v[112:115], v[182:185], v[190:193], v[112:115]
	s_setprio 0
	s_barrier
; #define PG8_STAGE(bufoff, gbase, voff) do { _Pragma("unroll") for (int _i = 0; _i < 2; ++_i) \
;         __builtin_amdgcn_global_load_lds((const unsigned*)((const char*)(gbase) + (voff)[_i]), (PG8_LAS unsigned*)(lds + (bufoff) + ldsw + _i * 8192), 16, 0, 0); } while (0)
; #define PG8_LDA(dst, b, h) do { _Pragma("unroll") for (int m = 0; m < 4; ++m) _Pragma("unroll") for (int k = 0; k < 2; ++k) dst[m][k] = *(const PG8_LAS bf16x8*)(lds + PG8_SA(b, h) + aoff + m * 2048 + k * 1024); } while (0)
; #define PG8_MMA(ai, bj, At, Bt) do { __builtin_amdgcn_s_setprio(1); _Pragma("unroll") for (int m = 0; m < 4; ++m) _Pragma("unroll") for (int n = 0; n < 2; ++n) _Pragma("unroll") for (int k = 0; k < 2; ++k) \
;         acc[ai][bj][m][n] = __builtin_amdgcn_mfma_f32_16x16x32_bf16(Bt[n][k], At[m][k], acc[ai][bj][m][n], 0, 0, 0); __builtin_amdgcn_s_setprio(0); } while (0)
; #define PG8_WAIT_V(n) asm volatile("s_waitcnt vmcnt(" #n ")" ::: "memory")
; #define PG8_WAIT_L(n) asm volatile("s_waitcnt lgkmcnt(" #n ")" ::: "memory")
; #define PG8_BAR __builtin_amdgcn_s_barrier()
; #define PG8_SCHED __builtin_amdgcn_sched_barrier(0)
; template <class Epi, class Sched, bool ALIGN_EPI = false, bool SP2 = false>
; __device__ __forceinline__ void gemm_phase(PG8_LAS unsigned char* lds, const Gemm g, const Sched& S, const Epi& E) {
;     ...
;         for (int t = 0; t < nt; t += 2) {
;             const bool last = (t == nt - 2);
;             const char* a1 = cA + (size_t)(t + 1) * kstep;
;             const char* a2 = last ? nA : cA + (size_t)(t + 2) * kstep; const char* b2 = last ? nB : cB + (size_t)(t + 2) * kstep;
;     ...
;             PG8_LDA(At, 1, 1); PG8_STAGE(PG8_SB(1, 0), b3, voffB); PG8_STAGE(PG8_SB(1, 1), b3 + hstep, voffB); PG8_STAGE(PG8_SA(1, 0), a3, voffA);
;             PG8_WAIT_V(8); PG8_WAIT_L(0); PG8_BAR; PG8_MMA(1, 0, At, B0); PG8_MMA(1, 1, At, B1); PG8_BAR; PG8_SCHED;
	s_add_i32 s25, s25, s3
	v_lshl_add_u64 v[146:147], v[146:147], 0, s[44:45]
	s_mov_b32 m0, s25
	ds_read_b128 v[186:189], v153 offset:49152
	ds_read_b128 v[190:193], v153 offset:50176
	ds_read_b128 v[194:197], v153 offset:51200
	ds_read_b128 v[198:201], v153 offset:52224
	ds_read_b128 v[202:205], v153 offset:53248
	ds_read_b128 v[206:209], v153 offset:54272
	ds_read_b128 v[210:213], v153 offset:55296
	ds_read_b128 v[214:217], v153 offset:56320
	global_load_lds_dwordx4 v[146:147], off
	v_lshl_add_u64 v[146:147], v[218:219], 0, s[44:45]
	s_add_i32 m0, s25, 0x2000
	s_add_i32 s25, s61, s3
	global_load_lds_dwordx4 v[146:147], off
	v_lshl_add_u64 v[146:147], v[220:221], 0, s[44:45]
	s_mov_b32 m0, s25
	s_nop 0
	global_load_lds_dwordx4 v[146:147], off
	v_lshl_add_u64 v[146:147], v[222:223], 0, s[44:45]
	s_add_i32 m0, s25, 0x2000
	s_nop 0
	global_load_lds_dwordx4 v[146:147], off
	v_lshl_add_u64 v[146:147], v[224:225], 0, s[44:45]
	s_mov_b32 m0, s26
	s_nop 0
	global_load_lds_dwordx4 v[146:147], off
	v_lshl_add_u64 v[146:147], v[226:227], 0, s[44:45]
	s_mov_b32 m0, s27
	s_nop 0
	global_load_lds_dwordx4 v[146:147], off
	s_waitcnt vmcnt(8)
	s_waitcnt lgkmcnt(0)
	s_barrier
	s_setprio 1
	s_waitcnt lgkmcnt(0)
	v_mfma_f32_16x16x32_bf16 v[60:63], v[154:157], v[186:189], v[60:63]
	v_mfma_f32_16x16x32_bf16 v[44:47], v[154:157], v[194:197], v[44:47]
	v_mfma_f32_16x16x32_bf16 v[28:31], v[154:157], v[202:205], v[28:31]
	v_mfma_f32_16x16x32_bf16 v[12:15], v[154:157], v[210:213], v[12:15]
	v_mfma_f32_16x16x32_bf16 v[8:11], v[162:165], v[210:213], v[8:11]
	v_mfma_f32_16x16x32_bf16 v[24:27], v[162:165], v[202:205], v[24:27]
	v_mfma_f32_16x16x32_bf16 v[40:43], v[162:165], v[194:197], v[40:43]
	v_mfma_f32_16x16x32_bf16 v[56:59], v[162:165], v[186:189], v[56:59]
	v_mfma_f32_16x16x32_bf16 v[60:63], v[158:161], v[190:193], v[60:63]
	v_mfma_f32_16x16x32_bf16 v[44:47], v[158:161], v[198:201], v[44:47]
	v_mfma_f32_16x16x32_bf16 v[28:31], v[158:161], v[206:209], v[28:31]
	v_mfma_f32_16x16x32_bf16 v[12:15], v[158:161], v[214:217], v[12:15]
	v_mfma_f32_16x16x32_bf16 v[8:11], v[166:169], v[214:217], v[8:11]
	v_mfma_f32_16x16x32_bf16 v[24:27], v[166:169], v[206:209], v[24:27]
	v_mfma_f32_16x16x32_bf16 v[40:43], v[166:169], v[198:201], v[40:43]
	v_mfma_f32_16x16x32_bf16 v[56:59], v[166:169], v[190:193], v[56:59]
	s_setprio 0
	s_setprio 1
	v_mfma_f32_16x16x32_bf16 v[52:55], v[170:173], v[186:189], v[52:55]
	v_mfma_f32_16x16x32_bf16 v[36:39], v[170:173], v[194:197], v[36:39]
	v_mfma_f32_16x16x32_bf16 v[20:23], v[170:173], v[202:205], v[20:23]
	v_mfma_f32_16x16x32_bf16 v[4:7], v[170:173], v[210:213], v[4:7]
	v_mfma_f32_16x16x32_bf16 v[0:3], v[178:181], v[210:213], v[0:3]
	v_mfma_f32_16x16x32_bf16 v[16:19], v[178:181], v[202:205], v[16:19]
	v_mfma_f32_16x16x32_bf16 v[32:35], v[178:181], v[194:197], v[32:35]
	v_mfma_f32_16x16x32_bf16 v[48:51], v[178:181], v[186:189], v[48:51]
	v_mfma_f32_16x16x32_bf16 v[52:55], v[174:177], v[190:193], v[52:55]
	v_mfma_f32_16x16x32_bf16 v[36:39], v[174:177], v[198:201], v[36:39]
	v_mfma_f32_16x16x32_bf16 v[20:23], v[174:177], v[206:209], v[20:23]
	v_mfma_f32_16x16x32_bf16 v[4:7], v[174:177], v[214:217], v[4:7]
	v_mfma_f32_16x16x32_bf16 v[0:3], v[182:185], v[214:217], v[0:3]
	v_mfma_f32_16x16x32_bf16 v[16:19], v[182:185], v[206:209], v[16:19]
	v_mfma_f32_16x16x32_bf16 v[32:35], v[182:185], v[198:201], v[32:35]
	v_mfma_f32_16x16x32_bf16 v[48:51], v[182:185], v[190:193], v[48:51]
	s_setprio 0
	s_barrier
	s_add_u32 s50, s50, 0x100
	s_addc_u32 s51, s51, 0
	s_add_u32 s2, s2, 0x100
	s_addc_u32 s24, s24, 0
	s_cmp_ge_i32 s60, s30
	s_mov_b32 s25, s60
	s_cbranch_scc0 .LBB0_2071

; #define PG8_STAGE(bufoff, gbase, voff) do { _Pragma("unroll") for (int _i = 0; _i < 2; ++_i) \
;         __builtin_amdgcn_global_load_lds((const unsigned*)((const char*)(gbase) + (voff)[_i]), (PG8_LAS unsigned*)(lds + (bufoff) + ldsw + _i * 8192), 16, 0, 0); } while (0)
; #define PG8_LDA(dst, b, h) do { _Pragma("unroll") for (int m = 0; m < 4; ++m) _Pragma("unroll") for (int k = 0; k < 2; ++k) dst[m][k] = *(const PG8_LAS bf16x8*)(lds + PG8_SA(b, h) + aoff + m * 2048 + k * 1024); } while (0)
; #define PG8_LDB(dst, b, h) do { _Pragma("unroll") for (int n = 0; n < 2; ++n) _Pragma("unroll") for (int k = 0; k < 2; ++k) dst[n][k] = *(const PG8_LAS bf16x8*)(lds + PG8_SB(b, h) + boff + n * 2048 + k * 1024); } while (0)
; #define PG8_MMA(ai, bj, At, Bt) do { __builtin_amdgcn_s_setprio(1); _Pragma("unroll") for (int m = 0; m < 4; ++m) _Pragma("unroll") for (int n = 0; n < 2; ++n) _Pragma("unroll") for (int k = 0; k < 2; ++k) \
;         acc[ai][bj][m][n] = __builtin_amdgcn_mfma_f32_16x16x32_bf16(Bt[n][k], At[m][k], acc[ai][bj][m][n], 0, 0, 0); __builtin_amdgcn_s_setprio(0); } while (0)
; #define PG8_WAIT_V(n) asm volatile("s_waitcnt vmcnt(" #n ")" ::: "memory")
; #define PG8_WAIT_L(n) asm volatile("s_waitcnt lgkmcnt(" #n ")" ::: "memory")
; #define PG8_BAR __builtin_amdgcn_s_barrier()
; #define PG8_SCHED __builtin_amdgcn_sched_barrier(0)
; template <class Epi, class Sched, bool ALIGN_EPI = false, bool SP2 = false>
; __device__ __forceinline__ void gemm_phase(PG8_LAS unsigned char* lds, const Gemm g, const Sched& S, const Epi& E) {
;     ...
;             PG8_LDB(B0, 0, 0); PG8_LDB(B1, 0, 1); PG8_SCHED; PG8_LDA(At, 0, 0); PG8_STAGE(PG8_SA(1, 1), a1 + hstep, voffA);
;             PG8_WAIT_V(8); PG8_WAIT_L(0); PG8_BAR; PG8_MMA(0, 0, At, B0); PG8_MMA(0, 1, At, B1); PG8_BAR; PG8_SCHED;
;             PG8_LDA(At, 0, 1); PG8_STAGE(PG8_SB(0, 0), b2, voffB); PG8_STAGE(PG8_SB(0, 1), b2 + hstep, voffB); PG8_STAGE(PG8_SA(0, 0), a2, voffA);
;             PG8_WAIT_V(8); PG8_WAIT_L(0); PG8_BAR; PG8_MMA(1, 0, At, B0); PG8_MMA(1, 1, At, B1); PG8_BAR; PG8_SCHED;
.LBB0_2283:
	s_and_b64 vcc, exec, s[12:13]
	s_cbranch_vccnz .Lcoldz_10
	s_add_u32 s48, s48, 0x80
	s_addc_u32 s49, s49, 0
	s_add_u32 s2, s50, 0x100
	s_addc_u32 s24, s51, 0
	s_mov_b32 s25, 0
	ds_read_b128 v[120:123], v246
	ds_read_b128 v[132:135], v246 offset:1024
	ds_read_b128 v[136:139], v246 offset:2048
	ds_read_b128 v[140:143], v246 offset:3072
	ds_read_b128 v[144:147], v247
	ds_read_b128 v[148:151], v247 offset:1024
	ds_read_b128 v[152:155], v247 offset:2048
	ds_read_b128 v[156:159], v247 offset:3072
	s_add_i32 s60, s25, 2
	s_add_u32 s50, s48, 0x80
	s_addc_u32 s51, s49, 0
	s_cmp_eq_u32 s54, s25
	s_cselect_b32 s51, s17, s51
	s_cselect_b32 s50, s16, s50
	s_cselect_b32 s63, s47, s24
	s_cselect_b32 s62, s46, s2
	v_lshl_add_u64 v[206:207], s[48:49], 0, v[200:201]
	s_add_i32 m0, s7, 0xc000
	ds_read_b128 v[160:163], v248
	ds_read_b128 v[164:167], v248 offset:1024
	ds_read_b128 v[168:171], v248 offset:2048
	ds_read_b128 v[172:175], v248 offset:3072
	ds_read_b128 v[176:179], v248 offset:4096
	ds_read_b128 v[180:183], v248 offset:5120
	ds_read_b128 v[184:187], v248 offset:6144
	ds_read_b128 v[188:191], v248 offset:7168
	global_load_lds_dwordx4 v[206:207], off
	v_lshl_add_u64 v[206:207], s[48:49], 0, v[202:203]
	s_add_i32 m0, s7, 0xe000
	s_nop 0
	global_load_lds_dwordx4 v[206:207], off
	s_waitcnt vmcnt(8)
	s_waitcnt lgkmcnt(0)
	s_barrier
	s_setprio 1
	s_waitcnt lgkmcnt(0)
	v_mfma_f32_16x16x32_bf16 v[128:131], v[120:123], v[160:163], 0
	v_mfma_f32_16x16x32_bf16 v[124:127], v[136:139], v[160:163], 0
	v_mfma_f32_16x16x32_bf16 v[108:111], v[120:123], v[168:171], 0
	v_mfma_f32_16x16x32_bf16 v[104:107], v[136:139], v[168:171], 0
	v_mfma_f32_16x16x32_bf16 v[92:95], v[120:123], v[176:179], 0
	v_mfma_f32_16x16x32_bf16 v[88:91], v[136:139], v[176:179], 0
	v_mfma_f32_16x16x32_bf16 v[76:79], v[120:123], v[184:187], 0
	v_mfma_f32_16x16x32_bf16 v[72:75], v[136:139], v[184:187], 0
	v_mfma_f32_16x16x32_bf16 v[128:131], v[132:135], v[164:167], v[128:131]
	v_mfma_f32_16x16x32_bf16 v[108:111], v[132:135], v[172:175], v[108:111]
	v_mfma_f32_16x16x32_bf16 v[92:95], v[132:135], v[180:183], v[92:95]
	v_mfma_f32_16x16x32_bf16 v[76:79], v[132:135], v[188:191], v[76:79]
	v_mfma_f32_16x16x32_bf16 v[72:75], v[140:143], v[188:191], v[72:75]
	v_mfma_f32_16x16x32_bf16 v[88:91], v[140:143], v[180:183], v[88:91]
	v_mfma_f32_16x16x32_bf16 v[104:107], v[140:143], v[172:175], v[104:107]
	v_mfma_f32_16x16x32_bf16 v[124:127], v[140:143], v[164:167], v[124:127]
	s_setprio 0
	s_setprio 1
	v_mfma_f32_16x16x32_bf16 v[116:119], v[144:147], v[160:163], 0
	v_mfma_f32_16x16x32_bf16 v[112:115], v[152:155], v[160:163], 0
	v_mfma_f32_16x16x32_bf16 v[100:103], v[144:147], v[168:171], 0
	v_mfma_f32_16x16x32_bf16 v[96:99], v[152:155], v[168:171], 0
	v_mfma_f32_16x16x32_bf16 v[84:87], v[144:147], v[176:179], 0
	v_mfma_f32_16x16x32_bf16 v[80:83], v[152:155], v[176:179], 0
	v_mfma_f32_16x16x32_bf16 v[68:71], v[144:147], v[184:187], 0
	v_mfma_f32_16x16x32_bf16 v[64:67], v[152:155], v[184:187], 0
	v_mfma_f32_16x16x32_bf16 v[116:119], v[148:151], v[164:167], v[116:119]
	v_mfma_f32_16x16x32_bf16 v[100:103], v[148:151], v[172:175], v[100:103]
	v_mfma_f32_16x16x32_bf16 v[84:87], v[148:151], v[180:183], v[84:87]
	v_mfma_f32_16x16x32_bf16 v[68:71], v[148:151], v[188:191], v[68:71]
	v_mfma_f32_16x16x32_bf16 v[64:67], v[156:159], v[188:191], v[64:67]
	v_mfma_f32_16x16x32_bf16 v[80:83], v[156:159], v[180:183], v[80:83]
	v_mfma_f32_16x16x32_bf16 v[96:99], v[156:159], v[172:175], v[96:99]
	v_mfma_f32_16x16x32_bf16 v[112:115], v[156:159], v[164:167], v[112:115]
	s_setprio 0
	s_barrier
	s_add_i32 s25, s55, s6
	v_lshl_add_u64 v[206:207], s[62:63], 0, v[194:195]
	s_mov_b32 m0, s25
	ds_read_b128 v[160:163], v248 offset:16384
	ds_read_b128 v[164:167], v248 offset:17408
	ds_read_b128 v[168:171], v248 offset:18432
	ds_read_b128 v[172:175], v248 offset:19456
	ds_read_b128 v[176:179], v248 offset:20480
	ds_read_b128 v[180:183], v248 offset:21504
	ds_read_b128 v[184:187], v248 offset:22528
	ds_read_b128 v[188:191], v248 offset:23552
	global_load_lds_dwordx4 v[206:207], off
	s_add_i32 m0, s25, 0x2000
	v_lshl_add_u64 v[208:209], s[62:63], 0, v[198:199]
	s_add_u32 s62, s62, s34
	s_addc_u32 s63, s63, s35
	s_add_i32 s25, s56, s6
	global_load_lds_dwordx4 v[208:209], off
	v_lshl_add_u64 v[210:211], s[62:63], 0, v[194:195]
	s_mov_b32 m0, s25
	v_lshl_add_u64 v[212:213], s[62:63], 0, v[198:199]
	global_load_lds_dwordx4 v[210:211], off
	s_add_i32 m0, s25, 0x2000
	v_lshl_add_u64 v[214:215], s[50:51], 0, v[192:193]
	global_load_lds_dwordx4 v[212:213], off
	s_mov_b32 m0, s7
	v_lshl_add_u64 v[216:217], s[50:51], 0, v[196:197]
	global_load_lds_dwordx4 v[214:215], off
	s_mov_b32 m0, s18
	s_nop 0
	global_load_lds_dwordx4 v[216:217], off
	s_waitcnt vmcnt(8)
	s_waitcnt lgkmcnt(0)
	s_barrier
; #define PG8_STAGE(bufoff, gbase, voff) do { _Pragma("unroll") for (int _i = 0; _i < 2; ++_i) \
;         __builtin_amdgcn_global_load_lds((const unsigned*)((const char*)(gbase) + (voff)[_i]), (PG8_LAS unsigned*)(lds + (bufoff) + ldsw + _i * 8192), 16, 0, 0); } while (0)
; #define PG8_LDA(dst, b, h) do { _Pragma("unroll") for (int m = 0; m < 4; ++m) _Pragma("unroll") for (int k = 0; k < 2; ++k) dst[m][k] = *(const PG8_LAS bf16x8*)(lds + PG8_SA(b, h) + aoff + m * 2048 + k * 1024); } while (0)
; #define PG8_LDB(dst, b, h) do { _Pragma("unroll") for (int n = 0; n < 2; ++n) _Pragma("unroll") for (int k = 0; k < 2; ++k) dst[n][k] = *(const PG8_LAS bf16x8*)(lds + PG8_SB(b, h) + boff + n * 2048 + k * 1024); } while (0)
; #define PG8_MMA(ai, bj, At, Bt) do { __builtin_amdgcn_s_setprio(1); _Pragma("unroll") for (int m = 0; m < 4; ++m) _Pragma("unroll") for (int n = 0; n < 2; ++n) _Pragma("unroll") for (int k = 0; k < 2; ++k) \
;         acc[ai][bj][m][n] = __builtin_amdgcn_mfma_f32_16x16x32_bf16(Bt[n][k], At[m][k], acc[ai][bj][m][n], 0, 0, 0); __builtin_amdgcn_s_setprio(0); } while (0)
; #define PG8_WAIT_V(n) asm volatile("s_waitcnt vmcnt(" #n ")" ::: "memory")
; #define PG8_WAIT_L(n) asm volatile("s_waitcnt lgkmcnt(" #n ")" ::: "memory")
; #define PG8_BAR __builtin_amdgcn_s_barrier()
; #define PG8_SCHED __builtin_amdgcn_sched_barrier(0)
; template <class Epi, class Sched, bool ALIGN_EPI = false, bool SP2 = false>
; __device__ __forceinline__ void gemm_phase(PG8_LAS unsigned char* lds, const Gemm g, const Sched& S, const Epi& E) {
;     ...
;             PG8_WAIT_V(8); PG8_WAIT_L(0); PG8_BAR; PG8_MMA(1, 0, At, B0); PG8_MMA(1, 1, At, B1); PG8_BAR; PG8_SCHED;
;             PG8_LDB(B0, 1, 0); PG8_LDB(B1, 1, 1); PG8_SCHED; PG8_LDA(At, 1, 0); PG8_STAGE(PG8_SA(0, 1), a2 + hstep, voffA);
;             PG8_WAIT_V(8); PG8_WAIT_L(0); PG8_BAR; PG8_MMA(0, 0, At, B0); PG8_MMA(0, 1, At, B1); PG8_BAR; PG8_SCHED;
	s_setprio 1
	s_waitcnt lgkmcnt(0)
	v_mfma_f32_16x16x32_bf16 v[60:63], v[120:123], v[160:163], 0
	v_mfma_f32_16x16x32_bf16 v[56:59], v[136:139], v[160:163], 0
	v_mfma_f32_16x16x32_bf16 v[44:47], v[120:123], v[168:171], 0
	v_mfma_f32_16x16x32_bf16 v[40:43], v[136:139], v[168:171], 0
	v_mfma_f32_16x16x32_bf16 v[28:31], v[120:123], v[176:179], 0
	v_mfma_f32_16x16x32_bf16 v[24:27], v[136:139], v[176:179], 0
	v_mfma_f32_16x16x32_bf16 v[12:15], v[120:123], v[184:187], 0
	v_mfma_f32_16x16x32_bf16 v[8:11], v[136:139], v[184:187], 0
	v_mfma_f32_16x16x32_bf16 v[60:63], v[132:135], v[164:167], v[60:63]
	v_mfma_f32_16x16x32_bf16 v[44:47], v[132:135], v[172:175], v[44:47]
	v_mfma_f32_16x16x32_bf16 v[28:31], v[132:135], v[180:183], v[28:31]
	v_mfma_f32_16x16x32_bf16 v[12:15], v[132:135], v[188:191], v[12:15]
	v_mfma_f32_16x16x32_bf16 v[8:11], v[140:143], v[188:191], v[8:11]
	v_mfma_f32_16x16x32_bf16 v[24:27], v[140:143], v[180:183], v[24:27]
	v_mfma_f32_16x16x32_bf16 v[40:43], v[140:143], v[172:175], v[40:43]
	v_mfma_f32_16x16x32_bf16 v[56:59], v[140:143], v[164:167], v[56:59]
	s_setprio 0
	s_setprio 1
	v_mfma_f32_16x16x32_bf16 v[52:55], v[144:147], v[160:163], 0
	v_mfma_f32_16x16x32_bf16 v[48:51], v[152:155], v[160:163], 0
	v_mfma_f32_16x16x32_bf16 v[36:39], v[144:147], v[168:171], 0
	v_mfma_f32_16x16x32_bf16 v[32:35], v[152:155], v[168:171], 0
	v_mfma_f32_16x16x32_bf16 v[20:23], v[144:147], v[176:179], 0
	v_mfma_f32_16x16x32_bf16 v[16:19], v[152:155], v[176:179], 0
	v_mfma_f32_16x16x32_bf16 v[4:7], v[144:147], v[184:187], 0
	v_mfma_f32_16x16x32_bf16 v[0:3], v[152:155], v[184:187], 0
	v_mfma_f32_16x16x32_bf16 v[52:55], v[148:151], v[164:167], v[52:55]
	v_mfma_f32_16x16x32_bf16 v[36:39], v[148:151], v[172:175], v[36:39]
	v_mfma_f32_16x16x32_bf16 v[20:23], v[148:151], v[180:183], v[20:23]
	v_mfma_f32_16x16x32_bf16 v[4:7], v[148:151], v[188:191], v[4:7]
	v_mfma_f32_16x16x32_bf16 v[0:3], v[156:159], v[188:191], v[0:3]
	v_mfma_f32_16x16x32_bf16 v[16:19], v[156:159], v[180:183], v[16:19]
	v_mfma_f32_16x16x32_bf16 v[32:35], v[156:159], v[172:175], v[32:35]
	v_mfma_f32_16x16x32_bf16 v[48:51], v[156:159], v[164:167], v[48:51]
	s_setprio 0
	s_barrier
	s_add_i32 s25, 0, 0x18000
	s_add_i32 s61, 0, 0x1c000
	v_add_u32_e32 v140, s25, v244
	v_add_u32_e32 v156, s61, v244
	ds_read_b128 v[120:123], v140
	ds_read_b128 v[132:135], v140 offset:1024
	ds_read_b128 v[136:139], v140 offset:2048
	ds_read_b128 v[140:143], v140 offset:3072
	ds_read_b128 v[144:147], v156
	ds_read_b128 v[148:151], v156 offset:1024
	ds_read_b128 v[152:155], v156 offset:2048
	ds_read_b128 v[156:159], v156 offset:3072
	s_add_u32 s50, s50, s34
	s_addc_u32 s51, s51, s35
	s_mov_b32 m0, s19
	v_lshl_add_u64 v[218:219], s[50:51], 0, v[192:193]
	ds_read_b128 v[160:163], v248 offset:32768
	ds_read_b128 v[164:167], v248 offset:33792
	ds_read_b128 v[168:171], v248 offset:34816
	ds_read_b128 v[172:175], v248 offset:35840
	ds_read_b128 v[176:179], v248 offset:36864
	ds_read_b128 v[180:183], v248 offset:37888
	ds_read_b128 v[184:187], v248 offset:38912
	ds_read_b128 v[188:191], v248 offset:39936
	global_load_lds_dwordx4 v[218:219], off
	v_lshl_add_u64 v[218:219], s[50:51], 0, v[196:197]
	s_mov_b32 m0, s26
	s_nop 0
	global_load_lds_dwordx4 v[218:219], off
	s_waitcnt vmcnt(8)
	s_waitcnt lgkmcnt(0)
	s_barrier
	s_setprio 1
	s_waitcnt lgkmcnt(0)
	v_mfma_f32_16x16x32_bf16 v[128:131], v[120:123], v[160:163], v[128:131]
	v_mfma_f32_16x16x32_bf16 v[108:111], v[120:123], v[168:171], v[108:111]
	v_mfma_f32_16x16x32_bf16 v[92:95], v[120:123], v[176:179], v[92:95]
	v_mfma_f32_16x16x32_bf16 v[76:79], v[120:123], v[184:187], v[76:79]
	v_mfma_f32_16x16x32_bf16 v[72:75], v[136:139], v[184:187], v[72:75]
	v_mfma_f32_16x16x32_bf16 v[88:91], v[136:139], v[176:179], v[88:91]
	v_mfma_f32_16x16x32_bf16 v[104:107], v[136:139], v[168:171], v[104:107]
	v_mfma_f32_16x16x32_bf16 v[124:127], v[136:139], v[160:163], v[124:127]
	v_mfma_f32_16x16x32_bf16 v[128:131], v[132:135], v[164:167], v[128:131]
	v_mfma_f32_16x16x32_bf16 v[108:111], v[132:135], v[172:175], v[108:111]
	v_mfma_f32_16x16x32_bf16 v[92:95], v[132:135], v[180:183], v[92:95]
	v_mfma_f32_16x16x32_bf16 v[76:79], v[132:135], v[188:191], v[76:79]
	v_mfma_f32_16x16x32_bf16 v[72:75], v[140:143], v[188:191], v[72:75]
	v_mfma_f32_16x16x32_bf16 v[88:91], v[140:143], v[180:183], v[88:91]
	v_mfma_f32_16x16x32_bf16 v[104:107], v[140:143], v[172:175], v[104:107]
	v_mfma_f32_16x16x32_bf16 v[124:127], v[140:143], v[164:167], v[124:127]
	s_setprio 0
	s_setprio 1
	v_mfma_f32_16x16x32_bf16 v[116:119], v[144:147], v[160:163], v[116:119]
	v_mfma_f32_16x16x32_bf16 v[100:103], v[144:147], v[168:171], v[100:103]
	v_mfma_f32_16x16x32_bf16 v[84:87], v[144:147], v[176:179], v[84:87]
	v_mfma_f32_16x16x32_bf16 v[68:71], v[144:147], v[184:187], v[68:71]
	v_mfma_f32_16x16x32_bf16 v[64:67], v[152:155], v[184:187], v[64:67]
	v_mfma_f32_16x16x32_bf16 v[80:83], v[152:155], v[176:179], v[80:83]
	v_mfma_f32_16x16x32_bf16 v[96:99], v[152:155], v[168:171], v[96:99]
	v_mfma_f32_16x16x32_bf16 v[112:115], v[152:155], v[160:163], v[112:115]
	v_mfma_f32_16x16x32_bf16 v[116:119], v[148:151], v[164:167], v[116:119]
	v_mfma_f32_16x16x32_bf16 v[100:103], v[148:151], v[172:175], v[100:103]
	v_mfma_f32_16x16x32_bf16 v[84:87], v[148:151], v[180:183], v[84:87]
	v_mfma_f32_16x16x32_bf16 v[68:71], v[148:151], v[188:191], v[68:71]
	v_mfma_f32_16x16x32_bf16 v[64:67], v[156:159], v[188:191], v[64:67]
	v_mfma_f32_16x16x32_bf16 v[80:83], v[156:159], v[180:183], v[80:83]
	v_mfma_f32_16x16x32_bf16 v[96:99], v[156:159], v[172:175], v[96:99]
	v_mfma_f32_16x16x32_bf16 v[112:115], v[156:159], v[164:167], v[112:115]
	s_setprio 0
	s_barrier
; #define PG8_STAGE(bufoff, gbase, voff) do { _Pragma("unroll") for (int _i = 0; _i < 2; ++_i) \
;         __builtin_amdgcn_global_load_lds((const unsigned*)((const char*)(gbase) + (voff)[_i]), (PG8_LAS unsigned*)(lds + (bufoff) + ldsw + _i * 8192), 16, 0, 0); } while (0)
; #define PG8_LDA(dst, b, h) do { _Pragma("unroll") for (int m = 0; m < 4; ++m) _Pragma("unroll") for (int k = 0; k < 2; ++k) dst[m][k] = *(const PG8_LAS bf16x8*)(lds + PG8_SA(b, h) + aoff + m * 2048 + k * 1024); } while (0)
; #define PG8_LDB(dst, b, h) do { _Pragma("unroll") for (int n = 0; n < 2; ++n) _Pragma("unroll") for (int k = 0; k < 2; ++k) dst[n][k] = *(const PG8_LAS bf16x8*)(lds + PG8_SB(b, h) + boff + n * 2048 + k * 1024); } while (0)
; #define PG8_MMA(ai, bj, At, Bt) do { __builtin_amdgcn_s_setprio(1); _Pragma("unroll") for (int m = 0; m < 4; ++m) _Pragma("unroll") for (int n = 0; n < 2; ++n) _Pragma("unroll") for (int k = 0; k < 2; ++k) \
;         acc[ai][bj][m][n] = __builtin_amdgcn_mfma_f32_16x16x32_bf16(Bt[n][k], At[m][k], acc[ai][bj][m][n], 0, 0, 0); __builtin_amdgcn_s_setprio(0); } while (0)
; #define PG8_WAIT_V(n) asm volatile("s_waitcnt vmcnt(" #n ")" ::: "memory")
; #define PG8_WAIT_L(n) asm volatile("s_waitcnt lgkmcnt(" #n ")" ::: "memory")
; #define PG8_BAR __builtin_amdgcn_s_barrier()
; #define PG8_SCHED __builtin_amdgcn_sched_barrier(0)
; template <class Epi, class Sched, bool ALIGN_EPI = false, bool SP2 = false>
; __device__ __forceinline__ void gemm_phase(PG8_LAS unsigned char* lds, const Gemm g, const Sched& S, const Epi& E) {
;     ...
;         for (int t = 0; t < nt; t += 2) {
;             const bool last = (t == nt - 2);
;             const char* a1 = cA + (size_t)(t + 1) * kstep;
;             const char* a2 = last ? nA : cA + (size_t)(t + 2) * kstep; const char* b2 = last ? nB : cB + (size_t)(t + 2) * kstep;
;     ...
;             PG8_LDB(B0, 0, 0); PG8_LDB(B1, 0, 1); PG8_SCHED; PG8_LDA(At, 0, 0); PG8_STAGE(PG8_SA(1, 1), a1 + hstep, voffA);
;             PG8_WAIT_V(8); PG8_WAIT_L(0); PG8_BAR; PG8_MMA(0, 0, At, B0); PG8_MMA(0, 1, At, B1); PG8_BAR; PG8_SCHED;
;     ...
;             PG8_LDA(At, 1, 1); PG8_STAGE(PG8_SB(1, 0), b3, voffB); PG8_STAGE(PG8_SB(1, 1), b3 + hstep, voffB); PG8_STAGE(PG8_SA(1, 0), a3, voffA);
;             PG8_WAIT_V(8); PG8_WAIT_L(0); PG8_BAR; PG8_MMA(1, 0, At, B0); PG8_MMA(1, 1, At, B1); PG8_BAR; PG8_SCHED;
	s_add_i32 s25, s25, s6
	v_lshl_add_u64 v[206:207], v[206:207], 0, s[42:43]
	s_mov_b32 m0, s25
	ds_read_b128 v[160:163], v248 offset:49152
	ds_read_b128 v[164:167], v248 offset:50176
	ds_read_b128 v[168:171], v248 offset:51200
	ds_read_b128 v[172:175], v248 offset:52224
	ds_read_b128 v[176:179], v248 offset:53248
	ds_read_b128 v[180:183], v248 offset:54272
	ds_read_b128 v[184:187], v248 offset:55296
	ds_read_b128 v[188:191], v248 offset:56320
	global_load_lds_dwordx4 v[206:207], off
	v_lshl_add_u64 v[206:207], v[208:209], 0, s[42:43]
	s_add_i32 m0, s25, 0x2000
	s_add_i32 s25, s61, s6
	global_load_lds_dwordx4 v[206:207], off
	v_lshl_add_u64 v[206:207], v[210:211], 0, s[42:43]
	s_mov_b32 m0, s25
	s_nop 0
	global_load_lds_dwordx4 v[206:207], off
	v_lshl_add_u64 v[206:207], v[212:213], 0, s[42:43]
	s_add_i32 m0, s25, 0x2000
	s_nop 0
	global_load_lds_dwordx4 v[206:207], off
	v_lshl_add_u64 v[206:207], v[214:215], 0, s[42:43]
	s_mov_b32 m0, s27
	s_nop 0
	global_load_lds_dwordx4 v[206:207], off
	v_lshl_add_u64 v[206:207], v[216:217], 0, s[42:43]
	s_mov_b32 m0, s33
	s_nop 0
	global_load_lds_dwordx4 v[206:207], off
	s_waitcnt vmcnt(8)
	s_waitcnt lgkmcnt(0)
	s_barrier
	s_setprio 1
	s_waitcnt lgkmcnt(0)
	v_mfma_f32_16x16x32_bf16 v[60:63], v[120:123], v[160:163], v[60:63]
	v_mfma_f32_16x16x32_bf16 v[44:47], v[120:123], v[168:171], v[44:47]
	v_mfma_f32_16x16x32_bf16 v[28:31], v[120:123], v[176:179], v[28:31]
	v_mfma_f32_16x16x32_bf16 v[12:15], v[120:123], v[184:187], v[12:15]
	v_mfma_f32_16x16x32_bf16 v[8:11], v[136:139], v[184:187], v[8:11]
	v_mfma_f32_16x16x32_bf16 v[24:27], v[136:139], v[176:179], v[24:27]
	v_mfma_f32_16x16x32_bf16 v[40:43], v[136:139], v[168:171], v[40:43]
	v_mfma_f32_16x16x32_bf16 v[56:59], v[136:139], v[160:163], v[56:59]
	v_mfma_f32_16x16x32_bf16 v[60:63], v[132:135], v[164:167], v[60:63]
	v_mfma_f32_16x16x32_bf16 v[44:47], v[132:135], v[172:175], v[44:47]
	v_mfma_f32_16x16x32_bf16 v[28:31], v[132:135], v[180:183], v[28:31]
	v_mfma_f32_16x16x32_bf16 v[12:15], v[132:135], v[188:191], v[12:15]
	v_mfma_f32_16x16x32_bf16 v[8:11], v[140:143], v[188:191], v[8:11]
	v_mfma_f32_16x16x32_bf16 v[24:27], v[140:143], v[180:183], v[24:27]
	v_mfma_f32_16x16x32_bf16 v[40:43], v[140:143], v[172:175], v[40:43]
	v_mfma_f32_16x16x32_bf16 v[56:59], v[140:143], v[164:167], v[56:59]
	s_setprio 0
	s_setprio 1
	v_mfma_f32_16x16x32_bf16 v[52:55], v[144:147], v[160:163], v[52:55]
	v_mfma_f32_16x16x32_bf16 v[36:39], v[144:147], v[168:171], v[36:39]
	v_mfma_f32_16x16x32_bf16 v[20:23], v[144:147], v[176:179], v[20:23]
	v_mfma_f32_16x16x32_bf16 v[4:7], v[144:147], v[184:187], v[4:7]
	v_mfma_f32_16x16x32_bf16 v[0:3], v[152:155], v[184:187], v[0:3]
	v_mfma_f32_16x16x32_bf16 v[16:19], v[152:155], v[176:179], v[16:19]
	v_mfma_f32_16x16x32_bf16 v[32:35], v[152:155], v[168:171], v[32:35]
	v_mfma_f32_16x16x32_bf16 v[48:51], v[152:155], v[160:163], v[48:51]
	v_mfma_f32_16x16x32_bf16 v[52:55], v[148:151], v[164:167], v[52:55]
	v_mfma_f32_16x16x32_bf16 v[36:39], v[148:151], v[172:175], v[36:39]
	v_mfma_f32_16x16x32_bf16 v[20:23], v[148:151], v[180:183], v[20:23]
	v_mfma_f32_16x16x32_bf16 v[4:7], v[148:151], v[188:191], v[4:7]
	v_mfma_f32_16x16x32_bf16 v[0:3], v[156:159], v[188:191], v[0:3]
	v_mfma_f32_16x16x32_bf16 v[16:19], v[156:159], v[180:183], v[16:19]
	v_mfma_f32_16x16x32_bf16 v[32:35], v[156:159], v[172:175], v[32:35]
	v_mfma_f32_16x16x32_bf16 v[48:51], v[156:159], v[164:167], v[48:51]
	s_setprio 0
	s_barrier
	s_add_u32 s48, s48, 0x100
	s_addc_u32 s49, s49, 0
	s_add_u32 s2, s2, 0x100
	s_addc_u32 s24, s24, 0
	s_cmp_ge_i32 s60, s53
	s_mov_b32 s25, s60
	s_cbranch_scc1 .Lpeelx_10
.LBB0_2285:
	ds_read_b128 v[120:123], v246
	ds_read_b128 v[132:135], v246 offset:1024
	ds_read_b128 v[136:139], v246 offset:2048
	ds_read_b128 v[140:143], v246 offset:3072
	ds_read_b128 v[144:147], v247
	ds_read_b128 v[148:151], v247 offset:1024
	ds_read_b128 v[152:155], v247 offset:2048
	ds_read_b128 v[156:159], v247 offset:3072
	s_add_i32 s60, s25, 2
	s_add_u32 s50, s48, 0x80
	s_addc_u32 s51, s49, 0
	s_cmp_eq_u32 s54, s25
	s_cselect_b32 s51, s17, s51
	s_cselect_b32 s50, s16, s50
	s_cselect_b32 s63, s47, s24
	s_cselect_b32 s62, s46, s2
	v_lshl_add_u64 v[206:207], s[48:49], 0, v[200:201]
	s_add_i32 m0, s7, 0xc000
	ds_read_b128 v[160:163], v248
	ds_read_b128 v[164:167], v248 offset:1024
	ds_read_b128 v[168:171], v248 offset:2048
	ds_read_b128 v[172:175], v248 offset:3072
	ds_read_b128 v[176:179], v248 offset:4096
	ds_read_b128 v[180:183], v248 offset:5120
	ds_read_b128 v[184:187], v248 offset:6144
	ds_read_b128 v[188:191], v248 offset:7168
	global_load_lds_dwordx4 v[206:207], off
	v_lshl_add_u64 v[206:207], s[48:49], 0, v[202:203]
	s_add_i32 m0, s7, 0xe000
	s_nop 0
	global_load_lds_dwordx4 v[206:207], off
	s_waitcnt vmcnt(8)
	s_waitcnt lgkmcnt(0)
	s_barrier
; #define PG8_STAGE(bufoff, gbase, voff) do { _Pragma("unroll") for (int _i = 0; _i < 2; ++_i) \
;         __builtin_amdgcn_global_load_lds((const unsigned*)((const char*)(gbase) + (voff)[_i]), (PG8_LAS unsigned*)(lds + (bufoff) + ldsw + _i * 8192), 16, 0, 0); } while (0)
; #define PG8_LDA(dst, b, h) do { _Pragma("unroll") for (int m = 0; m < 4; ++m) _Pragma("unroll") for (int k = 0; k < 2; ++k) dst[m][k] = *(const PG8_LAS bf16x8*)(lds + PG8_SA(b, h) + aoff + m * 2048 + k * 1024); } while (0)
; #define PG8_LDB(dst, b, h) do { _Pragma("unroll") for (int n = 0; n < 2; ++n) _Pragma("unroll") for (int k = 0; k < 2; ++k) dst[n][k] = *(const PG8_LAS bf16x8*)(lds + PG8_SB(b, h) + boff + n * 2048 + k * 1024); } while (0)
; #define PG8_MMA(ai, bj, At, Bt) do { __builtin_amdgcn_s_setprio(1); _Pragma("unroll") for (int m = 0; m < 4; ++m) _Pragma("unroll") for (int n = 0; n < 2; ++n) _Pragma("unroll") for (int k = 0; k < 2; ++k) \
;         acc[ai][bj][m][n] = __builtin_amdgcn_mfma_f32_16x16x32_bf16(Bt[n][k], At[m][k], acc[ai][bj][m][n], 0, 0, 0); __builtin_amdgcn_s_setprio(0); } while (0)
; #define PG8_WAIT_V(n) asm volatile("s_waitcnt vmcnt(" #n ")" ::: "memory")
; #define PG8_WAIT_L(n) asm volatile("s_waitcnt lgkmcnt(" #n ")" ::: "memory")
; #define PG8_BAR __builtin_amdgcn_s_barrier()
; #define PG8_SCHED __builtin_amdgcn_sched_barrier(0)
; template <class Epi, class Sched, bool ALIGN_EPI = false, bool SP2 = false>
; __device__ __forceinline__ void gemm_phase(PG8_LAS unsigned char* lds, const Gemm g, const Sched& S, const Epi& E) {
;     ...
;             PG8_WAIT_V(8); PG8_WAIT_L(0); PG8_BAR; PG8_MMA(0, 0, At, B0); PG8_MMA(0, 1, At, B1); PG8_BAR; PG8_SCHED;
;             PG8_LDA(At, 0, 1); PG8_STAGE(PG8_SB(0, 0), b2, voffB); PG8_STAGE(PG8_SB(0, 1), b2 + hstep, voffB); PG8_STAGE(PG8_SA(0, 0), a2, voffA);
;             PG8_WAIT_V(8); PG8_WAIT_L(0); PG8_BAR; PG8_MMA(1, 0, At, B0); PG8_MMA(1, 1, At, B1); PG8_BAR; PG8_SCHED;
;             PG8_LDB(B0, 1, 0); PG8_LDB(B1, 1, 1); PG8_SCHED; PG8_LDA(At, 1, 0); PG8_STAGE(PG8_SA(0, 1), a2 + hstep, voffA);
;             PG8_WAIT_V(8); PG8_WAIT_L(0); PG8_BAR; PG8_MMA(0, 0, At, B0); PG8_MMA(0, 1, At, B1); PG8_BAR; PG8_SCHED;
	s_setprio 1
	s_waitcnt lgkmcnt(0)
	v_mfma_f32_16x16x32_bf16 v[128:131], v[120:123], v[160:163], v[128:131]
	v_mfma_f32_16x16x32_bf16 v[108:111], v[120:123], v[168:171], v[108:111]
	v_mfma_f32_16x16x32_bf16 v[92:95], v[120:123], v[176:179], v[92:95]
	v_mfma_f32_16x16x32_bf16 v[76:79], v[120:123], v[184:187], v[76:79]
	v_mfma_f32_16x16x32_bf16 v[72:75], v[136:139], v[184:187], v[72:75]
	v_mfma_f32_16x16x32_bf16 v[88:91], v[136:139], v[176:179], v[88:91]
	v_mfma_f32_16x16x32_bf16 v[104:107], v[136:139], v[168:171], v[104:107]
	v_mfma_f32_16x16x32_bf16 v[124:127], v[136:139], v[160:163], v[124:127]
	v_mfma_f32_16x16x32_bf16 v[128:131], v[132:135], v[164:167], v[128:131]
	v_mfma_f32_16x16x32_bf16 v[108:111], v[132:135], v[172:175], v[108:111]
	v_mfma_f32_16x16x32_bf16 v[92:95], v[132:135], v[180:183], v[92:95]
	v_mfma_f32_16x16x32_bf16 v[76:79], v[132:135], v[188:191], v[76:79]
	v_mfma_f32_16x16x32_bf16 v[72:75], v[140:143], v[188:191], v[72:75]
	v_mfma_f32_16x16x32_bf16 v[88:91], v[140:143], v[180:183], v[88:91]
	v_mfma_f32_16x16x32_bf16 v[104:107], v[140:143], v[172:175], v[104:107]
	v_mfma_f32_16x16x32_bf16 v[124:127], v[140:143], v[164:167], v[124:127]
	s_setprio 0
	s_setprio 1
	v_mfma_f32_16x16x32_bf16 v[116:119], v[144:147], v[160:163], v[116:119]
	v_mfma_f32_16x16x32_bf16 v[100:103], v[144:147], v[168:171], v[100:103]
	v_mfma_f32_16x16x32_bf16 v[84:87], v[144:147], v[176:179], v[84:87]
	v_mfma_f32_16x16x32_bf16 v[68:71], v[144:147], v[184:187], v[68:71]
	v_mfma_f32_16x16x32_bf16 v[64:67], v[152:155], v[184:187], v[64:67]
	v_mfma_f32_16x16x32_bf16 v[80:83], v[152:155], v[176:179], v[80:83]
	v_mfma_f32_16x16x32_bf16 v[96:99], v[152:155], v[168:171], v[96:99]
	v_mfma_f32_16x16x32_bf16 v[112:115], v[152:155], v[160:163], v[112:115]
	v_mfma_f32_16x16x32_bf16 v[116:119], v[148:151], v[164:167], v[116:119]
	v_mfma_f32_16x16x32_bf16 v[100:103], v[148:151], v[172:175], v[100:103]
	v_mfma_f32_16x16x32_bf16 v[84:87], v[148:151], v[180:183], v[84:87]
	v_mfma_f32_16x16x32_bf16 v[68:71], v[148:151], v[188:191], v[68:71]
	v_mfma_f32_16x16x32_bf16 v[64:67], v[156:159], v[188:191], v[64:67]
	v_mfma_f32_16x16x32_bf16 v[80:83], v[156:159], v[180:183], v[80:83]
	v_mfma_f32_16x16x32_bf16 v[96:99], v[156:159], v[172:175], v[96:99]
	v_mfma_f32_16x16x32_bf16 v[112:115], v[156:159], v[164:167], v[112:115]
	s_setprio 0
	s_barrier
	s_add_i32 s25, s55, s6
	v_lshl_add_u64 v[206:207], s[62:63], 0, v[194:195]
	s_mov_b32 m0, s25
	ds_read_b128 v[160:163], v248 offset:16384
	ds_read_b128 v[164:167], v248 offset:17408
	ds_read_b128 v[168:171], v248 offset:18432
	ds_read_b128 v[172:175], v248 offset:19456
	ds_read_b128 v[176:179], v248 offset:20480
	ds_read_b128 v[180:183], v248 offset:21504
	ds_read_b128 v[184:187], v248 offset:22528
	ds_read_b128 v[188:191], v248 offset:23552
	global_load_lds_dwordx4 v[206:207], off
	s_add_i32 m0, s25, 0x2000
	v_lshl_add_u64 v[208:209], s[62:63], 0, v[198:199]
	s_add_u32 s62, s62, s34
	s_addc_u32 s63, s63, s35
	s_add_i32 s25, s56, s6
	global_load_lds_dwordx4 v[208:209], off
	v_lshl_add_u64 v[210:211], s[62:63], 0, v[194:195]
	s_mov_b32 m0, s25
	v_lshl_add_u64 v[212:213], s[62:63], 0, v[198:199]
	global_load_lds_dwordx4 v[210:211], off
	s_add_i32 m0, s25, 0x2000
	v_lshl_add_u64 v[214:215], s[50:51], 0, v[192:193]
	global_load_lds_dwordx4 v[212:213], off
	s_mov_b32 m0, s7
	v_lshl_add_u64 v[216:217], s[50:51], 0, v[196:197]
	global_load_lds_dwordx4 v[214:215], off
	s_mov_b32 m0, s18
	s_nop 0
	global_load_lds_dwordx4 v[216:217], off
	s_waitcnt vmcnt(8)
	s_waitcnt lgkmcnt(0)
	s_barrier
	s_setprio 1
	s_waitcnt lgkmcnt(0)
	v_mfma_f32_16x16x32_bf16 v[60:63], v[120:123], v[160:163], v[60:63]
	v_mfma_f32_16x16x32_bf16 v[44:47], v[120:123], v[168:171], v[44:47]
	v_mfma_f32_16x16x32_bf16 v[28:31], v[120:123], v[176:179], v[28:31]
	v_mfma_f32_16x16x32_bf16 v[12:15], v[120:123], v[184:187], v[12:15]
	v_mfma_f32_16x16x32_bf16 v[8:11], v[136:139], v[184:187], v[8:11]
	v_mfma_f32_16x16x32_bf16 v[24:27], v[136:139], v[176:179], v[24:27]
	v_mfma_f32_16x16x32_bf16 v[40:43], v[136:139], v[168:171], v[40:43]
	v_mfma_f32_16x16x32_bf16 v[56:59], v[136:139], v[160:163], v[56:59]
	v_mfma_f32_16x16x32_bf16 v[60:63], v[132:135], v[164:167], v[60:63]
	v_mfma_f32_16x16x32_bf16 v[44:47], v[132:135], v[172:175], v[44:47]
	v_mfma_f32_16x16x32_bf16 v[28:31], v[132:135], v[180:183], v[28:31]
	v_mfma_f32_16x16x32_bf16 v[12:15], v[132:135], v[188:191], v[12:15]
	v_mfma_f32_16x16x32_bf16 v[8:11], v[140:143], v[188:191], v[8:11]
	v_mfma_f32_16x16x32_bf16 v[24:27], v[140:143], v[180:183], v[24:27]
	v_mfma_f32_16x16x32_bf16 v[40:43], v[140:143], v[172:175], v[40:43]
	v_mfma_f32_16x16x32_bf16 v[56:59], v[140:143], v[164:167], v[56:59]
	s_setprio 0
	s_setprio 1
	v_mfma_f32_16x16x32_bf16 v[52:55], v[144:147], v[160:163], v[52:55]
	v_mfma_f32_16x16x32_bf16 v[36:39], v[144:147], v[168:171], v[36:39]
	v_mfma_f32_16x16x32_bf16 v[20:23], v[144:147], v[176:179], v[20:23]
	v_mfma_f32_16x16x32_bf16 v[4:7], v[144:147], v[184:187], v[4:7]
	v_mfma_f32_16x16x32_bf16 v[0:3], v[152:155], v[184:187], v[0:3]
	v_mfma_f32_16x16x32_bf16 v[16:19], v[152:155], v[176:179], v[16:19]
	v_mfma_f32_16x16x32_bf16 v[32:35], v[152:155], v[168:171], v[32:35]
	v_mfma_f32_16x16x32_bf16 v[48:51], v[152:155], v[160:163], v[48:51]
	v_mfma_f32_16x16x32_bf16 v[52:55], v[148:151], v[164:167], v[52:55]
	v_mfma_f32_16x16x32_bf16 v[36:39], v[148:151], v[172:175], v[36:39]
	v_mfma_f32_16x16x32_bf16 v[20:23], v[148:151], v[180:183], v[20:23]
	v_mfma_f32_16x16x32_bf16 v[4:7], v[148:151], v[188:191], v[4:7]
	v_mfma_f32_16x16x32_bf16 v[0:3], v[156:159], v[188:191], v[0:3]
	v_mfma_f32_16x16x32_bf16 v[16:19], v[156:159], v[180:183], v[16:19]
	v_mfma_f32_16x16x32_bf16 v[32:35], v[156:159], v[172:175], v[32:35]
	v_mfma_f32_16x16x32_bf16 v[48:51], v[156:159], v[164:167], v[48:51]
	s_setprio 0
	s_barrier
; #define PG8_STAGE(bufoff, gbase, voff) do { _Pragma("unroll") for (int _i = 0; _i < 2; ++_i) \
;         __builtin_amdgcn_global_load_lds((const unsigned*)((const char*)(gbase) + (voff)[_i]), (PG8_LAS unsigned*)(lds + (bufoff) + ldsw + _i * 8192), 16, 0, 0); } while (0)
; #define PG8_LDA(dst, b, h) do { _Pragma("unroll") for (int m = 0; m < 4; ++m) _Pragma("unroll") for (int k = 0; k < 2; ++k) dst[m][k] = *(const PG8_LAS bf16x8*)(lds + PG8_SA(b, h) + aoff + m * 2048 + k * 1024); } while (0)
; #define PG8_LDB(dst, b, h) do { _Pragma("unroll") for (int n = 0; n < 2; ++n) _Pragma("unroll") for (int k = 0; k < 2; ++k) dst[n][k] = *(const PG8_LAS bf16x8*)(lds + PG8_SB(b, h) + boff + n * 2048 + k * 1024); } while (0)
; #define PG8_MMA(ai, bj, At, Bt) do { __builtin_amdgcn_s_setprio(1); _Pragma("unroll") for (int m = 0; m < 4; ++m) _Pragma("unroll") for (int n = 0; n < 2; ++n) _Pragma("unroll") for (int k = 0; k < 2; ++k) \
;         acc[ai][bj][m][n] = __builtin_amdgcn_mfma_f32_16x16x32_bf16(Bt[n][k], At[m][k], acc[ai][bj][m][n], 0, 0, 0); __builtin_amdgcn_s_setprio(0); } while (0)
; #define PG8_WAIT_V(n) asm volatile("s_waitcnt vmcnt(" #n ")" ::: "memory")
; #define PG8_WAIT_L(n) asm volatile("s_waitcnt lgkmcnt(" #n ")" ::: "memory")
; #define PG8_BAR __builtin_amdgcn_s_barrier()
; #define PG8_SCHED __builtin_amdgcn_sched_barrier(0)
; template <class Epi, class Sched, bool ALIGN_EPI = false, bool SP2 = false>
; __device__ __forceinline__ void gemm_phase(PG8_LAS unsigned char* lds, const Gemm g, const Sched& S, const Epi& E) {
;     ...
;             PG8_LDB(B0, 1, 0); PG8_LDB(B1, 1, 1); PG8_SCHED; PG8_LDA(At, 1, 0); PG8_STAGE(PG8_SA(0, 1), a2 + hstep, voffA);
;             PG8_WAIT_V(8); PG8_WAIT_L(0); PG8_BAR; PG8_MMA(0, 0, At, B0); PG8_MMA(0, 1, At, B1); PG8_BAR; PG8_SCHED;
	s_add_i32 s25, 0, 0x18000
	s_add_i32 s61, 0, 0x1c000
	v_add_u32_e32 v140, s25, v244
	v_add_u32_e32 v156, s61, v244
	ds_read_b128 v[120:123], v140
	ds_read_b128 v[132:135], v140 offset:1024
	ds_read_b128 v[136:139], v140 offset:2048
	ds_read_b128 v[140:143], v140 offset:3072
	ds_read_b128 v[144:147], v156
	ds_read_b128 v[148:151], v156 offset:1024
	ds_read_b128 v[152:155], v156 offset:2048
	ds_read_b128 v[156:159], v156 offset:3072
	s_add_u32 s50, s50, s34
	s_addc_u32 s51, s51, s35
	s_mov_b32 m0, s19
	v_lshl_add_u64 v[218:219], s[50:51], 0, v[192:193]
	ds_read_b128 v[160:163], v248 offset:32768
	ds_read_b128 v[164:167], v248 offset:33792
	ds_read_b128 v[168:171], v248 offset:34816
	ds_read_b128 v[172:175], v248 offset:35840
	ds_read_b128 v[176:179], v248 offset:36864
	ds_read_b128 v[180:183], v248 offset:37888
	ds_read_b128 v[184:187], v248 offset:38912
	ds_read_b128 v[188:191], v248 offset:39936
	global_load_lds_dwordx4 v[218:219], off
	v_lshl_add_u64 v[218:219], s[50:51], 0, v[196:197]
	s_mov_b32 m0, s26
	s_nop 0
	global_load_lds_dwordx4 v[218:219], off
	s_waitcnt vmcnt(8)
	s_waitcnt lgkmcnt(0)
	s_barrier
	s_setprio 1
	s_waitcnt lgkmcnt(0)
	v_mfma_f32_16x16x32_bf16 v[128:131], v[120:123], v[160:163], v[128:131]
	v_mfma_f32_16x16x32_bf16 v[108:111], v[120:123], v[168:171], v[108:111]
	v_mfma_f32_16x16x32_bf16 v[92:95], v[120:123], v[176:179], v[92:95]
	v_mfma_f32_16x16x32_bf16 v[76:79], v[120:123], v[184:187], v[76:79]
	v_mfma_f32_16x16x32_bf16 v[72:75], v[136:139], v[184:187], v[72:75]
	v_mfma_f32_16x16x32_bf16 v[88:91], v[136:139], v[176:179], v[88:91]
	v_mfma_f32_16x16x32_bf16 v[104:107], v[136:139], v[168:171], v[104:107]
	v_mfma_f32_16x16x32_bf16 v[124:127], v[136:139], v[160:163], v[124:127]
	v_mfma_f32_16x16x32_bf16 v[128:131], v[132:135], v[164:167], v[128:131]
	v_mfma_f32_16x16x32_bf16 v[108:111], v[132:135], v[172:175], v[108:111]
	v_mfma_f32_16x16x32_bf16 v[92:95], v[132:135], v[180:183], v[92:95]
	v_mfma_f32_16x16x32_bf16 v[76:79], v[132:135], v[188:191], v[76:79]
	v_mfma_f32_16x16x32_bf16 v[72:75], v[140:143], v[188:191], v[72:75]
	v_mfma_f32_16x16x32_bf16 v[88:91], v[140:143], v[180:183], v[88:91]
	v_mfma_f32_16x16x32_bf16 v[104:107], v[140:143], v[172:175], v[104:107]
	v_mfma_f32_16x16x32_bf16 v[124:127], v[140:143], v[164:167], v[124:127]
	s_setprio 0
	s_setprio 1
	v_mfma_f32_16x16x32_bf16 v[116:119], v[144:147], v[160:163], v[116:119]
	v_mfma_f32_16x16x32_bf16 v[100:103], v[144:147], v[168:171], v[100:103]
	v_mfma_f32_16x16x32_bf16 v[84:87], v[144:147], v[176:179], v[84:87]
	v_mfma_f32_16x16x32_bf16 v[68:71], v[144:147], v[184:187], v[68:71]
	v_mfma_f32_16x16x32_bf16 v[64:67], v[152:155], v[184:187], v[64:67]
	v_mfma_f32_16x16x32_bf16 v[80:83], v[152:155], v[176:179], v[80:83]
	v_mfma_f32_16x16x32_bf16 v[96:99], v[152:155], v[168:171], v[96:99]
	v_mfma_f32_16x16x32_bf16 v[112:115], v[152:155], v[160:163], v[112:115]
	v_mfma_f32_16x16x32_bf16 v[116:119], v[148:151], v[164:167], v[116:119]
	v_mfma_f32_16x16x32_bf16 v[100:103], v[148:151], v[172:175], v[100:103]
	v_mfma_f32_16x16x32_bf16 v[84:87], v[148:151], v[180:183], v[84:87]
	v_mfma_f32_16x16x32_bf16 v[68:71], v[148:151], v[188:191], v[68:71]
	v_mfma_f32_16x16x32_bf16 v[64:67], v[156:159], v[188:191], v[64:67]
	v_mfma_f32_16x16x32_bf16 v[80:83], v[156:159], v[180:183], v[80:83]
	v_mfma_f32_16x16x32_bf16 v[96:99], v[156:159], v[172:175], v[96:99]
	v_mfma_f32_16x16x32_bf16 v[112:115], v[156:159], v[164:167], v[112:115]
	s_setprio 0
	s_barrier
; #define PG8_STAGE(bufoff, gbase, voff) do { _Pragma("unroll") for (int _i = 0; _i < 2; ++_i) \
;         __builtin_amdgcn_global_load_lds((const unsigned*)((const char*)(gbase) + (voff)[_i]), (PG8_LAS unsigned*)(lds + (bufoff) + ldsw + _i * 8192), 16, 0, 0); } while (0)
; #define PG8_LDA(dst, b, h) do { _Pragma("unroll") for (int m = 0; m < 4; ++m) _Pragma("unroll") for (int k = 0; k < 2; ++k) dst[m][k] = *(const PG8_LAS bf16x8*)(lds + PG8_SA(b, h) + aoff + m * 2048 + k * 1024); } while (0)
; #define PG8_MMA(ai, bj, At, Bt) do { __builtin_amdgcn_s_setprio(1); _Pragma("unroll") for (int m = 0; m < 4; ++m) _Pragma("unroll") for (int n = 0; n < 2; ++n) _Pragma("unroll") for (int k = 0; k < 2; ++k) \
;         acc[ai][bj][m][n] = __builtin_amdgcn_mfma_f32_16x16x32_bf16(Bt[n][k], At[m][k], acc[ai][bj][m][n], 0, 0, 0); __builtin_amdgcn_s_setprio(0); } while (0)
; #define PG8_WAIT_V(n) asm volatile("s_waitcnt vmcnt(" #n ")" ::: "memory")
; #define PG8_WAIT_L(n) asm volatile("s_waitcnt lgkmcnt(" #n ")" ::: "memory")
; #define PG8_BAR __builtin_amdgcn_s_barrier()
; #define PG8_SCHED __builtin_amdgcn_sched_barrier(0)
; template <class Epi, class Sched, bool ALIGN_EPI = false, bool SP2 = false>
; __device__ __forceinline__ void gemm_phase(PG8_LAS unsigned char* lds, const Gemm g, const Sched& S, const Epi& E) {
;     ...
;         for (int t = 0; t < nt; t += 2) {
;             const bool last = (t == nt - 2);
;             const char* a1 = cA + (size_t)(t + 1) * kstep;
;             const char* a2 = last ? nA : cA + (size_t)(t + 2) * kstep; const char* b2 = last ? nB : cB + (size_t)(t + 2) * kstep;
;     ...
;             PG8_LDA(At, 1, 1); PG8_STAGE(PG8_SB(1, 0), b3, voffB); PG8_STAGE(PG8_SB(1, 1), b3 + hstep, voffB); PG8_STAGE(PG8_SA(1, 0), a3, voffA);
;             PG8_WAIT_V(8); PG8_WAIT_L(0); PG8_BAR; PG8_MMA(1, 0, At, B0); PG8_MMA(1, 1, At, B1); PG8_BAR; PG8_SCHED;
	s_add_i32 s25, s25, s6
	v_lshl_add_u64 v[206:207], v[206:207], 0, s[42:43]
	s_mov_b32 m0, s25
	ds_read_b128 v[160:163], v248 offset:49152
	ds_read_b128 v[164:167], v248 offset:50176
	ds_read_b128 v[168:171], v248 offset:51200
	ds_read_b128 v[172:175], v248 offset:52224
	ds_read_b128 v[176:179], v248 offset:53248
	ds_read_b128 v[180:183], v248 offset:54272
	ds_read_b128 v[184:187], v248 offset:55296
	ds_read_b128 v[188:191], v248 offset:56320
	global_load_lds_dwordx4 v[206:207], off
	v_lshl_add_u64 v[206:207], v[208:209], 0, s[42:43]
	s_add_i32 m0, s25, 0x2000
	s_add_i32 s25, s61, s6
	global_load_lds_dwordx4 v[206:207], off
	v_lshl_add_u64 v[206:207], v[210:211], 0, s[42:43]
	s_mov_b32 m0, s25
	s_nop 0
	global_load_lds_dwordx4 v[206:207], off
	v_lshl_add_u64 v[206:207], v[212:213], 0, s[42:43]
	s_add_i32 m0, s25, 0x2000
	s_nop 0
	global_load_lds_dwordx4 v[206:207], off
	v_lshl_add_u64 v[206:207], v[214:215], 0, s[42:43]
	s_mov_b32 m0, s27
	s_nop 0
	global_load_lds_dwordx4 v[206:207], off
	v_lshl_add_u64 v[206:207], v[216:217], 0, s[42:43]
	s_mov_b32 m0, s33
	s_nop 0
	global_load_lds_dwordx4 v[206:207], off
	s_waitcnt vmcnt(8)
	s_waitcnt lgkmcnt(0)
	s_barrier
	s_setprio 1
	s_waitcnt lgkmcnt(0)
	v_mfma_f32_16x16x32_bf16 v[60:63], v[120:123], v[160:163], v[60:63]
	v_mfma_f32_16x16x32_bf16 v[44:47], v[120:123], v[168:171], v[44:47]
	v_mfma_f32_16x16x32_bf16 v[28:31], v[120:123], v[176:179], v[28:31]
	v_mfma_f32_16x16x32_bf16 v[12:15], v[120:123], v[184:187], v[12:15]
	v_mfma_f32_16x16x32_bf16 v[8:11], v[136:139], v[184:187], v[8:11]
	v_mfma_f32_16x16x32_bf16 v[24:27], v[136:139], v[176:179], v[24:27]
	v_mfma_f32_16x16x32_bf16 v[40:43], v[136:139], v[168:171], v[40:43]
	v_mfma_f32_16x16x32_bf16 v[56:59], v[136:139], v[160:163], v[56:59]
	v_mfma_f32_16x16x32_bf16 v[60:63], v[132:135], v[164:167], v[60:63]
	v_mfma_f32_16x16x32_bf16 v[44:47], v[132:135], v[172:175], v[44:47]
	v_mfma_f32_16x16x32_bf16 v[28:31], v[132:135], v[180:183], v[28:31]
	v_mfma_f32_16x16x32_bf16 v[12:15], v[132:135], v[188:191], v[12:15]
	v_mfma_f32_16x16x32_bf16 v[8:11], v[140:143], v[188:191], v[8:11]
	v_mfma_f32_16x16x32_bf16 v[24:27], v[140:143], v[180:183], v[24:27]
	v_mfma_f32_16x16x32_bf16 v[40:43], v[140:143], v[172:175], v[40:43]
	v_mfma_f32_16x16x32_bf16 v[56:59], v[140:143], v[164:167], v[56:59]
	s_setprio 0
	s_setprio 1
	v_mfma_f32_16x16x32_bf16 v[52:55], v[144:147], v[160:163], v[52:55]
	v_mfma_f32_16x16x32_bf16 v[36:39], v[144:147], v[168:171], v[36:39]
	v_mfma_f32_16x16x32_bf16 v[20:23], v[144:147], v[176:179], v[20:23]
	v_mfma_f32_16x16x32_bf16 v[4:7], v[144:147], v[184:187], v[4:7]
	v_mfma_f32_16x16x32_bf16 v[0:3], v[152:155], v[184:187], v[0:3]
	v_mfma_f32_16x16x32_bf16 v[16:19], v[152:155], v[176:179], v[16:19]
	v_mfma_f32_16x16x32_bf16 v[32:35], v[152:155], v[168:171], v[32:35]
	v_mfma_f32_16x16x32_bf16 v[48:51], v[152:155], v[160:163], v[48:51]
	v_mfma_f32_16x16x32_bf16 v[52:55], v[148:151], v[164:167], v[52:55]
	v_mfma_f32_16x16x32_bf16 v[36:39], v[148:151], v[172:175], v[36:39]
	v_mfma_f32_16x16x32_bf16 v[20:23], v[148:151], v[180:183], v[20:23]
	v_mfma_f32_16x16x32_bf16 v[4:7], v[148:151], v[188:191], v[4:7]
	v_mfma_f32_16x16x32_bf16 v[0:3], v[156:159], v[188:191], v[0:3]
	v_mfma_f32_16x16x32_bf16 v[16:19], v[156:159], v[180:183], v[16:19]
	v_mfma_f32_16x16x32_bf16 v[32:35], v[156:159], v[172:175], v[32:35]
	v_mfma_f32_16x16x32_bf16 v[48:51], v[156:159], v[164:167], v[48:51]
	s_setprio 0
	s_barrier
	s_add_u32 s48, s48, 0x100
	s_addc_u32 s49, s49, 0
	s_add_u32 s2, s2, 0x100
	s_addc_u32 s24, s24, 0
	s_cmp_ge_i32 s60, s53
	s_mov_b32 s25, s60
	s_cbranch_scc0 .LBB0_2285

; #define PG8_STAGE(bufoff, gbase, voff) do { _Pragma("unroll") for (int _i = 0; _i < 2; ++_i) \
;         __builtin_amdgcn_global_load_lds((const unsigned*)((const char*)(gbase) + (voff)[_i]), (PG8_LAS unsigned*)(lds + (bufoff) + ldsw + _i * 8192), 16, 0, 0); } while (0)
; #define PG8_LDA(dst, b, h) do { _Pragma("unroll") for (int m = 0; m < 4; ++m) _Pragma("unroll") for (int k = 0; k < 2; ++k) dst[m][k] = *(const PG8_LAS bf16x8*)(lds + PG8_SA(b, h) + aoff + m * 2048 + k * 1024); } while (0)
; #define PG8_LDB(dst, b, h) do { _Pragma("unroll") for (int n = 0; n < 2; ++n) _Pragma("unroll") for (int k = 0; k < 2; ++k) dst[n][k] = *(const PG8_LAS bf16x8*)(lds + PG8_SB(b, h) + boff + n * 2048 + k * 1024); } while (0)
; #define PG8_MMA(ai, bj, At, Bt) do { __builtin_amdgcn_s_setprio(1); _Pragma("unroll") for (int m = 0; m < 4; ++m) _Pragma("unroll") for (int n = 0; n < 2; ++n) _Pragma("unroll") for (int k = 0; k < 2; ++k) \
;         acc[ai][bj][m][n] = __builtin_amdgcn_mfma_f32_16x16x32_bf16(Bt[n][k], At[m][k], acc[ai][bj][m][n], 0, 0, 0); __builtin_amdgcn_s_setprio(0); } while (0)
; #define PG8_WAIT_V(n) asm volatile("s_waitcnt vmcnt(" #n ")" ::: "memory")
; #define PG8_WAIT_L(n) asm volatile("s_waitcnt lgkmcnt(" #n ")" ::: "memory")
; #define PG8_BAR __builtin_amdgcn_s_barrier()
; #define PG8_SCHED __builtin_amdgcn_sched_barrier(0)
; template <class Epi, class Sched, bool ALIGN_EPI = false, bool SP2 = false>
; __device__ __forceinline__ void gemm_phase(PG8_LAS unsigned char* lds, const Gemm g, const Sched& S, const Epi& E) {
;     ...
;             PG8_LDB(B0, 0, 0); PG8_LDB(B1, 0, 1); PG8_SCHED; PG8_LDA(At, 0, 0); PG8_STAGE(PG8_SA(1, 1), a1 + hstep, voffA);
;             PG8_WAIT_V(8); PG8_WAIT_L(0); PG8_BAR; PG8_MMA(0, 0, At, B0); PG8_MMA(0, 1, At, B1); PG8_BAR; PG8_SCHED;
;             PG8_LDA(At, 0, 1); PG8_STAGE(PG8_SB(0, 0), b2, voffB); PG8_STAGE(PG8_SB(0, 1), b2 + hstep, voffB); PG8_STAGE(PG8_SA(0, 0), a2, voffA);
;             PG8_WAIT_V(8); PG8_WAIT_L(0); PG8_BAR; PG8_MMA(1, 0, At, B0); PG8_MMA(1, 1, At, B1); PG8_BAR; PG8_SCHED;
.LBB0_2385:
	s_and_b64 vcc, exec, s[10:11]
	s_cbranch_vccnz .Lcoldz_11
	s_add_u32 s42, s42, 0x80
	s_addc_u32 s43, s43, 0
	s_add_u32 s24, s44, 0x100
	s_addc_u32 s25, s45, 0
	s_mov_b32 s44, 0
	ds_read_b128 v[152:155], v148
	ds_read_b128 v[156:159], v148 offset:1024
	ds_read_b128 v[160:163], v148 offset:2048
	ds_read_b128 v[164:167], v148 offset:3072
	ds_read_b128 v[168:171], v149
	ds_read_b128 v[172:175], v149 offset:1024
	ds_read_b128 v[176:179], v149 offset:2048
	ds_read_b128 v[180:183], v149 offset:3072
	s_add_i32 s58, s44, 2
	s_add_u32 s59, s42, 0x80
	s_addc_u32 s45, s43, 0
	s_cmp_eq_u32 s47, s44
	s_cselect_b32 s44, s14, s59
	s_cselect_b32 s45, s15, s45
	s_cselect_b32 s61, s41, s25
	s_cselect_b32 s60, s40, s24
	s_mov_b32 m0, s51
	v_lshl_add_u64 v[216:217], s[42:43], 0, v[136:137]
	ds_read_b128 v[184:187], v150
	ds_read_b128 v[188:191], v150 offset:1024
	ds_read_b128 v[192:195], v150 offset:2048
	ds_read_b128 v[196:199], v150 offset:3072
	ds_read_b128 v[200:203], v150 offset:4096
	ds_read_b128 v[204:207], v150 offset:5120
	ds_read_b128 v[208:211], v150 offset:6144
	ds_read_b128 v[212:215], v150 offset:7168
	global_load_lds_dwordx4 v[216:217], off
	v_lshl_add_u64 v[216:217], s[42:43], 0, v[138:139]
	s_mov_b32 m0, s52
	s_nop 0
	global_load_lds_dwordx4 v[216:217], off
	s_waitcnt vmcnt(8)
	s_waitcnt lgkmcnt(0)
	s_barrier
	s_setprio 1
	s_waitcnt lgkmcnt(0)
	v_mfma_f32_16x16x32_bf16 v[120:123], v[152:155], v[184:187], 0
	v_mfma_f32_16x16x32_bf16 v[116:119], v[160:163], v[184:187], 0
	v_mfma_f32_16x16x32_bf16 v[108:111], v[152:155], v[192:195], 0
	v_mfma_f32_16x16x32_bf16 v[100:103], v[160:163], v[192:195], 0
	v_mfma_f32_16x16x32_bf16 v[92:95], v[152:155], v[200:203], 0
	v_mfma_f32_16x16x32_bf16 v[84:87], v[160:163], v[200:203], 0
	v_mfma_f32_16x16x32_bf16 v[76:79], v[152:155], v[208:211], 0
	v_mfma_f32_16x16x32_bf16 v[68:71], v[160:163], v[208:211], 0
	v_mfma_f32_16x16x32_bf16 v[120:123], v[156:159], v[188:191], v[120:123]
	v_mfma_f32_16x16x32_bf16 v[108:111], v[156:159], v[196:199], v[108:111]
	v_mfma_f32_16x16x32_bf16 v[92:95], v[156:159], v[204:207], v[92:95]
	v_mfma_f32_16x16x32_bf16 v[76:79], v[156:159], v[212:215], v[76:79]
	v_mfma_f32_16x16x32_bf16 v[68:71], v[164:167], v[212:215], v[68:71]
	v_mfma_f32_16x16x32_bf16 v[84:87], v[164:167], v[204:207], v[84:87]
	v_mfma_f32_16x16x32_bf16 v[100:103], v[164:167], v[196:199], v[100:103]
	v_mfma_f32_16x16x32_bf16 v[116:119], v[164:167], v[188:191], v[116:119]
	s_setprio 0
	s_setprio 1
	v_mfma_f32_16x16x32_bf16 v[124:127], v[168:171], v[184:187], 0
	v_mfma_f32_16x16x32_bf16 v[112:115], v[176:179], v[184:187], 0
	v_mfma_f32_16x16x32_bf16 v[104:107], v[168:171], v[192:195], 0
	v_mfma_f32_16x16x32_bf16 v[96:99], v[176:179], v[192:195], 0
	v_mfma_f32_16x16x32_bf16 v[88:91], v[168:171], v[200:203], 0
	v_mfma_f32_16x16x32_bf16 v[80:83], v[176:179], v[200:203], 0
	v_mfma_f32_16x16x32_bf16 v[72:75], v[168:171], v[208:211], 0
	v_mfma_f32_16x16x32_bf16 v[64:67], v[176:179], v[208:211], 0
	v_mfma_f32_16x16x32_bf16 v[124:127], v[172:175], v[188:191], v[124:127]
	v_mfma_f32_16x16x32_bf16 v[104:107], v[172:175], v[196:199], v[104:107]
	v_mfma_f32_16x16x32_bf16 v[88:91], v[172:175], v[204:207], v[88:91]
	v_mfma_f32_16x16x32_bf16 v[72:75], v[172:175], v[212:215], v[72:75]
	v_mfma_f32_16x16x32_bf16 v[64:67], v[180:183], v[212:215], v[64:67]
	v_mfma_f32_16x16x32_bf16 v[80:83], v[180:183], v[204:207], v[80:83]
	v_mfma_f32_16x16x32_bf16 v[96:99], v[180:183], v[196:199], v[96:99]
	v_mfma_f32_16x16x32_bf16 v[112:115], v[180:183], v[188:191], v[112:115]
	s_setprio 0
	s_barrier
	s_add_i32 s59, s48, s3
	v_lshl_add_u64 v[216:217], s[60:61], 0, v[132:133]
	s_mov_b32 m0, s59
	ds_read_b128 v[184:187], v150 offset:16384
	ds_read_b128 v[188:191], v150 offset:17408
	ds_read_b128 v[192:195], v150 offset:18432
	ds_read_b128 v[196:199], v150 offset:19456
	ds_read_b128 v[200:203], v150 offset:20480
	ds_read_b128 v[204:207], v150 offset:21504
	ds_read_b128 v[208:211], v150 offset:22528
	ds_read_b128 v[212:215], v150 offset:23552
	global_load_lds_dwordx4 v[216:217], off
	s_add_i32 m0, s59, 0x2000
	v_lshl_add_u64 v[218:219], s[60:61], 0, v[128:129]
	s_add_u32 s60, s60, s16
	s_addc_u32 s61, s61, s17
	s_add_i32 s59, s49, s3
	global_load_lds_dwordx4 v[218:219], off
	v_lshl_add_u64 v[220:221], s[60:61], 0, v[132:133]
	s_mov_b32 m0, s59
	v_lshl_add_u64 v[222:223], s[60:61], 0, v[128:129]
	global_load_lds_dwordx4 v[220:221], off
	s_add_i32 m0, s59, 0x2000
	v_lshl_add_u64 v[224:225], s[44:45], 0, v[134:135]
	global_load_lds_dwordx4 v[222:223], off
	s_mov_b32 m0, s7
	v_lshl_add_u64 v[226:227], s[44:45], 0, v[130:131]
	global_load_lds_dwordx4 v[224:225], off
	s_mov_b32 m0, s18
	s_nop 0
	global_load_lds_dwordx4 v[226:227], off
	s_waitcnt vmcnt(8)
	s_waitcnt lgkmcnt(0)
	s_barrier
; #define PG8_STAGE(bufoff, gbase, voff) do { _Pragma("unroll") for (int _i = 0; _i < 2; ++_i) \
;         __builtin_amdgcn_global_load_lds((const unsigned*)((const char*)(gbase) + (voff)[_i]), (PG8_LAS unsigned*)(lds + (bufoff) + ldsw + _i * 8192), 16, 0, 0); } while (0)
; #define PG8_LDA(dst, b, h) do { _Pragma("unroll") for (int m = 0; m < 4; ++m) _Pragma("unroll") for (int k = 0; k < 2; ++k) dst[m][k] = *(const PG8_LAS bf16x8*)(lds + PG8_SA(b, h) + aoff + m * 2048 + k * 1024); } while (0)
; #define PG8_LDB(dst, b, h) do { _Pragma("unroll") for (int n = 0; n < 2; ++n) _Pragma("unroll") for (int k = 0; k < 2; ++k) dst[n][k] = *(const PG8_LAS bf16x8*)(lds + PG8_SB(b, h) + boff + n * 2048 + k * 1024); } while (0)
; #define PG8_MMA(ai, bj, At, Bt) do { __builtin_amdgcn_s_setprio(1); _Pragma("unroll") for (int m = 0; m < 4; ++m) _Pragma("unroll") for (int n = 0; n < 2; ++n) _Pragma("unroll") for (int k = 0; k < 2; ++k) \
;         acc[ai][bj][m][n] = __builtin_amdgcn_mfma_f32_16x16x32_bf16(Bt[n][k], At[m][k], acc[ai][bj][m][n], 0, 0, 0); __builtin_amdgcn_s_setprio(0); } while (0)
; #define PG8_WAIT_V(n) asm volatile("s_waitcnt vmcnt(" #n ")" ::: "memory")
; #define PG8_WAIT_L(n) asm volatile("s_waitcnt lgkmcnt(" #n ")" ::: "memory")
; #define PG8_BAR __builtin_amdgcn_s_barrier()
; #define PG8_SCHED __builtin_amdgcn_sched_barrier(0)
; template <class Epi, class Sched, bool ALIGN_EPI = false, bool SP2 = false>
; __device__ __forceinline__ void gemm_phase(PG8_LAS unsigned char* lds, const Gemm g, const Sched& S, const Epi& E) {
;     ...
;             PG8_WAIT_V(8); PG8_WAIT_L(0); PG8_BAR; PG8_MMA(1, 0, At, B0); PG8_MMA(1, 1, At, B1); PG8_BAR; PG8_SCHED;
;             PG8_LDB(B0, 1, 0); PG8_LDB(B1, 1, 1); PG8_SCHED; PG8_LDA(At, 1, 0); PG8_STAGE(PG8_SA(0, 1), a2 + hstep, voffA);
;             PG8_WAIT_V(8); PG8_WAIT_L(0); PG8_BAR; PG8_MMA(0, 0, At, B0); PG8_MMA(0, 1, At, B1); PG8_BAR; PG8_SCHED;
	s_setprio 1
	s_waitcnt lgkmcnt(0)
	v_mfma_f32_16x16x32_bf16 v[60:63], v[152:155], v[184:187], 0
	v_mfma_f32_16x16x32_bf16 v[52:55], v[160:163], v[184:187], 0
	v_mfma_f32_16x16x32_bf16 v[44:47], v[152:155], v[192:195], 0
	v_mfma_f32_16x16x32_bf16 v[36:39], v[160:163], v[192:195], 0
	v_mfma_f32_16x16x32_bf16 v[28:31], v[152:155], v[200:203], 0
	v_mfma_f32_16x16x32_bf16 v[20:23], v[160:163], v[200:203], 0
	v_mfma_f32_16x16x32_bf16 v[12:15], v[152:155], v[208:211], 0
	v_mfma_f32_16x16x32_bf16 v[4:7], v[160:163], v[208:211], 0
	v_mfma_f32_16x16x32_bf16 v[60:63], v[156:159], v[188:191], v[60:63]
	v_mfma_f32_16x16x32_bf16 v[44:47], v[156:159], v[196:199], v[44:47]
	v_mfma_f32_16x16x32_bf16 v[28:31], v[156:159], v[204:207], v[28:31]
	v_mfma_f32_16x16x32_bf16 v[12:15], v[156:159], v[212:215], v[12:15]
	v_mfma_f32_16x16x32_bf16 v[4:7], v[164:167], v[212:215], v[4:7]
	v_mfma_f32_16x16x32_bf16 v[20:23], v[164:167], v[204:207], v[20:23]
	v_mfma_f32_16x16x32_bf16 v[36:39], v[164:167], v[196:199], v[36:39]
	v_mfma_f32_16x16x32_bf16 v[52:55], v[164:167], v[188:191], v[52:55]
	s_setprio 0
	s_setprio 1
	v_mfma_f32_16x16x32_bf16 v[56:59], v[168:171], v[184:187], 0
	v_mfma_f32_16x16x32_bf16 v[48:51], v[176:179], v[184:187], 0
	v_mfma_f32_16x16x32_bf16 v[40:43], v[168:171], v[192:195], 0
	v_mfma_f32_16x16x32_bf16 v[32:35], v[176:179], v[192:195], 0
	v_mfma_f32_16x16x32_bf16 v[24:27], v[168:171], v[200:203], 0
	v_mfma_f32_16x16x32_bf16 v[16:19], v[176:179], v[200:203], 0
	v_mfma_f32_16x16x32_bf16 v[8:11], v[168:171], v[208:211], 0
	v_mfma_f32_16x16x32_bf16 v[0:3], v[176:179], v[208:211], 0
	v_mfma_f32_16x16x32_bf16 v[56:59], v[172:175], v[188:191], v[56:59]
	v_mfma_f32_16x16x32_bf16 v[40:43], v[172:175], v[196:199], v[40:43]
	v_mfma_f32_16x16x32_bf16 v[24:27], v[172:175], v[204:207], v[24:27]
	v_mfma_f32_16x16x32_bf16 v[8:11], v[172:175], v[212:215], v[8:11]
	v_mfma_f32_16x16x32_bf16 v[0:3], v[180:183], v[212:215], v[0:3]
	v_mfma_f32_16x16x32_bf16 v[16:19], v[180:183], v[204:207], v[16:19]
	v_mfma_f32_16x16x32_bf16 v[32:35], v[180:183], v[196:199], v[32:35]
	v_mfma_f32_16x16x32_bf16 v[48:51], v[180:183], v[188:191], v[48:51]
	s_setprio 0
	s_barrier
	s_add_i32 s59, 0, 0x18000
	v_add_u32_e32 v151, s59, v145
	s_add_i32 s60, 0, 0x1c000
	ds_read_b128 v[152:155], v151
	ds_read_b128 v[156:159], v151 offset:1024
	ds_read_b128 v[160:163], v151 offset:2048
	ds_read_b128 v[164:167], v151 offset:3072
	v_add_u32_e32 v151, s60, v145
	ds_read_b128 v[168:171], v151
	ds_read_b128 v[172:175], v151 offset:1024
	ds_read_b128 v[176:179], v151 offset:2048
	ds_read_b128 v[180:183], v151 offset:3072
	s_add_u32 s44, s44, s16
	s_addc_u32 s45, s45, s17
	s_mov_b32 m0, s19
	v_lshl_add_u64 v[228:229], s[44:45], 0, v[134:135]
	ds_read_b128 v[184:187], v150 offset:32768
	ds_read_b128 v[188:191], v150 offset:33792
	ds_read_b128 v[192:195], v150 offset:34816
	ds_read_b128 v[196:199], v150 offset:35840
	ds_read_b128 v[200:203], v150 offset:36864
	ds_read_b128 v[204:207], v150 offset:37888
	ds_read_b128 v[208:211], v150 offset:38912
	ds_read_b128 v[212:215], v150 offset:39936
	global_load_lds_dwordx4 v[228:229], off
	v_lshl_add_u64 v[228:229], s[44:45], 0, v[130:131]
	s_mov_b32 m0, s26
	s_nop 0
	global_load_lds_dwordx4 v[228:229], off
	s_waitcnt vmcnt(8)
	s_waitcnt lgkmcnt(0)
	s_barrier
	s_setprio 1
	s_waitcnt lgkmcnt(0)
	v_mfma_f32_16x16x32_bf16 v[120:123], v[152:155], v[184:187], v[120:123]
	v_mfma_f32_16x16x32_bf16 v[108:111], v[152:155], v[192:195], v[108:111]
	v_mfma_f32_16x16x32_bf16 v[92:95], v[152:155], v[200:203], v[92:95]
	v_mfma_f32_16x16x32_bf16 v[76:79], v[152:155], v[208:211], v[76:79]
	v_mfma_f32_16x16x32_bf16 v[68:71], v[160:163], v[208:211], v[68:71]
	v_mfma_f32_16x16x32_bf16 v[84:87], v[160:163], v[200:203], v[84:87]
	v_mfma_f32_16x16x32_bf16 v[100:103], v[160:163], v[192:195], v[100:103]
	v_mfma_f32_16x16x32_bf16 v[116:119], v[160:163], v[184:187], v[116:119]
	v_mfma_f32_16x16x32_bf16 v[120:123], v[156:159], v[188:191], v[120:123]
	v_mfma_f32_16x16x32_bf16 v[108:111], v[156:159], v[196:199], v[108:111]
	v_mfma_f32_16x16x32_bf16 v[92:95], v[156:159], v[204:207], v[92:95]
	v_mfma_f32_16x16x32_bf16 v[76:79], v[156:159], v[212:215], v[76:79]
	v_mfma_f32_16x16x32_bf16 v[68:71], v[164:167], v[212:215], v[68:71]
	v_mfma_f32_16x16x32_bf16 v[84:87], v[164:167], v[204:207], v[84:87]
	v_mfma_f32_16x16x32_bf16 v[100:103], v[164:167], v[196:199], v[100:103]
	v_mfma_f32_16x16x32_bf16 v[116:119], v[164:167], v[188:191], v[116:119]
	s_setprio 0
	s_setprio 1
	v_mfma_f32_16x16x32_bf16 v[124:127], v[168:171], v[184:187], v[124:127]
	v_mfma_f32_16x16x32_bf16 v[104:107], v[168:171], v[192:195], v[104:107]
	v_mfma_f32_16x16x32_bf16 v[88:91], v[168:171], v[200:203], v[88:91]
	v_mfma_f32_16x16x32_bf16 v[72:75], v[168:171], v[208:211], v[72:75]
	v_mfma_f32_16x16x32_bf16 v[64:67], v[176:179], v[208:211], v[64:67]
	v_mfma_f32_16x16x32_bf16 v[80:83], v[176:179], v[200:203], v[80:83]
	v_mfma_f32_16x16x32_bf16 v[96:99], v[176:179], v[192:195], v[96:99]
	v_mfma_f32_16x16x32_bf16 v[112:115], v[176:179], v[184:187], v[112:115]
	v_mfma_f32_16x16x32_bf16 v[124:127], v[172:175], v[188:191], v[124:127]
	v_mfma_f32_16x16x32_bf16 v[104:107], v[172:175], v[196:199], v[104:107]
	v_mfma_f32_16x16x32_bf16 v[88:91], v[172:175], v[204:207], v[88:91]
	v_mfma_f32_16x16x32_bf16 v[72:75], v[172:175], v[212:215], v[72:75]
	v_mfma_f32_16x16x32_bf16 v[64:67], v[180:183], v[212:215], v[64:67]
	v_mfma_f32_16x16x32_bf16 v[80:83], v[180:183], v[204:207], v[80:83]
	v_mfma_f32_16x16x32_bf16 v[96:99], v[180:183], v[196:199], v[96:99]
	v_mfma_f32_16x16x32_bf16 v[112:115], v[180:183], v[188:191], v[112:115]
	s_setprio 0
	s_barrier
; #define PG8_STAGE(bufoff, gbase, voff) do { _Pragma("unroll") for (int _i = 0; _i < 2; ++_i) \
;         __builtin_amdgcn_global_load_lds((const unsigned*)((const char*)(gbase) + (voff)[_i]), (PG8_LAS unsigned*)(lds + (bufoff) + ldsw + _i * 8192), 16, 0, 0); } while (0)
; #define PG8_LDA(dst, b, h) do { _Pragma("unroll") for (int m = 0; m < 4; ++m) _Pragma("unroll") for (int k = 0; k < 2; ++k) dst[m][k] = *(const PG8_LAS bf16x8*)(lds + PG8_SA(b, h) + aoff + m * 2048 + k * 1024); } while (0)
; #define PG8_LDB(dst, b, h) do { _Pragma("unroll") for (int n = 0; n < 2; ++n) _Pragma("unroll") for (int k = 0; k < 2; ++k) dst[n][k] = *(const PG8_LAS bf16x8*)(lds + PG8_SB(b, h) + boff + n * 2048 + k * 1024); } while (0)
; #define PG8_MMA(ai, bj, At, Bt) do { __builtin_amdgcn_s_setprio(1); _Pragma("unroll") for (int m = 0; m < 4; ++m) _Pragma("unroll") for (int n = 0; n < 2; ++n) _Pragma("unroll") for (int k = 0; k < 2; ++k) \
;         acc[ai][bj][m][n] = __builtin_amdgcn_mfma_f32_16x16x32_bf16(Bt[n][k], At[m][k], acc[ai][bj][m][n], 0, 0, 0); __builtin_amdgcn_s_setprio(0); } while (0)
; #define PG8_WAIT_V(n) asm volatile("s_waitcnt vmcnt(" #n ")" ::: "memory")
; #define PG8_WAIT_L(n) asm volatile("s_waitcnt lgkmcnt(" #n ")" ::: "memory")
; #define PG8_BAR __builtin_amdgcn_s_barrier()
; #define PG8_SCHED __builtin_amdgcn_sched_barrier(0)
; template <class Epi, class Sched, bool ALIGN_EPI = false, bool SP2 = false>
; __device__ __forceinline__ void gemm_phase(PG8_LAS unsigned char* lds, const Gemm g, const Sched& S, const Epi& E) {
;     ...
;         for (int t = 0; t < nt; t += 2) {
;             const bool last = (t == nt - 2);
;             const char* a1 = cA + (size_t)(t + 1) * kstep;
;             const char* a2 = last ? nA : cA + (size_t)(t + 2) * kstep; const char* b2 = last ? nB : cB + (size_t)(t + 2) * kstep;
;     ...
;             PG8_LDB(B0, 0, 0); PG8_LDB(B1, 0, 1); PG8_SCHED; PG8_LDA(At, 0, 0); PG8_STAGE(PG8_SA(1, 1), a1 + hstep, voffA);
;             PG8_WAIT_V(8); PG8_WAIT_L(0); PG8_BAR; PG8_MMA(0, 0, At, B0); PG8_MMA(0, 1, At, B1); PG8_BAR; PG8_SCHED;
;     ...
;             PG8_LDA(At, 1, 1); PG8_STAGE(PG8_SB(1, 0), b3, voffB); PG8_STAGE(PG8_SB(1, 1), b3 + hstep, voffB); PG8_STAGE(PG8_SA(1, 0), a3, voffA);
;             PG8_WAIT_V(8); PG8_WAIT_L(0); PG8_BAR; PG8_MMA(1, 0, At, B0); PG8_MMA(1, 1, At, B1); PG8_BAR; PG8_SCHED;
	s_add_i32 s44, s59, s3
	v_lshl_add_u64 v[216:217], v[216:217], 0, s[36:37]
	s_mov_b32 m0, s44
	ds_read_b128 v[184:187], v150 offset:49152
	ds_read_b128 v[188:191], v150 offset:50176
	ds_read_b128 v[192:195], v150 offset:51200
	ds_read_b128 v[196:199], v150 offset:52224
	ds_read_b128 v[200:203], v150 offset:53248
	ds_read_b128 v[204:207], v150 offset:54272
	ds_read_b128 v[208:211], v150 offset:55296
	ds_read_b128 v[212:215], v150 offset:56320
	global_load_lds_dwordx4 v[216:217], off
	v_lshl_add_u64 v[216:217], v[218:219], 0, s[36:37]
	s_add_i32 m0, s44, 0x2000
	s_add_i32 s44, s60, s3
	global_load_lds_dwordx4 v[216:217], off
	v_lshl_add_u64 v[216:217], v[220:221], 0, s[36:37]
	s_mov_b32 m0, s44
	s_nop 0
	global_load_lds_dwordx4 v[216:217], off
	v_lshl_add_u64 v[216:217], v[222:223], 0, s[36:37]
	s_add_i32 m0, s44, 0x2000
	s_nop 0
	global_load_lds_dwordx4 v[216:217], off
	v_lshl_add_u64 v[216:217], v[224:225], 0, s[36:37]
	s_mov_b32 m0, s27
	s_nop 0
	global_load_lds_dwordx4 v[216:217], off
	v_lshl_add_u64 v[216:217], v[226:227], 0, s[36:37]
	s_mov_b32 m0, s33
	s_nop 0
	global_load_lds_dwordx4 v[216:217], off
	s_waitcnt vmcnt(8)
	s_waitcnt lgkmcnt(0)
	s_barrier
	s_setprio 1
	s_waitcnt lgkmcnt(0)
	v_mfma_f32_16x16x32_bf16 v[60:63], v[152:155], v[184:187], v[60:63]
	v_mfma_f32_16x16x32_bf16 v[44:47], v[152:155], v[192:195], v[44:47]
	v_mfma_f32_16x16x32_bf16 v[28:31], v[152:155], v[200:203], v[28:31]
	v_mfma_f32_16x16x32_bf16 v[12:15], v[152:155], v[208:211], v[12:15]
	v_mfma_f32_16x16x32_bf16 v[4:7], v[160:163], v[208:211], v[4:7]
	v_mfma_f32_16x16x32_bf16 v[20:23], v[160:163], v[200:203], v[20:23]
	v_mfma_f32_16x16x32_bf16 v[36:39], v[160:163], v[192:195], v[36:39]
	v_mfma_f32_16x16x32_bf16 v[52:55], v[160:163], v[184:187], v[52:55]
	v_mfma_f32_16x16x32_bf16 v[60:63], v[156:159], v[188:191], v[60:63]
	v_mfma_f32_16x16x32_bf16 v[44:47], v[156:159], v[196:199], v[44:47]
	v_mfma_f32_16x16x32_bf16 v[28:31], v[156:159], v[204:207], v[28:31]
	v_mfma_f32_16x16x32_bf16 v[12:15], v[156:159], v[212:215], v[12:15]
	v_mfma_f32_16x16x32_bf16 v[4:7], v[164:167], v[212:215], v[4:7]
	v_mfma_f32_16x16x32_bf16 v[20:23], v[164:167], v[204:207], v[20:23]
	v_mfma_f32_16x16x32_bf16 v[36:39], v[164:167], v[196:199], v[36:39]
	v_mfma_f32_16x16x32_bf16 v[52:55], v[164:167], v[188:191], v[52:55]
	s_setprio 0
	s_setprio 1
	v_mfma_f32_16x16x32_bf16 v[56:59], v[168:171], v[184:187], v[56:59]
	v_mfma_f32_16x16x32_bf16 v[40:43], v[168:171], v[192:195], v[40:43]
	v_mfma_f32_16x16x32_bf16 v[24:27], v[168:171], v[200:203], v[24:27]
	v_mfma_f32_16x16x32_bf16 v[8:11], v[168:171], v[208:211], v[8:11]
	v_mfma_f32_16x16x32_bf16 v[0:3], v[176:179], v[208:211], v[0:3]
	v_mfma_f32_16x16x32_bf16 v[16:19], v[176:179], v[200:203], v[16:19]
	v_mfma_f32_16x16x32_bf16 v[32:35], v[176:179], v[192:195], v[32:35]
	v_mfma_f32_16x16x32_bf16 v[48:51], v[176:179], v[184:187], v[48:51]
	v_mfma_f32_16x16x32_bf16 v[56:59], v[172:175], v[188:191], v[56:59]
	v_mfma_f32_16x16x32_bf16 v[40:43], v[172:175], v[196:199], v[40:43]
	v_mfma_f32_16x16x32_bf16 v[24:27], v[172:175], v[204:207], v[24:27]
	v_mfma_f32_16x16x32_bf16 v[8:11], v[172:175], v[212:215], v[8:11]
	v_mfma_f32_16x16x32_bf16 v[0:3], v[180:183], v[212:215], v[0:3]
	v_mfma_f32_16x16x32_bf16 v[16:19], v[180:183], v[204:207], v[16:19]
	v_mfma_f32_16x16x32_bf16 v[32:35], v[180:183], v[196:199], v[32:35]
	v_mfma_f32_16x16x32_bf16 v[48:51], v[180:183], v[188:191], v[48:51]
	s_setprio 0
	s_barrier
	s_add_u32 s42, s42, 0x100
	s_addc_u32 s43, s43, 0
	s_add_u32 s24, s24, 0x100
	s_addc_u32 s25, s25, 0
	s_cmp_ge_i32 s58, s46
	s_mov_b32 s44, s58
	s_cbranch_scc1 .Lpeelx_11
.LBB0_2387:
	ds_read_b128 v[152:155], v148
	ds_read_b128 v[156:159], v148 offset:1024
	ds_read_b128 v[160:163], v148 offset:2048
	ds_read_b128 v[164:167], v148 offset:3072
	ds_read_b128 v[168:171], v149
	ds_read_b128 v[172:175], v149 offset:1024
	ds_read_b128 v[176:179], v149 offset:2048
	ds_read_b128 v[180:183], v149 offset:3072
	s_add_i32 s58, s44, 2
	s_add_u32 s59, s42, 0x80
	s_addc_u32 s45, s43, 0
	s_cmp_eq_u32 s47, s44
	s_cselect_b32 s44, s14, s59
	s_cselect_b32 s45, s15, s45
	s_cselect_b32 s61, s41, s25
	s_cselect_b32 s60, s40, s24
	s_mov_b32 m0, s51
	v_lshl_add_u64 v[216:217], s[42:43], 0, v[136:137]
	ds_read_b128 v[184:187], v150
	ds_read_b128 v[188:191], v150 offset:1024
	ds_read_b128 v[192:195], v150 offset:2048
	ds_read_b128 v[196:199], v150 offset:3072
	ds_read_b128 v[200:203], v150 offset:4096
	ds_read_b128 v[204:207], v150 offset:5120
	ds_read_b128 v[208:211], v150 offset:6144
	ds_read_b128 v[212:215], v150 offset:7168
	global_load_lds_dwordx4 v[216:217], off
	v_lshl_add_u64 v[216:217], s[42:43], 0, v[138:139]
	s_mov_b32 m0, s52
	s_nop 0
	global_load_lds_dwordx4 v[216:217], off
	s_waitcnt vmcnt(8)
	s_waitcnt lgkmcnt(0)
	s_barrier
; #define PG8_STAGE(bufoff, gbase, voff) do { _Pragma("unroll") for (int _i = 0; _i < 2; ++_i) \
;         __builtin_amdgcn_global_load_lds((const unsigned*)((const char*)(gbase) + (voff)[_i]), (PG8_LAS unsigned*)(lds + (bufoff) + ldsw + _i * 8192), 16, 0, 0); } while (0)
; #define PG8_LDA(dst, b, h) do { _Pragma("unroll") for (int m = 0; m < 4; ++m) _Pragma("unroll") for (int k = 0; k < 2; ++k) dst[m][k] = *(const PG8_LAS bf16x8*)(lds + PG8_SA(b, h) + aoff + m * 2048 + k * 1024); } while (0)
; #define PG8_LDB(dst, b, h) do { _Pragma("unroll") for (int n = 0; n < 2; ++n) _Pragma("unroll") for (int k = 0; k < 2; ++k) dst[n][k] = *(const PG8_LAS bf16x8*)(lds + PG8_SB(b, h) + boff + n * 2048 + k * 1024); } while (0)
; #define PG8_MMA(ai, bj, At, Bt) do { __builtin_amdgcn_s_setprio(1); _Pragma("unroll") for (int m = 0; m < 4; ++m) _Pragma("unroll") for (int n = 0; n < 2; ++n) _Pragma("unroll") for (int k = 0; k < 2; ++k) \
;         acc[ai][bj][m][n] = __builtin_amdgcn_mfma_f32_16x16x32_bf16(Bt[n][k], At[m][k], acc[ai][bj][m][n], 0, 0, 0); __builtin_amdgcn_s_setprio(0); } while (0)
; #define PG8_WAIT_V(n) asm volatile("s_waitcnt vmcnt(" #n ")" ::: "memory")
; #define PG8_WAIT_L(n) asm volatile("s_waitcnt lgkmcnt(" #n ")" ::: "memory")
; #define PG8_BAR __builtin_amdgcn_s_barrier()
; #define PG8_SCHED __builtin_amdgcn_sched_barrier(0)
; template <class Epi, class Sched, bool ALIGN_EPI = false, bool SP2 = false>
; __device__ __forceinline__ void gemm_phase(PG8_LAS unsigned char* lds, const Gemm g, const Sched& S, const Epi& E) {
;     ...
;             PG8_LDB(B0, 0, 0); PG8_LDB(B1, 0, 1); PG8_SCHED; PG8_LDA(At, 0, 0); PG8_STAGE(PG8_SA(1, 1), a1 + hstep, voffA);
;             PG8_WAIT_V(8); PG8_WAIT_L(0); PG8_BAR; PG8_MMA(0, 0, At, B0); PG8_MMA(0, 1, At, B1); PG8_BAR; PG8_SCHED;
;             PG8_LDA(At, 0, 1); PG8_STAGE(PG8_SB(0, 0), b2, voffB); PG8_STAGE(PG8_SB(0, 1), b2 + hstep, voffB); PG8_STAGE(PG8_SA(0, 0), a2, voffA);
;             PG8_WAIT_V(8); PG8_WAIT_L(0); PG8_BAR; PG8_MMA(1, 0, At, B0); PG8_MMA(1, 1, At, B1); PG8_BAR; PG8_SCHED;
	s_setprio 1
	s_waitcnt lgkmcnt(0)
	v_mfma_f32_16x16x32_bf16 v[120:123], v[152:155], v[184:187], v[120:123]
	v_mfma_f32_16x16x32_bf16 v[108:111], v[152:155], v[192:195], v[108:111]
	v_mfma_f32_16x16x32_bf16 v[92:95], v[152:155], v[200:203], v[92:95]
	v_mfma_f32_16x16x32_bf16 v[76:79], v[152:155], v[208:211], v[76:79]
	v_mfma_f32_16x16x32_bf16 v[68:71], v[160:163], v[208:211], v[68:71]
	v_mfma_f32_16x16x32_bf16 v[84:87], v[160:163], v[200:203], v[84:87]
	v_mfma_f32_16x16x32_bf16 v[100:103], v[160:163], v[192:195], v[100:103]
	v_mfma_f32_16x16x32_bf16 v[116:119], v[160:163], v[184:187], v[116:119]
	v_mfma_f32_16x16x32_bf16 v[120:123], v[156:159], v[188:191], v[120:123]
	v_mfma_f32_16x16x32_bf16 v[108:111], v[156:159], v[196:199], v[108:111]
	v_mfma_f32_16x16x32_bf16 v[92:95], v[156:159], v[204:207], v[92:95]
	v_mfma_f32_16x16x32_bf16 v[76:79], v[156:159], v[212:215], v[76:79]
	v_mfma_f32_16x16x32_bf16 v[68:71], v[164:167], v[212:215], v[68:71]
	v_mfma_f32_16x16x32_bf16 v[84:87], v[164:167], v[204:207], v[84:87]
	v_mfma_f32_16x16x32_bf16 v[100:103], v[164:167], v[196:199], v[100:103]
	v_mfma_f32_16x16x32_bf16 v[116:119], v[164:167], v[188:191], v[116:119]
	s_setprio 0
	s_setprio 1
	v_mfma_f32_16x16x32_bf16 v[124:127], v[168:171], v[184:187], v[124:127]
	v_mfma_f32_16x16x32_bf16 v[104:107], v[168:171], v[192:195], v[104:107]
	v_mfma_f32_16x16x32_bf16 v[88:91], v[168:171], v[200:203], v[88:91]
	v_mfma_f32_16x16x32_bf16 v[72:75], v[168:171], v[208:211], v[72:75]
	v_mfma_f32_16x16x32_bf16 v[64:67], v[176:179], v[208:211], v[64:67]
	v_mfma_f32_16x16x32_bf16 v[80:83], v[176:179], v[200:203], v[80:83]
	v_mfma_f32_16x16x32_bf16 v[96:99], v[176:179], v[192:195], v[96:99]
	v_mfma_f32_16x16x32_bf16 v[112:115], v[176:179], v[184:187], v[112:115]
	v_mfma_f32_16x16x32_bf16 v[124:127], v[172:175], v[188:191], v[124:127]
	v_mfma_f32_16x16x32_bf16 v[104:107], v[172:175], v[196:199], v[104:107]
	v_mfma_f32_16x16x32_bf16 v[88:91], v[172:175], v[204:207], v[88:91]
	v_mfma_f32_16x16x32_bf16 v[72:75], v[172:175], v[212:215], v[72:75]
	v_mfma_f32_16x16x32_bf16 v[64:67], v[180:183], v[212:215], v[64:67]
	v_mfma_f32_16x16x32_bf16 v[80:83], v[180:183], v[204:207], v[80:83]
	v_mfma_f32_16x16x32_bf16 v[96:99], v[180:183], v[196:199], v[96:99]
	v_mfma_f32_16x16x32_bf16 v[112:115], v[180:183], v[188:191], v[112:115]
	s_setprio 0
	s_barrier
	s_add_i32 s59, s48, s3
	v_lshl_add_u64 v[216:217], s[60:61], 0, v[132:133]
	s_mov_b32 m0, s59
	ds_read_b128 v[184:187], v150 offset:16384
	ds_read_b128 v[188:191], v150 offset:17408
	ds_read_b128 v[192:195], v150 offset:18432
	ds_read_b128 v[196:199], v150 offset:19456
	ds_read_b128 v[200:203], v150 offset:20480
	ds_read_b128 v[204:207], v150 offset:21504
	ds_read_b128 v[208:211], v150 offset:22528
	ds_read_b128 v[212:215], v150 offset:23552
	global_load_lds_dwordx4 v[216:217], off
	s_add_i32 m0, s59, 0x2000
	v_lshl_add_u64 v[218:219], s[60:61], 0, v[128:129]
	s_add_u32 s60, s60, s16
	s_addc_u32 s61, s61, s17
	s_add_i32 s59, s49, s3
	global_load_lds_dwordx4 v[218:219], off
	v_lshl_add_u64 v[220:221], s[60:61], 0, v[132:133]
	s_mov_b32 m0, s59
	v_lshl_add_u64 v[222:223], s[60:61], 0, v[128:129]
	global_load_lds_dwordx4 v[220:221], off
	s_add_i32 m0, s59, 0x2000
	v_lshl_add_u64 v[224:225], s[44:45], 0, v[134:135]
	global_load_lds_dwordx4 v[222:223], off
	s_mov_b32 m0, s7
	v_lshl_add_u64 v[226:227], s[44:45], 0, v[130:131]
	global_load_lds_dwordx4 v[224:225], off
	s_mov_b32 m0, s18
	s_nop 0
	global_load_lds_dwordx4 v[226:227], off
	s_waitcnt vmcnt(8)
	s_waitcnt lgkmcnt(0)
	s_barrier
	s_setprio 1
	s_waitcnt lgkmcnt(0)
	v_mfma_f32_16x16x32_bf16 v[60:63], v[152:155], v[184:187], v[60:63]
	v_mfma_f32_16x16x32_bf16 v[44:47], v[152:155], v[192:195], v[44:47]
	v_mfma_f32_16x16x32_bf16 v[28:31], v[152:155], v[200:203], v[28:31]
	v_mfma_f32_16x16x32_bf16 v[12:15], v[152:155], v[208:211], v[12:15]
	v_mfma_f32_16x16x32_bf16 v[4:7], v[160:163], v[208:211], v[4:7]
	v_mfma_f32_16x16x32_bf16 v[20:23], v[160:163], v[200:203], v[20:23]
	v_mfma_f32_16x16x32_bf16 v[36:39], v[160:163], v[192:195], v[36:39]
	v_mfma_f32_16x16x32_bf16 v[52:55], v[160:163], v[184:187], v[52:55]
	v_mfma_f32_16x16x32_bf16 v[60:63], v[156:159], v[188:191], v[60:63]
	v_mfma_f32_16x16x32_bf16 v[44:47], v[156:159], v[196:199], v[44:47]
	v_mfma_f32_16x16x32_bf16 v[28:31], v[156:159], v[204:207], v[28:31]
	v_mfma_f32_16x16x32_bf16 v[12:15], v[156:159], v[212:215], v[12:15]
	v_mfma_f32_16x16x32_bf16 v[4:7], v[164:167], v[212:215], v[4:7]
	v_mfma_f32_16x16x32_bf16 v[20:23], v[164:167], v[204:207], v[20:23]
	v_mfma_f32_16x16x32_bf16 v[36:39], v[164:167], v[196:199], v[36:39]
	v_mfma_f32_16x16x32_bf16 v[52:55], v[164:167], v[188:191], v[52:55]
	s_setprio 0
	s_setprio 1
	v_mfma_f32_16x16x32_bf16 v[56:59], v[168:171], v[184:187], v[56:59]
	v_mfma_f32_16x16x32_bf16 v[40:43], v[168:171], v[192:195], v[40:43]
	v_mfma_f32_16x16x32_bf16 v[24:27], v[168:171], v[200:203], v[24:27]
	v_mfma_f32_16x16x32_bf16 v[8:11], v[168:171], v[208:211], v[8:11]
	v_mfma_f32_16x16x32_bf16 v[0:3], v[176:179], v[208:211], v[0:3]
	v_mfma_f32_16x16x32_bf16 v[16:19], v[176:179], v[200:203], v[16:19]
	v_mfma_f32_16x16x32_bf16 v[32:35], v[176:179], v[192:195], v[32:35]
	v_mfma_f32_16x16x32_bf16 v[48:51], v[176:179], v[184:187], v[48:51]
	v_mfma_f32_16x16x32_bf16 v[56:59], v[172:175], v[188:191], v[56:59]
	v_mfma_f32_16x16x32_bf16 v[40:43], v[172:175], v[196:199], v[40:43]
	v_mfma_f32_16x16x32_bf16 v[24:27], v[172:175], v[204:207], v[24:27]
	v_mfma_f32_16x16x32_bf16 v[8:11], v[172:175], v[212:215], v[8:11]
	v_mfma_f32_16x16x32_bf16 v[0:3], v[180:183], v[212:215], v[0:3]
	v_mfma_f32_16x16x32_bf16 v[16:19], v[180:183], v[204:207], v[16:19]
	v_mfma_f32_16x16x32_bf16 v[32:35], v[180:183], v[196:199], v[32:35]
	v_mfma_f32_16x16x32_bf16 v[48:51], v[180:183], v[188:191], v[48:51]
	s_setprio 0
	s_barrier
; #define PG8_STAGE(bufoff, gbase, voff) do { _Pragma("unroll") for (int _i = 0; _i < 2; ++_i) \
;         __builtin_amdgcn_global_load_lds((const unsigned*)((const char*)(gbase) + (voff)[_i]), (PG8_LAS unsigned*)(lds + (bufoff) + ldsw + _i * 8192), 16, 0, 0); } while (0)
; #define PG8_LDA(dst, b, h) do { _Pragma("unroll") for (int m = 0; m < 4; ++m) _Pragma("unroll") for (int k = 0; k < 2; ++k) dst[m][k] = *(const PG8_LAS bf16x8*)(lds + PG8_SA(b, h) + aoff + m * 2048 + k * 1024); } while (0)
; #define PG8_LDB(dst, b, h) do { _Pragma("unroll") for (int n = 0; n < 2; ++n) _Pragma("unroll") for (int k = 0; k < 2; ++k) dst[n][k] = *(const PG8_LAS bf16x8*)(lds + PG8_SB(b, h) + boff + n * 2048 + k * 1024); } while (0)
; #define PG8_MMA(ai, bj, At, Bt) do { __builtin_amdgcn_s_setprio(1); _Pragma("unroll") for (int m = 0; m < 4; ++m) _Pragma("unroll") for (int n = 0; n < 2; ++n) _Pragma("unroll") for (int k = 0; k < 2; ++k) \
;         acc[ai][bj][m][n] = __builtin_amdgcn_mfma_f32_16x16x32_bf16(Bt[n][k], At[m][k], acc[ai][bj][m][n], 0, 0, 0); __builtin_amdgcn_s_setprio(0); } while (0)
; #define PG8_WAIT_V(n) asm volatile("s_waitcnt vmcnt(" #n ")" ::: "memory")
; #define PG8_WAIT_L(n) asm volatile("s_waitcnt lgkmcnt(" #n ")" ::: "memory")
; #define PG8_BAR __builtin_amdgcn_s_barrier()
; #define PG8_SCHED __builtin_amdgcn_sched_barrier(0)
; template <class Epi, class Sched, bool ALIGN_EPI = false, bool SP2 = false>
; __device__ __forceinline__ void gemm_phase(PG8_LAS unsigned char* lds, const Gemm g, const Sched& S, const Epi& E) {
;     ...
;             PG8_LDB(B0, 1, 0); PG8_LDB(B1, 1, 1); PG8_SCHED; PG8_LDA(At, 1, 0); PG8_STAGE(PG8_SA(0, 1), a2 + hstep, voffA);
;             PG8_WAIT_V(8); PG8_WAIT_L(0); PG8_BAR; PG8_MMA(0, 0, At, B0); PG8_MMA(0, 1, At, B1); PG8_BAR; PG8_SCHED;
	s_add_i32 s59, 0, 0x18000
	v_add_u32_e32 v151, s59, v145
	s_add_i32 s60, 0, 0x1c000
	ds_read_b128 v[152:155], v151
	ds_read_b128 v[156:159], v151 offset:1024
	ds_read_b128 v[160:163], v151 offset:2048
	ds_read_b128 v[164:167], v151 offset:3072
	v_add_u32_e32 v151, s60, v145
	ds_read_b128 v[168:171], v151
	ds_read_b128 v[172:175], v151 offset:1024
	ds_read_b128 v[176:179], v151 offset:2048
	ds_read_b128 v[180:183], v151 offset:3072
	s_add_u32 s44, s44, s16
	s_addc_u32 s45, s45, s17
	s_mov_b32 m0, s19
	v_lshl_add_u64 v[228:229], s[44:45], 0, v[134:135]
	ds_read_b128 v[184:187], v150 offset:32768
	ds_read_b128 v[188:191], v150 offset:33792
	ds_read_b128 v[192:195], v150 offset:34816
	ds_read_b128 v[196:199], v150 offset:35840
	ds_read_b128 v[200:203], v150 offset:36864
	ds_read_b128 v[204:207], v150 offset:37888
	ds_read_b128 v[208:211], v150 offset:38912
	ds_read_b128 v[212:215], v150 offset:39936
	global_load_lds_dwordx4 v[228:229], off
	v_lshl_add_u64 v[228:229], s[44:45], 0, v[130:131]
	s_mov_b32 m0, s26
	s_nop 0
	global_load_lds_dwordx4 v[228:229], off
	s_waitcnt vmcnt(8)
	s_waitcnt lgkmcnt(0)
	s_barrier
	s_setprio 1
	s_waitcnt lgkmcnt(0)
	v_mfma_f32_16x16x32_bf16 v[120:123], v[152:155], v[184:187], v[120:123]
	v_mfma_f32_16x16x32_bf16 v[108:111], v[152:155], v[192:195], v[108:111]
	v_mfma_f32_16x16x32_bf16 v[92:95], v[152:155], v[200:203], v[92:95]
	v_mfma_f32_16x16x32_bf16 v[76:79], v[152:155], v[208:211], v[76:79]
	v_mfma_f32_16x16x32_bf16 v[68:71], v[160:163], v[208:211], v[68:71]
	v_mfma_f32_16x16x32_bf16 v[84:87], v[160:163], v[200:203], v[84:87]
	v_mfma_f32_16x16x32_bf16 v[100:103], v[160:163], v[192:195], v[100:103]
	v_mfma_f32_16x16x32_bf16 v[116:119], v[160:163], v[184:187], v[116:119]
	v_mfma_f32_16x16x32_bf16 v[120:123], v[156:159], v[188:191], v[120:123]
	v_mfma_f32_16x16x32_bf16 v[108:111], v[156:159], v[196:199], v[108:111]
	v_mfma_f32_16x16x32_bf16 v[92:95], v[156:159], v[204:207], v[92:95]
	v_mfma_f32_16x16x32_bf16 v[76:79], v[156:159], v[212:215], v[76:79]
	v_mfma_f32_16x16x32_bf16 v[68:71], v[164:167], v[212:215], v[68:71]
	v_mfma_f32_16x16x32_bf16 v[84:87], v[164:167], v[204:207], v[84:87]
	v_mfma_f32_16x16x32_bf16 v[100:103], v[164:167], v[196:199], v[100:103]
	v_mfma_f32_16x16x32_bf16 v[116:119], v[164:167], v[188:191], v[116:119]
	s_setprio 0
	s_setprio 1
	v_mfma_f32_16x16x32_bf16 v[124:127], v[168:171], v[184:187], v[124:127]
	v_mfma_f32_16x16x32_bf16 v[104:107], v[168:171], v[192:195], v[104:107]
	v_mfma_f32_16x16x32_bf16 v[88:91], v[168:171], v[200:203], v[88:91]
	v_mfma_f32_16x16x32_bf16 v[72:75], v[168:171], v[208:211], v[72:75]
	v_mfma_f32_16x16x32_bf16 v[64:67], v[176:179], v[208:211], v[64:67]
	v_mfma_f32_16x16x32_bf16 v[80:83], v[176:179], v[200:203], v[80:83]
	v_mfma_f32_16x16x32_bf16 v[96:99], v[176:179], v[192:195], v[96:99]
	v_mfma_f32_16x16x32_bf16 v[112:115], v[176:179], v[184:187], v[112:115]
	v_mfma_f32_16x16x32_bf16 v[124:127], v[172:175], v[188:191], v[124:127]
	v_mfma_f32_16x16x32_bf16 v[104:107], v[172:175], v[196:199], v[104:107]
	v_mfma_f32_16x16x32_bf16 v[88:91], v[172:175], v[204:207], v[88:91]
	v_mfma_f32_16x16x32_bf16 v[72:75], v[172:175], v[212:215], v[72:75]
	v_mfma_f32_16x16x32_bf16 v[64:67], v[180:183], v[212:215], v[64:67]
	v_mfma_f32_16x16x32_bf16 v[80:83], v[180:183], v[204:207], v[80:83]
	v_mfma_f32_16x16x32_bf16 v[96:99], v[180:183], v[196:199], v[96:99]
	v_mfma_f32_16x16x32_bf16 v[112:115], v[180:183], v[188:191], v[112:115]
	s_setprio 0
	s_barrier
; #define PG8_STAGE(bufoff, gbase, voff) do { _Pragma("unroll") for (int _i = 0; _i < 2; ++_i) \
;         __builtin_amdgcn_global_load_lds((const unsigned*)((const char*)(gbase) + (voff)[_i]), (PG8_LAS unsigned*)(lds + (bufoff) + ldsw + _i * 8192), 16, 0, 0); } while (0)
; #define PG8_LDA(dst, b, h) do { _Pragma("unroll") for (int m = 0; m < 4; ++m) _Pragma("unroll") for (int k = 0; k < 2; ++k) dst[m][k] = *(const PG8_LAS bf16x8*)(lds + PG8_SA(b, h) + aoff + m * 2048 + k * 1024); } while (0)
; #define PG8_MMA(ai, bj, At, Bt) do { __builtin_amdgcn_s_setprio(1); _Pragma("unroll") for (int m = 0; m < 4; ++m) _Pragma("unroll") for (int n = 0; n < 2; ++n) _Pragma("unroll") for (int k = 0; k < 2; ++k) \
;         acc[ai][bj][m][n] = __builtin_amdgcn_mfma_f32_16x16x32_bf16(Bt[n][k], At[m][k], acc[ai][bj][m][n], 0, 0, 0); __builtin_amdgcn_s_setprio(0); } while (0)
; #define PG8_WAIT_V(n) asm volatile("s_waitcnt vmcnt(" #n ")" ::: "memory")
; #define PG8_WAIT_L(n) asm volatile("s_waitcnt lgkmcnt(" #n ")" ::: "memory")
; #define PG8_BAR __builtin_amdgcn_s_barrier()
; #define PG8_SCHED __builtin_amdgcn_sched_barrier(0)
; template <class Epi, class Sched, bool ALIGN_EPI = false, bool SP2 = false>
; __device__ __forceinline__ void gemm_phase(PG8_LAS unsigned char* lds, const Gemm g, const Sched& S, const Epi& E) {
;     ...
;             PG8_LDA(At, 1, 1); PG8_STAGE(PG8_SB(1, 0), b3, voffB); PG8_STAGE(PG8_SB(1, 1), b3 + hstep, voffB); PG8_STAGE(PG8_SA(1, 0), a3, voffA);
;             PG8_WAIT_V(8); PG8_WAIT_L(0); PG8_BAR; PG8_MMA(1, 0, At, B0); PG8_MMA(1, 1, At, B1); PG8_BAR; PG8_SCHED;
	s_add_i32 s44, s59, s3
	v_lshl_add_u64 v[216:217], v[216:217], 0, s[36:37]
	s_mov_b32 m0, s44
	ds_read_b128 v[184:187], v150 offset:49152
	ds_read_b128 v[188:191], v150 offset:50176
	ds_read_b128 v[192:195], v150 offset:51200
	ds_read_b128 v[196:199], v150 offset:52224
	ds_read_b128 v[200:203], v150 offset:53248
	ds_read_b128 v[204:207], v150 offset:54272
	ds_read_b128 v[208:211], v150 offset:55296
	ds_read_b128 v[212:215], v150 offset:56320
	global_load_lds_dwordx4 v[216:217], off
	v_lshl_add_u64 v[216:217], v[218:219], 0, s[36:37]
	s_add_i32 m0, s44, 0x2000
	s_add_i32 s44, s60, s3
	global_load_lds_dwordx4 v[216:217], off
	v_lshl_add_u64 v[216:217], v[220:221], 0, s[36:37]
	s_mov_b32 m0, s44
	s_nop 0
	global_load_lds_dwordx4 v[216:217], off
	v_lshl_add_u64 v[216:217], v[222:223], 0, s[36:37]
	s_add_i32 m0, s44, 0x2000
	s_nop 0
	global_load_lds_dwordx4 v[216:217], off
	v_lshl_add_u64 v[216:217], v[224:225], 0, s[36:37]
	s_mov_b32 m0, s27
	s_nop 0
	global_load_lds_dwordx4 v[216:217], off
	v_lshl_add_u64 v[216:217], v[226:227], 0, s[36:37]
	s_mov_b32 m0, s33
	s_nop 0
	global_load_lds_dwordx4 v[216:217], off
	s_waitcnt vmcnt(8)
	s_waitcnt lgkmcnt(0)
	s_barrier
	s_setprio 1
	s_waitcnt lgkmcnt(0)
	v_mfma_f32_16x16x32_bf16 v[60:63], v[152:155], v[184:187], v[60:63]
	v_mfma_f32_16x16x32_bf16 v[44:47], v[152:155], v[192:195], v[44:47]
	v_mfma_f32_16x16x32_bf16 v[28:31], v[152:155], v[200:203], v[28:31]
	v_mfma_f32_16x16x32_bf16 v[12:15], v[152:155], v[208:211], v[12:15]
	v_mfma_f32_16x16x32_bf16 v[4:7], v[160:163], v[208:211], v[4:7]
	v_mfma_f32_16x16x32_bf16 v[20:23], v[160:163], v[200:203], v[20:23]
	v_mfma_f32_16x16x32_bf16 v[36:39], v[160:163], v[192:195], v[36:39]
	v_mfma_f32_16x16x32_bf16 v[52:55], v[160:163], v[184:187], v[52:55]
	v_mfma_f32_16x16x32_bf16 v[60:63], v[156:159], v[188:191], v[60:63]
	v_mfma_f32_16x16x32_bf16 v[44:47], v[156:159], v[196:199], v[44:47]
	v_mfma_f32_16x16x32_bf16 v[28:31], v[156:159], v[204:207], v[28:31]
	v_mfma_f32_16x16x32_bf16 v[12:15], v[156:159], v[212:215], v[12:15]
	v_mfma_f32_16x16x32_bf16 v[4:7], v[164:167], v[212:215], v[4:7]
	v_mfma_f32_16x16x32_bf16 v[20:23], v[164:167], v[204:207], v[20:23]
	v_mfma_f32_16x16x32_bf16 v[36:39], v[164:167], v[196:199], v[36:39]
	v_mfma_f32_16x16x32_bf16 v[52:55], v[164:167], v[188:191], v[52:55]
	s_setprio 0
	s_setprio 1
	v_mfma_f32_16x16x32_bf16 v[56:59], v[168:171], v[184:187], v[56:59]
	v_mfma_f32_16x16x32_bf16 v[40:43], v[168:171], v[192:195], v[40:43]
	v_mfma_f32_16x16x32_bf16 v[24:27], v[168:171], v[200:203], v[24:27]
	v_mfma_f32_16x16x32_bf16 v[8:11], v[168:171], v[208:211], v[8:11]
	v_mfma_f32_16x16x32_bf16 v[0:3], v[176:179], v[208:211], v[0:3]
	v_mfma_f32_16x16x32_bf16 v[16:19], v[176:179], v[200:203], v[16:19]
	v_mfma_f32_16x16x32_bf16 v[32:35], v[176:179], v[192:195], v[32:35]
	v_mfma_f32_16x16x32_bf16 v[48:51], v[176:179], v[184:187], v[48:51]
	v_mfma_f32_16x16x32_bf16 v[56:59], v[172:175], v[188:191], v[56:59]
	v_mfma_f32_16x16x32_bf16 v[40:43], v[172:175], v[196:199], v[40:43]
	v_mfma_f32_16x16x32_bf16 v[24:27], v[172:175], v[204:207], v[24:27]
	v_mfma_f32_16x16x32_bf16 v[8:11], v[172:175], v[212:215], v[8:11]
	v_mfma_f32_16x16x32_bf16 v[0:3], v[180:183], v[212:215], v[0:3]
	v_mfma_f32_16x16x32_bf16 v[16:19], v[180:183], v[204:207], v[16:19]
	v_mfma_f32_16x16x32_bf16 v[32:35], v[180:183], v[196:199], v[32:35]
	v_mfma_f32_16x16x32_bf16 v[48:51], v[180:183], v[188:191], v[48:51]
	s_setprio 0
	s_barrier
	s_add_u32 s42, s42, 0x100
	s_addc_u32 s43, s43, 0
	s_add_u32 s24, s24, 0x100
	s_addc_u32 s25, s25, 0
	s_cmp_ge_i32 s58, s46
	s_mov_b32 s44, s58
	s_cbranch_scc0 .LBB0_2387

; #define PG8_STAGE(bufoff, gbase, voff) do { _Pragma("unroll") for (int _i = 0; _i < 2; ++_i) \
;         __builtin_amdgcn_global_load_lds((const unsigned*)((const char*)(gbase) + (voff)[_i]), (PG8_LAS unsigned*)(lds + (bufoff) + ldsw + _i * 8192), 16, 0, 0); } while (0)
; #define PG8_LDA(dst, b, h) do { _Pragma("unroll") for (int m = 0; m < 4; ++m) _Pragma("unroll") for (int k = 0; k < 2; ++k) dst[m][k] = *(const PG8_LAS bf16x8*)(lds + PG8_SA(b, h) + aoff + m * 2048 + k * 1024); } while (0)
; #define PG8_LDB(dst, b, h) do { _Pragma("unroll") for (int n = 0; n < 2; ++n) _Pragma("unroll") for (int k = 0; k < 2; ++k) dst[n][k] = *(const PG8_LAS bf16x8*)(lds + PG8_SB(b, h) + boff + n * 2048 + k * 1024); } while (0)
; #define PG8_MMA(ai, bj, At, Bt) do { __builtin_amdgcn_s_setprio(1); _Pragma("unroll") for (int m = 0; m < 4; ++m) _Pragma("unroll") for (int n = 0; n < 2; ++n) _Pragma("unroll") for (int k = 0; k < 2; ++k) \
;         acc[ai][bj][m][n] = __builtin_amdgcn_mfma_f32_16x16x32_bf16(Bt[n][k], At[m][k], acc[ai][bj][m][n], 0, 0, 0); __builtin_amdgcn_s_setprio(0); } while (0)
; #define PG8_WAIT_V(n) asm volatile("s_waitcnt vmcnt(" #n ")" ::: "memory")
; #define PG8_WAIT_L(n) asm volatile("s_waitcnt lgkmcnt(" #n ")" ::: "memory")
; #define PG8_BAR __builtin_amdgcn_s_barrier()
; #define PG8_SCHED __builtin_amdgcn_sched_barrier(0)
; template <class Epi, class Sched, bool ALIGN_EPI = false, bool SP2 = false>
; __device__ __forceinline__ void gemm_phase(PG8_LAS unsigned char* lds, const Gemm g, const Sched& S, const Epi& E) {
;     ...
;             PG8_LDB(B0, 0, 0); PG8_LDB(B1, 0, 1); PG8_SCHED; PG8_LDA(At, 0, 0); PG8_STAGE(PG8_SA(1, 1), a1 + hstep, voffA);
;             PG8_WAIT_V(8); PG8_WAIT_L(0); PG8_BAR; PG8_MMA(0, 0, At, B0); PG8_MMA(0, 1, At, B1); PG8_BAR; PG8_SCHED;
;             PG8_LDA(At, 0, 1); PG8_STAGE(PG8_SB(0, 0), b2, voffB); PG8_STAGE(PG8_SB(0, 1), b2 + hstep, voffB); PG8_STAGE(PG8_SA(0, 0), a2, voffA);
;     ...
; #pragma unroll
;         for (int a = 0; a < 2; ++a)
; #pragma unroll
;             for (int b = 0; b < 2; ++b)
; #pragma unroll
;                 for (int m = 0; m < 4; ++m)
; #pragma unroll
;                     for (int n = 0; n < 2; ++n) acc[a][b][m][n] = (f32x4){0.f, 0.f, 0.f, 0.f};
.LBB0_2468:
	s_and_b64 vcc, exec, s[12:13]
	s_cbranch_vccnz .Lcoldz_12
	s_add_u32 s48, s48, 0x80
	s_addc_u32 s49, s49, 0
	s_add_u32 s2, s50, 0x100
	s_addc_u32 s24, s51, 0
	s_mov_b32 s25, 0
	ds_read_b128 v[142:145], v246
	ds_read_b128 v[146:149], v246 offset:1024
	ds_read_b128 v[150:153], v246 offset:2048
	ds_read_b128 v[154:157], v246 offset:3072
	ds_read_b128 v[158:161], v247
	ds_read_b128 v[162:165], v247 offset:1024
	ds_read_b128 v[166:169], v247 offset:2048
	ds_read_b128 v[170:173], v247 offset:3072
	s_add_i32 s62, s25, 2
	s_add_u32 s50, s48, 0x80
	s_addc_u32 s51, s49, 0
	s_cmp_eq_u32 s56, s25
	s_cselect_b32 s51, s17, s51
	s_cselect_b32 s50, s16, s50
	s_cselect_b32 s65, s47, s24
	s_cselect_b32 s64, s46, s2
	v_lshl_add_u64 v[206:207], s[48:49], 0, v[136:137]
	s_add_i32 m0, s19, 0xc000
	ds_read_b128 v[174:177], v248
	ds_read_b128 v[178:181], v248 offset:1024
	ds_read_b128 v[182:185], v248 offset:2048
	ds_read_b128 v[186:189], v248 offset:3072
	ds_read_b128 v[190:193], v248 offset:4096
	ds_read_b128 v[194:197], v248 offset:5120
	ds_read_b128 v[198:201], v248 offset:6144
	ds_read_b128 v[202:205], v248 offset:7168
	global_load_lds_dwordx4 v[206:207], off
	v_lshl_add_u64 v[206:207], s[48:49], 0, v[138:139]
	s_add_i32 m0, s19, 0xe000
	s_nop 0
	global_load_lds_dwordx4 v[206:207], off
	s_waitcnt vmcnt(8)
	s_waitcnt lgkmcnt(0)
	s_barrier
	s_setprio 1
	s_waitcnt lgkmcnt(0)
	v_mfma_f32_16x16x32_bf16 v[124:127], v[142:145], v[174:177], 0
	v_mfma_f32_16x16x32_bf16 v[120:123], v[150:153], v[174:177], 0
	v_mfma_f32_16x16x32_bf16 v[116:119], v[142:145], v[182:185], 0
	v_mfma_f32_16x16x32_bf16 v[112:115], v[150:153], v[182:185], 0
	v_mfma_f32_16x16x32_bf16 v[104:107], v[142:145], v[190:193], 0
	v_mfma_f32_16x16x32_bf16 v[96:99], v[150:153], v[190:193], 0
	v_mfma_f32_16x16x32_bf16 v[88:91], v[142:145], v[198:201], 0
	v_mfma_f32_16x16x32_bf16 v[80:83], v[150:153], v[198:201], 0
	v_mfma_f32_16x16x32_bf16 v[124:127], v[146:149], v[178:181], v[124:127]
	v_mfma_f32_16x16x32_bf16 v[116:119], v[146:149], v[186:189], v[116:119]
	v_mfma_f32_16x16x32_bf16 v[104:107], v[146:149], v[194:197], v[104:107]
	v_mfma_f32_16x16x32_bf16 v[88:91], v[146:149], v[202:205], v[88:91]
	v_mfma_f32_16x16x32_bf16 v[80:83], v[154:157], v[202:205], v[80:83]
	v_mfma_f32_16x16x32_bf16 v[96:99], v[154:157], v[194:197], v[96:99]
	v_mfma_f32_16x16x32_bf16 v[112:115], v[154:157], v[186:189], v[112:115]
	v_mfma_f32_16x16x32_bf16 v[120:123], v[154:157], v[178:181], v[120:123]
	s_setprio 0
	s_setprio 1
	v_mfma_f32_16x16x32_bf16 v[108:111], v[158:161], v[174:177], 0
	v_mfma_f32_16x16x32_bf16 v[100:103], v[166:169], v[174:177], 0
	v_mfma_f32_16x16x32_bf16 v[92:95], v[158:161], v[182:185], 0
	v_mfma_f32_16x16x32_bf16 v[84:87], v[166:169], v[182:185], 0
	v_mfma_f32_16x16x32_bf16 v[76:79], v[158:161], v[190:193], 0
	v_mfma_f32_16x16x32_bf16 v[72:75], v[166:169], v[190:193], 0
	v_mfma_f32_16x16x32_bf16 v[68:71], v[158:161], v[198:201], 0
	v_mfma_f32_16x16x32_bf16 v[64:67], v[166:169], v[198:201], 0
	v_mfma_f32_16x16x32_bf16 v[108:111], v[162:165], v[178:181], v[108:111]
	v_mfma_f32_16x16x32_bf16 v[92:95], v[162:165], v[186:189], v[92:95]
	v_mfma_f32_16x16x32_bf16 v[76:79], v[162:165], v[194:197], v[76:79]
	v_mfma_f32_16x16x32_bf16 v[68:71], v[162:165], v[202:205], v[68:71]
	v_mfma_f32_16x16x32_bf16 v[64:67], v[170:173], v[202:205], v[64:67]
	v_mfma_f32_16x16x32_bf16 v[72:75], v[170:173], v[194:197], v[72:75]
	v_mfma_f32_16x16x32_bf16 v[84:87], v[170:173], v[186:189], v[84:87]
	v_mfma_f32_16x16x32_bf16 v[100:103], v[170:173], v[178:181], v[100:103]
	s_setprio 0
	s_barrier
	s_add_i32 s25, s57, s18
	v_lshl_add_u64 v[206:207], s[64:65], 0, v[130:131]
	s_mov_b32 m0, s25
	ds_read_b128 v[174:177], v248 offset:16384
	ds_read_b128 v[178:181], v248 offset:17408
	ds_read_b128 v[182:185], v248 offset:18432
	ds_read_b128 v[186:189], v248 offset:19456
	ds_read_b128 v[190:193], v248 offset:20480
	ds_read_b128 v[194:197], v248 offset:21504
	ds_read_b128 v[198:201], v248 offset:22528
	ds_read_b128 v[202:205], v248 offset:23552
	global_load_lds_dwordx4 v[206:207], off
	s_add_i32 m0, s25, 0x2000
	v_lshl_add_u64 v[208:209], s[64:65], 0, v[134:135]
	s_add_u32 s64, s64, s34
	s_addc_u32 s65, s65, s35
	s_add_i32 s25, s58, s18
	global_load_lds_dwordx4 v[208:209], off
	v_lshl_add_u64 v[210:211], s[64:65], 0, v[130:131]
	s_mov_b32 m0, s25
	v_lshl_add_u64 v[212:213], s[64:65], 0, v[134:135]
	global_load_lds_dwordx4 v[210:211], off
	s_add_i32 m0, s25, 0x2000
	v_lshl_add_u64 v[214:215], s[50:51], 0, v[128:129]
	global_load_lds_dwordx4 v[212:213], off
	s_mov_b32 m0, s19
	v_lshl_add_u64 v[216:217], s[50:51], 0, v[132:133]
	global_load_lds_dwordx4 v[214:215], off
	s_mov_b32 m0, s26
	s_nop 0
	global_load_lds_dwordx4 v[216:217], off
	s_waitcnt vmcnt(8)
	s_waitcnt lgkmcnt(0)
	s_barrier
; #define PG8_STAGE(bufoff, gbase, voff) do { _Pragma("unroll") for (int _i = 0; _i < 2; ++_i) \
;         __builtin_amdgcn_global_load_lds((const unsigned*)((const char*)(gbase) + (voff)[_i]), (PG8_LAS unsigned*)(lds + (bufoff) + ldsw + _i * 8192), 16, 0, 0); } while (0)
; #define PG8_LDA(dst, b, h) do { _Pragma("unroll") for (int m = 0; m < 4; ++m) _Pragma("unroll") for (int k = 0; k < 2; ++k) dst[m][k] = *(const PG8_LAS bf16x8*)(lds + PG8_SA(b, h) + aoff + m * 2048 + k * 1024); } while (0)
; #define PG8_LDB(dst, b, h) do { _Pragma("unroll") for (int n = 0; n < 2; ++n) _Pragma("unroll") for (int k = 0; k < 2; ++k) dst[n][k] = *(const PG8_LAS bf16x8*)(lds + PG8_SB(b, h) + boff + n * 2048 + k * 1024); } while (0)
; #define PG8_MMA(ai, bj, At, Bt) do { __builtin_amdgcn_s_setprio(1); _Pragma("unroll") for (int m = 0; m < 4; ++m) _Pragma("unroll") for (int n = 0; n < 2; ++n) _Pragma("unroll") for (int k = 0; k < 2; ++k) \
;         acc[ai][bj][m][n] = __builtin_amdgcn_mfma_f32_16x16x32_bf16(Bt[n][k], At[m][k], acc[ai][bj][m][n], 0, 0, 0); __builtin_amdgcn_s_setprio(0); } while (0)
; #define PG8_WAIT_V(n) asm volatile("s_waitcnt vmcnt(" #n ")" ::: "memory")
; #define PG8_WAIT_L(n) asm volatile("s_waitcnt lgkmcnt(" #n ")" ::: "memory")
; #define PG8_BAR __builtin_amdgcn_s_barrier()
; #define PG8_SCHED __builtin_amdgcn_sched_barrier(0)
; template <class Epi, class Sched, bool ALIGN_EPI = false, bool SP2 = false>
; __device__ __forceinline__ void gemm_phase(PG8_LAS unsigned char* lds, const Gemm g, const Sched& S, const Epi& E) {
;     ...
;             PG8_WAIT_V(8); PG8_WAIT_L(0); PG8_BAR; PG8_MMA(1, 0, At, B0); PG8_MMA(1, 1, At, B1); PG8_BAR; PG8_SCHED;
;             PG8_LDB(B0, 1, 0); PG8_LDB(B1, 1, 1); PG8_SCHED; PG8_LDA(At, 1, 0); PG8_STAGE(PG8_SA(0, 1), a2 + hstep, voffA);
;             PG8_WAIT_V(8); PG8_WAIT_L(0); PG8_BAR; PG8_MMA(0, 0, At, B0); PG8_MMA(0, 1, At, B1); PG8_BAR; PG8_SCHED;
	s_setprio 1
	s_waitcnt lgkmcnt(0)
	v_mfma_f32_16x16x32_bf16 v[60:63], v[142:145], v[174:177], 0
	v_mfma_f32_16x16x32_bf16 v[56:59], v[150:153], v[174:177], 0
	v_mfma_f32_16x16x32_bf16 v[52:55], v[142:145], v[182:185], 0
	v_mfma_f32_16x16x32_bf16 v[48:51], v[150:153], v[182:185], 0
	v_mfma_f32_16x16x32_bf16 v[40:43], v[142:145], v[190:193], 0
	v_mfma_f32_16x16x32_bf16 v[32:35], v[150:153], v[190:193], 0
	v_mfma_f32_16x16x32_bf16 v[24:27], v[142:145], v[198:201], 0
	v_mfma_f32_16x16x32_bf16 v[16:19], v[150:153], v[198:201], 0
	v_mfma_f32_16x16x32_bf16 v[60:63], v[146:149], v[178:181], v[60:63]
	v_mfma_f32_16x16x32_bf16 v[52:55], v[146:149], v[186:189], v[52:55]
	v_mfma_f32_16x16x32_bf16 v[40:43], v[146:149], v[194:197], v[40:43]
	v_mfma_f32_16x16x32_bf16 v[24:27], v[146:149], v[202:205], v[24:27]
	v_mfma_f32_16x16x32_bf16 v[16:19], v[154:157], v[202:205], v[16:19]
	v_mfma_f32_16x16x32_bf16 v[32:35], v[154:157], v[194:197], v[32:35]
	v_mfma_f32_16x16x32_bf16 v[48:51], v[154:157], v[186:189], v[48:51]
	v_mfma_f32_16x16x32_bf16 v[56:59], v[154:157], v[178:181], v[56:59]
	s_setprio 0
	s_setprio 1
	v_mfma_f32_16x16x32_bf16 v[44:47], v[158:161], v[174:177], 0
	v_mfma_f32_16x16x32_bf16 v[36:39], v[166:169], v[174:177], 0
	v_mfma_f32_16x16x32_bf16 v[28:31], v[158:161], v[182:185], 0
	v_mfma_f32_16x16x32_bf16 v[20:23], v[166:169], v[182:185], 0
	v_mfma_f32_16x16x32_bf16 v[12:15], v[158:161], v[190:193], 0
	v_mfma_f32_16x16x32_bf16 v[8:11], v[166:169], v[190:193], 0
	v_mfma_f32_16x16x32_bf16 v[4:7], v[158:161], v[198:201], 0
	v_mfma_f32_16x16x32_bf16 v[0:3], v[166:169], v[198:201], 0
	v_mfma_f32_16x16x32_bf16 v[44:47], v[162:165], v[178:181], v[44:47]
	v_mfma_f32_16x16x32_bf16 v[28:31], v[162:165], v[186:189], v[28:31]
	v_mfma_f32_16x16x32_bf16 v[12:15], v[162:165], v[194:197], v[12:15]
	v_mfma_f32_16x16x32_bf16 v[4:7], v[162:165], v[202:205], v[4:7]
	v_mfma_f32_16x16x32_bf16 v[0:3], v[170:173], v[202:205], v[0:3]
	v_mfma_f32_16x16x32_bf16 v[8:11], v[170:173], v[194:197], v[8:11]
	v_mfma_f32_16x16x32_bf16 v[20:23], v[170:173], v[186:189], v[20:23]
	v_mfma_f32_16x16x32_bf16 v[36:39], v[170:173], v[178:181], v[36:39]
	s_setprio 0
	s_barrier
	s_add_i32 s25, 0, 0x18000
	s_add_i32 s63, 0, 0x1c000
	v_add_u32_e32 v154, s25, v244
	v_add_u32_e32 v170, s63, v244
	ds_read_b128 v[142:145], v154
	ds_read_b128 v[146:149], v154 offset:1024
	ds_read_b128 v[150:153], v154 offset:2048
	ds_read_b128 v[154:157], v154 offset:3072
	ds_read_b128 v[158:161], v170
	ds_read_b128 v[162:165], v170 offset:1024
	ds_read_b128 v[166:169], v170 offset:2048
	ds_read_b128 v[170:173], v170 offset:3072
	s_add_u32 s50, s50, s34
	s_addc_u32 s51, s51, s35
	s_mov_b32 m0, s27
	v_lshl_add_u64 v[218:219], s[50:51], 0, v[128:129]
	ds_read_b128 v[174:177], v248 offset:32768
	ds_read_b128 v[178:181], v248 offset:33792
	ds_read_b128 v[182:185], v248 offset:34816
	ds_read_b128 v[186:189], v248 offset:35840
	ds_read_b128 v[190:193], v248 offset:36864
	ds_read_b128 v[194:197], v248 offset:37888
	ds_read_b128 v[198:201], v248 offset:38912
	ds_read_b128 v[202:205], v248 offset:39936
	global_load_lds_dwordx4 v[218:219], off
	v_lshl_add_u64 v[218:219], s[50:51], 0, v[132:133]
	s_mov_b32 m0, s33
	s_nop 0
	global_load_lds_dwordx4 v[218:219], off
	s_waitcnt vmcnt(8)
	s_waitcnt lgkmcnt(0)
	s_barrier
	s_setprio 1
	s_waitcnt lgkmcnt(0)
	v_mfma_f32_16x16x32_bf16 v[124:127], v[142:145], v[174:177], v[124:127]
	v_mfma_f32_16x16x32_bf16 v[116:119], v[142:145], v[182:185], v[116:119]
	v_mfma_f32_16x16x32_bf16 v[104:107], v[142:145], v[190:193], v[104:107]
	v_mfma_f32_16x16x32_bf16 v[88:91], v[142:145], v[198:201], v[88:91]
	v_mfma_f32_16x16x32_bf16 v[80:83], v[150:153], v[198:201], v[80:83]
	v_mfma_f32_16x16x32_bf16 v[96:99], v[150:153], v[190:193], v[96:99]
	v_mfma_f32_16x16x32_bf16 v[112:115], v[150:153], v[182:185], v[112:115]
	v_mfma_f32_16x16x32_bf16 v[120:123], v[150:153], v[174:177], v[120:123]
	v_mfma_f32_16x16x32_bf16 v[124:127], v[146:149], v[178:181], v[124:127]
	v_mfma_f32_16x16x32_bf16 v[116:119], v[146:149], v[186:189], v[116:119]
	v_mfma_f32_16x16x32_bf16 v[104:107], v[146:149], v[194:197], v[104:107]
	v_mfma_f32_16x16x32_bf16 v[88:91], v[146:149], v[202:205], v[88:91]
	v_mfma_f32_16x16x32_bf16 v[80:83], v[154:157], v[202:205], v[80:83]
	v_mfma_f32_16x16x32_bf16 v[96:99], v[154:157], v[194:197], v[96:99]
	v_mfma_f32_16x16x32_bf16 v[112:115], v[154:157], v[186:189], v[112:115]
	v_mfma_f32_16x16x32_bf16 v[120:123], v[154:157], v[178:181], v[120:123]
	s_setprio 0
	s_setprio 1
	v_mfma_f32_16x16x32_bf16 v[108:111], v[158:161], v[174:177], v[108:111]
	v_mfma_f32_16x16x32_bf16 v[92:95], v[158:161], v[182:185], v[92:95]
	v_mfma_f32_16x16x32_bf16 v[76:79], v[158:161], v[190:193], v[76:79]
	v_mfma_f32_16x16x32_bf16 v[68:71], v[158:161], v[198:201], v[68:71]
	v_mfma_f32_16x16x32_bf16 v[64:67], v[166:169], v[198:201], v[64:67]
	v_mfma_f32_16x16x32_bf16 v[72:75], v[166:169], v[190:193], v[72:75]
	v_mfma_f32_16x16x32_bf16 v[84:87], v[166:169], v[182:185], v[84:87]
	v_mfma_f32_16x16x32_bf16 v[100:103], v[166:169], v[174:177], v[100:103]
	v_mfma_f32_16x16x32_bf16 v[108:111], v[162:165], v[178:181], v[108:111]
	v_mfma_f32_16x16x32_bf16 v[92:95], v[162:165], v[186:189], v[92:95]
	v_mfma_f32_16x16x32_bf16 v[76:79], v[162:165], v[194:197], v[76:79]
	v_mfma_f32_16x16x32_bf16 v[68:71], v[162:165], v[202:205], v[68:71]
	v_mfma_f32_16x16x32_bf16 v[64:67], v[170:173], v[202:205], v[64:67]
	v_mfma_f32_16x16x32_bf16 v[72:75], v[170:173], v[194:197], v[72:75]
	v_mfma_f32_16x16x32_bf16 v[84:87], v[170:173], v[186:189], v[84:87]
	v_mfma_f32_16x16x32_bf16 v[100:103], v[170:173], v[178:181], v[100:103]
	s_setprio 0
	s_barrier
; #define PG8_STAGE(bufoff, gbase, voff) do { _Pragma("unroll") for (int _i = 0; _i < 2; ++_i) \
;         __builtin_amdgcn_global_load_lds((const unsigned*)((const char*)(gbase) + (voff)[_i]), (PG8_LAS unsigned*)(lds + (bufoff) + ldsw + _i * 8192), 16, 0, 0); } while (0)
; #define PG8_LDA(dst, b, h) do { _Pragma("unroll") for (int m = 0; m < 4; ++m) _Pragma("unroll") for (int k = 0; k < 2; ++k) dst[m][k] = *(const PG8_LAS bf16x8*)(lds + PG8_SA(b, h) + aoff + m * 2048 + k * 1024); } while (0)
; #define PG8_LDB(dst, b, h) do { _Pragma("unroll") for (int n = 0; n < 2; ++n) _Pragma("unroll") for (int k = 0; k < 2; ++k) dst[n][k] = *(const PG8_LAS bf16x8*)(lds + PG8_SB(b, h) + boff + n * 2048 + k * 1024); } while (0)
; #define PG8_MMA(ai, bj, At, Bt) do { __builtin_amdgcn_s_setprio(1); _Pragma("unroll") for (int m = 0; m < 4; ++m) _Pragma("unroll") for (int n = 0; n < 2; ++n) _Pragma("unroll") for (int k = 0; k < 2; ++k) \
;         acc[ai][bj][m][n] = __builtin_amdgcn_mfma_f32_16x16x32_bf16(Bt[n][k], At[m][k], acc[ai][bj][m][n], 0, 0, 0); __builtin_amdgcn_s_setprio(0); } while (0)
; #define PG8_WAIT_V(n) asm volatile("s_waitcnt vmcnt(" #n ")" ::: "memory")
; #define PG8_WAIT_L(n) asm volatile("s_waitcnt lgkmcnt(" #n ")" ::: "memory")
; #define PG8_BAR __builtin_amdgcn_s_barrier()
; #define PG8_SCHED __builtin_amdgcn_sched_barrier(0)
; template <class Epi, class Sched, bool ALIGN_EPI = false, bool SP2 = false>
; __device__ __forceinline__ void gemm_phase(PG8_LAS unsigned char* lds, const Gemm g, const Sched& S, const Epi& E) {
;     ...
;             PG8_LDB(B0, 0, 0); PG8_LDB(B1, 0, 1); PG8_SCHED; PG8_LDA(At, 0, 0); PG8_STAGE(PG8_SA(1, 1), a1 + hstep, voffA);
;             PG8_WAIT_V(8); PG8_WAIT_L(0); PG8_BAR; PG8_MMA(0, 0, At, B0); PG8_MMA(0, 1, At, B1); PG8_BAR; PG8_SCHED;
;             PG8_LDA(At, 0, 1); PG8_STAGE(PG8_SB(0, 0), b2, voffB); PG8_STAGE(PG8_SB(0, 1), b2 + hstep, voffB); PG8_STAGE(PG8_SA(0, 0), a2, voffA);
;     ...
;             PG8_LDA(At, 1, 1); PG8_STAGE(PG8_SB(1, 0), b3, voffB); PG8_STAGE(PG8_SB(1, 1), b3 + hstep, voffB); PG8_STAGE(PG8_SA(1, 0), a3, voffA);
;             PG8_WAIT_V(8); PG8_WAIT_L(0); PG8_BAR; PG8_MMA(1, 0, At, B0); PG8_MMA(1, 1, At, B1); PG8_BAR; PG8_SCHED;
	s_add_i32 s25, s25, s18
	v_lshl_add_u64 v[206:207], v[206:207], 0, s[42:43]
	s_mov_b32 m0, s25
	ds_read_b128 v[174:177], v248 offset:49152
	ds_read_b128 v[178:181], v248 offset:50176
	ds_read_b128 v[182:185], v248 offset:51200
	ds_read_b128 v[186:189], v248 offset:52224
	ds_read_b128 v[190:193], v248 offset:53248
	ds_read_b128 v[194:197], v248 offset:54272
	ds_read_b128 v[198:201], v248 offset:55296
	ds_read_b128 v[202:205], v248 offset:56320
	global_load_lds_dwordx4 v[206:207], off
	v_lshl_add_u64 v[206:207], v[208:209], 0, s[42:43]
	s_add_i32 m0, s25, 0x2000
	s_add_i32 s25, s63, s18
	global_load_lds_dwordx4 v[206:207], off
	v_lshl_add_u64 v[206:207], v[210:211], 0, s[42:43]
	s_mov_b32 m0, s25
	s_nop 0
	global_load_lds_dwordx4 v[206:207], off
	v_lshl_add_u64 v[206:207], v[212:213], 0, s[42:43]
	s_add_i32 m0, s25, 0x2000
	s_nop 0
	global_load_lds_dwordx4 v[206:207], off
	v_lshl_add_u64 v[206:207], v[214:215], 0, s[42:43]
	s_mov_b32 m0, s52
	s_nop 0
	global_load_lds_dwordx4 v[206:207], off
	v_lshl_add_u64 v[206:207], v[216:217], 0, s[42:43]
	s_mov_b32 m0, s53
	s_nop 0
	global_load_lds_dwordx4 v[206:207], off
	s_waitcnt vmcnt(8)
	s_waitcnt lgkmcnt(0)
	s_barrier
	s_setprio 1
	s_waitcnt lgkmcnt(0)
	v_mfma_f32_16x16x32_bf16 v[60:63], v[142:145], v[174:177], v[60:63]
	v_mfma_f32_16x16x32_bf16 v[52:55], v[142:145], v[182:185], v[52:55]
	v_mfma_f32_16x16x32_bf16 v[40:43], v[142:145], v[190:193], v[40:43]
	v_mfma_f32_16x16x32_bf16 v[24:27], v[142:145], v[198:201], v[24:27]
	v_mfma_f32_16x16x32_bf16 v[16:19], v[150:153], v[198:201], v[16:19]
	v_mfma_f32_16x16x32_bf16 v[32:35], v[150:153], v[190:193], v[32:35]
	v_mfma_f32_16x16x32_bf16 v[48:51], v[150:153], v[182:185], v[48:51]
	v_mfma_f32_16x16x32_bf16 v[56:59], v[150:153], v[174:177], v[56:59]
	v_mfma_f32_16x16x32_bf16 v[60:63], v[146:149], v[178:181], v[60:63]
	v_mfma_f32_16x16x32_bf16 v[52:55], v[146:149], v[186:189], v[52:55]
	v_mfma_f32_16x16x32_bf16 v[40:43], v[146:149], v[194:197], v[40:43]
	v_mfma_f32_16x16x32_bf16 v[24:27], v[146:149], v[202:205], v[24:27]
	v_mfma_f32_16x16x32_bf16 v[16:19], v[154:157], v[202:205], v[16:19]
	v_mfma_f32_16x16x32_bf16 v[32:35], v[154:157], v[194:197], v[32:35]
	v_mfma_f32_16x16x32_bf16 v[48:51], v[154:157], v[186:189], v[48:51]
	v_mfma_f32_16x16x32_bf16 v[56:59], v[154:157], v[178:181], v[56:59]
	s_setprio 0
	s_setprio 1
	v_mfma_f32_16x16x32_bf16 v[44:47], v[158:161], v[174:177], v[44:47]
	v_mfma_f32_16x16x32_bf16 v[28:31], v[158:161], v[182:185], v[28:31]
	v_mfma_f32_16x16x32_bf16 v[12:15], v[158:161], v[190:193], v[12:15]
	v_mfma_f32_16x16x32_bf16 v[4:7], v[158:161], v[198:201], v[4:7]
	v_mfma_f32_16x16x32_bf16 v[0:3], v[166:169], v[198:201], v[0:3]
	v_mfma_f32_16x16x32_bf16 v[8:11], v[166:169], v[190:193], v[8:11]
	v_mfma_f32_16x16x32_bf16 v[20:23], v[166:169], v[182:185], v[20:23]
	v_mfma_f32_16x16x32_bf16 v[36:39], v[166:169], v[174:177], v[36:39]
	v_mfma_f32_16x16x32_bf16 v[44:47], v[162:165], v[178:181], v[44:47]
	v_mfma_f32_16x16x32_bf16 v[28:31], v[162:165], v[186:189], v[28:31]
	v_mfma_f32_16x16x32_bf16 v[12:15], v[162:165], v[194:197], v[12:15]
	v_mfma_f32_16x16x32_bf16 v[4:7], v[162:165], v[202:205], v[4:7]
	v_mfma_f32_16x16x32_bf16 v[0:3], v[170:173], v[202:205], v[0:3]
	v_mfma_f32_16x16x32_bf16 v[8:11], v[170:173], v[194:197], v[8:11]
	v_mfma_f32_16x16x32_bf16 v[20:23], v[170:173], v[186:189], v[20:23]
	v_mfma_f32_16x16x32_bf16 v[36:39], v[170:173], v[178:181], v[36:39]
	s_setprio 0
	s_barrier
	s_add_u32 s48, s48, 0x100
	s_addc_u32 s49, s49, 0
	s_add_u32 s2, s2, 0x100
	s_addc_u32 s24, s24, 0
	s_cmp_ge_i32 s62, s55
	s_mov_b32 s25, s62
	s_cbranch_scc1 .Lpeelx_12
.LBB0_2470:
	ds_read_b128 v[142:145], v246
	ds_read_b128 v[146:149], v246 offset:1024
	ds_read_b128 v[150:153], v246 offset:2048
	ds_read_b128 v[154:157], v246 offset:3072
	ds_read_b128 v[158:161], v247
	ds_read_b128 v[162:165], v247 offset:1024
	ds_read_b128 v[166:169], v247 offset:2048
	ds_read_b128 v[170:173], v247 offset:3072
	s_add_i32 s62, s25, 2
	s_add_u32 s50, s48, 0x80
	s_addc_u32 s51, s49, 0
	s_cmp_eq_u32 s56, s25
	s_cselect_b32 s51, s17, s51
	s_cselect_b32 s50, s16, s50
	s_cselect_b32 s65, s47, s24
	s_cselect_b32 s64, s46, s2
	v_lshl_add_u64 v[206:207], s[48:49], 0, v[136:137]
	s_add_i32 m0, s19, 0xc000
	ds_read_b128 v[174:177], v248
	ds_read_b128 v[178:181], v248 offset:1024
	ds_read_b128 v[182:185], v248 offset:2048
	ds_read_b128 v[186:189], v248 offset:3072
	ds_read_b128 v[190:193], v248 offset:4096
	ds_read_b128 v[194:197], v248 offset:5120
	ds_read_b128 v[198:201], v248 offset:6144
	ds_read_b128 v[202:205], v248 offset:7168
	global_load_lds_dwordx4 v[206:207], off
	v_lshl_add_u64 v[206:207], s[48:49], 0, v[138:139]
	s_add_i32 m0, s19, 0xe000
	s_nop 0
	global_load_lds_dwordx4 v[206:207], off
	s_waitcnt vmcnt(8)
	s_waitcnt lgkmcnt(0)
	s_barrier
; #define PG8_STAGE(bufoff, gbase, voff) do { _Pragma("unroll") for (int _i = 0; _i < 2; ++_i) \
;         __builtin_amdgcn_global_load_lds((const unsigned*)((const char*)(gbase) + (voff)[_i]), (PG8_LAS unsigned*)(lds + (bufoff) + ldsw + _i * 8192), 16, 0, 0); } while (0)
; #define PG8_LDA(dst, b, h) do { _Pragma("unroll") for (int m = 0; m < 4; ++m) _Pragma("unroll") for (int k = 0; k < 2; ++k) dst[m][k] = *(const PG8_LAS bf16x8*)(lds + PG8_SA(b, h) + aoff + m * 2048 + k * 1024); } while (0)
; #define PG8_MMA(ai, bj, At, Bt) do { __builtin_amdgcn_s_setprio(1); _Pragma("unroll") for (int m = 0; m < 4; ++m) _Pragma("unroll") for (int n = 0; n < 2; ++n) _Pragma("unroll") for (int k = 0; k < 2; ++k) \
;         acc[ai][bj][m][n] = __builtin_amdgcn_mfma_f32_16x16x32_bf16(Bt[n][k], At[m][k], acc[ai][bj][m][n], 0, 0, 0); __builtin_amdgcn_s_setprio(0); } while (0)
; #define PG8_WAIT_V(n) asm volatile("s_waitcnt vmcnt(" #n ")" ::: "memory")
; #define PG8_WAIT_L(n) asm volatile("s_waitcnt lgkmcnt(" #n ")" ::: "memory")
; #define PG8_BAR __builtin_amdgcn_s_barrier()
; #define PG8_SCHED __builtin_amdgcn_sched_barrier(0)
; template <class Epi, class Sched, bool ALIGN_EPI = false, bool SP2 = false>
; __device__ __forceinline__ void gemm_phase(PG8_LAS unsigned char* lds, const Gemm g, const Sched& S, const Epi& E) {
;     ...
;             PG8_WAIT_V(8); PG8_WAIT_L(0); PG8_BAR; PG8_MMA(0, 0, At, B0); PG8_MMA(0, 1, At, B1); PG8_BAR; PG8_SCHED;
;             PG8_LDA(At, 0, 1); PG8_STAGE(PG8_SB(0, 0), b2, voffB); PG8_STAGE(PG8_SB(0, 1), b2 + hstep, voffB); PG8_STAGE(PG8_SA(0, 0), a2, voffA);
;             PG8_WAIT_V(8); PG8_WAIT_L(0); PG8_BAR; PG8_MMA(1, 0, At, B0); PG8_MMA(1, 1, At, B1); PG8_BAR; PG8_SCHED;
	s_setprio 1
	s_waitcnt lgkmcnt(0)
	v_mfma_f32_16x16x32_bf16 v[124:127], v[142:145], v[174:177], v[124:127]
	v_mfma_f32_16x16x32_bf16 v[116:119], v[142:145], v[182:185], v[116:119]
	v_mfma_f32_16x16x32_bf16 v[104:107], v[142:145], v[190:193], v[104:107]
	v_mfma_f32_16x16x32_bf16 v[88:91], v[142:145], v[198:201], v[88:91]
	v_mfma_f32_16x16x32_bf16 v[80:83], v[150:153], v[198:201], v[80:83]
	v_mfma_f32_16x16x32_bf16 v[96:99], v[150:153], v[190:193], v[96:99]
	v_mfma_f32_16x16x32_bf16 v[112:115], v[150:153], v[182:185], v[112:115]
	v_mfma_f32_16x16x32_bf16 v[120:123], v[150:153], v[174:177], v[120:123]
	v_mfma_f32_16x16x32_bf16 v[124:127], v[146:149], v[178:181], v[124:127]
	v_mfma_f32_16x16x32_bf16 v[116:119], v[146:149], v[186:189], v[116:119]
	v_mfma_f32_16x16x32_bf16 v[104:107], v[146:149], v[194:197], v[104:107]
	v_mfma_f32_16x16x32_bf16 v[88:91], v[146:149], v[202:205], v[88:91]
	v_mfma_f32_16x16x32_bf16 v[80:83], v[154:157], v[202:205], v[80:83]
	v_mfma_f32_16x16x32_bf16 v[96:99], v[154:157], v[194:197], v[96:99]
	v_mfma_f32_16x16x32_bf16 v[112:115], v[154:157], v[186:189], v[112:115]
	v_mfma_f32_16x16x32_bf16 v[120:123], v[154:157], v[178:181], v[120:123]
	s_setprio 0
	s_setprio 1
	v_mfma_f32_16x16x32_bf16 v[108:111], v[158:161], v[174:177], v[108:111]
	v_mfma_f32_16x16x32_bf16 v[92:95], v[158:161], v[182:185], v[92:95]
	v_mfma_f32_16x16x32_bf16 v[76:79], v[158:161], v[190:193], v[76:79]
	v_mfma_f32_16x16x32_bf16 v[68:71], v[158:161], v[198:201], v[68:71]
	v_mfma_f32_16x16x32_bf16 v[64:67], v[166:169], v[198:201], v[64:67]
	v_mfma_f32_16x16x32_bf16 v[72:75], v[166:169], v[190:193], v[72:75]
	v_mfma_f32_16x16x32_bf16 v[84:87], v[166:169], v[182:185], v[84:87]
	v_mfma_f32_16x16x32_bf16 v[100:103], v[166:169], v[174:177], v[100:103]
	v_mfma_f32_16x16x32_bf16 v[108:111], v[162:165], v[178:181], v[108:111]
	v_mfma_f32_16x16x32_bf16 v[92:95], v[162:165], v[186:189], v[92:95]
	v_mfma_f32_16x16x32_bf16 v[76:79], v[162:165], v[194:197], v[76:79]
	v_mfma_f32_16x16x32_bf16 v[68:71], v[162:165], v[202:205], v[68:71]
	v_mfma_f32_16x16x32_bf16 v[64:67], v[170:173], v[202:205], v[64:67]
	v_mfma_f32_16x16x32_bf16 v[72:75], v[170:173], v[194:197], v[72:75]
	v_mfma_f32_16x16x32_bf16 v[84:87], v[170:173], v[186:189], v[84:87]
	v_mfma_f32_16x16x32_bf16 v[100:103], v[170:173], v[178:181], v[100:103]
	s_setprio 0
	s_barrier
	s_add_i32 s25, s57, s18
	v_lshl_add_u64 v[206:207], s[64:65], 0, v[130:131]
	s_mov_b32 m0, s25
	ds_read_b128 v[174:177], v248 offset:16384
	ds_read_b128 v[178:181], v248 offset:17408
	ds_read_b128 v[182:185], v248 offset:18432
	ds_read_b128 v[186:189], v248 offset:19456
	ds_read_b128 v[190:193], v248 offset:20480
	ds_read_b128 v[194:197], v248 offset:21504
	ds_read_b128 v[198:201], v248 offset:22528
	ds_read_b128 v[202:205], v248 offset:23552
	global_load_lds_dwordx4 v[206:207], off
	s_add_i32 m0, s25, 0x2000
	v_lshl_add_u64 v[208:209], s[64:65], 0, v[134:135]
	s_add_u32 s64, s64, s34
	s_addc_u32 s65, s65, s35
	s_add_i32 s25, s58, s18
	global_load_lds_dwordx4 v[208:209], off
	v_lshl_add_u64 v[210:211], s[64:65], 0, v[130:131]
	s_mov_b32 m0, s25
	v_lshl_add_u64 v[212:213], s[64:65], 0, v[134:135]
	global_load_lds_dwordx4 v[210:211], off
	s_add_i32 m0, s25, 0x2000
	v_lshl_add_u64 v[214:215], s[50:51], 0, v[128:129]
	global_load_lds_dwordx4 v[212:213], off
	s_mov_b32 m0, s19
	v_lshl_add_u64 v[216:217], s[50:51], 0, v[132:133]
	global_load_lds_dwordx4 v[214:215], off
	s_mov_b32 m0, s26
	s_nop 0
	global_load_lds_dwordx4 v[216:217], off
	s_waitcnt vmcnt(8)
	s_waitcnt lgkmcnt(0)
	s_barrier
	s_setprio 1
	s_waitcnt lgkmcnt(0)
	v_mfma_f32_16x16x32_bf16 v[60:63], v[142:145], v[174:177], v[60:63]
	v_mfma_f32_16x16x32_bf16 v[52:55], v[142:145], v[182:185], v[52:55]
	v_mfma_f32_16x16x32_bf16 v[40:43], v[142:145], v[190:193], v[40:43]
	v_mfma_f32_16x16x32_bf16 v[24:27], v[142:145], v[198:201], v[24:27]
	v_mfma_f32_16x16x32_bf16 v[16:19], v[150:153], v[198:201], v[16:19]
	v_mfma_f32_16x16x32_bf16 v[32:35], v[150:153], v[190:193], v[32:35]
	v_mfma_f32_16x16x32_bf16 v[48:51], v[150:153], v[182:185], v[48:51]
	v_mfma_f32_16x16x32_bf16 v[56:59], v[150:153], v[174:177], v[56:59]
	v_mfma_f32_16x16x32_bf16 v[60:63], v[146:149], v[178:181], v[60:63]
	v_mfma_f32_16x16x32_bf16 v[52:55], v[146:149], v[186:189], v[52:55]
	v_mfma_f32_16x16x32_bf16 v[40:43], v[146:149], v[194:197], v[40:43]
	v_mfma_f32_16x16x32_bf16 v[24:27], v[146:149], v[202:205], v[24:27]
	v_mfma_f32_16x16x32_bf16 v[16:19], v[154:157], v[202:205], v[16:19]
	v_mfma_f32_16x16x32_bf16 v[32:35], v[154:157], v[194:197], v[32:35]
	v_mfma_f32_16x16x32_bf16 v[48:51], v[154:157], v[186:189], v[48:51]
	v_mfma_f32_16x16x32_bf16 v[56:59], v[154:157], v[178:181], v[56:59]
	s_setprio 0
	s_setprio 1
	v_mfma_f32_16x16x32_bf16 v[44:47], v[158:161], v[174:177], v[44:47]
	v_mfma_f32_16x16x32_bf16 v[28:31], v[158:161], v[182:185], v[28:31]
	v_mfma_f32_16x16x32_bf16 v[12:15], v[158:161], v[190:193], v[12:15]
	v_mfma_f32_16x16x32_bf16 v[4:7], v[158:161], v[198:201], v[4:7]
	v_mfma_f32_16x16x32_bf16 v[0:3], v[166:169], v[198:201], v[0:3]
	v_mfma_f32_16x16x32_bf16 v[8:11], v[166:169], v[190:193], v[8:11]
	v_mfma_f32_16x16x32_bf16 v[20:23], v[166:169], v[182:185], v[20:23]
	v_mfma_f32_16x16x32_bf16 v[36:39], v[166:169], v[174:177], v[36:39]
	v_mfma_f32_16x16x32_bf16 v[44:47], v[162:165], v[178:181], v[44:47]
	v_mfma_f32_16x16x32_bf16 v[28:31], v[162:165], v[186:189], v[28:31]
	v_mfma_f32_16x16x32_bf16 v[12:15], v[162:165], v[194:197], v[12:15]
	v_mfma_f32_16x16x32_bf16 v[4:7], v[162:165], v[202:205], v[4:7]
	v_mfma_f32_16x16x32_bf16 v[0:3], v[170:173], v[202:205], v[0:3]
	v_mfma_f32_16x16x32_bf16 v[8:11], v[170:173], v[194:197], v[8:11]
	v_mfma_f32_16x16x32_bf16 v[20:23], v[170:173], v[186:189], v[20:23]
	v_mfma_f32_16x16x32_bf16 v[36:39], v[170:173], v[178:181], v[36:39]
	s_setprio 0
	s_barrier
; #define PG8_STAGE(bufoff, gbase, voff) do { _Pragma("unroll") for (int _i = 0; _i < 2; ++_i) \
;         __builtin_amdgcn_global_load_lds((const unsigned*)((const char*)(gbase) + (voff)[_i]), (PG8_LAS unsigned*)(lds + (bufoff) + ldsw + _i * 8192), 16, 0, 0); } while (0)
; #define PG8_LDA(dst, b, h) do { _Pragma("unroll") for (int m = 0; m < 4; ++m) _Pragma("unroll") for (int k = 0; k < 2; ++k) dst[m][k] = *(const PG8_LAS bf16x8*)(lds + PG8_SA(b, h) + aoff + m * 2048 + k * 1024); } while (0)
; #define PG8_LDB(dst, b, h) do { _Pragma("unroll") for (int n = 0; n < 2; ++n) _Pragma("unroll") for (int k = 0; k < 2; ++k) dst[n][k] = *(const PG8_LAS bf16x8*)(lds + PG8_SB(b, h) + boff + n * 2048 + k * 1024); } while (0)
; #define PG8_MMA(ai, bj, At, Bt) do { __builtin_amdgcn_s_setprio(1); _Pragma("unroll") for (int m = 0; m < 4; ++m) _Pragma("unroll") for (int n = 0; n < 2; ++n) _Pragma("unroll") for (int k = 0; k < 2; ++k) \
;         acc[ai][bj][m][n] = __builtin_amdgcn_mfma_f32_16x16x32_bf16(Bt[n][k], At[m][k], acc[ai][bj][m][n], 0, 0, 0); __builtin_amdgcn_s_setprio(0); } while (0)
; #define PG8_WAIT_V(n) asm volatile("s_waitcnt vmcnt(" #n ")" ::: "memory")
; #define PG8_WAIT_L(n) asm volatile("s_waitcnt lgkmcnt(" #n ")" ::: "memory")
; #define PG8_BAR __builtin_amdgcn_s_barrier()
; #define PG8_SCHED __builtin_amdgcn_sched_barrier(0)
; template <class Epi, class Sched, bool ALIGN_EPI = false, bool SP2 = false>
; __device__ __forceinline__ void gemm_phase(PG8_LAS unsigned char* lds, const Gemm g, const Sched& S, const Epi& E) {
;     ...
;             PG8_LDB(B0, 1, 0); PG8_LDB(B1, 1, 1); PG8_SCHED; PG8_LDA(At, 1, 0); PG8_STAGE(PG8_SA(0, 1), a2 + hstep, voffA);
;             PG8_WAIT_V(8); PG8_WAIT_L(0); PG8_BAR; PG8_MMA(0, 0, At, B0); PG8_MMA(0, 1, At, B1); PG8_BAR; PG8_SCHED;
	s_add_i32 s25, 0, 0x18000
	s_add_i32 s63, 0, 0x1c000
	v_add_u32_e32 v154, s25, v244
	v_add_u32_e32 v170, s63, v244
	ds_read_b128 v[142:145], v154
	ds_read_b128 v[146:149], v154 offset:1024
	ds_read_b128 v[150:153], v154 offset:2048
	ds_read_b128 v[154:157], v154 offset:3072
	ds_read_b128 v[158:161], v170
	ds_read_b128 v[162:165], v170 offset:1024
	ds_read_b128 v[166:169], v170 offset:2048
	ds_read_b128 v[170:173], v170 offset:3072
	s_add_u32 s50, s50, s34
	s_addc_u32 s51, s51, s35
	s_mov_b32 m0, s27
	v_lshl_add_u64 v[218:219], s[50:51], 0, v[128:129]
	ds_read_b128 v[174:177], v248 offset:32768
	ds_read_b128 v[178:181], v248 offset:33792
	ds_read_b128 v[182:185], v248 offset:34816
	ds_read_b128 v[186:189], v248 offset:35840
	ds_read_b128 v[190:193], v248 offset:36864
	ds_read_b128 v[194:197], v248 offset:37888
	ds_read_b128 v[198:201], v248 offset:38912
	ds_read_b128 v[202:205], v248 offset:39936
	global_load_lds_dwordx4 v[218:219], off
	v_lshl_add_u64 v[218:219], s[50:51], 0, v[132:133]
	s_mov_b32 m0, s33
	s_nop 0
	global_load_lds_dwordx4 v[218:219], off
	s_waitcnt vmcnt(8)
	s_waitcnt lgkmcnt(0)
	s_barrier
	s_setprio 1
	s_waitcnt lgkmcnt(0)
	v_mfma_f32_16x16x32_bf16 v[124:127], v[142:145], v[174:177], v[124:127]
	v_mfma_f32_16x16x32_bf16 v[116:119], v[142:145], v[182:185], v[116:119]
	v_mfma_f32_16x16x32_bf16 v[104:107], v[142:145], v[190:193], v[104:107]
	v_mfma_f32_16x16x32_bf16 v[88:91], v[142:145], v[198:201], v[88:91]
	v_mfma_f32_16x16x32_bf16 v[80:83], v[150:153], v[198:201], v[80:83]
	v_mfma_f32_16x16x32_bf16 v[96:99], v[150:153], v[190:193], v[96:99]
	v_mfma_f32_16x16x32_bf16 v[112:115], v[150:153], v[182:185], v[112:115]
	v_mfma_f32_16x16x32_bf16 v[120:123], v[150:153], v[174:177], v[120:123]
	v_mfma_f32_16x16x32_bf16 v[124:127], v[146:149], v[178:181], v[124:127]
	v_mfma_f32_16x16x32_bf16 v[116:119], v[146:149], v[186:189], v[116:119]
	v_mfma_f32_16x16x32_bf16 v[104:107], v[146:149], v[194:197], v[104:107]
	v_mfma_f32_16x16x32_bf16 v[88:91], v[146:149], v[202:205], v[88:91]
	v_mfma_f32_16x16x32_bf16 v[80:83], v[154:157], v[202:205], v[80:83]
	v_mfma_f32_16x16x32_bf16 v[96:99], v[154:157], v[194:197], v[96:99]
	v_mfma_f32_16x16x32_bf16 v[112:115], v[154:157], v[186:189], v[112:115]
	v_mfma_f32_16x16x32_bf16 v[120:123], v[154:157], v[178:181], v[120:123]
	s_setprio 0
	s_setprio 1
	v_mfma_f32_16x16x32_bf16 v[108:111], v[158:161], v[174:177], v[108:111]
	v_mfma_f32_16x16x32_bf16 v[92:95], v[158:161], v[182:185], v[92:95]
	v_mfma_f32_16x16x32_bf16 v[76:79], v[158:161], v[190:193], v[76:79]
	v_mfma_f32_16x16x32_bf16 v[68:71], v[158:161], v[198:201], v[68:71]
	v_mfma_f32_16x16x32_bf16 v[64:67], v[166:169], v[198:201], v[64:67]
	v_mfma_f32_16x16x32_bf16 v[72:75], v[166:169], v[190:193], v[72:75]
	v_mfma_f32_16x16x32_bf16 v[84:87], v[166:169], v[182:185], v[84:87]
	v_mfma_f32_16x16x32_bf16 v[100:103], v[166:169], v[174:177], v[100:103]
	v_mfma_f32_16x16x32_bf16 v[108:111], v[162:165], v[178:181], v[108:111]
	v_mfma_f32_16x16x32_bf16 v[92:95], v[162:165], v[186:189], v[92:95]
	v_mfma_f32_16x16x32_bf16 v[76:79], v[162:165], v[194:197], v[76:79]
	v_mfma_f32_16x16x32_bf16 v[68:71], v[162:165], v[202:205], v[68:71]
	v_mfma_f32_16x16x32_bf16 v[64:67], v[170:173], v[202:205], v[64:67]
	v_mfma_f32_16x16x32_bf16 v[72:75], v[170:173], v[194:197], v[72:75]
	v_mfma_f32_16x16x32_bf16 v[84:87], v[170:173], v[186:189], v[84:87]
	v_mfma_f32_16x16x32_bf16 v[100:103], v[170:173], v[178:181], v[100:103]
	s_setprio 0
	s_barrier
; #define PG8_STAGE(bufoff, gbase, voff) do { _Pragma("unroll") for (int _i = 0; _i < 2; ++_i) \
;         __builtin_amdgcn_global_load_lds((const unsigned*)((const char*)(gbase) + (voff)[_i]), (PG8_LAS unsigned*)(lds + (bufoff) + ldsw + _i * 8192), 16, 0, 0); } while (0)
; #define PG8_LDA(dst, b, h) do { _Pragma("unroll") for (int m = 0; m < 4; ++m) _Pragma("unroll") for (int k = 0; k < 2; ++k) dst[m][k] = *(const PG8_LAS bf16x8*)(lds + PG8_SA(b, h) + aoff + m * 2048 + k * 1024); } while (0)
; #define PG8_MMA(ai, bj, At, Bt) do { __builtin_amdgcn_s_setprio(1); _Pragma("unroll") for (int m = 0; m < 4; ++m) _Pragma("unroll") for (int n = 0; n < 2; ++n) _Pragma("unroll") for (int k = 0; k < 2; ++k) \
;         acc[ai][bj][m][n] = __builtin_amdgcn_mfma_f32_16x16x32_bf16(Bt[n][k], At[m][k], acc[ai][bj][m][n], 0, 0, 0); __builtin_amdgcn_s_setprio(0); } while (0)
; #define PG8_WAIT_V(n) asm volatile("s_waitcnt vmcnt(" #n ")" ::: "memory")
; #define PG8_WAIT_L(n) asm volatile("s_waitcnt lgkmcnt(" #n ")" ::: "memory")
; #define PG8_BAR __builtin_amdgcn_s_barrier()
; #define PG8_SCHED __builtin_amdgcn_sched_barrier(0)
; template <class Epi, class Sched, bool ALIGN_EPI = false, bool SP2 = false>
; __device__ __forceinline__ void gemm_phase(PG8_LAS unsigned char* lds, const Gemm g, const Sched& S, const Epi& E) {
;     ...
;             PG8_LDA(At, 1, 1); PG8_STAGE(PG8_SB(1, 0), b3, voffB); PG8_STAGE(PG8_SB(1, 1), b3 + hstep, voffB); PG8_STAGE(PG8_SA(1, 0), a3, voffA);
;             PG8_WAIT_V(8); PG8_WAIT_L(0); PG8_BAR; PG8_MMA(1, 0, At, B0); PG8_MMA(1, 1, At, B1); PG8_BAR; PG8_SCHED;
	s_add_i32 s25, s25, s18
	v_lshl_add_u64 v[206:207], v[206:207], 0, s[42:43]
	s_mov_b32 m0, s25
	ds_read_b128 v[174:177], v248 offset:49152
	ds_read_b128 v[178:181], v248 offset:50176
	ds_read_b128 v[182:185], v248 offset:51200
	ds_read_b128 v[186:189], v248 offset:52224
	ds_read_b128 v[190:193], v248 offset:53248
	ds_read_b128 v[194:197], v248 offset:54272
	ds_read_b128 v[198:201], v248 offset:55296
	ds_read_b128 v[202:205], v248 offset:56320
	global_load_lds_dwordx4 v[206:207], off
	v_lshl_add_u64 v[206:207], v[208:209], 0, s[42:43]
	s_add_i32 m0, s25, 0x2000
	s_add_i32 s25, s63, s18
	global_load_lds_dwordx4 v[206:207], off
	v_lshl_add_u64 v[206:207], v[210:211], 0, s[42:43]
	s_mov_b32 m0, s25
	s_nop 0
	global_load_lds_dwordx4 v[206:207], off
	v_lshl_add_u64 v[206:207], v[212:213], 0, s[42:43]
	s_add_i32 m0, s25, 0x2000
	s_nop 0
	global_load_lds_dwordx4 v[206:207], off
	v_lshl_add_u64 v[206:207], v[214:215], 0, s[42:43]
	s_mov_b32 m0, s52
	s_nop 0
	global_load_lds_dwordx4 v[206:207], off
	v_lshl_add_u64 v[206:207], v[216:217], 0, s[42:43]
	s_mov_b32 m0, s53
	s_nop 0
	global_load_lds_dwordx4 v[206:207], off
	s_waitcnt vmcnt(8)
	s_waitcnt lgkmcnt(0)
	s_barrier
	s_setprio 1
	s_waitcnt lgkmcnt(0)
	v_mfma_f32_16x16x32_bf16 v[60:63], v[142:145], v[174:177], v[60:63]
	v_mfma_f32_16x16x32_bf16 v[52:55], v[142:145], v[182:185], v[52:55]
	v_mfma_f32_16x16x32_bf16 v[40:43], v[142:145], v[190:193], v[40:43]
	v_mfma_f32_16x16x32_bf16 v[24:27], v[142:145], v[198:201], v[24:27]
	v_mfma_f32_16x16x32_bf16 v[16:19], v[150:153], v[198:201], v[16:19]
	v_mfma_f32_16x16x32_bf16 v[32:35], v[150:153], v[190:193], v[32:35]
	v_mfma_f32_16x16x32_bf16 v[48:51], v[150:153], v[182:185], v[48:51]
	v_mfma_f32_16x16x32_bf16 v[56:59], v[150:153], v[174:177], v[56:59]
	v_mfma_f32_16x16x32_bf16 v[60:63], v[146:149], v[178:181], v[60:63]
	v_mfma_f32_16x16x32_bf16 v[52:55], v[146:149], v[186:189], v[52:55]
	v_mfma_f32_16x16x32_bf16 v[40:43], v[146:149], v[194:197], v[40:43]
	v_mfma_f32_16x16x32_bf16 v[24:27], v[146:149], v[202:205], v[24:27]
	v_mfma_f32_16x16x32_bf16 v[16:19], v[154:157], v[202:205], v[16:19]
	v_mfma_f32_16x16x32_bf16 v[32:35], v[154:157], v[194:197], v[32:35]
	v_mfma_f32_16x16x32_bf16 v[48:51], v[154:157], v[186:189], v[48:51]
	v_mfma_f32_16x16x32_bf16 v[56:59], v[154:157], v[178:181], v[56:59]
	s_setprio 0
	s_setprio 1
	v_mfma_f32_16x16x32_bf16 v[44:47], v[158:161], v[174:177], v[44:47]
	v_mfma_f32_16x16x32_bf16 v[28:31], v[158:161], v[182:185], v[28:31]
	v_mfma_f32_16x16x32_bf16 v[12:15], v[158:161], v[190:193], v[12:15]
	v_mfma_f32_16x16x32_bf16 v[4:7], v[158:161], v[198:201], v[4:7]
	v_mfma_f32_16x16x32_bf16 v[0:3], v[166:169], v[198:201], v[0:3]
	v_mfma_f32_16x16x32_bf16 v[8:11], v[166:169], v[190:193], v[8:11]
	v_mfma_f32_16x16x32_bf16 v[20:23], v[166:169], v[182:185], v[20:23]
	v_mfma_f32_16x16x32_bf16 v[36:39], v[166:169], v[174:177], v[36:39]
	v_mfma_f32_16x16x32_bf16 v[44:47], v[162:165], v[178:181], v[44:47]
	v_mfma_f32_16x16x32_bf16 v[28:31], v[162:165], v[186:189], v[28:31]
	v_mfma_f32_16x16x32_bf16 v[12:15], v[162:165], v[194:197], v[12:15]
	v_mfma_f32_16x16x32_bf16 v[4:7], v[162:165], v[202:205], v[4:7]
	v_mfma_f32_16x16x32_bf16 v[0:3], v[170:173], v[202:205], v[0:3]
	v_mfma_f32_16x16x32_bf16 v[8:11], v[170:173], v[194:197], v[8:11]
	v_mfma_f32_16x16x32_bf16 v[20:23], v[170:173], v[186:189], v[20:23]
	v_mfma_f32_16x16x32_bf16 v[36:39], v[170:173], v[178:181], v[36:39]
	s_setprio 0
	s_barrier
	s_add_u32 s48, s48, 0x100
	s_addc_u32 s49, s49, 0
	s_add_u32 s2, s2, 0x100
	s_addc_u32 s24, s24, 0
	s_cmp_ge_i32 s62, s55
	s_mov_b32 s25, s62
	s_cbranch_scc0 .LBB0_2470

; #define PG8_STAGE(bufoff, gbase, voff) do { _Pragma("unroll") for (int _i = 0; _i < 2; ++_i) \
;         __builtin_amdgcn_global_load_lds((const unsigned*)((const char*)(gbase) + (voff)[_i]), (PG8_LAS unsigned*)(lds + (bufoff) + ldsw + _i * 8192), 16, 0, 0); } while (0)
; #define PG8_LDA(dst, b, h) do { _Pragma("unroll") for (int m = 0; m < 4; ++m) _Pragma("unroll") for (int k = 0; k < 2; ++k) dst[m][k] = *(const PG8_LAS bf16x8*)(lds + PG8_SA(b, h) + aoff + m * 2048 + k * 1024); } while (0)
; #define PG8_LDB(dst, b, h) do { _Pragma("unroll") for (int n = 0; n < 2; ++n) _Pragma("unroll") for (int k = 0; k < 2; ++k) dst[n][k] = *(const PG8_LAS bf16x8*)(lds + PG8_SB(b, h) + boff + n * 2048 + k * 1024); } while (0)
; #define PG8_MMA(ai, bj, At, Bt) do { __builtin_amdgcn_s_setprio(1); _Pragma("unroll") for (int m = 0; m < 4; ++m) _Pragma("unroll") for (int n = 0; n < 2; ++n) _Pragma("unroll") for (int k = 0; k < 2; ++k) \
;         acc[ai][bj][m][n] = __builtin_amdgcn_mfma_f32_16x16x32_bf16(Bt[n][k], At[m][k], acc[ai][bj][m][n], 0, 0, 0); __builtin_amdgcn_s_setprio(0); } while (0)
; #define PG8_WAIT_V(n) asm volatile("s_waitcnt vmcnt(" #n ")" ::: "memory")
; #define PG8_WAIT_L(n) asm volatile("s_waitcnt lgkmcnt(" #n ")" ::: "memory")
; #define PG8_BAR __builtin_amdgcn_s_barrier()
; #define PG8_SCHED __builtin_amdgcn_sched_barrier(0)
; template <class Epi, class Sched, bool ALIGN_EPI = false, bool SP2 = false>
; __device__ __forceinline__ void gemm_phase(PG8_LAS unsigned char* lds, const Gemm g, const Sched& S, const Epi& E) {
;     ...
;             PG8_LDB(B0, 0, 0); PG8_LDB(B1, 0, 1); PG8_SCHED; PG8_LDA(At, 0, 0); PG8_STAGE(PG8_SA(1, 1), a1 + hstep, voffA);
;             PG8_WAIT_V(8); PG8_WAIT_L(0); PG8_BAR; PG8_MMA(0, 0, At, B0); PG8_MMA(0, 1, At, B1); PG8_BAR; PG8_SCHED;
;             PG8_LDA(At, 0, 1); PG8_STAGE(PG8_SB(0, 0), b2, voffB); PG8_STAGE(PG8_SB(0, 1), b2 + hstep, voffB); PG8_STAGE(PG8_SA(0, 0), a2, voffA);
;     ...
; #pragma unroll
;         for (int a = 0; a < 2; ++a)
; #pragma unroll
;             for (int b = 0; b < 2; ++b)
; #pragma unroll
;                 for (int m = 0; m < 4; ++m)
; #pragma unroll
;                     for (int n = 0; n < 2; ++n) acc[a][b][m][n] = (f32x4){0.f, 0.f, 0.f, 0.f};
.LBB0_2577:
	s_and_b64 vcc, exec, s[8:9]
	s_cbranch_vccnz .Lcoldz_13
	s_add_u32 s40, s40, 0x80
	s_addc_u32 s41, s41, 0
	s_add_u32 s24, s42, 0x100
	s_addc_u32 s25, s43, 0
	s_mov_b32 s42, 0
	ds_read_b128 v[152:155], v147
	ds_read_b128 v[156:159], v147 offset:1024
	ds_read_b128 v[160:163], v147 offset:2048
	ds_read_b128 v[164:167], v147 offset:3072
	ds_read_b128 v[168:171], v148
	ds_read_b128 v[172:175], v148 offset:1024
	ds_read_b128 v[176:179], v148 offset:2048
	ds_read_b128 v[180:183], v148 offset:3072
	s_add_i32 s59, s42, 2
	s_add_u32 s60, s40, 0x80
	s_addc_u32 s43, s41, 0
	s_cmp_eq_u32 s44, s42
	s_cselect_b32 s42, s12, s60
	s_cselect_b32 s43, s13, s43
	s_cselect_b32 s61, s39, s25
	s_cselect_b32 s60, s38, s24
	s_mov_b32 m0, s46
	v_lshl_add_u64 v[216:217], s[40:41], 0, v[136:137]
	ds_read_b128 v[184:187], v149
	ds_read_b128 v[188:191], v149 offset:1024
	ds_read_b128 v[192:195], v149 offset:2048
	ds_read_b128 v[196:199], v149 offset:3072
	ds_read_b128 v[200:203], v149 offset:4096
	ds_read_b128 v[204:207], v149 offset:5120
	ds_read_b128 v[208:211], v149 offset:6144
	ds_read_b128 v[212:215], v149 offset:7168
	global_load_lds_dwordx4 v[216:217], off
	v_lshl_add_u64 v[216:217], s[40:41], 0, v[138:139]
	s_mov_b32 m0, s47
	s_nop 0
	global_load_lds_dwordx4 v[216:217], off
	s_waitcnt vmcnt(8)
	s_waitcnt lgkmcnt(0)
	s_barrier
	s_setprio 1
	s_waitcnt lgkmcnt(0)
	v_mfma_f32_16x16x32_bf16 v[120:123], v[152:155], v[184:187], 0
	v_mfma_f32_16x16x32_bf16 v[116:119], v[160:163], v[184:187], 0
	v_mfma_f32_16x16x32_bf16 v[108:111], v[152:155], v[192:195], 0
	v_mfma_f32_16x16x32_bf16 v[100:103], v[160:163], v[192:195], 0
	v_mfma_f32_16x16x32_bf16 v[92:95], v[152:155], v[200:203], 0
	v_mfma_f32_16x16x32_bf16 v[84:87], v[160:163], v[200:203], 0
	v_mfma_f32_16x16x32_bf16 v[76:79], v[152:155], v[208:211], 0
	v_mfma_f32_16x16x32_bf16 v[68:71], v[160:163], v[208:211], 0
	v_mfma_f32_16x16x32_bf16 v[120:123], v[156:159], v[188:191], v[120:123]
	v_mfma_f32_16x16x32_bf16 v[108:111], v[156:159], v[196:199], v[108:111]
	v_mfma_f32_16x16x32_bf16 v[92:95], v[156:159], v[204:207], v[92:95]
	v_mfma_f32_16x16x32_bf16 v[76:79], v[156:159], v[212:215], v[76:79]
	v_mfma_f32_16x16x32_bf16 v[68:71], v[164:167], v[212:215], v[68:71]
	v_mfma_f32_16x16x32_bf16 v[84:87], v[164:167], v[204:207], v[84:87]
	v_mfma_f32_16x16x32_bf16 v[100:103], v[164:167], v[196:199], v[100:103]
	v_mfma_f32_16x16x32_bf16 v[116:119], v[164:167], v[188:191], v[116:119]
	s_setprio 0
	s_setprio 1
	v_mfma_f32_16x16x32_bf16 v[124:127], v[168:171], v[184:187], 0
	v_mfma_f32_16x16x32_bf16 v[112:115], v[176:179], v[184:187], 0
	v_mfma_f32_16x16x32_bf16 v[104:107], v[168:171], v[192:195], 0
	v_mfma_f32_16x16x32_bf16 v[96:99], v[176:179], v[192:195], 0
	v_mfma_f32_16x16x32_bf16 v[88:91], v[168:171], v[200:203], 0
	v_mfma_f32_16x16x32_bf16 v[80:83], v[176:179], v[200:203], 0
	v_mfma_f32_16x16x32_bf16 v[72:75], v[168:171], v[208:211], 0
	v_mfma_f32_16x16x32_bf16 v[64:67], v[176:179], v[208:211], 0
	v_mfma_f32_16x16x32_bf16 v[124:127], v[172:175], v[188:191], v[124:127]
	v_mfma_f32_16x16x32_bf16 v[104:107], v[172:175], v[196:199], v[104:107]
	v_mfma_f32_16x16x32_bf16 v[88:91], v[172:175], v[204:207], v[88:91]
	v_mfma_f32_16x16x32_bf16 v[72:75], v[172:175], v[212:215], v[72:75]
	v_mfma_f32_16x16x32_bf16 v[64:67], v[180:183], v[212:215], v[64:67]
	v_mfma_f32_16x16x32_bf16 v[80:83], v[180:183], v[204:207], v[80:83]
	v_mfma_f32_16x16x32_bf16 v[96:99], v[180:183], v[196:199], v[96:99]
	v_mfma_f32_16x16x32_bf16 v[112:115], v[180:183], v[188:191], v[112:115]
	s_setprio 0
	s_barrier
	s_mov_b32 m0, s48
	v_lshl_add_u64 v[216:217], s[60:61], 0, v[132:133]
	v_lshl_add_u64 v[218:219], s[60:61], 0, v[128:129]
	s_add_u32 s60, s60, s14
	ds_read_b128 v[184:187], v149 offset:16384
	ds_read_b128 v[188:191], v149 offset:17408
	ds_read_b128 v[192:195], v149 offset:18432
	ds_read_b128 v[196:199], v149 offset:19456
	ds_read_b128 v[200:203], v149 offset:20480
	ds_read_b128 v[204:207], v149 offset:21504
	ds_read_b128 v[208:211], v149 offset:22528
	ds_read_b128 v[212:215], v149 offset:23552
	global_load_lds_dwordx4 v[216:217], off
	s_mov_b32 m0, s49
	s_addc_u32 s61, s61, s15
	global_load_lds_dwordx4 v[218:219], off
	v_lshl_add_u64 v[220:221], s[60:61], 0, v[132:133]
	s_mov_b32 m0, s50
	v_lshl_add_u64 v[222:223], s[60:61], 0, v[128:129]
	global_load_lds_dwordx4 v[220:221], off
	s_mov_b32 m0, s51
	v_lshl_add_u64 v[224:225], s[42:43], 0, v[134:135]
	global_load_lds_dwordx4 v[222:223], off
	s_mov_b32 m0, s6
	v_lshl_add_u64 v[226:227], s[42:43], 0, v[130:131]
	global_load_lds_dwordx4 v[224:225], off
	s_mov_b32 m0, s7
	s_nop 0
	global_load_lds_dwordx4 v[226:227], off
	s_waitcnt vmcnt(8)
	s_waitcnt lgkmcnt(0)
	s_barrier
; #define PG8_STAGE(bufoff, gbase, voff) do { _Pragma("unroll") for (int _i = 0; _i < 2; ++_i) \
;         __builtin_amdgcn_global_load_lds((const unsigned*)((const char*)(gbase) + (voff)[_i]), (PG8_LAS unsigned*)(lds + (bufoff) + ldsw + _i * 8192), 16, 0, 0); } while (0)
; #define PG8_LDA(dst, b, h) do { _Pragma("unroll") for (int m = 0; m < 4; ++m) _Pragma("unroll") for (int k = 0; k < 2; ++k) dst[m][k] = *(const PG8_LAS bf16x8*)(lds + PG8_SA(b, h) + aoff + m * 2048 + k * 1024); } while (0)
; #define PG8_LDB(dst, b, h) do { _Pragma("unroll") for (int n = 0; n < 2; ++n) _Pragma("unroll") for (int k = 0; k < 2; ++k) dst[n][k] = *(const PG8_LAS bf16x8*)(lds + PG8_SB(b, h) + boff + n * 2048 + k * 1024); } while (0)
; #define PG8_MMA(ai, bj, At, Bt) do { __builtin_amdgcn_s_setprio(1); _Pragma("unroll") for (int m = 0; m < 4; ++m) _Pragma("unroll") for (int n = 0; n < 2; ++n) _Pragma("unroll") for (int k = 0; k < 2; ++k) \
;         acc[ai][bj][m][n] = __builtin_amdgcn_mfma_f32_16x16x32_bf16(Bt[n][k], At[m][k], acc[ai][bj][m][n], 0, 0, 0); __builtin_amdgcn_s_setprio(0); } while (0)
; #define PG8_WAIT_V(n) asm volatile("s_waitcnt vmcnt(" #n ")" ::: "memory")
; #define PG8_WAIT_L(n) asm volatile("s_waitcnt lgkmcnt(" #n ")" ::: "memory")
; #define PG8_BAR __builtin_amdgcn_s_barrier()
; #define PG8_SCHED __builtin_amdgcn_sched_barrier(0)
; template <class Epi, class Sched, bool ALIGN_EPI = false, bool SP2 = false>
; __device__ __forceinline__ void gemm_phase(PG8_LAS unsigned char* lds, const Gemm g, const Sched& S, const Epi& E) {
;     ...
;             PG8_WAIT_V(8); PG8_WAIT_L(0); PG8_BAR; PG8_MMA(1, 0, At, B0); PG8_MMA(1, 1, At, B1); PG8_BAR; PG8_SCHED;
;             PG8_LDB(B0, 1, 0); PG8_LDB(B1, 1, 1); PG8_SCHED; PG8_LDA(At, 1, 0); PG8_STAGE(PG8_SA(0, 1), a2 + hstep, voffA);
;             PG8_WAIT_V(8); PG8_WAIT_L(0); PG8_BAR; PG8_MMA(0, 0, At, B0); PG8_MMA(0, 1, At, B1); PG8_BAR; PG8_SCHED;
	s_setprio 1
	s_waitcnt lgkmcnt(0)
	v_mfma_f32_16x16x32_bf16 v[60:63], v[152:155], v[184:187], 0
	v_mfma_f32_16x16x32_bf16 v[52:55], v[160:163], v[184:187], 0
	v_mfma_f32_16x16x32_bf16 v[44:47], v[152:155], v[192:195], 0
	v_mfma_f32_16x16x32_bf16 v[36:39], v[160:163], v[192:195], 0
	v_mfma_f32_16x16x32_bf16 v[28:31], v[152:155], v[200:203], 0
	v_mfma_f32_16x16x32_bf16 v[20:23], v[160:163], v[200:203], 0
	v_mfma_f32_16x16x32_bf16 v[12:15], v[152:155], v[208:211], 0
	v_mfma_f32_16x16x32_bf16 v[4:7], v[160:163], v[208:211], 0
	v_mfma_f32_16x16x32_bf16 v[60:63], v[156:159], v[188:191], v[60:63]
	v_mfma_f32_16x16x32_bf16 v[44:47], v[156:159], v[196:199], v[44:47]
	v_mfma_f32_16x16x32_bf16 v[28:31], v[156:159], v[204:207], v[28:31]
	v_mfma_f32_16x16x32_bf16 v[12:15], v[156:159], v[212:215], v[12:15]
	v_mfma_f32_16x16x32_bf16 v[4:7], v[164:167], v[212:215], v[4:7]
	v_mfma_f32_16x16x32_bf16 v[20:23], v[164:167], v[204:207], v[20:23]
	v_mfma_f32_16x16x32_bf16 v[36:39], v[164:167], v[196:199], v[36:39]
	v_mfma_f32_16x16x32_bf16 v[52:55], v[164:167], v[188:191], v[52:55]
	s_setprio 0
	s_setprio 1
	v_mfma_f32_16x16x32_bf16 v[56:59], v[168:171], v[184:187], 0
	v_mfma_f32_16x16x32_bf16 v[48:51], v[176:179], v[184:187], 0
	v_mfma_f32_16x16x32_bf16 v[40:43], v[168:171], v[192:195], 0
	v_mfma_f32_16x16x32_bf16 v[32:35], v[176:179], v[192:195], 0
	v_mfma_f32_16x16x32_bf16 v[24:27], v[168:171], v[200:203], 0
	v_mfma_f32_16x16x32_bf16 v[16:19], v[176:179], v[200:203], 0
	v_mfma_f32_16x16x32_bf16 v[8:11], v[168:171], v[208:211], 0
	v_mfma_f32_16x16x32_bf16 v[0:3], v[176:179], v[208:211], 0
	v_mfma_f32_16x16x32_bf16 v[56:59], v[172:175], v[188:191], v[56:59]
	v_mfma_f32_16x16x32_bf16 v[40:43], v[172:175], v[196:199], v[40:43]
	v_mfma_f32_16x16x32_bf16 v[24:27], v[172:175], v[204:207], v[24:27]
	v_mfma_f32_16x16x32_bf16 v[8:11], v[172:175], v[212:215], v[8:11]
	v_mfma_f32_16x16x32_bf16 v[0:3], v[180:183], v[212:215], v[0:3]
	v_mfma_f32_16x16x32_bf16 v[16:19], v[180:183], v[204:207], v[16:19]
	v_mfma_f32_16x16x32_bf16 v[32:35], v[180:183], v[196:199], v[32:35]
	v_mfma_f32_16x16x32_bf16 v[48:51], v[180:183], v[188:191], v[48:51]
	s_setprio 0
	s_barrier
	ds_read_b128 v[152:155], v150
	ds_read_b128 v[156:159], v150 offset:1024
	ds_read_b128 v[160:163], v150 offset:2048
	ds_read_b128 v[164:167], v150 offset:3072
	ds_read_b128 v[168:171], v151
	ds_read_b128 v[172:175], v151 offset:1024
	ds_read_b128 v[176:179], v151 offset:2048
	ds_read_b128 v[180:183], v151 offset:3072
	s_add_u32 s42, s42, s14
	s_addc_u32 s43, s43, s15
	s_mov_b32 m0, s18
	v_lshl_add_u64 v[228:229], s[42:43], 0, v[134:135]
	ds_read_b128 v[184:187], v149 offset:32768
	ds_read_b128 v[188:191], v149 offset:33792
	ds_read_b128 v[192:195], v149 offset:34816
	ds_read_b128 v[196:199], v149 offset:35840
	ds_read_b128 v[200:203], v149 offset:36864
	ds_read_b128 v[204:207], v149 offset:37888
	ds_read_b128 v[208:211], v149 offset:38912
	ds_read_b128 v[212:215], v149 offset:39936
	global_load_lds_dwordx4 v[228:229], off
	v_lshl_add_u64 v[228:229], s[42:43], 0, v[130:131]
	s_mov_b32 m0, s19
	s_nop 0
	global_load_lds_dwordx4 v[228:229], off
	s_waitcnt vmcnt(8)
	s_waitcnt lgkmcnt(0)
	s_barrier
	s_setprio 1
	s_waitcnt lgkmcnt(0)
	v_mfma_f32_16x16x32_bf16 v[120:123], v[152:155], v[184:187], v[120:123]
	v_mfma_f32_16x16x32_bf16 v[108:111], v[152:155], v[192:195], v[108:111]
	v_mfma_f32_16x16x32_bf16 v[92:95], v[152:155], v[200:203], v[92:95]
	v_mfma_f32_16x16x32_bf16 v[76:79], v[152:155], v[208:211], v[76:79]
	v_mfma_f32_16x16x32_bf16 v[68:71], v[160:163], v[208:211], v[68:71]
	v_mfma_f32_16x16x32_bf16 v[84:87], v[160:163], v[200:203], v[84:87]
	v_mfma_f32_16x16x32_bf16 v[100:103], v[160:163], v[192:195], v[100:103]
	v_mfma_f32_16x16x32_bf16 v[116:119], v[160:163], v[184:187], v[116:119]
	v_mfma_f32_16x16x32_bf16 v[120:123], v[156:159], v[188:191], v[120:123]
	v_mfma_f32_16x16x32_bf16 v[108:111], v[156:159], v[196:199], v[108:111]
	v_mfma_f32_16x16x32_bf16 v[92:95], v[156:159], v[204:207], v[92:95]
	v_mfma_f32_16x16x32_bf16 v[76:79], v[156:159], v[212:215], v[76:79]
	v_mfma_f32_16x16x32_bf16 v[68:71], v[164:167], v[212:215], v[68:71]
	v_mfma_f32_16x16x32_bf16 v[84:87], v[164:167], v[204:207], v[84:87]
	v_mfma_f32_16x16x32_bf16 v[100:103], v[164:167], v[196:199], v[100:103]
	v_mfma_f32_16x16x32_bf16 v[116:119], v[164:167], v[188:191], v[116:119]
	s_setprio 0
	s_setprio 1
	v_mfma_f32_16x16x32_bf16 v[124:127], v[168:171], v[184:187], v[124:127]
	v_mfma_f32_16x16x32_bf16 v[104:107], v[168:171], v[192:195], v[104:107]
	v_mfma_f32_16x16x32_bf16 v[88:91], v[168:171], v[200:203], v[88:91]
	v_mfma_f32_16x16x32_bf16 v[72:75], v[168:171], v[208:211], v[72:75]
	v_mfma_f32_16x16x32_bf16 v[64:67], v[176:179], v[208:211], v[64:67]
	v_mfma_f32_16x16x32_bf16 v[80:83], v[176:179], v[200:203], v[80:83]
	v_mfma_f32_16x16x32_bf16 v[96:99], v[176:179], v[192:195], v[96:99]
	v_mfma_f32_16x16x32_bf16 v[112:115], v[176:179], v[184:187], v[112:115]
	v_mfma_f32_16x16x32_bf16 v[124:127], v[172:175], v[188:191], v[124:127]
	v_mfma_f32_16x16x32_bf16 v[104:107], v[172:175], v[196:199], v[104:107]
	v_mfma_f32_16x16x32_bf16 v[88:91], v[172:175], v[204:207], v[88:91]
	v_mfma_f32_16x16x32_bf16 v[72:75], v[172:175], v[212:215], v[72:75]
	v_mfma_f32_16x16x32_bf16 v[64:67], v[180:183], v[212:215], v[64:67]
	v_mfma_f32_16x16x32_bf16 v[80:83], v[180:183], v[204:207], v[80:83]
	v_mfma_f32_16x16x32_bf16 v[96:99], v[180:183], v[196:199], v[96:99]
	v_mfma_f32_16x16x32_bf16 v[112:115], v[180:183], v[188:191], v[112:115]
	s_setprio 0
	s_barrier
; #define PG8_STAGE(bufoff, gbase, voff) do { _Pragma("unroll") for (int _i = 0; _i < 2; ++_i) \
;         __builtin_amdgcn_global_load_lds((const unsigned*)((const char*)(gbase) + (voff)[_i]), (PG8_LAS unsigned*)(lds + (bufoff) + ldsw + _i * 8192), 16, 0, 0); } while (0)
; #define PG8_LDA(dst, b, h) do { _Pragma("unroll") for (int m = 0; m < 4; ++m) _Pragma("unroll") for (int k = 0; k < 2; ++k) dst[m][k] = *(const PG8_LAS bf16x8*)(lds + PG8_SA(b, h) + aoff + m * 2048 + k * 1024); } while (0)
; #define PG8_LDB(dst, b, h) do { _Pragma("unroll") for (int n = 0; n < 2; ++n) _Pragma("unroll") for (int k = 0; k < 2; ++k) dst[n][k] = *(const PG8_LAS bf16x8*)(lds + PG8_SB(b, h) + boff + n * 2048 + k * 1024); } while (0)
; #define PG8_MMA(ai, bj, At, Bt) do { __builtin_amdgcn_s_setprio(1); _Pragma("unroll") for (int m = 0; m < 4; ++m) _Pragma("unroll") for (int n = 0; n < 2; ++n) _Pragma("unroll") for (int k = 0; k < 2; ++k) \
;         acc[ai][bj][m][n] = __builtin_amdgcn_mfma_f32_16x16x32_bf16(Bt[n][k], At[m][k], acc[ai][bj][m][n], 0, 0, 0); __builtin_amdgcn_s_setprio(0); } while (0)
; #define PG8_WAIT_V(n) asm volatile("s_waitcnt vmcnt(" #n ")" ::: "memory")
; #define PG8_WAIT_L(n) asm volatile("s_waitcnt lgkmcnt(" #n ")" ::: "memory")
; #define PG8_BAR __builtin_amdgcn_s_barrier()
; #define PG8_SCHED __builtin_amdgcn_sched_barrier(0)
; template <class Epi, class Sched, bool ALIGN_EPI = false, bool SP2 = false>
; __device__ __forceinline__ void gemm_phase(PG8_LAS unsigned char* lds, const Gemm g, const Sched& S, const Epi& E) {
;     ...
;             PG8_LDB(B0, 0, 0); PG8_LDB(B1, 0, 1); PG8_SCHED; PG8_LDA(At, 0, 0); PG8_STAGE(PG8_SA(1, 1), a1 + hstep, voffA);
;             PG8_WAIT_V(8); PG8_WAIT_L(0); PG8_BAR; PG8_MMA(0, 0, At, B0); PG8_MMA(0, 1, At, B1); PG8_BAR; PG8_SCHED;
;             PG8_LDA(At, 0, 1); PG8_STAGE(PG8_SB(0, 0), b2, voffB); PG8_STAGE(PG8_SB(0, 1), b2 + hstep, voffB); PG8_STAGE(PG8_SA(0, 0), a2, voffA);
;     ...
;             PG8_LDA(At, 1, 1); PG8_STAGE(PG8_SB(1, 0), b3, voffB); PG8_STAGE(PG8_SB(1, 1), b3 + hstep, voffB); PG8_STAGE(PG8_SA(1, 0), a3, voffA);
;             PG8_WAIT_V(8); PG8_WAIT_L(0); PG8_BAR; PG8_MMA(1, 0, At, B0); PG8_MMA(1, 1, At, B1); PG8_BAR; PG8_SCHED;
	s_mov_b32 m0, s53
	v_lshl_add_u64 v[216:217], v[216:217], 0, s[34:35]
	ds_read_b128 v[184:187], v149 offset:49152
	ds_read_b128 v[188:191], v149 offset:50176
	ds_read_b128 v[192:195], v149 offset:51200
	ds_read_b128 v[196:199], v149 offset:52224
	ds_read_b128 v[200:203], v149 offset:53248
	ds_read_b128 v[204:207], v149 offset:54272
	ds_read_b128 v[208:211], v149 offset:55296
	ds_read_b128 v[212:215], v149 offset:56320
	global_load_lds_dwordx4 v[216:217], off
	v_lshl_add_u64 v[216:217], v[218:219], 0, s[34:35]
	s_add_i32 m0, s53, 0x2000
	s_add_i32 s42, s52, s2
	global_load_lds_dwordx4 v[216:217], off
	v_lshl_add_u64 v[216:217], v[220:221], 0, s[34:35]
	s_mov_b32 m0, s42
	s_nop 0
	global_load_lds_dwordx4 v[216:217], off
	v_lshl_add_u64 v[216:217], v[222:223], 0, s[34:35]
	s_add_i32 m0, s42, 0x2000
	s_nop 0
	global_load_lds_dwordx4 v[216:217], off
	v_lshl_add_u64 v[216:217], v[224:225], 0, s[34:35]
	s_mov_b32 m0, s26
	s_nop 0
	global_load_lds_dwordx4 v[216:217], off
	v_lshl_add_u64 v[216:217], v[226:227], 0, s[34:35]
	s_mov_b32 m0, s27
	s_nop 0
	global_load_lds_dwordx4 v[216:217], off
	s_waitcnt vmcnt(8)
	s_waitcnt lgkmcnt(0)
	s_barrier
	s_setprio 1
	s_waitcnt lgkmcnt(0)
	v_mfma_f32_16x16x32_bf16 v[60:63], v[152:155], v[184:187], v[60:63]
	v_mfma_f32_16x16x32_bf16 v[44:47], v[152:155], v[192:195], v[44:47]
	v_mfma_f32_16x16x32_bf16 v[28:31], v[152:155], v[200:203], v[28:31]
	v_mfma_f32_16x16x32_bf16 v[12:15], v[152:155], v[208:211], v[12:15]
	v_mfma_f32_16x16x32_bf16 v[4:7], v[160:163], v[208:211], v[4:7]
	v_mfma_f32_16x16x32_bf16 v[20:23], v[160:163], v[200:203], v[20:23]
	v_mfma_f32_16x16x32_bf16 v[36:39], v[160:163], v[192:195], v[36:39]
	v_mfma_f32_16x16x32_bf16 v[52:55], v[160:163], v[184:187], v[52:55]
	v_mfma_f32_16x16x32_bf16 v[60:63], v[156:159], v[188:191], v[60:63]
	v_mfma_f32_16x16x32_bf16 v[44:47], v[156:159], v[196:199], v[44:47]
	v_mfma_f32_16x16x32_bf16 v[28:31], v[156:159], v[204:207], v[28:31]
	v_mfma_f32_16x16x32_bf16 v[12:15], v[156:159], v[212:215], v[12:15]
	v_mfma_f32_16x16x32_bf16 v[4:7], v[164:167], v[212:215], v[4:7]
	v_mfma_f32_16x16x32_bf16 v[20:23], v[164:167], v[204:207], v[20:23]
	v_mfma_f32_16x16x32_bf16 v[36:39], v[164:167], v[196:199], v[36:39]
	v_mfma_f32_16x16x32_bf16 v[52:55], v[164:167], v[188:191], v[52:55]
	s_setprio 0
	s_setprio 1
	v_mfma_f32_16x16x32_bf16 v[56:59], v[168:171], v[184:187], v[56:59]
	v_mfma_f32_16x16x32_bf16 v[40:43], v[168:171], v[192:195], v[40:43]
	v_mfma_f32_16x16x32_bf16 v[24:27], v[168:171], v[200:203], v[24:27]
	v_mfma_f32_16x16x32_bf16 v[8:11], v[168:171], v[208:211], v[8:11]
	v_mfma_f32_16x16x32_bf16 v[0:3], v[176:179], v[208:211], v[0:3]
	v_mfma_f32_16x16x32_bf16 v[16:19], v[176:179], v[200:203], v[16:19]
	v_mfma_f32_16x16x32_bf16 v[32:35], v[176:179], v[192:195], v[32:35]
	v_mfma_f32_16x16x32_bf16 v[48:51], v[176:179], v[184:187], v[48:51]
	v_mfma_f32_16x16x32_bf16 v[56:59], v[172:175], v[188:191], v[56:59]
	v_mfma_f32_16x16x32_bf16 v[40:43], v[172:175], v[196:199], v[40:43]
	v_mfma_f32_16x16x32_bf16 v[24:27], v[172:175], v[204:207], v[24:27]
	v_mfma_f32_16x16x32_bf16 v[8:11], v[172:175], v[212:215], v[8:11]
	v_mfma_f32_16x16x32_bf16 v[0:3], v[180:183], v[212:215], v[0:3]
	v_mfma_f32_16x16x32_bf16 v[16:19], v[180:183], v[204:207], v[16:19]
	v_mfma_f32_16x16x32_bf16 v[32:35], v[180:183], v[196:199], v[32:35]
	v_mfma_f32_16x16x32_bf16 v[48:51], v[180:183], v[188:191], v[48:51]
	s_setprio 0
	s_barrier
	s_add_u32 s40, s40, 0x100
	s_addc_u32 s41, s41, 0
	s_add_u32 s24, s24, 0x100
	s_addc_u32 s25, s25, 0
	s_cmp_ge_i32 s59, s33
	s_mov_b32 s42, s59
	s_cbranch_scc1 .Lpeelx_13
.LBB0_2579:
	ds_read_b128 v[152:155], v147
	ds_read_b128 v[156:159], v147 offset:1024
	ds_read_b128 v[160:163], v147 offset:2048
	ds_read_b128 v[164:167], v147 offset:3072
	ds_read_b128 v[168:171], v148
	ds_read_b128 v[172:175], v148 offset:1024
	ds_read_b128 v[176:179], v148 offset:2048
	ds_read_b128 v[180:183], v148 offset:3072
	s_add_i32 s59, s42, 2
	s_add_u32 s60, s40, 0x80
	s_addc_u32 s43, s41, 0
	s_cmp_eq_u32 s44, s42
	s_cselect_b32 s42, s12, s60
	s_cselect_b32 s43, s13, s43
	s_cselect_b32 s61, s39, s25
	s_cselect_b32 s60, s38, s24
	s_mov_b32 m0, s46
	v_lshl_add_u64 v[216:217], s[40:41], 0, v[136:137]
	ds_read_b128 v[184:187], v149
	ds_read_b128 v[188:191], v149 offset:1024
	ds_read_b128 v[192:195], v149 offset:2048
	ds_read_b128 v[196:199], v149 offset:3072
	ds_read_b128 v[200:203], v149 offset:4096
	ds_read_b128 v[204:207], v149 offset:5120
	ds_read_b128 v[208:211], v149 offset:6144
	ds_read_b128 v[212:215], v149 offset:7168
	global_load_lds_dwordx4 v[216:217], off
	v_lshl_add_u64 v[216:217], s[40:41], 0, v[138:139]
	s_mov_b32 m0, s47
	s_nop 0
	global_load_lds_dwordx4 v[216:217], off
	s_waitcnt vmcnt(8)
	s_waitcnt lgkmcnt(0)
	s_barrier
; #define PG8_STAGE(bufoff, gbase, voff) do { _Pragma("unroll") for (int _i = 0; _i < 2; ++_i) \
;         __builtin_amdgcn_global_load_lds((const unsigned*)((const char*)(gbase) + (voff)[_i]), (PG8_LAS unsigned*)(lds + (bufoff) + ldsw + _i * 8192), 16, 0, 0); } while (0)
; #define PG8_LDA(dst, b, h) do { _Pragma("unroll") for (int m = 0; m < 4; ++m) _Pragma("unroll") for (int k = 0; k < 2; ++k) dst[m][k] = *(const PG8_LAS bf16x8*)(lds + PG8_SA(b, h) + aoff + m * 2048 + k * 1024); } while (0)
; #define PG8_MMA(ai, bj, At, Bt) do { __builtin_amdgcn_s_setprio(1); _Pragma("unroll") for (int m = 0; m < 4; ++m) _Pragma("unroll") for (int n = 0; n < 2; ++n) _Pragma("unroll") for (int k = 0; k < 2; ++k) \
;         acc[ai][bj][m][n] = __builtin_amdgcn_mfma_f32_16x16x32_bf16(Bt[n][k], At[m][k], acc[ai][bj][m][n], 0, 0, 0); __builtin_amdgcn_s_setprio(0); } while (0)
; #define PG8_WAIT_V(n) asm volatile("s_waitcnt vmcnt(" #n ")" ::: "memory")
; #define PG8_WAIT_L(n) asm volatile("s_waitcnt lgkmcnt(" #n ")" ::: "memory")
; #define PG8_BAR __builtin_amdgcn_s_barrier()
; #define PG8_SCHED __builtin_amdgcn_sched_barrier(0)
; template <class Epi, class Sched, bool ALIGN_EPI = false, bool SP2 = false>
; __device__ __forceinline__ void gemm_phase(PG8_LAS unsigned char* lds, const Gemm g, const Sched& S, const Epi& E) {
;     ...
;             PG8_WAIT_V(8); PG8_WAIT_L(0); PG8_BAR; PG8_MMA(0, 0, At, B0); PG8_MMA(0, 1, At, B1); PG8_BAR; PG8_SCHED;
;             PG8_LDA(At, 0, 1); PG8_STAGE(PG8_SB(0, 0), b2, voffB); PG8_STAGE(PG8_SB(0, 1), b2 + hstep, voffB); PG8_STAGE(PG8_SA(0, 0), a2, voffA);
;             PG8_WAIT_V(8); PG8_WAIT_L(0); PG8_BAR; PG8_MMA(1, 0, At, B0); PG8_MMA(1, 1, At, B1); PG8_BAR; PG8_SCHED;
	s_setprio 1
	s_waitcnt lgkmcnt(0)
	v_mfma_f32_16x16x32_bf16 v[120:123], v[152:155], v[184:187], v[120:123]
	v_mfma_f32_16x16x32_bf16 v[108:111], v[152:155], v[192:195], v[108:111]
	v_mfma_f32_16x16x32_bf16 v[92:95], v[152:155], v[200:203], v[92:95]
	v_mfma_f32_16x16x32_bf16 v[76:79], v[152:155], v[208:211], v[76:79]
	v_mfma_f32_16x16x32_bf16 v[68:71], v[160:163], v[208:211], v[68:71]
	v_mfma_f32_16x16x32_bf16 v[84:87], v[160:163], v[200:203], v[84:87]
	v_mfma_f32_16x16x32_bf16 v[100:103], v[160:163], v[192:195], v[100:103]
	v_mfma_f32_16x16x32_bf16 v[116:119], v[160:163], v[184:187], v[116:119]
	v_mfma_f32_16x16x32_bf16 v[120:123], v[156:159], v[188:191], v[120:123]
	v_mfma_f32_16x16x32_bf16 v[108:111], v[156:159], v[196:199], v[108:111]
	v_mfma_f32_16x16x32_bf16 v[92:95], v[156:159], v[204:207], v[92:95]
	v_mfma_f32_16x16x32_bf16 v[76:79], v[156:159], v[212:215], v[76:79]
	v_mfma_f32_16x16x32_bf16 v[68:71], v[164:167], v[212:215], v[68:71]
	v_mfma_f32_16x16x32_bf16 v[84:87], v[164:167], v[204:207], v[84:87]
	v_mfma_f32_16x16x32_bf16 v[100:103], v[164:167], v[196:199], v[100:103]
	v_mfma_f32_16x16x32_bf16 v[116:119], v[164:167], v[188:191], v[116:119]
	s_setprio 0
	s_setprio 1
	v_mfma_f32_16x16x32_bf16 v[124:127], v[168:171], v[184:187], v[124:127]
	v_mfma_f32_16x16x32_bf16 v[104:107], v[168:171], v[192:195], v[104:107]
	v_mfma_f32_16x16x32_bf16 v[88:91], v[168:171], v[200:203], v[88:91]
	v_mfma_f32_16x16x32_bf16 v[72:75], v[168:171], v[208:211], v[72:75]
	v_mfma_f32_16x16x32_bf16 v[64:67], v[176:179], v[208:211], v[64:67]
	v_mfma_f32_16x16x32_bf16 v[80:83], v[176:179], v[200:203], v[80:83]
	v_mfma_f32_16x16x32_bf16 v[96:99], v[176:179], v[192:195], v[96:99]
	v_mfma_f32_16x16x32_bf16 v[112:115], v[176:179], v[184:187], v[112:115]
	v_mfma_f32_16x16x32_bf16 v[124:127], v[172:175], v[188:191], v[124:127]
	v_mfma_f32_16x16x32_bf16 v[104:107], v[172:175], v[196:199], v[104:107]
	v_mfma_f32_16x16x32_bf16 v[88:91], v[172:175], v[204:207], v[88:91]
	v_mfma_f32_16x16x32_bf16 v[72:75], v[172:175], v[212:215], v[72:75]
	v_mfma_f32_16x16x32_bf16 v[64:67], v[180:183], v[212:215], v[64:67]
	v_mfma_f32_16x16x32_bf16 v[80:83], v[180:183], v[204:207], v[80:83]
	v_mfma_f32_16x16x32_bf16 v[96:99], v[180:183], v[196:199], v[96:99]
	v_mfma_f32_16x16x32_bf16 v[112:115], v[180:183], v[188:191], v[112:115]
	s_setprio 0
	s_barrier
	s_mov_b32 m0, s48
	v_lshl_add_u64 v[216:217], s[60:61], 0, v[132:133]
	v_lshl_add_u64 v[218:219], s[60:61], 0, v[128:129]
	s_add_u32 s60, s60, s14
	ds_read_b128 v[184:187], v149 offset:16384
	ds_read_b128 v[188:191], v149 offset:17408
	ds_read_b128 v[192:195], v149 offset:18432
	ds_read_b128 v[196:199], v149 offset:19456
	ds_read_b128 v[200:203], v149 offset:20480
	ds_read_b128 v[204:207], v149 offset:21504
	ds_read_b128 v[208:211], v149 offset:22528
	ds_read_b128 v[212:215], v149 offset:23552
	global_load_lds_dwordx4 v[216:217], off
	s_mov_b32 m0, s49
	s_addc_u32 s61, s61, s15
	global_load_lds_dwordx4 v[218:219], off
	v_lshl_add_u64 v[220:221], s[60:61], 0, v[132:133]
	s_mov_b32 m0, s50
	v_lshl_add_u64 v[222:223], s[60:61], 0, v[128:129]
	global_load_lds_dwordx4 v[220:221], off
	s_mov_b32 m0, s51
	v_lshl_add_u64 v[224:225], s[42:43], 0, v[134:135]
	global_load_lds_dwordx4 v[222:223], off
	s_mov_b32 m0, s6
	v_lshl_add_u64 v[226:227], s[42:43], 0, v[130:131]
	global_load_lds_dwordx4 v[224:225], off
	s_mov_b32 m0, s7
	s_nop 0
	global_load_lds_dwordx4 v[226:227], off
	s_waitcnt vmcnt(8)
	s_waitcnt lgkmcnt(0)
	s_barrier
	s_setprio 1
	s_waitcnt lgkmcnt(0)
	v_mfma_f32_16x16x32_bf16 v[60:63], v[152:155], v[184:187], v[60:63]
	v_mfma_f32_16x16x32_bf16 v[44:47], v[152:155], v[192:195], v[44:47]
	v_mfma_f32_16x16x32_bf16 v[28:31], v[152:155], v[200:203], v[28:31]
	v_mfma_f32_16x16x32_bf16 v[12:15], v[152:155], v[208:211], v[12:15]
	v_mfma_f32_16x16x32_bf16 v[4:7], v[160:163], v[208:211], v[4:7]
	v_mfma_f32_16x16x32_bf16 v[20:23], v[160:163], v[200:203], v[20:23]
	v_mfma_f32_16x16x32_bf16 v[36:39], v[160:163], v[192:195], v[36:39]
	v_mfma_f32_16x16x32_bf16 v[52:55], v[160:163], v[184:187], v[52:55]
	v_mfma_f32_16x16x32_bf16 v[60:63], v[156:159], v[188:191], v[60:63]
	v_mfma_f32_16x16x32_bf16 v[44:47], v[156:159], v[196:199], v[44:47]
	v_mfma_f32_16x16x32_bf16 v[28:31], v[156:159], v[204:207], v[28:31]
	v_mfma_f32_16x16x32_bf16 v[12:15], v[156:159], v[212:215], v[12:15]
	v_mfma_f32_16x16x32_bf16 v[4:7], v[164:167], v[212:215], v[4:7]
	v_mfma_f32_16x16x32_bf16 v[20:23], v[164:167], v[204:207], v[20:23]
	v_mfma_f32_16x16x32_bf16 v[36:39], v[164:167], v[196:199], v[36:39]
	v_mfma_f32_16x16x32_bf16 v[52:55], v[164:167], v[188:191], v[52:55]
	s_setprio 0
	s_setprio 1
	v_mfma_f32_16x16x32_bf16 v[56:59], v[168:171], v[184:187], v[56:59]
	v_mfma_f32_16x16x32_bf16 v[40:43], v[168:171], v[192:195], v[40:43]
	v_mfma_f32_16x16x32_bf16 v[24:27], v[168:171], v[200:203], v[24:27]
	v_mfma_f32_16x16x32_bf16 v[8:11], v[168:171], v[208:211], v[8:11]
	v_mfma_f32_16x16x32_bf16 v[0:3], v[176:179], v[208:211], v[0:3]
	v_mfma_f32_16x16x32_bf16 v[16:19], v[176:179], v[200:203], v[16:19]
	v_mfma_f32_16x16x32_bf16 v[32:35], v[176:179], v[192:195], v[32:35]
	v_mfma_f32_16x16x32_bf16 v[48:51], v[176:179], v[184:187], v[48:51]
	v_mfma_f32_16x16x32_bf16 v[56:59], v[172:175], v[188:191], v[56:59]
	v_mfma_f32_16x16x32_bf16 v[40:43], v[172:175], v[196:199], v[40:43]
	v_mfma_f32_16x16x32_bf16 v[24:27], v[172:175], v[204:207], v[24:27]
	v_mfma_f32_16x16x32_bf16 v[8:11], v[172:175], v[212:215], v[8:11]
	v_mfma_f32_16x16x32_bf16 v[0:3], v[180:183], v[212:215], v[0:3]
	v_mfma_f32_16x16x32_bf16 v[16:19], v[180:183], v[204:207], v[16:19]
	v_mfma_f32_16x16x32_bf16 v[32:35], v[180:183], v[196:199], v[32:35]
	v_mfma_f32_16x16x32_bf16 v[48:51], v[180:183], v[188:191], v[48:51]
	s_setprio 0
	s_barrier
; #define PG8_STAGE(bufoff, gbase, voff) do { _Pragma("unroll") for (int _i = 0; _i < 2; ++_i) \
;         __builtin_amdgcn_global_load_lds((const unsigned*)((const char*)(gbase) + (voff)[_i]), (PG8_LAS unsigned*)(lds + (bufoff) + ldsw + _i * 8192), 16, 0, 0); } while (0)
; #define PG8_LDA(dst, b, h) do { _Pragma("unroll") for (int m = 0; m < 4; ++m) _Pragma("unroll") for (int k = 0; k < 2; ++k) dst[m][k] = *(const PG8_LAS bf16x8*)(lds + PG8_SA(b, h) + aoff + m * 2048 + k * 1024); } while (0)
; #define PG8_LDB(dst, b, h) do { _Pragma("unroll") for (int n = 0; n < 2; ++n) _Pragma("unroll") for (int k = 0; k < 2; ++k) dst[n][k] = *(const PG8_LAS bf16x8*)(lds + PG8_SB(b, h) + boff + n * 2048 + k * 1024); } while (0)
; #define PG8_MMA(ai, bj, At, Bt) do { __builtin_amdgcn_s_setprio(1); _Pragma("unroll") for (int m = 0; m < 4; ++m) _Pragma("unroll") for (int n = 0; n < 2; ++n) _Pragma("unroll") for (int k = 0; k < 2; ++k) \
;         acc[ai][bj][m][n] = __builtin_amdgcn_mfma_f32_16x16x32_bf16(Bt[n][k], At[m][k], acc[ai][bj][m][n], 0, 0, 0); __builtin_amdgcn_s_setprio(0); } while (0)
; #define PG8_WAIT_V(n) asm volatile("s_waitcnt vmcnt(" #n ")" ::: "memory")
; #define PG8_WAIT_L(n) asm volatile("s_waitcnt lgkmcnt(" #n ")" ::: "memory")
; #define PG8_BAR __builtin_amdgcn_s_barrier()
; #define PG8_SCHED __builtin_amdgcn_sched_barrier(0)
; template <class Epi, class Sched, bool ALIGN_EPI = false, bool SP2 = false>
; __device__ __forceinline__ void gemm_phase(PG8_LAS unsigned char* lds, const Gemm g, const Sched& S, const Epi& E) {
;     ...
;             PG8_LDB(B0, 1, 0); PG8_LDB(B1, 1, 1); PG8_SCHED; PG8_LDA(At, 1, 0); PG8_STAGE(PG8_SA(0, 1), a2 + hstep, voffA);
;             PG8_WAIT_V(8); PG8_WAIT_L(0); PG8_BAR; PG8_MMA(0, 0, At, B0); PG8_MMA(0, 1, At, B1); PG8_BAR; PG8_SCHED;
;             PG8_LDA(At, 1, 1); PG8_STAGE(PG8_SB(1, 0), b3, voffB); PG8_STAGE(PG8_SB(1, 1), b3 + hstep, voffB); PG8_STAGE(PG8_SA(1, 0), a3, voffA);
;             PG8_WAIT_V(8); PG8_WAIT_L(0); PG8_BAR; PG8_MMA(1, 0, At, B0); PG8_MMA(1, 1, At, B1); PG8_BAR; PG8_SCHED;
	ds_read_b128 v[152:155], v150
	ds_read_b128 v[156:159], v150 offset:1024
	ds_read_b128 v[160:163], v150 offset:2048
	ds_read_b128 v[164:167], v150 offset:3072
	ds_read_b128 v[168:171], v151
	ds_read_b128 v[172:175], v151 offset:1024
	ds_read_b128 v[176:179], v151 offset:2048
	ds_read_b128 v[180:183], v151 offset:3072
	s_add_u32 s42, s42, s14
	s_addc_u32 s43, s43, s15
	s_mov_b32 m0, s18
	v_lshl_add_u64 v[228:229], s[42:43], 0, v[134:135]
	ds_read_b128 v[184:187], v149 offset:32768
	ds_read_b128 v[188:191], v149 offset:33792
	ds_read_b128 v[192:195], v149 offset:34816
	ds_read_b128 v[196:199], v149 offset:35840
	ds_read_b128 v[200:203], v149 offset:36864
	ds_read_b128 v[204:207], v149 offset:37888
	ds_read_b128 v[208:211], v149 offset:38912
	ds_read_b128 v[212:215], v149 offset:39936
	global_load_lds_dwordx4 v[228:229], off
	v_lshl_add_u64 v[228:229], s[42:43], 0, v[130:131]
	s_mov_b32 m0, s19
	s_nop 0
	global_load_lds_dwordx4 v[228:229], off
	s_waitcnt vmcnt(8)
	s_waitcnt lgkmcnt(0)
	s_barrier
	s_setprio 1
	s_waitcnt lgkmcnt(0)
	v_mfma_f32_16x16x32_bf16 v[120:123], v[152:155], v[184:187], v[120:123]
	v_mfma_f32_16x16x32_bf16 v[108:111], v[152:155], v[192:195], v[108:111]
	v_mfma_f32_16x16x32_bf16 v[92:95], v[152:155], v[200:203], v[92:95]
	v_mfma_f32_16x16x32_bf16 v[76:79], v[152:155], v[208:211], v[76:79]
	v_mfma_f32_16x16x32_bf16 v[68:71], v[160:163], v[208:211], v[68:71]
	v_mfma_f32_16x16x32_bf16 v[84:87], v[160:163], v[200:203], v[84:87]
	v_mfma_f32_16x16x32_bf16 v[100:103], v[160:163], v[192:195], v[100:103]
	v_mfma_f32_16x16x32_bf16 v[116:119], v[160:163], v[184:187], v[116:119]
	v_mfma_f32_16x16x32_bf16 v[120:123], v[156:159], v[188:191], v[120:123]
	v_mfma_f32_16x16x32_bf16 v[108:111], v[156:159], v[196:199], v[108:111]
	v_mfma_f32_16x16x32_bf16 v[92:95], v[156:159], v[204:207], v[92:95]
	v_mfma_f32_16x16x32_bf16 v[76:79], v[156:159], v[212:215], v[76:79]
	v_mfma_f32_16x16x32_bf16 v[68:71], v[164:167], v[212:215], v[68:71]
	v_mfma_f32_16x16x32_bf16 v[84:87], v[164:167], v[204:207], v[84:87]
	v_mfma_f32_16x16x32_bf16 v[100:103], v[164:167], v[196:199], v[100:103]
	v_mfma_f32_16x16x32_bf16 v[116:119], v[164:167], v[188:191], v[116:119]
	s_setprio 0
	s_setprio 1
	v_mfma_f32_16x16x32_bf16 v[124:127], v[168:171], v[184:187], v[124:127]
	v_mfma_f32_16x16x32_bf16 v[104:107], v[168:171], v[192:195], v[104:107]
	v_mfma_f32_16x16x32_bf16 v[88:91], v[168:171], v[200:203], v[88:91]
	v_mfma_f32_16x16x32_bf16 v[72:75], v[168:171], v[208:211], v[72:75]
	v_mfma_f32_16x16x32_bf16 v[64:67], v[176:179], v[208:211], v[64:67]
	v_mfma_f32_16x16x32_bf16 v[80:83], v[176:179], v[200:203], v[80:83]
	v_mfma_f32_16x16x32_bf16 v[96:99], v[176:179], v[192:195], v[96:99]
	v_mfma_f32_16x16x32_bf16 v[112:115], v[176:179], v[184:187], v[112:115]
	v_mfma_f32_16x16x32_bf16 v[124:127], v[172:175], v[188:191], v[124:127]
	v_mfma_f32_16x16x32_bf16 v[104:107], v[172:175], v[196:199], v[104:107]
	v_mfma_f32_16x16x32_bf16 v[88:91], v[172:175], v[204:207], v[88:91]
	v_mfma_f32_16x16x32_bf16 v[72:75], v[172:175], v[212:215], v[72:75]
	v_mfma_f32_16x16x32_bf16 v[64:67], v[180:183], v[212:215], v[64:67]
	v_mfma_f32_16x16x32_bf16 v[80:83], v[180:183], v[204:207], v[80:83]
	v_mfma_f32_16x16x32_bf16 v[96:99], v[180:183], v[196:199], v[96:99]
	v_mfma_f32_16x16x32_bf16 v[112:115], v[180:183], v[188:191], v[112:115]
	s_setprio 0
	s_barrier
	s_mov_b32 m0, s53
	v_lshl_add_u64 v[216:217], v[216:217], 0, s[34:35]
	ds_read_b128 v[184:187], v149 offset:49152
	ds_read_b128 v[188:191], v149 offset:50176
	ds_read_b128 v[192:195], v149 offset:51200
	ds_read_b128 v[196:199], v149 offset:52224
	ds_read_b128 v[200:203], v149 offset:53248
	ds_read_b128 v[204:207], v149 offset:54272
	ds_read_b128 v[208:211], v149 offset:55296
	ds_read_b128 v[212:215], v149 offset:56320
	global_load_lds_dwordx4 v[216:217], off
	v_lshl_add_u64 v[216:217], v[218:219], 0, s[34:35]
	s_add_i32 m0, s53, 0x2000
	s_add_i32 s42, s52, s2
	global_load_lds_dwordx4 v[216:217], off
	v_lshl_add_u64 v[216:217], v[220:221], 0, s[34:35]
	s_mov_b32 m0, s42
	s_nop 0
	global_load_lds_dwordx4 v[216:217], off
	v_lshl_add_u64 v[216:217], v[222:223], 0, s[34:35]
	s_add_i32 m0, s42, 0x2000
	s_nop 0
	global_load_lds_dwordx4 v[216:217], off
	v_lshl_add_u64 v[216:217], v[224:225], 0, s[34:35]
	s_mov_b32 m0, s26
	s_nop 0
	global_load_lds_dwordx4 v[216:217], off
	v_lshl_add_u64 v[216:217], v[226:227], 0, s[34:35]
	s_mov_b32 m0, s27
	s_nop 0
	global_load_lds_dwordx4 v[216:217], off
	s_waitcnt vmcnt(8)
	s_waitcnt lgkmcnt(0)
	s_barrier
	s_setprio 1
	s_waitcnt lgkmcnt(0)
	v_mfma_f32_16x16x32_bf16 v[60:63], v[152:155], v[184:187], v[60:63]
	v_mfma_f32_16x16x32_bf16 v[44:47], v[152:155], v[192:195], v[44:47]
	v_mfma_f32_16x16x32_bf16 v[28:31], v[152:155], v[200:203], v[28:31]
	v_mfma_f32_16x16x32_bf16 v[12:15], v[152:155], v[208:211], v[12:15]
	v_mfma_f32_16x16x32_bf16 v[4:7], v[160:163], v[208:211], v[4:7]
	v_mfma_f32_16x16x32_bf16 v[20:23], v[160:163], v[200:203], v[20:23]
	v_mfma_f32_16x16x32_bf16 v[36:39], v[160:163], v[192:195], v[36:39]
	v_mfma_f32_16x16x32_bf16 v[52:55], v[160:163], v[184:187], v[52:55]
	v_mfma_f32_16x16x32_bf16 v[60:63], v[156:159], v[188:191], v[60:63]
	v_mfma_f32_16x16x32_bf16 v[44:47], v[156:159], v[196:199], v[44:47]
	v_mfma_f32_16x16x32_bf16 v[28:31], v[156:159], v[204:207], v[28:31]
	v_mfma_f32_16x16x32_bf16 v[12:15], v[156:159], v[212:215], v[12:15]
	v_mfma_f32_16x16x32_bf16 v[4:7], v[164:167], v[212:215], v[4:7]
	v_mfma_f32_16x16x32_bf16 v[20:23], v[164:167], v[204:207], v[20:23]
	v_mfma_f32_16x16x32_bf16 v[36:39], v[164:167], v[196:199], v[36:39]
	v_mfma_f32_16x16x32_bf16 v[52:55], v[164:167], v[188:191], v[52:55]
	s_setprio 0
	s_setprio 1
	v_mfma_f32_16x16x32_bf16 v[56:59], v[168:171], v[184:187], v[56:59]
	v_mfma_f32_16x16x32_bf16 v[40:43], v[168:171], v[192:195], v[40:43]
	v_mfma_f32_16x16x32_bf16 v[24:27], v[168:171], v[200:203], v[24:27]
	v_mfma_f32_16x16x32_bf16 v[8:11], v[168:171], v[208:211], v[8:11]
	v_mfma_f32_16x16x32_bf16 v[0:3], v[176:179], v[208:211], v[0:3]
	v_mfma_f32_16x16x32_bf16 v[16:19], v[176:179], v[200:203], v[16:19]
	v_mfma_f32_16x16x32_bf16 v[32:35], v[176:179], v[192:195], v[32:35]
	v_mfma_f32_16x16x32_bf16 v[48:51], v[176:179], v[184:187], v[48:51]
	v_mfma_f32_16x16x32_bf16 v[56:59], v[172:175], v[188:191], v[56:59]
	v_mfma_f32_16x16x32_bf16 v[40:43], v[172:175], v[196:199], v[40:43]
	v_mfma_f32_16x16x32_bf16 v[24:27], v[172:175], v[204:207], v[24:27]
	v_mfma_f32_16x16x32_bf16 v[8:11], v[172:175], v[212:215], v[8:11]
	v_mfma_f32_16x16x32_bf16 v[0:3], v[180:183], v[212:215], v[0:3]
	v_mfma_f32_16x16x32_bf16 v[16:19], v[180:183], v[204:207], v[16:19]
	v_mfma_f32_16x16x32_bf16 v[32:35], v[180:183], v[196:199], v[32:35]
	v_mfma_f32_16x16x32_bf16 v[48:51], v[180:183], v[188:191], v[48:51]
	s_setprio 0
	s_barrier
	s_add_u32 s40, s40, 0x100
	s_addc_u32 s41, s41, 0
	s_add_u32 s24, s24, 0x100
	s_addc_u32 s25, s25, 0
	s_cmp_ge_i32 s59, s33
	s_mov_b32 s42, s59
	s_cbranch_scc0 .LBB0_2579

; #define PG8_STAGE(bufoff, gbase, voff) do { _Pragma("unroll") for (int _i = 0; _i < 2; ++_i) \
;         __builtin_amdgcn_global_load_lds((const unsigned*)((const char*)(gbase) + (voff)[_i]), (PG8_LAS unsigned*)(lds + (bufoff) + ldsw + _i * 8192), 16, 0, 0); } while (0)
; #define PG8_LDA(dst, b, h) do { _Pragma("unroll") for (int m = 0; m < 4; ++m) _Pragma("unroll") for (int k = 0; k < 2; ++k) dst[m][k] = *(const PG8_LAS bf16x8*)(lds + PG8_SA(b, h) + aoff + m * 2048 + k * 1024); } while (0)
; #define PG8_LDB(dst, b, h) do { _Pragma("unroll") for (int n = 0; n < 2; ++n) _Pragma("unroll") for (int k = 0; k < 2; ++k) dst[n][k] = *(const PG8_LAS bf16x8*)(lds + PG8_SB(b, h) + boff + n * 2048 + k * 1024); } while (0)
; #define PG8_MMA(ai, bj, At, Bt) do { __builtin_amdgcn_s_setprio(1); _Pragma("unroll") for (int m = 0; m < 4; ++m) _Pragma("unroll") for (int n = 0; n < 2; ++n) _Pragma("unroll") for (int k = 0; k < 2; ++k) \
;         acc[ai][bj][m][n] = __builtin_amdgcn_mfma_f32_16x16x32_bf16(Bt[n][k], At[m][k], acc[ai][bj][m][n], 0, 0, 0); __builtin_amdgcn_s_setprio(0); } while (0)
; #define PG8_WAIT_V(n) asm volatile("s_waitcnt vmcnt(" #n ")" ::: "memory")
; #define PG8_WAIT_L(n) asm volatile("s_waitcnt lgkmcnt(" #n ")" ::: "memory")
; #define PG8_BAR __builtin_amdgcn_s_barrier()
; #define PG8_SCHED __builtin_amdgcn_sched_barrier(0)
; template <class Epi, class Sched, bool ALIGN_EPI = false, bool SP2 = false>
; __device__ __forceinline__ void gemm_phase(PG8_LAS unsigned char* lds, const Gemm g, const Sched& S, const Epi& E) {
;     ...
;             PG8_LDB(B0, 0, 0); PG8_LDB(B1, 0, 1); PG8_SCHED; PG8_LDA(At, 0, 0); PG8_STAGE(PG8_SA(1, 1), a1 + hstep, voffA);
;             PG8_WAIT_V(8); PG8_WAIT_L(0); PG8_BAR; PG8_MMA(0, 0, At, B0); PG8_MMA(0, 1, At, B1); PG8_BAR; PG8_SCHED;
;             PG8_LDA(At, 0, 1); PG8_STAGE(PG8_SB(0, 0), b2, voffB); PG8_STAGE(PG8_SB(0, 1), b2 + hstep, voffB); PG8_STAGE(PG8_SA(0, 0), a2, voffA);
.LBB0_2662:
	ds_read_b128 v[144:147], v240
	ds_read_b128 v[148:151], v240 offset:1024
	ds_read_b128 v[152:155], v240 offset:2048
	ds_read_b128 v[156:159], v240 offset:3072
	ds_read_b128 v[160:163], v241
	ds_read_b128 v[164:167], v241 offset:1024
	ds_read_b128 v[168:171], v241 offset:2048
	ds_read_b128 v[172:175], v241 offset:3072
	s_add_i32 s42, s25, 2
	s_add_u32 s40, s38, 0x80
	s_addc_u32 s41, s39, 0
	s_cmp_eq_u32 s54, s25
	s_cselect_b32 s41, s9, s41
	s_cselect_b32 s40, s8, s40
	s_cselect_b32 s63, s37, s24
	s_cselect_b32 s62, s36, s3
	v_lshl_add_u64 v[208:209], s[38:39], 0, v[136:137]
	s_add_i32 m0, s27, 0xc000
	ds_read_b128 v[176:179], v243
	ds_read_b128 v[180:183], v243 offset:1024
	ds_read_b128 v[184:187], v243 offset:2048
	ds_read_b128 v[188:191], v243 offset:3072
	ds_read_b128 v[192:195], v243 offset:4096
	ds_read_b128 v[196:199], v243 offset:5120
	ds_read_b128 v[200:203], v243 offset:6144
	ds_read_b128 v[204:207], v243 offset:7168
	global_load_lds_dwordx4 v[208:209], off
	v_lshl_add_u64 v[208:209], s[38:39], 0, v[138:139]
	s_add_i32 m0, s27, 0xe000
	s_nop 0
	global_load_lds_dwordx4 v[208:209], off
	s_waitcnt vmcnt(8)
	s_waitcnt lgkmcnt(0)
	s_barrier
	s_setprio 1
	s_waitcnt lgkmcnt(0)
	v_mfma_f32_16x16x32_bf16 v[124:127], v[144:147], v[176:179], v[124:127]
	v_mfma_f32_16x16x32_bf16 v[116:119], v[144:147], v[184:187], v[116:119]
	v_mfma_f32_16x16x32_bf16 v[104:107], v[144:147], v[192:195], v[104:107]
	v_mfma_f32_16x16x32_bf16 v[88:91], v[144:147], v[200:203], v[88:91]
	v_mfma_f32_16x16x32_bf16 v[80:83], v[152:155], v[200:203], v[80:83]
	v_mfma_f32_16x16x32_bf16 v[96:99], v[152:155], v[192:195], v[96:99]
	v_mfma_f32_16x16x32_bf16 v[112:115], v[152:155], v[184:187], v[112:115]
	v_mfma_f32_16x16x32_bf16 v[120:123], v[152:155], v[176:179], v[120:123]
	v_mfma_f32_16x16x32_bf16 v[124:127], v[148:151], v[180:183], v[124:127]
	v_mfma_f32_16x16x32_bf16 v[116:119], v[148:151], v[188:191], v[116:119]
	v_mfma_f32_16x16x32_bf16 v[104:107], v[148:151], v[196:199], v[104:107]
	v_mfma_f32_16x16x32_bf16 v[88:91], v[148:151], v[204:207], v[88:91]
	v_mfma_f32_16x16x32_bf16 v[80:83], v[156:159], v[204:207], v[80:83]
	v_mfma_f32_16x16x32_bf16 v[96:99], v[156:159], v[196:199], v[96:99]
	v_mfma_f32_16x16x32_bf16 v[112:115], v[156:159], v[188:191], v[112:115]
	v_mfma_f32_16x16x32_bf16 v[120:123], v[156:159], v[180:183], v[120:123]
	s_setprio 0
	s_setprio 1
	v_mfma_f32_16x16x32_bf16 v[108:111], v[160:163], v[176:179], v[108:111]
	v_mfma_f32_16x16x32_bf16 v[92:95], v[160:163], v[184:187], v[92:95]
	v_mfma_f32_16x16x32_bf16 v[76:79], v[160:163], v[192:195], v[76:79]
	v_mfma_f32_16x16x32_bf16 v[68:71], v[160:163], v[200:203], v[68:71]
	v_mfma_f32_16x16x32_bf16 v[64:67], v[168:171], v[200:203], v[64:67]
	v_mfma_f32_16x16x32_bf16 v[72:75], v[168:171], v[192:195], v[72:75]
	v_mfma_f32_16x16x32_bf16 v[84:87], v[168:171], v[184:187], v[84:87]
	v_mfma_f32_16x16x32_bf16 v[100:103], v[168:171], v[176:179], v[100:103]
	v_mfma_f32_16x16x32_bf16 v[108:111], v[164:167], v[180:183], v[108:111]
	v_mfma_f32_16x16x32_bf16 v[92:95], v[164:167], v[188:191], v[92:95]
	v_mfma_f32_16x16x32_bf16 v[76:79], v[164:167], v[196:199], v[76:79]
	v_mfma_f32_16x16x32_bf16 v[68:71], v[164:167], v[204:207], v[68:71]
	v_mfma_f32_16x16x32_bf16 v[64:67], v[172:175], v[204:207], v[64:67]
	v_mfma_f32_16x16x32_bf16 v[72:75], v[172:175], v[196:199], v[72:75]
	v_mfma_f32_16x16x32_bf16 v[84:87], v[172:175], v[188:191], v[84:87]
	v_mfma_f32_16x16x32_bf16 v[100:103], v[172:175], v[180:183], v[100:103]
	s_setprio 0
	s_barrier
	s_add_i32 s25, s56, s26
	v_lshl_add_u64 v[208:209], s[62:63], 0, v[130:131]
	s_mov_b32 m0, s25
	ds_read_b128 v[176:179], v243 offset:16384
	ds_read_b128 v[180:183], v243 offset:17408
	ds_read_b128 v[184:187], v243 offset:18432
	ds_read_b128 v[188:191], v243 offset:19456
	ds_read_b128 v[192:195], v243 offset:20480
	ds_read_b128 v[196:199], v243 offset:21504
	ds_read_b128 v[200:203], v243 offset:22528
	ds_read_b128 v[204:207], v243 offset:23552
	global_load_lds_dwordx4 v[208:209], off
	s_add_i32 m0, s25, 0x2000
	v_lshl_add_u64 v[210:211], s[62:63], 0, v[134:135]
	s_add_u32 s62, s62, s12
	s_addc_u32 s63, s63, s13
	s_add_i32 s25, s57, s26
	global_load_lds_dwordx4 v[210:211], off
	v_lshl_add_u64 v[212:213], s[62:63], 0, v[130:131]
	s_mov_b32 m0, s25
	v_lshl_add_u64 v[214:215], s[62:63], 0, v[134:135]
	global_load_lds_dwordx4 v[212:213], off
	s_add_i32 m0, s25, 0x2000
	v_lshl_add_u64 v[216:217], s[40:41], 0, v[128:129]
	global_load_lds_dwordx4 v[214:215], off
	s_mov_b32 m0, s27
	v_lshl_add_u64 v[218:219], s[40:41], 0, v[132:133]
	global_load_lds_dwordx4 v[216:217], off
	s_mov_b32 m0, s33
	s_nop 0
	global_load_lds_dwordx4 v[218:219], off
	s_waitcnt vmcnt(8)
	s_waitcnt lgkmcnt(0)
	s_barrier
; #define PG8_STAGE(bufoff, gbase, voff) do { _Pragma("unroll") for (int _i = 0; _i < 2; ++_i) \
;         __builtin_amdgcn_global_load_lds((const unsigned*)((const char*)(gbase) + (voff)[_i]), (PG8_LAS unsigned*)(lds + (bufoff) + ldsw + _i * 8192), 16, 0, 0); } while (0)
; #define PG8_LDA(dst, b, h) do { _Pragma("unroll") for (int m = 0; m < 4; ++m) _Pragma("unroll") for (int k = 0; k < 2; ++k) dst[m][k] = *(const PG8_LAS bf16x8*)(lds + PG8_SA(b, h) + aoff + m * 2048 + k * 1024); } while (0)
; #define PG8_LDB(dst, b, h) do { _Pragma("unroll") for (int n = 0; n < 2; ++n) _Pragma("unroll") for (int k = 0; k < 2; ++k) dst[n][k] = *(const PG8_LAS bf16x8*)(lds + PG8_SB(b, h) + boff + n * 2048 + k * 1024); } while (0)
; #define PG8_MMA(ai, bj, At, Bt) do { __builtin_amdgcn_s_setprio(1); _Pragma("unroll") for (int m = 0; m < 4; ++m) _Pragma("unroll") for (int n = 0; n < 2; ++n) _Pragma("unroll") for (int k = 0; k < 2; ++k) \
;         acc[ai][bj][m][n] = __builtin_amdgcn_mfma_f32_16x16x32_bf16(Bt[n][k], At[m][k], acc[ai][bj][m][n], 0, 0, 0); __builtin_amdgcn_s_setprio(0); } while (0)
; #define PG8_WAIT_V(n) asm volatile("s_waitcnt vmcnt(" #n ")" ::: "memory")
; #define PG8_WAIT_L(n) asm volatile("s_waitcnt lgkmcnt(" #n ")" ::: "memory")
; #define PG8_BAR __builtin_amdgcn_s_barrier()
; #define PG8_SCHED __builtin_amdgcn_sched_barrier(0)
; template <class Epi, class Sched, bool ALIGN_EPI = false, bool SP2 = false>
; __device__ __forceinline__ void gemm_phase(PG8_LAS unsigned char* lds, const Gemm g, const Sched& S, const Epi& E) {
;     ...
;             PG8_WAIT_V(8); PG8_WAIT_L(0); PG8_BAR; PG8_MMA(1, 0, At, B0); PG8_MMA(1, 1, At, B1); PG8_BAR; PG8_SCHED;
;             PG8_LDB(B0, 1, 0); PG8_LDB(B1, 1, 1); PG8_SCHED; PG8_LDA(At, 1, 0); PG8_STAGE(PG8_SA(0, 1), a2 + hstep, voffA);
;             PG8_WAIT_V(8); PG8_WAIT_L(0); PG8_BAR; PG8_MMA(0, 0, At, B0); PG8_MMA(0, 1, At, B1); PG8_BAR; PG8_SCHED;
	s_setprio 1
	s_waitcnt lgkmcnt(0)
	v_mfma_f32_16x16x32_bf16 v[60:63], v[144:147], v[176:179], v[60:63]
	v_mfma_f32_16x16x32_bf16 v[52:55], v[144:147], v[184:187], v[52:55]
	v_mfma_f32_16x16x32_bf16 v[40:43], v[144:147], v[192:195], v[40:43]
	v_mfma_f32_16x16x32_bf16 v[24:27], v[144:147], v[200:203], v[24:27]
	v_mfma_f32_16x16x32_bf16 v[16:19], v[152:155], v[200:203], v[16:19]
	v_mfma_f32_16x16x32_bf16 v[32:35], v[152:155], v[192:195], v[32:35]
	v_mfma_f32_16x16x32_bf16 v[48:51], v[152:155], v[184:187], v[48:51]
	v_mfma_f32_16x16x32_bf16 v[56:59], v[152:155], v[176:179], v[56:59]
	v_mfma_f32_16x16x32_bf16 v[60:63], v[148:151], v[180:183], v[60:63]
	v_mfma_f32_16x16x32_bf16 v[52:55], v[148:151], v[188:191], v[52:55]
	v_mfma_f32_16x16x32_bf16 v[40:43], v[148:151], v[196:199], v[40:43]
	v_mfma_f32_16x16x32_bf16 v[24:27], v[148:151], v[204:207], v[24:27]
	v_mfma_f32_16x16x32_bf16 v[16:19], v[156:159], v[204:207], v[16:19]
	v_mfma_f32_16x16x32_bf16 v[32:35], v[156:159], v[196:199], v[32:35]
	v_mfma_f32_16x16x32_bf16 v[48:51], v[156:159], v[188:191], v[48:51]
	v_mfma_f32_16x16x32_bf16 v[56:59], v[156:159], v[180:183], v[56:59]
	s_setprio 0
	s_setprio 1
	v_mfma_f32_16x16x32_bf16 v[44:47], v[160:163], v[176:179], v[44:47]
	v_mfma_f32_16x16x32_bf16 v[28:31], v[160:163], v[184:187], v[28:31]
	v_mfma_f32_16x16x32_bf16 v[12:15], v[160:163], v[192:195], v[12:15]
	v_mfma_f32_16x16x32_bf16 v[4:7], v[160:163], v[200:203], v[4:7]
	v_mfma_f32_16x16x32_bf16 v[0:3], v[168:171], v[200:203], v[0:3]
	v_mfma_f32_16x16x32_bf16 v[8:11], v[168:171], v[192:195], v[8:11]
	v_mfma_f32_16x16x32_bf16 v[20:23], v[168:171], v[184:187], v[20:23]
	v_mfma_f32_16x16x32_bf16 v[36:39], v[168:171], v[176:179], v[36:39]
	v_mfma_f32_16x16x32_bf16 v[44:47], v[164:167], v[180:183], v[44:47]
	v_mfma_f32_16x16x32_bf16 v[28:31], v[164:167], v[188:191], v[28:31]
	v_mfma_f32_16x16x32_bf16 v[12:15], v[164:167], v[196:199], v[12:15]
	v_mfma_f32_16x16x32_bf16 v[4:7], v[164:167], v[204:207], v[4:7]
	v_mfma_f32_16x16x32_bf16 v[0:3], v[172:175], v[204:207], v[0:3]
	v_mfma_f32_16x16x32_bf16 v[8:11], v[172:175], v[196:199], v[8:11]
	v_mfma_f32_16x16x32_bf16 v[20:23], v[172:175], v[188:191], v[20:23]
	v_mfma_f32_16x16x32_bf16 v[36:39], v[172:175], v[180:183], v[36:39]
	s_setprio 0
	s_barrier
	s_add_i32 s25, 0, 0x18000
	s_add_i32 s43, 0, 0x1c000
	v_add_u32_e32 v156, s25, v223
	v_add_u32_e32 v172, s43, v223
	ds_read_b128 v[144:147], v156
	ds_read_b128 v[148:151], v156 offset:1024
	ds_read_b128 v[152:155], v156 offset:2048
	ds_read_b128 v[156:159], v156 offset:3072
	ds_read_b128 v[160:163], v172
	ds_read_b128 v[164:167], v172 offset:1024
	ds_read_b128 v[168:171], v172 offset:2048
	ds_read_b128 v[172:175], v172 offset:3072
	s_add_u32 s40, s40, s12
	s_addc_u32 s41, s41, s13
	s_mov_b32 m0, s46
	v_lshl_add_u64 v[220:221], s[40:41], 0, v[128:129]
	ds_read_b128 v[176:179], v243 offset:32768
	ds_read_b128 v[180:183], v243 offset:33792
	ds_read_b128 v[184:187], v243 offset:34816
	ds_read_b128 v[188:191], v243 offset:35840
	ds_read_b128 v[192:195], v243 offset:36864
	ds_read_b128 v[196:199], v243 offset:37888
	ds_read_b128 v[200:203], v243 offset:38912
	ds_read_b128 v[204:207], v243 offset:39936
	global_load_lds_dwordx4 v[220:221], off
	v_lshl_add_u64 v[220:221], s[40:41], 0, v[132:133]
	s_mov_b32 m0, s47
	s_nop 0
	global_load_lds_dwordx4 v[220:221], off
	s_waitcnt vmcnt(8)
	s_waitcnt lgkmcnt(0)
	s_barrier
	s_setprio 1
	s_waitcnt lgkmcnt(0)
	v_mfma_f32_16x16x32_bf16 v[124:127], v[144:147], v[176:179], v[124:127]
	v_mfma_f32_16x16x32_bf16 v[116:119], v[144:147], v[184:187], v[116:119]
	v_mfma_f32_16x16x32_bf16 v[104:107], v[144:147], v[192:195], v[104:107]
	v_mfma_f32_16x16x32_bf16 v[88:91], v[144:147], v[200:203], v[88:91]
	v_mfma_f32_16x16x32_bf16 v[80:83], v[152:155], v[200:203], v[80:83]
	v_mfma_f32_16x16x32_bf16 v[96:99], v[152:155], v[192:195], v[96:99]
	v_mfma_f32_16x16x32_bf16 v[112:115], v[152:155], v[184:187], v[112:115]
	v_mfma_f32_16x16x32_bf16 v[120:123], v[152:155], v[176:179], v[120:123]
	v_mfma_f32_16x16x32_bf16 v[124:127], v[148:151], v[180:183], v[124:127]
	v_mfma_f32_16x16x32_bf16 v[116:119], v[148:151], v[188:191], v[116:119]
	v_mfma_f32_16x16x32_bf16 v[104:107], v[148:151], v[196:199], v[104:107]
	v_mfma_f32_16x16x32_bf16 v[88:91], v[148:151], v[204:207], v[88:91]
	v_mfma_f32_16x16x32_bf16 v[80:83], v[156:159], v[204:207], v[80:83]
	v_mfma_f32_16x16x32_bf16 v[96:99], v[156:159], v[196:199], v[96:99]
	v_mfma_f32_16x16x32_bf16 v[112:115], v[156:159], v[188:191], v[112:115]
	v_mfma_f32_16x16x32_bf16 v[120:123], v[156:159], v[180:183], v[120:123]
	s_setprio 0
	s_setprio 1
	v_mfma_f32_16x16x32_bf16 v[108:111], v[160:163], v[176:179], v[108:111]
	v_mfma_f32_16x16x32_bf16 v[92:95], v[160:163], v[184:187], v[92:95]
	v_mfma_f32_16x16x32_bf16 v[76:79], v[160:163], v[192:195], v[76:79]
	v_mfma_f32_16x16x32_bf16 v[68:71], v[160:163], v[200:203], v[68:71]
	v_mfma_f32_16x16x32_bf16 v[64:67], v[168:171], v[200:203], v[64:67]
	v_mfma_f32_16x16x32_bf16 v[72:75], v[168:171], v[192:195], v[72:75]
	v_mfma_f32_16x16x32_bf16 v[84:87], v[168:171], v[184:187], v[84:87]
	v_mfma_f32_16x16x32_bf16 v[100:103], v[168:171], v[176:179], v[100:103]
	v_mfma_f32_16x16x32_bf16 v[108:111], v[164:167], v[180:183], v[108:111]
	v_mfma_f32_16x16x32_bf16 v[92:95], v[164:167], v[188:191], v[92:95]
	v_mfma_f32_16x16x32_bf16 v[76:79], v[164:167], v[196:199], v[76:79]
	v_mfma_f32_16x16x32_bf16 v[68:71], v[164:167], v[204:207], v[68:71]
	v_mfma_f32_16x16x32_bf16 v[64:67], v[172:175], v[204:207], v[64:67]
	v_mfma_f32_16x16x32_bf16 v[72:75], v[172:175], v[196:199], v[72:75]
	v_mfma_f32_16x16x32_bf16 v[84:87], v[172:175], v[188:191], v[84:87]
	v_mfma_f32_16x16x32_bf16 v[100:103], v[172:175], v[180:183], v[100:103]
	s_setprio 0
	s_barrier
; #define PG8_STAGE(bufoff, gbase, voff) do { _Pragma("unroll") for (int _i = 0; _i < 2; ++_i) \
;         __builtin_amdgcn_global_load_lds((const unsigned*)((const char*)(gbase) + (voff)[_i]), (PG8_LAS unsigned*)(lds + (bufoff) + ldsw + _i * 8192), 16, 0, 0); } while (0)
; #define PG8_LDA(dst, b, h) do { _Pragma("unroll") for (int m = 0; m < 4; ++m) _Pragma("unroll") for (int k = 0; k < 2; ++k) dst[m][k] = *(const PG8_LAS bf16x8*)(lds + PG8_SA(b, h) + aoff + m * 2048 + k * 1024); } while (0)
; #define PG8_MMA(ai, bj, At, Bt) do { __builtin_amdgcn_s_setprio(1); _Pragma("unroll") for (int m = 0; m < 4; ++m) _Pragma("unroll") for (int n = 0; n < 2; ++n) _Pragma("unroll") for (int k = 0; k < 2; ++k) \
;         acc[ai][bj][m][n] = __builtin_amdgcn_mfma_f32_16x16x32_bf16(Bt[n][k], At[m][k], acc[ai][bj][m][n], 0, 0, 0); __builtin_amdgcn_s_setprio(0); } while (0)
; #define PG8_WAIT_V(n) asm volatile("s_waitcnt vmcnt(" #n ")" ::: "memory")
; #define PG8_WAIT_L(n) asm volatile("s_waitcnt lgkmcnt(" #n ")" ::: "memory")
; #define PG8_BAR __builtin_amdgcn_s_barrier()
; #define PG8_SCHED __builtin_amdgcn_sched_barrier(0)
; template <class Epi, class Sched, bool ALIGN_EPI = false, bool SP2 = false>
; __device__ __forceinline__ void gemm_phase(PG8_LAS unsigned char* lds, const Gemm g, const Sched& S, const Epi& E) {
;     ...
;             PG8_LDA(At, 1, 1); PG8_STAGE(PG8_SB(1, 0), b3, voffB); PG8_STAGE(PG8_SB(1, 1), b3 + hstep, voffB); PG8_STAGE(PG8_SA(1, 0), a3, voffA);
;             PG8_WAIT_V(8); PG8_WAIT_L(0); PG8_BAR; PG8_MMA(1, 0, At, B0); PG8_MMA(1, 1, At, B1); PG8_BAR; PG8_SCHED;
	s_add_i32 s25, s25, s26
	v_lshl_add_u64 v[208:209], v[208:209], 0, s[22:23]
	s_mov_b32 m0, s25
	ds_read_b128 v[176:179], v243 offset:49152
	ds_read_b128 v[180:183], v243 offset:50176
	ds_read_b128 v[184:187], v243 offset:51200
	ds_read_b128 v[188:191], v243 offset:52224
	ds_read_b128 v[192:195], v243 offset:53248
	ds_read_b128 v[196:199], v243 offset:54272
	ds_read_b128 v[200:203], v243 offset:55296
	ds_read_b128 v[204:207], v243 offset:56320
	global_load_lds_dwordx4 v[208:209], off
	v_lshl_add_u64 v[208:209], v[210:211], 0, s[22:23]
	s_add_i32 m0, s25, 0x2000
	s_add_i32 s25, s43, s26
	global_load_lds_dwordx4 v[208:209], off
	v_lshl_add_u64 v[208:209], v[212:213], 0, s[22:23]
	s_mov_b32 m0, s25
	s_nop 0
	global_load_lds_dwordx4 v[208:209], off
	v_lshl_add_u64 v[208:209], v[214:215], 0, s[22:23]
	s_add_i32 m0, s25, 0x2000
	s_nop 0
	global_load_lds_dwordx4 v[208:209], off
	v_lshl_add_u64 v[208:209], v[216:217], 0, s[22:23]
	s_mov_b32 m0, s50
	s_nop 0
	global_load_lds_dwordx4 v[208:209], off
	v_lshl_add_u64 v[208:209], v[218:219], 0, s[22:23]
	s_mov_b32 m0, s51
	s_nop 0
	global_load_lds_dwordx4 v[208:209], off
	s_waitcnt vmcnt(8)
	s_waitcnt lgkmcnt(0)
	s_barrier
	s_setprio 1
	s_waitcnt lgkmcnt(0)
	v_mfma_f32_16x16x32_bf16 v[60:63], v[144:147], v[176:179], v[60:63]
	v_mfma_f32_16x16x32_bf16 v[52:55], v[144:147], v[184:187], v[52:55]
	v_mfma_f32_16x16x32_bf16 v[40:43], v[144:147], v[192:195], v[40:43]
	v_mfma_f32_16x16x32_bf16 v[24:27], v[144:147], v[200:203], v[24:27]
	v_mfma_f32_16x16x32_bf16 v[16:19], v[152:155], v[200:203], v[16:19]
	v_mfma_f32_16x16x32_bf16 v[32:35], v[152:155], v[192:195], v[32:35]
	v_mfma_f32_16x16x32_bf16 v[48:51], v[152:155], v[184:187], v[48:51]
	v_mfma_f32_16x16x32_bf16 v[56:59], v[152:155], v[176:179], v[56:59]
	v_mfma_f32_16x16x32_bf16 v[60:63], v[148:151], v[180:183], v[60:63]
	v_mfma_f32_16x16x32_bf16 v[52:55], v[148:151], v[188:191], v[52:55]
	v_mfma_f32_16x16x32_bf16 v[40:43], v[148:151], v[196:199], v[40:43]
	v_mfma_f32_16x16x32_bf16 v[24:27], v[148:151], v[204:207], v[24:27]
	v_mfma_f32_16x16x32_bf16 v[16:19], v[156:159], v[204:207], v[16:19]
	v_mfma_f32_16x16x32_bf16 v[32:35], v[156:159], v[196:199], v[32:35]
	v_mfma_f32_16x16x32_bf16 v[48:51], v[156:159], v[188:191], v[48:51]
	v_mfma_f32_16x16x32_bf16 v[56:59], v[156:159], v[180:183], v[56:59]
	s_setprio 0
	s_setprio 1
	v_mfma_f32_16x16x32_bf16 v[44:47], v[160:163], v[176:179], v[44:47]
	v_mfma_f32_16x16x32_bf16 v[28:31], v[160:163], v[184:187], v[28:31]
	v_mfma_f32_16x16x32_bf16 v[12:15], v[160:163], v[192:195], v[12:15]
	v_mfma_f32_16x16x32_bf16 v[4:7], v[160:163], v[200:203], v[4:7]
	v_mfma_f32_16x16x32_bf16 v[0:3], v[168:171], v[200:203], v[0:3]
	v_mfma_f32_16x16x32_bf16 v[8:11], v[168:171], v[192:195], v[8:11]
	v_mfma_f32_16x16x32_bf16 v[20:23], v[168:171], v[184:187], v[20:23]
	v_mfma_f32_16x16x32_bf16 v[36:39], v[168:171], v[176:179], v[36:39]
	v_mfma_f32_16x16x32_bf16 v[44:47], v[164:167], v[180:183], v[44:47]
	v_mfma_f32_16x16x32_bf16 v[28:31], v[164:167], v[188:191], v[28:31]
	v_mfma_f32_16x16x32_bf16 v[12:15], v[164:167], v[196:199], v[12:15]
	v_mfma_f32_16x16x32_bf16 v[4:7], v[164:167], v[204:207], v[4:7]
	v_mfma_f32_16x16x32_bf16 v[0:3], v[172:175], v[204:207], v[0:3]
	v_mfma_f32_16x16x32_bf16 v[8:11], v[172:175], v[196:199], v[8:11]
	v_mfma_f32_16x16x32_bf16 v[20:23], v[172:175], v[188:191], v[20:23]
	v_mfma_f32_16x16x32_bf16 v[36:39], v[172:175], v[180:183], v[36:39]
	s_setprio 0
	s_barrier
	s_add_u32 s38, s38, 0x100
	s_addc_u32 s39, s39, 0
	s_add_u32 s3, s3, 0x100
	s_addc_u32 s24, s24, 0
	s_cmp_ge_i32 s42, s53
	s_mov_b32 s25, s42
	s_cbranch_scc0 .LBB0_2662
;     __device__ __forceinline__ void operator()(const f32x4 (&acc)[2][2][4][2], const Unit& u, int wr, int wc, int fr, int fq) const {
;     ...
;                     v0 = v0 + acc[ai][bj][m][0] * scale; v1 = v1 + acc[ai][bj][m][1] * scale;
	v_pk_mul_f32 v[200:201], v[126:127], 0.5 op_sel_hi:[1,0]
	v_pk_mul_f32 v[202:203], v[124:125], 0.5 op_sel_hi:[1,0]
	v_pk_mul_f32 v[204:205], v[122:123], 0.5 op_sel_hi:[1,0]
	v_pk_mul_f32 v[206:207], v[120:121], 0.5 op_sel_hi:[1,0]
	v_pk_mul_f32 v[214:215], v[110:111], 0.5 op_sel_hi:[1,0]
	v_pk_mul_f32 v[212:213], v[108:109], 0.5 op_sel_hi:[1,0]
	v_pk_mul_f32 v[210:211], v[102:103], 0.5 op_sel_hi:[1,0]
	v_pk_mul_f32 v[208:209], v[100:101], 0.5 op_sel_hi:[1,0]
	v_pk_mul_f32 v[198:199], v[118:119], 0.5 op_sel_hi:[1,0]
	v_pk_mul_f32 v[196:197], v[116:117], 0.5 op_sel_hi:[1,0]
	v_pk_mul_f32 v[194:195], v[114:115], 0.5 op_sel_hi:[1,0]
	v_pk_mul_f32 v[192:193], v[112:113], 0.5 op_sel_hi:[1,0]
	v_pk_mul_f32 v[190:191], v[94:95], 0.5 op_sel_hi:[1,0]
	v_pk_mul_f32 v[188:189], v[92:93], 0.5 op_sel_hi:[1,0]
	v_pk_mul_f32 v[186:187], v[86:87], 0.5 op_sel_hi:[1,0]
	v_pk_mul_f32 v[184:185], v[84:85], 0.5 op_sel_hi:[1,0]
	v_pk_mul_f32 v[182:183], v[106:107], 0.5 op_sel_hi:[1,0]
	v_pk_mul_f32 v[180:181], v[104:105], 0.5 op_sel_hi:[1,0]
	v_pk_mul_f32 v[178:179], v[98:99], 0.5 op_sel_hi:[1,0]
	v_pk_mul_f32 v[176:177], v[96:97], 0.5 op_sel_hi:[1,0]
	v_pk_mul_f32 v[174:175], v[78:79], 0.5 op_sel_hi:[1,0]
	v_pk_mul_f32 v[172:173], v[76:77], 0.5 op_sel_hi:[1,0]
	v_pk_mul_f32 v[86:87], v[74:75], 0.5 op_sel_hi:[1,0]
	v_pk_mul_f32 v[84:85], v[72:73], 0.5 op_sel_hi:[1,0]
	v_pk_mul_f32 v[98:99], v[90:91], 0.5 op_sel_hi:[1,0]
	v_pk_mul_f32 v[96:97], v[88:89], 0.5 op_sel_hi:[1,0]
	v_pk_mul_f32 v[94:95], v[82:83], 0.5 op_sel_hi:[1,0]
	v_pk_mul_f32 v[92:93], v[80:81], 0.5 op_sel_hi:[1,0]
	v_pk_mul_f32 v[122:123], v[70:71], 0.5 op_sel_hi:[1,0]
	v_pk_mul_f32 v[120:121], v[68:69], 0.5 op_sel_hi:[1,0]
	v_pk_mul_f32 v[118:119], v[66:67], 0.5 op_sel_hi:[1,0]
	v_pk_mul_f32 v[116:117], v[64:65], 0.5 op_sel_hi:[1,0]
	v_pk_mul_f32 v[156:157], v[62:63], 0.5 op_sel_hi:[1,0]
	v_pk_mul_f32 v[158:159], v[60:61], 0.5 op_sel_hi:[1,0]
	v_pk_mul_f32 v[160:161], v[58:59], 0.5 op_sel_hi:[1,0]
	v_pk_mul_f32 v[162:163], v[56:57], 0.5 op_sel_hi:[1,0]
	v_pk_mul_f32 v[170:171], v[46:47], 0.5 op_sel_hi:[1,0]
	v_pk_mul_f32 v[168:169], v[44:45], 0.5 op_sel_hi:[1,0]
	v_pk_mul_f32 v[166:167], v[38:39], 0.5 op_sel_hi:[1,0]
	v_pk_mul_f32 v[164:165], v[36:37], 0.5 op_sel_hi:[1,0]
	v_pk_mul_f32 v[154:155], v[54:55], 0.5 op_sel_hi:[1,0]
	v_pk_mul_f32 v[152:153], v[52:53], 0.5 op_sel_hi:[1,0]
	v_pk_mul_f32 v[150:151], v[50:51], 0.5 op_sel_hi:[1,0]
	v_pk_mul_f32 v[148:149], v[48:49], 0.5 op_sel_hi:[1,0]
	v_pk_mul_f32 v[146:147], v[30:31], 0.5 op_sel_hi:[1,0]
	v_pk_mul_f32 v[144:145], v[28:29], 0.5 op_sel_hi:[1,0]
	v_pk_mul_f32 v[126:127], v[22:23], 0.5 op_sel_hi:[1,0]
	v_pk_mul_f32 v[124:125], v[20:21], 0.5 op_sel_hi:[1,0]
	v_pk_mul_f32 v[114:115], v[42:43], 0.5 op_sel_hi:[1,0]
	v_pk_mul_f32 v[112:113], v[40:41], 0.5 op_sel_hi:[1,0]
	v_pk_mul_f32 v[110:111], v[34:35], 0.5 op_sel_hi:[1,0]
	v_pk_mul_f32 v[108:109], v[32:33], 0.5 op_sel_hi:[1,0]
	v_pk_mul_f32 v[106:107], v[14:15], 0.5 op_sel_hi:[1,0]
	v_pk_mul_f32 v[104:105], v[12:13], 0.5 op_sel_hi:[1,0]
	v_pk_mul_f32 v[102:103], v[10:11], 0.5 op_sel_hi:[1,0]
	v_pk_mul_f32 v[100:101], v[8:9], 0.5 op_sel_hi:[1,0]
	v_pk_mul_f32 v[78:79], v[26:27], 0.5 op_sel_hi:[1,0]
	v_pk_mul_f32 v[76:77], v[24:25], 0.5 op_sel_hi:[1,0]
	v_pk_mul_f32 v[74:75], v[18:19], 0.5 op_sel_hi:[1,0]
	v_pk_mul_f32 v[72:73], v[16:17], 0.5 op_sel_hi:[1,0]
	v_pk_mul_f32 v[62:63], v[6:7], 0.5 op_sel_hi:[1,0]
	v_pk_mul_f32 v[60:61], v[4:5], 0.5 op_sel_hi:[1,0]
	v_pk_mul_f32 v[58:59], v[2:3], 0.5 op_sel_hi:[1,0]
	v_pk_mul_f32 v[56:57], v[0:1], 0.5 op_sel_hi:[1,0]
